# 144 scalar re-loads of the workspace pointer (kernarg+0x108) replaced by s_mov_b64 from s[86:87], which holds it since entry
# baseline (speedup 1.0000x reference)
; #define LAS __attribute__((address_space(3)))
; __device__ __forceinline__ void xpose_item(const float* W, int ldw, int c0, int K, int ncols, bf16* WT, int d0, int mode, int sel, LAS float* scr, int item, int lane) {
;     const int nblk = ncols >> 5, kb = item / nblk, nb = item - kb * nblk, k0 = 64 * kb, n0 = 32 * nb;
;     const int drow = mode ? d0 + 256 * (n0 >> 7) + 128 * sel + (n0 & 127) : d0 + n0;
;     f32x4 tv[8];
; #pragma unroll
;     for (int i = 0; i < 8; ++i) tv[i] = __builtin_nontemporal_load((const f32x4*)(W + (size_t)(k0 + 8 * i + (lane >> 3)) * ldw + c0 + n0 + 4 * (lane & 7)));
; #pragma unroll
;     for (int i = 0; i < 8; ++i) { LAS float* d = scr + (8 * i + (lane >> 3)) * 33 + 4 * (lane & 7); d[0] = tv[i][0]; d[1] = tv[i][1]; d[2] = tv[i][2]; d[3] = tv[i][3]; }
;     asm volatile("s_waitcnt lgkmcnt(0)" ::: "memory");
;     const int c = lane & 7;
; #pragma unroll
;     for (int j = 0; j < 4; ++j) { const int n = (lane >> 3) + 8 * j; const LAS float* s = scr + (8 * c) * 33 + n;
;         u32x4 o; o.x = cvt_pk_bf16(s[0 * 33], s[1 * 33]); o.y = cvt_pk_bf16(s[2 * 33], s[3 * 33]); o.z = cvt_pk_bf16(s[4 * 33], s[5 * 33]); o.w = cvt_pk_bf16(s[6 * 33], s[7 * 33]);
;         *(u32x4*)(WT + (size_t)(drow + n) * K + k0 + 8 * c) = o; }
;     asm volatile("s_waitcnt lgkmcnt(0)" ::: "memory");
; }
.LBB0_23:
	s_cmpk_gt_i32 s22, 0x57f
	s_cselect_b64 s[12:13], -1, 0
	s_mov_b64 s[0:1], -1
	s_and_b64 vcc, exec, s[12:13]
	s_cbranch_vccnz .LBB0_26
	s_mul_hi_i32 s23, s22, 0x2e8ba2e9
	s_mov_b64 s[0:1], s[56:57]
	s_lshr_b32 s24, s23, 31
	s_ashr_i32 s23, s23, 4
	s_add_i32 s23, s23, s24
	s_load_dwordx2 s[0:1], s[0:1], 0x38
	s_mul_i32 s24, s23, 0xfffff500
	s_mul_i32 s25, s23, 0xffffea00
	s_add_i32 s24, s16, s24
	s_add_i32 s25, s18, s25
	s_and_b32 s25, s25, 0xffffff00
	s_and_b32 s26, s24, 0x60
	s_or_b32 s28, s25, s26
	s_ashr_i32 s25, s24, 31
	s_lshl_b32 s26, s23, 6
	s_lshl_b64 s[24:25], s[24:25], 2
	s_waitcnt lgkmcnt(0)
	s_add_u32 s0, s0, s24
	s_addc_u32 s1, s1, s25
	v_or_b32_e32 v3, s26, v4
	v_lshl_add_u64 v[52:53], s[0:1], 0, v[0:1]
	s_mov_b64 s[14:15], s[56:57]
	v_mad_i64_i32 v[32:33], s[0:1], v3, s20, v[52:53]
	v_or_b32_e32 v24, 8, v3
	v_mad_i64_i32 v[34:35], s[0:1], v24, s20, v[52:53]
	global_load_dwordx4 v[24:27], v[32:33], off nt
	global_load_dwordx4 v[28:31], v[34:35], off nt
	v_or_b32_e32 v32, 16, v3
	v_mad_i64_i32 v[40:41], s[0:1], v32, s20, v[52:53]
	v_or_b32_e32 v32, 24, v3
	v_mad_i64_i32 v[42:43], s[0:1], v32, s20, v[52:53]
	global_load_dwordx4 v[32:35], v[40:41], off nt
	global_load_dwordx4 v[36:39], v[42:43], off nt
	v_or_b32_e32 v40, 32, v3
	v_mad_i64_i32 v[48:49], s[0:1], v40, s20, v[52:53]
	v_or_b32_e32 v40, 40, v3
	v_mad_i64_i32 v[50:51], s[0:1], v40, s20, v[52:53]
	global_load_dwordx4 v[40:43], v[48:49], off nt
	global_load_dwordx4 v[44:47], v[50:51], off nt
	v_or_b32_e32 v48, 48, v3
	v_mad_i64_i32 v[48:49], s[0:1], v48, s20, v[52:53]
	global_load_dwordx4 v[48:51], v[48:49], off nt
	v_or_b32_e32 v3, 56, v3
	v_mad_i64_i32 v[52:53], s[0:1], v3, s20, v[52:53]
	global_load_dwordx4 v[52:55], v[52:53], off nt
	s_mov_b64 s[0:1], s[86:87]
	s_nop 4
	s_ashr_i32 s27, s26, 31
	s_lshl_b64 s[14:15], s[26:27], 1
	v_mov_b32_e32 v3, v1
	v_or_b32_e32 v56, s28, v4
	s_waitcnt lgkmcnt(0)
	s_add_u32 s0, s0, s14
	s_addc_u32 s1, s1, s15
	v_ashrrev_i32_e32 v57, 31, v56
	v_lshl_add_u64 v[58:59], s[0:1], 0, v[2:3]
	v_lshlrev_b64 v[56:57], 11, v[56:57]
	v_lshl_add_u64 v[58:59], v[58:59], 0, s[8:9]
	s_waitcnt vmcnt(7)
	ds_write2_b32 v9, v24, v25 offset1:1
	ds_write2_b32 v9, v26, v27 offset0:2 offset1:3
	s_waitcnt vmcnt(6)
	ds_write2_b32 v10, v28, v29 offset1:1
	ds_write2_b32 v11, v30, v31 offset1:1
	s_waitcnt vmcnt(5)
	ds_write2_b32 v12, v32, v33 offset1:1
	ds_write2_b32 v13, v34, v35 offset1:1
	s_waitcnt vmcnt(4)
	ds_write2_b32 v14, v36, v37 offset1:1
	ds_write2_b32 v15, v38, v39 offset1:1
	s_waitcnt vmcnt(3)
	ds_write2_b32 v16, v40, v41 offset1:1
	ds_write2_b32 v17, v42, v43 offset1:1
	s_waitcnt vmcnt(2)
	ds_write2_b32 v18, v44, v45 offset1:1
	ds_write2_b32 v19, v46, v47 offset1:1
	s_waitcnt vmcnt(1)
	ds_write2_b32 v20, v48, v49 offset1:1
	ds_write2_b32 v21, v50, v51 offset1:1
	s_waitcnt vmcnt(0)
	ds_write2_b32 v22, v52, v53 offset1:1
	ds_write2_b32 v23, v54, v55 offset1:1
	s_waitcnt lgkmcnt(0)
	ds_read2_b32 v[28:29], v8 offset0:33 offset1:41
	ds_read2_b32 v[30:31], v8 offset1:8
	ds_read2_b32 v[32:33], v8 offset0:66 offset1:74
	ds_read2_b32 v[34:35], v8 offset0:99 offset1:107
	ds_read2_b32 v[36:37], v8 offset0:132 offset1:140
	ds_read2_b32 v[38:39], v8 offset0:165 offset1:173
	ds_read2_b32 v[40:41], v8 offset0:198 offset1:206
	ds_read2_b32 v[42:43], v8 offset0:231 offset1:239
	v_lshl_add_u64 v[44:45], v[58:59], 0, v[56:57]
	s_waitcnt lgkmcnt(6)
	v_cvt_pk_bf16_f32 v24, v30, v28
	s_waitcnt lgkmcnt(4)
	v_cvt_pk_bf16_f32 v25, v32, v34
	s_waitcnt lgkmcnt(2)
	v_cvt_pk_bf16_f32 v26, v36, v38
	s_waitcnt lgkmcnt(0)
	v_cvt_pk_bf16_f32 v27, v40, v42
	global_store_dwordx4 v[44:45], v[24:27], off
	v_cvt_pk_bf16_f32 v28, v31, v29
	v_cvt_pk_bf16_f32 v29, v33, v35
	v_or_b32_e32 v24, s28, v5
	v_ashrrev_i32_e32 v25, 31, v24
	v_cvt_pk_bf16_f32 v30, v37, v39
	v_cvt_pk_bf16_f32 v31, v41, v43
	v_lshlrev_b64 v[24:25], 11, v[24:25]
	ds_read2_b32 v[32:33], v8 offset0:49 offset1:57
	ds_read2_b32 v[34:35], v8 offset0:16 offset1:24
	ds_read2_b32 v[36:37], v8 offset0:82 offset1:90
	ds_read2_b32 v[38:39], v8 offset0:115 offset1:123
	ds_read2_b32 v[40:41], v8 offset0:148 offset1:156
	ds_read2_b32 v[42:43], v8 offset0:181 offset1:189
	ds_read2_b32 v[44:45], v8 offset0:214 offset1:222
	ds_read2_b32 v[46:47], v8 offset0:247 offset1:255
	v_lshl_add_u64 v[24:25], v[58:59], 0, v[24:25]
	global_store_dwordx4 v[24:25], v[28:31], off
	s_waitcnt lgkmcnt(6)
	v_cvt_pk_bf16_f32 v24, v34, v32
	s_waitcnt lgkmcnt(4)
	v_cvt_pk_bf16_f32 v25, v36, v38
	v_or_b32_e32 v28, s28, v6
	v_ashrrev_i32_e32 v29, 31, v28
	v_lshlrev_b64 v[28:29], 11, v[28:29]
	s_waitcnt lgkmcnt(2)
	v_cvt_pk_bf16_f32 v26, v40, v42
	s_waitcnt lgkmcnt(0)
	v_cvt_pk_bf16_f32 v27, v44, v46
	v_lshl_add_u64 v[28:29], v[58:59], 0, v[28:29]
	global_store_dwordx4 v[28:29], v[24:27], off
	v_or_b32_e32 v28, s28, v7
	v_ashrrev_i32_e32 v29, 31, v28
	v_lshlrev_b64 v[28:29], 11, v[28:29]
	v_cvt_pk_bf16_f32 v24, v35, v33
	v_cvt_pk_bf16_f32 v25, v37, v39
	v_cvt_pk_bf16_f32 v26, v41, v43
	v_cvt_pk_bf16_f32 v27, v45, v47
	v_lshl_add_u64 v[28:29], v[58:59], 0, v[28:29]
	global_store_dwordx4 v[28:29], v[24:27], off
	s_waitcnt lgkmcnt(0)
	s_mov_b32 s23, s22
	s_cbranch_execz .LBB0_27

; #define LAS __attribute__((address_space(3)))
; __device__ __forceinline__ void xpose_item(const float* W, int ldw, int c0, int K, int ncols, bf16* WT, int d0, int mode, int sel, LAS float* scr, int item, int lane) {
;     const int nblk = ncols >> 5, kb = item / nblk, nb = item - kb * nblk, k0 = 64 * kb, n0 = 32 * nb;
;     const int drow = mode ? d0 + 256 * (n0 >> 7) + 128 * sel + (n0 & 127) : d0 + n0;
;     f32x4 tv[8];
; #pragma unroll
;     for (int i = 0; i < 8; ++i) tv[i] = __builtin_nontemporal_load((const f32x4*)(W + (size_t)(k0 + 8 * i + (lane >> 3)) * ldw + c0 + n0 + 4 * (lane & 7)));
; #pragma unroll
;     for (int i = 0; i < 8; ++i) { LAS float* d = scr + (8 * i + (lane >> 3)) * 33 + 4 * (lane & 7); d[0] = tv[i][0]; d[1] = tv[i][1]; d[2] = tv[i][2]; d[3] = tv[i][3]; }
;     asm volatile("s_waitcnt lgkmcnt(0)" ::: "memory");
;     const int c = lane & 7;
; #pragma unroll
;     for (int j = 0; j < 4; ++j) { const int n = (lane >> 3) + 8 * j; const LAS float* s = scr + (8 * c) * 33 + n;
;         u32x4 o; o.x = cvt_pk_bf16(s[0 * 33], s[1 * 33]); o.y = cvt_pk_bf16(s[2 * 33], s[3 * 33]); o.z = cvt_pk_bf16(s[4 * 33], s[5 * 33]); o.w = cvt_pk_bf16(s[6 * 33], s[7 * 33]);
;         *(u32x4*)(WT + (size_t)(drow + n) * K + k0 + 8 * c) = o; }
;     asm volatile("s_waitcnt lgkmcnt(0)" ::: "memory");
; }
.LBB0_28:
	s_cmpk_gt_i32 s23, 0x57f
	s_cselect_b64 s[12:13], -1, 0
	s_mov_b64 s[0:1], -1
	s_and_b64 vcc, exec, s[12:13]
	s_cbranch_vccnz .LBB0_31
	s_mul_hi_i32 s14, s23, 0x2e8ba2e9
	s_lshr_b32 s15, s14, 31
	s_ashr_i32 s14, s14, 4
	s_mov_b64 s[0:1], s[56:57]
	s_add_i32 s14, s14, s15
	s_mul_i32 s15, s14, 0xffffffa8
	s_load_dwordx2 s[0:1], s[0:1], 0x40
	s_add_i32 s15, s15, s23
	s_lshl_b32 s26, s15, 5
	s_lshl_b32 s15, s15, 6
	s_and_b32 s15, s15, 0xffffff00
	s_and_b32 s27, s26, 0x60
	s_or_b32 s15, s27, s15
	s_ashr_i32 s27, s26, 31
	s_or_b32 s28, s15, 0x80
	s_lshl_b32 s14, s14, 6
	s_lshl_b64 s[26:27], s[26:27], 2
	s_waitcnt lgkmcnt(0)
	s_add_u32 s0, s0, s26
	s_addc_u32 s1, s1, s27
	v_or_b32_e32 v3, s14, v4
	v_lshl_add_u64 v[52:53], s[0:1], 0, v[0:1]
	s_mov_b64 s[24:25], s[56:57]
	v_mad_i64_i32 v[32:33], s[0:1], v3, s20, v[52:53]
	v_or_b32_e32 v24, 8, v3
	v_mad_i64_i32 v[34:35], s[0:1], v24, s20, v[52:53]
	global_load_dwordx4 v[24:27], v[32:33], off nt
	global_load_dwordx4 v[28:31], v[34:35], off nt
	v_or_b32_e32 v32, 16, v3
	v_mad_i64_i32 v[40:41], s[0:1], v32, s20, v[52:53]
	v_or_b32_e32 v32, 24, v3
	v_mad_i64_i32 v[42:43], s[0:1], v32, s20, v[52:53]
	global_load_dwordx4 v[32:35], v[40:41], off nt
	global_load_dwordx4 v[36:39], v[42:43], off nt
	v_or_b32_e32 v40, 32, v3
	v_mad_i64_i32 v[48:49], s[0:1], v40, s20, v[52:53]
	v_or_b32_e32 v40, 40, v3
	v_mad_i64_i32 v[50:51], s[0:1], v40, s20, v[52:53]
	global_load_dwordx4 v[40:43], v[48:49], off nt
	global_load_dwordx4 v[44:47], v[50:51], off nt
	v_or_b32_e32 v48, 48, v3
	v_mad_i64_i32 v[48:49], s[0:1], v48, s20, v[52:53]
	global_load_dwordx4 v[48:51], v[48:49], off nt
	v_or_b32_e32 v3, 56, v3
	v_mad_i64_i32 v[52:53], s[0:1], v3, s20, v[52:53]
	global_load_dwordx4 v[52:55], v[52:53], off nt
	s_mov_b64 s[0:1], s[86:87]
	s_nop 4
	s_ashr_i32 s15, s14, 31
	s_lshl_b64 s[14:15], s[14:15], 1
	v_mov_b32_e32 v3, v1
	v_or_b32_e32 v56, s28, v4
	s_waitcnt lgkmcnt(0)
	s_add_u32 s0, s0, s14
	s_addc_u32 s1, s1, s15
	v_ashrrev_i32_e32 v57, 31, v56
	v_lshl_add_u64 v[60:61], s[0:1], 0, v[2:3]
	v_lshlrev_b64 v[56:57], 11, v[56:57]
	v_lshl_add_u64 v[60:61], v[60:61], 0, s[8:9]
	v_or_b32_e32 v58, s28, v5
	v_ashrrev_i32_e32 v59, 31, v58
	s_waitcnt vmcnt(7)
	ds_write2_b32 v9, v24, v25 offset1:1
	ds_write2_b32 v9, v26, v27 offset0:2 offset1:3
	s_waitcnt vmcnt(6)
	ds_write2_b32 v10, v28, v29 offset1:1
	ds_write2_b32 v11, v30, v31 offset1:1
	s_waitcnt vmcnt(5)
	ds_write2_b32 v12, v32, v33 offset1:1
	ds_write2_b32 v13, v34, v35 offset1:1
	s_waitcnt vmcnt(4)
	ds_write2_b32 v14, v36, v37 offset1:1
	ds_write2_b32 v15, v38, v39 offset1:1
	s_waitcnt vmcnt(3)
	ds_write2_b32 v16, v40, v41 offset1:1
	ds_write2_b32 v17, v42, v43 offset1:1
	s_waitcnt vmcnt(2)
	ds_write2_b32 v18, v44, v45 offset1:1
	ds_write2_b32 v19, v46, v47 offset1:1
	s_waitcnt vmcnt(1)
	ds_write2_b32 v20, v48, v49 offset1:1
	ds_write2_b32 v21, v50, v51 offset1:1
	s_waitcnt vmcnt(0)
	ds_write2_b32 v22, v52, v53 offset1:1
	ds_write2_b32 v23, v54, v55 offset1:1
	s_waitcnt lgkmcnt(0)
	ds_read2_b32 v[28:29], v8 offset0:33 offset1:41
	ds_read2_b32 v[30:31], v8 offset1:8
	ds_read2_b32 v[32:33], v8 offset0:66 offset1:74
	ds_read2_b32 v[34:35], v8 offset0:99 offset1:107
	ds_read2_b32 v[36:37], v8 offset0:132 offset1:140
	ds_read2_b32 v[38:39], v8 offset0:165 offset1:173
	ds_read2_b32 v[40:41], v8 offset0:198 offset1:206
	ds_read2_b32 v[42:43], v8 offset0:231 offset1:239
	v_lshl_add_u64 v[44:45], v[60:61], 0, v[56:57]
	s_waitcnt lgkmcnt(6)
	v_cvt_pk_bf16_f32 v24, v30, v28
	s_waitcnt lgkmcnt(4)
	v_cvt_pk_bf16_f32 v25, v32, v34
	s_waitcnt lgkmcnt(2)
	v_cvt_pk_bf16_f32 v26, v36, v38
	s_waitcnt lgkmcnt(0)
	v_cvt_pk_bf16_f32 v27, v40, v42
	global_store_dwordx4 v[44:45], v[24:27], off
	v_cvt_pk_bf16_f32 v28, v31, v29
	v_cvt_pk_bf16_f32 v29, v33, v35
	v_cvt_pk_bf16_f32 v30, v37, v39
	v_cvt_pk_bf16_f32 v31, v41, v43
	v_lshlrev_b64 v[24:25], 11, v[58:59]
	ds_read2_b32 v[32:33], v8 offset0:49 offset1:57
	ds_read2_b32 v[34:35], v8 offset0:16 offset1:24
	ds_read2_b32 v[36:37], v8 offset0:82 offset1:90
	ds_read2_b32 v[38:39], v8 offset0:115 offset1:123
	ds_read2_b32 v[40:41], v8 offset0:148 offset1:156
	ds_read2_b32 v[42:43], v8 offset0:181 offset1:189
	ds_read2_b32 v[44:45], v8 offset0:214 offset1:222
	ds_read2_b32 v[46:47], v8 offset0:247 offset1:255
	v_lshl_add_u64 v[24:25], v[60:61], 0, v[24:25]
	global_store_dwordx4 v[24:25], v[28:31], off
	s_waitcnt lgkmcnt(6)
	v_cvt_pk_bf16_f32 v24, v34, v32
	s_waitcnt lgkmcnt(4)
	v_cvt_pk_bf16_f32 v25, v36, v38
	v_or_b32_e32 v28, s28, v6
	v_ashrrev_i32_e32 v29, 31, v28
	v_lshlrev_b64 v[28:29], 11, v[28:29]
	s_waitcnt lgkmcnt(2)
	v_cvt_pk_bf16_f32 v26, v40, v42
	s_waitcnt lgkmcnt(0)
	v_cvt_pk_bf16_f32 v27, v44, v46
	v_lshl_add_u64 v[28:29], v[60:61], 0, v[28:29]
	global_store_dwordx4 v[28:29], v[24:27], off
	v_or_b32_e32 v28, s28, v7
	v_ashrrev_i32_e32 v29, 31, v28
	v_lshlrev_b64 v[28:29], 11, v[28:29]
	v_cvt_pk_bf16_f32 v24, v35, v33
	v_cvt_pk_bf16_f32 v25, v37, v39
	v_cvt_pk_bf16_f32 v26, v41, v43
	v_cvt_pk_bf16_f32 v27, v45, v47
	v_lshl_add_u64 v[28:29], v[60:61], 0, v[28:29]
	global_store_dwordx4 v[28:29], v[24:27], off
	s_waitcnt lgkmcnt(0)
	s_cbranch_execz .LBB0_32

; #define LAS __attribute__((address_space(3)))
; __device__ __forceinline__ void xpose_item(const float* W, int ldw, int c0, int K, int ncols, bf16* WT, int d0, int mode, int sel, LAS float* scr, int item, int lane) {
;     const int nblk = ncols >> 5, kb = item / nblk, nb = item - kb * nblk, k0 = 64 * kb, n0 = 32 * nb;
;     const int drow = mode ? d0 + 256 * (n0 >> 7) + 128 * sel + (n0 & 127) : d0 + n0;
;     f32x4 tv[8];
; #pragma unroll
;     for (int i = 0; i < 8; ++i) tv[i] = __builtin_nontemporal_load((const f32x4*)(W + (size_t)(k0 + 8 * i + (lane >> 3)) * ldw + c0 + n0 + 4 * (lane & 7)));
; #pragma unroll
;     for (int i = 0; i < 8; ++i) { LAS float* d = scr + (8 * i + (lane >> 3)) * 33 + 4 * (lane & 7); d[0] = tv[i][0]; d[1] = tv[i][1]; d[2] = tv[i][2]; d[3] = tv[i][3]; }
;     asm volatile("s_waitcnt lgkmcnt(0)" ::: "memory");
;     const int c = lane & 7;
; #pragma unroll
;     for (int j = 0; j < 4; ++j) { const int n = (lane >> 3) + 8 * j; const LAS float* s = scr + (8 * c) * 33 + n;
;         u32x4 o; o.x = cvt_pk_bf16(s[0 * 33], s[1 * 33]); o.y = cvt_pk_bf16(s[2 * 33], s[3 * 33]); o.z = cvt_pk_bf16(s[4 * 33], s[5 * 33]); o.w = cvt_pk_bf16(s[6 * 33], s[7 * 33]);
;         *(u32x4*)(WT + (size_t)(drow + n) * K + k0 + 8 * c) = o; }
;     asm volatile("s_waitcnt lgkmcnt(0)" ::: "memory");
; }
.LBB0_33:
	s_ashr_i32 s12, s23, 31
	s_mov_b64 s[0:1], s[56:57]
	s_lshr_b32 s12, s12, 27
	s_add_i32 s12, s23, s12
	s_load_dwordx2 s[0:1], s[0:1], 0x48
	s_ashr_i32 s13, s12, 5
	s_lshl_b32 s12, s13, 10
	s_lshl_b32 s14, s23, 5
	s_sub_i32 s12, s14, s12
	s_lshl_b32 s14, s13, 6
	s_ashr_i32 s13, s12, 31
	s_lshl_b64 s[26:27], s[12:13], 2
	v_or_b32_e32 v52, s14, v4
	s_waitcnt lgkmcnt(0)
	s_add_u32 s0, s0, s26
	s_addc_u32 s1, s1, s27
	v_ashrrev_i32_e32 v53, 31, v52
	v_lshl_add_u64 v[54:55], s[0:1], 0, v[0:1]
	v_lshlrev_b64 v[24:25], 12, v[52:53]
	v_lshl_add_u64 v[32:33], v[54:55], 0, v[24:25]
	v_or_b32_e32 v24, 8, v52
	v_ashrrev_i32_e32 v25, 31, v24
	s_mov_b64 s[24:25], s[56:57]
	v_lshlrev_b64 v[24:25], 12, v[24:25]
	v_lshl_add_u64 v[34:35], v[54:55], 0, v[24:25]
	global_load_dwordx4 v[24:27], v[32:33], off nt
	global_load_dwordx4 v[28:31], v[34:35], off nt
	v_or_b32_e32 v32, 16, v52
	v_ashrrev_i32_e32 v33, 31, v32
	v_lshlrev_b64 v[32:33], 12, v[32:33]
	v_lshl_add_u64 v[40:41], v[54:55], 0, v[32:33]
	v_or_b32_e32 v32, 24, v52
	v_ashrrev_i32_e32 v33, 31, v32
	v_lshlrev_b64 v[32:33], 12, v[32:33]
	v_lshl_add_u64 v[42:43], v[54:55], 0, v[32:33]
	global_load_dwordx4 v[32:35], v[40:41], off nt
	global_load_dwordx4 v[36:39], v[42:43], off nt
	v_or_b32_e32 v40, 32, v52
	v_ashrrev_i32_e32 v41, 31, v40
	v_lshlrev_b64 v[40:41], 12, v[40:41]
	v_lshl_add_u64 v[48:49], v[54:55], 0, v[40:41]
	v_or_b32_e32 v40, 40, v52
	v_ashrrev_i32_e32 v41, 31, v40
	v_lshlrev_b64 v[40:41], 12, v[40:41]
	v_lshl_add_u64 v[50:51], v[54:55], 0, v[40:41]
	global_load_dwordx4 v[40:43], v[48:49], off nt
	global_load_dwordx4 v[44:47], v[50:51], off nt
	v_or_b32_e32 v48, 48, v52
	v_ashrrev_i32_e32 v49, 31, v48
	v_lshlrev_b64 v[48:49], 12, v[48:49]
	v_or_b32_e32 v52, 56, v52
	v_lshl_add_u64 v[48:49], v[54:55], 0, v[48:49]
	v_ashrrev_i32_e32 v53, 31, v52
	global_load_dwordx4 v[48:51], v[48:49], off nt
	v_lshlrev_b64 v[52:53], 12, v[52:53]
	v_lshl_add_u64 v[52:53], v[54:55], 0, v[52:53]
	global_load_dwordx4 v[52:55], v[52:53], off nt
	s_mov_b64 s[0:1], s[86:87]
	s_nop 4
	s_ashr_i32 s15, s14, 31
	s_lshl_b64 s[14:15], s[14:15], 1
	v_mov_b32_e32 v3, v1
	v_or_b32_e32 v58, s12, v4
	s_waitcnt lgkmcnt(0)
	s_add_u32 s0, s0, s14
	s_addc_u32 s1, s1, s15
	v_lshl_add_u64 v[56:57], s[0:1], 0, v[2:3]
	v_lshl_add_u64 v[56:57], v[56:57], 0, s[10:11]
	v_or_b32_e32 v3, s12, v5
	s_waitcnt vmcnt(7)
	ds_write2_b32 v9, v24, v25 offset1:1
	ds_write2_b32 v9, v26, v27 offset0:2 offset1:3
	s_waitcnt vmcnt(6)
	ds_write2_b32 v10, v28, v29 offset1:1
	ds_write2_b32 v11, v30, v31 offset1:1
	s_waitcnt vmcnt(5)
	ds_write2_b32 v12, v32, v33 offset1:1
	ds_write2_b32 v13, v34, v35 offset1:1
	s_waitcnt vmcnt(4)
	ds_write2_b32 v14, v36, v37 offset1:1
	ds_write2_b32 v15, v38, v39 offset1:1
	s_waitcnt vmcnt(3)
	ds_write2_b32 v16, v40, v41 offset1:1
	ds_write2_b32 v17, v42, v43 offset1:1
	s_waitcnt vmcnt(2)
	ds_write2_b32 v18, v44, v45 offset1:1
	ds_write2_b32 v19, v46, v47 offset1:1
	s_waitcnt vmcnt(1)
	ds_write2_b32 v20, v48, v49 offset1:1
	ds_write2_b32 v21, v50, v51 offset1:1
	s_waitcnt vmcnt(0)
	ds_write2_b32 v22, v52, v53 offset1:1
	ds_write2_b32 v23, v54, v55 offset1:1
	s_waitcnt lgkmcnt(0)
	ds_read2_b32 v[28:29], v8 offset0:33 offset1:41
	ds_read2_b32 v[30:31], v8 offset1:8
	ds_read2_b32 v[32:33], v8 offset0:66 offset1:74
	ds_read2_b32 v[34:35], v8 offset0:99 offset1:107
	ds_read2_b32 v[36:37], v8 offset0:132 offset1:140
	ds_read2_b32 v[38:39], v8 offset0:165 offset1:173
	ds_read2_b32 v[40:41], v8 offset0:198 offset1:206
	ds_read2_b32 v[42:43], v8 offset0:231 offset1:239
	v_mad_i64_i32 v[44:45], s[0:1], v58, s21, v[56:57]
	s_waitcnt lgkmcnt(6)
	v_cvt_pk_bf16_f32 v24, v30, v28
	s_waitcnt lgkmcnt(4)
	v_cvt_pk_bf16_f32 v25, v32, v34
	s_waitcnt lgkmcnt(2)
	v_cvt_pk_bf16_f32 v26, v36, v38
	s_waitcnt lgkmcnt(0)
	v_cvt_pk_bf16_f32 v27, v40, v42
	global_store_dwordx4 v[44:45], v[24:27], off
	v_cvt_pk_bf16_f32 v28, v31, v29
	v_cvt_pk_bf16_f32 v29, v33, v35
	v_cvt_pk_bf16_f32 v30, v37, v39
	v_cvt_pk_bf16_f32 v31, v41, v43
	ds_read2_b32 v[32:33], v8 offset0:49 offset1:57
	ds_read2_b32 v[34:35], v8 offset0:16 offset1:24
	ds_read2_b32 v[36:37], v8 offset0:82 offset1:90
	ds_read2_b32 v[38:39], v8 offset0:115 offset1:123
	ds_read2_b32 v[40:41], v8 offset0:148 offset1:156
	ds_read2_b32 v[42:43], v8 offset0:181 offset1:189
	ds_read2_b32 v[44:45], v8 offset0:214 offset1:222
	ds_read2_b32 v[46:47], v8 offset0:247 offset1:255
	v_mad_i64_i32 v[24:25], s[0:1], v3, s21, v[56:57]
	v_or_b32_e32 v3, s12, v6
	global_store_dwordx4 v[24:25], v[28:31], off
	s_waitcnt lgkmcnt(6)
	v_cvt_pk_bf16_f32 v24, v34, v32
	s_waitcnt lgkmcnt(4)
	v_cvt_pk_bf16_f32 v25, v36, v38
	s_waitcnt lgkmcnt(2)
	v_cvt_pk_bf16_f32 v26, v40, v42
	s_waitcnt lgkmcnt(0)
	v_cvt_pk_bf16_f32 v27, v44, v46
	v_mad_i64_i32 v[28:29], s[0:1], v3, s21, v[56:57]
	v_or_b32_e32 v3, s12, v7
	global_store_dwordx4 v[28:29], v[24:27], off
	v_mad_i64_i32 v[28:29], s[0:1], v3, s21, v[56:57]
	s_nop 0
	v_cvt_pk_bf16_f32 v24, v35, v33
	v_cvt_pk_bf16_f32 v25, v37, v39
	v_cvt_pk_bf16_f32 v26, v41, v43
	v_cvt_pk_bf16_f32 v27, v45, v47
	global_store_dwordx4 v[28:29], v[24:27], off
	s_waitcnt lgkmcnt(0)
	s_branch .LBB0_22

; __device__ __forceinline__ unsigned short f2bf(float f) { return (unsigned short)(cvt_pk_bf16(f, 0.f) & 0xffffu); }
; template <int W>
; __device__ __forceinline__ void cvt_rows(const float* srcP, const float* srcS, bf16* dst, int gw, int NGW, int lane) {
;     for (int m = gw; m < MP; m += NGW) {
;         const float* src = m < MPROMPT ? srcP + (size_t)m * W : srcS + (size_t)(m - MPROMPT) * W;
; #pragma unroll
;         for (int j = 0; j < W / 256; ++j) { f32x4 v = (f32x4){0.f, 0.f, 0.f, 0.f}; if (m < MREAL) v = __builtin_nontemporal_load((const f32x4*)src + 64 * j + lane);
;             u32x2 w; w.x = cvt_pk_bf16(v[0], v[1]); w.y = cvt_pk_bf16(v[2], v[3]); *((u32x2*)(dst + (size_t)m * W) + 64 * j + lane) = w; }
;     }
; __global__ void __launch_bounds__(NWAVES * 64, 2) mega_fwd(Args args) {
;     ...
;         for (int e = blockIdx.x * 512 + tid; e < 16 * 1024; e += G * 512) { const int c = e >> 10, k = e & 1023; const float wv = w_in[(size_t)k * INW + 4096 + c]; WBA[e] = wv; WBAB[e] = f2bf(wv); }
.LBB0_36:
	v_and_b32_e32 v1, 0x3ff, v0
	v_mul_u32_u24_e32 v1, 0x2410, v1
	v_ashrrev_i32_e32 v8, 10, v0
	v_lshlrev_b32_e32 v6, 2, v1
	v_ashrrev_i32_e32 v9, 31, v8
	s_waitcnt lgkmcnt(0)
	v_lshl_add_u64 v[10:11], s[6:7], 0, v[6:7]
	v_lshl_add_u64 v[8:9], v[8:9], 2, v[10:11]
	v_add_co_u32_e32 v8, vcc, 0x4000, v8
	s_mov_b64 s[16:17], s[56:57]
	s_nop 0
	v_addc_co_u32_e32 v9, vcc, 0, v9, vcc
	global_load_dword v1, v[8:9], off
	s_mov_b64 s[16:17], s[86:87]
	s_nop 4
	s_mov_b64 s[18:19], s[56:57]
	v_add_u32_e32 v0, s10, v0
	v_cmp_lt_i32_e32 vcc, s3, v0
	s_or_b64 s[14:15], vcc, s[14:15]
	s_waitcnt lgkmcnt(0)
	v_lshl_add_u64 v[8:9], s[16:17], 0, v[2:3]
	v_lshl_add_u64 v[2:3], v[2:3], 0, s[12:13]
	s_waitcnt vmcnt(0)
	global_store_dword v[8:9], v1, off
	s_mov_b64 s[16:17], s[86:87]
	s_nop 4
	v_cvt_pk_bf16_f32 v1, v1, s0
	s_waitcnt lgkmcnt(0)
	v_lshl_add_u64 v[8:9], s[16:17], 0, v[4:5]
	v_lshl_add_u64 v[4:5], v[4:5], 0, s[0:1]
	global_store_short v[8:9], v1, off
	s_andn2_b64 exec, exec, s[14:15]
	s_cbranch_execnz .LBB0_36
.LBB0_37:
	s_or_b64 exec, exec, s[8:9]
	s_mov_b64 s[0:1], s[56:57]
	s_waitcnt lgkmcnt(0)
	s_mov_b64 s[6:7], s[56:57]
	s_mov_b64 s[10:11], s[56:57]
	s_cmpk_gt_i32 s94, 0x40ff
	s_cbranch_scc1 .LBB0_51
	s_mov_b64 s[12:13], s[86:87]
	s_nop 4
	s_load_dwordx2 s[14:15], s[0:1], 0x0
	s_load_dwordx2 s[8:9], s[6:7], 0x8
	s_mov_b32 s93, s95
	v_lshlrev_b32_e32 v8, 4, v152
	v_lshlrev_b32_e32 v9, 3, v152
	s_waitcnt lgkmcnt(0)
	s_lshl_b32 s0, s94, 12
	s_add_u32 s10, s14, s0
	s_addc_u32 s11, s15, 0
	s_lshl_b32 s0, s94, 11
	s_add_u32 s18, s12, 0x2b30000
	s_addc_u32 s19, s13, 0
	s_add_u32 s18, s18, s0
	s_addc_u32 s19, s19, 0
	global_load_dwordx4 v[16:19], v8, s[10:11] nt
	global_load_dwordx4 v[20:23], v8, s[10:11] offset:1024 nt
	global_load_dwordx4 v[24:27], v8, s[10:11] offset:2048 nt
	global_load_dwordx4 v[28:31], v8, s[10:11] offset:3072 nt
	s_add_u32 s10, s10, 0x800000
	s_addc_u32 s11, s11, 0
	global_load_dwordx4 v[32:35], v8, s[10:11] nt
	global_load_dwordx4 v[36:39], v8, s[10:11] offset:1024 nt
	global_load_dwordx4 v[40:43], v8, s[10:11] offset:2048 nt
	global_load_dwordx4 v[44:47], v8, s[10:11] offset:3072 nt
	s_waitcnt vmcnt(4)
	v_cvt_pk_bf16_f32 v0, v16, v17
	v_cvt_pk_bf16_f32 v1, v18, v19
	v_cvt_pk_bf16_f32 v2, v20, v21
	v_cvt_pk_bf16_f32 v3, v22, v23
	v_cvt_pk_bf16_f32 v4, v24, v25
	v_cvt_pk_bf16_f32 v5, v26, v27
	v_cvt_pk_bf16_f32 v6, v28, v29
	v_cvt_pk_bf16_f32 v7, v30, v31
	global_store_dwordx2 v9, v[0:1], s[18:19]
	global_store_dwordx2 v9, v[2:3], s[18:19] offset:512
	global_store_dwordx2 v9, v[4:5], s[18:19] offset:1024
	global_store_dwordx2 v9, v[6:7], s[18:19] offset:1536
	s_add_u32 s18, s18, 0x400000
	s_addc_u32 s19, s19, 0
	s_add_u32 s10, s10, 0x800000
	s_addc_u32 s11, s11, 0
	global_load_dwordx4 v[16:19], v8, s[10:11] nt
	global_load_dwordx4 v[20:23], v8, s[10:11] offset:1024 nt
	global_load_dwordx4 v[24:27], v8, s[10:11] offset:2048 nt
	global_load_dwordx4 v[28:31], v8, s[10:11] offset:3072 nt
	s_waitcnt vmcnt(4)
	v_cvt_pk_bf16_f32 v0, v32, v33
	v_cvt_pk_bf16_f32 v1, v34, v35
	v_cvt_pk_bf16_f32 v2, v36, v37
	v_cvt_pk_bf16_f32 v3, v38, v39
	v_cvt_pk_bf16_f32 v4, v40, v41
	v_cvt_pk_bf16_f32 v5, v42, v43
	v_cvt_pk_bf16_f32 v6, v44, v45
	v_cvt_pk_bf16_f32 v7, v46, v47
	global_store_dwordx2 v9, v[0:1], s[18:19]
	global_store_dwordx2 v9, v[2:3], s[18:19] offset:512
	global_store_dwordx2 v9, v[4:5], s[18:19] offset:1024
	global_store_dwordx2 v9, v[6:7], s[18:19] offset:1536
	s_add_u32 s18, s18, 0x400000
	s_addc_u32 s19, s19, 0
	s_add_u32 s10, s10, 0x800000
	s_addc_u32 s11, s11, 0
	global_load_dwordx4 v[32:35], v8, s[10:11] nt
	global_load_dwordx4 v[36:39], v8, s[10:11] offset:1024 nt
	global_load_dwordx4 v[40:43], v8, s[10:11] offset:2048 nt
	global_load_dwordx4 v[44:47], v8, s[10:11] offset:3072 nt
	s_waitcnt vmcnt(4)
	v_cvt_pk_bf16_f32 v0, v16, v17
	v_cvt_pk_bf16_f32 v1, v18, v19
	v_cvt_pk_bf16_f32 v2, v20, v21
	v_cvt_pk_bf16_f32 v3, v22, v23
	v_cvt_pk_bf16_f32 v4, v24, v25
	v_cvt_pk_bf16_f32 v5, v26, v27
	v_cvt_pk_bf16_f32 v6, v28, v29
	v_cvt_pk_bf16_f32 v7, v30, v31
	global_store_dwordx2 v9, v[0:1], s[18:19]
	global_store_dwordx2 v9, v[2:3], s[18:19] offset:512
	global_store_dwordx2 v9, v[4:5], s[18:19] offset:1024
	global_store_dwordx2 v9, v[6:7], s[18:19] offset:1536
	s_add_u32 s18, s18, 0x400000
	s_addc_u32 s19, s19, 0
	s_add_u32 s10, s10, 0x800000
	s_addc_u32 s11, s11, 0
	global_load_dwordx4 v[16:19], v8, s[10:11] nt
	global_load_dwordx4 v[20:23], v8, s[10:11] offset:1024 nt
	global_load_dwordx4 v[24:27], v8, s[10:11] offset:2048 nt
	global_load_dwordx4 v[28:31], v8, s[10:11] offset:3072 nt
	s_waitcnt vmcnt(4)
; template <int W>
; __device__ __forceinline__ void cvt_rows(const float* srcP, const float* srcS, bf16* dst, int gw, int NGW, int lane) {
;     for (int m = gw; m < MP; m += NGW) {
;         const float* src = m < MPROMPT ? srcP + (size_t)m * W : srcS + (size_t)(m - MPROMPT) * W;
; #pragma unroll
;         for (int j = 0; j < W / 256; ++j) { f32x4 v = (f32x4){0.f, 0.f, 0.f, 0.f}; if (m < MREAL) v = __builtin_nontemporal_load((const f32x4*)src + 64 * j + lane);
;             u32x2 w; w.x = cvt_pk_bf16(v[0], v[1]); w.y = cvt_pk_bf16(v[2], v[3]); *((u32x2*)(dst + (size_t)m * W) + 64 * j + lane) = w; }
;     }
	v_cvt_pk_bf16_f32 v0, v32, v33
	v_cvt_pk_bf16_f32 v1, v34, v35
	v_cvt_pk_bf16_f32 v2, v36, v37
	v_cvt_pk_bf16_f32 v3, v38, v39
	v_cvt_pk_bf16_f32 v4, v40, v41
	v_cvt_pk_bf16_f32 v5, v42, v43
	v_cvt_pk_bf16_f32 v6, v44, v45
	v_cvt_pk_bf16_f32 v7, v46, v47
	global_store_dwordx2 v9, v[0:1], s[18:19]
	global_store_dwordx2 v9, v[2:3], s[18:19] offset:512
	global_store_dwordx2 v9, v[4:5], s[18:19] offset:1024
	global_store_dwordx2 v9, v[6:7], s[18:19] offset:1536
	s_add_u32 s18, s18, 0x400000
	s_addc_u32 s19, s19, 0
	s_add_u32 s10, s10, 0x800000
	s_addc_u32 s11, s11, 0
	global_load_dwordx4 v[32:35], v8, s[10:11] nt
	global_load_dwordx4 v[36:39], v8, s[10:11] offset:1024 nt
	global_load_dwordx4 v[40:43], v8, s[10:11] offset:2048 nt
	global_load_dwordx4 v[44:47], v8, s[10:11] offset:3072 nt
	s_waitcnt vmcnt(4)
	v_cvt_pk_bf16_f32 v0, v16, v17
	v_cvt_pk_bf16_f32 v1, v18, v19
	v_cvt_pk_bf16_f32 v2, v20, v21
	v_cvt_pk_bf16_f32 v3, v22, v23
	v_cvt_pk_bf16_f32 v4, v24, v25
	v_cvt_pk_bf16_f32 v5, v26, v27
	v_cvt_pk_bf16_f32 v6, v28, v29
	v_cvt_pk_bf16_f32 v7, v30, v31
	global_store_dwordx2 v9, v[0:1], s[18:19]
	global_store_dwordx2 v9, v[2:3], s[18:19] offset:512
	global_store_dwordx2 v9, v[4:5], s[18:19] offset:1024
	global_store_dwordx2 v9, v[6:7], s[18:19] offset:1536
	s_add_u32 s18, s18, 0x400000
	s_addc_u32 s19, s19, 0
	s_add_u32 s10, s10, 0x800000
	s_addc_u32 s11, s11, 0
	global_load_dwordx4 v[16:19], v8, s[10:11] nt
	global_load_dwordx4 v[20:23], v8, s[10:11] offset:1024 nt
	global_load_dwordx4 v[24:27], v8, s[10:11] offset:2048 nt
	global_load_dwordx4 v[28:31], v8, s[10:11] offset:3072 nt
	s_waitcnt vmcnt(4)
	v_cvt_pk_bf16_f32 v0, v32, v33
	v_cvt_pk_bf16_f32 v1, v34, v35
	v_cvt_pk_bf16_f32 v2, v36, v37
	v_cvt_pk_bf16_f32 v3, v38, v39
	v_cvt_pk_bf16_f32 v4, v40, v41
	v_cvt_pk_bf16_f32 v5, v42, v43
	v_cvt_pk_bf16_f32 v6, v44, v45
	v_cvt_pk_bf16_f32 v7, v46, v47
	global_store_dwordx2 v9, v[0:1], s[18:19]
	global_store_dwordx2 v9, v[2:3], s[18:19] offset:512
	global_store_dwordx2 v9, v[4:5], s[18:19] offset:1024
	global_store_dwordx2 v9, v[6:7], s[18:19] offset:1536
	s_add_u32 s18, s18, 0x400000
	s_addc_u32 s19, s19, 0
	s_add_u32 s10, s10, 0x800000
	s_addc_u32 s11, s11, 0
	global_load_dwordx4 v[32:35], v8, s[10:11] nt
	global_load_dwordx4 v[36:39], v8, s[10:11] offset:1024 nt
	global_load_dwordx4 v[40:43], v8, s[10:11] offset:2048 nt
	global_load_dwordx4 v[44:47], v8, s[10:11] offset:3072 nt
	s_waitcnt vmcnt(4)
	v_cvt_pk_bf16_f32 v0, v16, v17
	v_cvt_pk_bf16_f32 v1, v18, v19
	v_cvt_pk_bf16_f32 v2, v20, v21
	v_cvt_pk_bf16_f32 v3, v22, v23
	v_cvt_pk_bf16_f32 v4, v24, v25
	v_cvt_pk_bf16_f32 v5, v26, v27
	v_cvt_pk_bf16_f32 v6, v28, v29
	v_cvt_pk_bf16_f32 v7, v30, v31
	global_store_dwordx2 v9, v[0:1], s[18:19]
	global_store_dwordx2 v9, v[2:3], s[18:19] offset:512
	global_store_dwordx2 v9, v[4:5], s[18:19] offset:1024
	global_store_dwordx2 v9, v[6:7], s[18:19] offset:1536
	s_add_u32 s18, s18, 0x400000
	s_addc_u32 s19, s19, 0
	s_waitcnt vmcnt(0)
	v_cvt_pk_bf16_f32 v0, v32, v33
	v_cvt_pk_bf16_f32 v1, v34, v35
	v_cvt_pk_bf16_f32 v2, v36, v37
	v_cvt_pk_bf16_f32 v3, v38, v39
	v_cvt_pk_bf16_f32 v4, v40, v41
	v_cvt_pk_bf16_f32 v5, v42, v43
	v_cvt_pk_bf16_f32 v6, v44, v45
	v_cvt_pk_bf16_f32 v7, v46, v47
	global_store_dwordx2 v9, v[0:1], s[18:19]
	global_store_dwordx2 v9, v[2:3], s[18:19] offset:512
	global_store_dwordx2 v9, v[4:5], s[18:19] offset:1024
	global_store_dwordx2 v9, v[6:7], s[18:19] offset:1536
	s_add_u32 s18, s18, 0x400000
	s_addc_u32 s19, s19, 0
	s_cmpk_gt_u32 s94, 0xff
	s_cbranch_scc1 .LBB0_50
	s_cmpk_gt_u32 s94, 0x7f
	s_cbranch_scc1 .Lcvt_zero
	s_lshl_b32 s0, s94, 12
	s_add_u32 s10, s8, s0
	s_addc_u32 s11, s9, 0
	global_load_dwordx4 v[16:19], v8, s[10:11] nt
	global_load_dwordx4 v[20:23], v8, s[10:11] offset:1024 nt
	global_load_dwordx4 v[24:27], v8, s[10:11] offset:2048 nt
	global_load_dwordx4 v[28:31], v8, s[10:11] offset:3072 nt
	s_waitcnt vmcnt(0)
	v_cvt_pk_bf16_f32 v0, v16, v17
	v_cvt_pk_bf16_f32 v1, v18, v19
	v_cvt_pk_bf16_f32 v2, v20, v21
	v_cvt_pk_bf16_f32 v3, v22, v23
	v_cvt_pk_bf16_f32 v4, v24, v25
	v_cvt_pk_bf16_f32 v5, v26, v27
	v_cvt_pk_bf16_f32 v6, v28, v29
	v_cvt_pk_bf16_f32 v7, v30, v31
	global_store_dwordx2 v9, v[0:1], s[18:19]
	global_store_dwordx2 v9, v[2:3], s[18:19] offset:512
	global_store_dwordx2 v9, v[4:5], s[18:19] offset:1024
	global_store_dwordx2 v9, v[6:7], s[18:19] offset:1536
	s_branch .LBB0_50

; #define GEMM(EpiT, E, Aop, Bop, M_, N_, K_) do { int k_ = K_; asm volatile("" : "+s"(k_)); pg8::Gemm g_{Aop, Bop, M_, N_, k_}; pg8::StaticOrder S_; S_.init(M_, N_, G, (int)blockIdx.x); \
;         pg8::gemm_phase<EpiT, pg8::StaticOrder, true, true>(lds, g_, S_, E); } while (0)
;     __host__ __device__ bool next(int i, Unit& u) const {
;         const long L = (long)i * G + c; if (L >= nwg) return false;
;         int wgid = (int)L; { const int q = nwg / NXCD, r = nwg % NXCD, xcd = wgid % NXCD, off = wgid / NXCD; wgid = (xcd < r ? xcd * (q + 1) : r * (q + 1) + (xcd - r) * q) + off; }
;         const int nig = WGM * nN, gid = wgid / nig, fm = gid * WGM, gsz = (nM - fm) < WGM ? (nM - fm) : WGM;
;         u.pm = fm + ((wgid % nig) % gsz); u.pn = (wgid % nig) / gsz; return true;
; __global__ void __launch_bounds__(NWAVES * 64, 2) mega_fwd(Args args) {
;     ...
;     if (IN(1)) { EpiGU E{R0}; GEMM(EpiGU, E, XB, WGU, MP, 5632, 1024);
.LBB0_105:
	s_cmp_lt_i32 s64, 2
	s_cselect_b64 s[0:1], -1, 0
	s_and_b64 s[4:5], s[0:1], s[6:7]
	s_andn2_b64 vcc, exec, s[4:5]
	s_cbranch_vccnz .LBB0_195
	s_mov_b64 s[0:1], s[56:57]
	s_movk_i32 s6, 0x400
	s_mov_b64 s[8:9], s[56:57]
	s_mov_b64 s[14:15], s[56:57]
	v_readfirstlane_b32 s22, v154
	s_cmpk_gt_i32 s2, 0x595
	v_lshlrev_b32_e32 v144, 2, v154
	s_cbranch_scc1 .LBB0_135
	s_ashr_i32 s3, s2, 31
	s_mov_b64 s[12:13], s[86:87]
	s_nop 4
	s_mov_b64 s[10:11], s[86:87]
	s_nop 4
	s_lshr_b32 s7, s3, 29
	s_add_i32 s7, s2, s7
	s_and_b32 s8, s7, -8
	s_sub_i32 s17, s2, s8
	s_cmp_gt_i32 s17, 5
	s_cbranch_scc0 .LBB0_109
	s_mul_i32 s8, s17, 0xb2
	s_add_i32 s16, s8, 6
	s_mov_b64 s[8:9], s[86:87]
	s_nop 4
	s_cbranch_execz .LBB0_110
	s_branch .LBB0_111
.LBB0_109:
	s_mov_b64 s[8:9], s[86:87]
	s_nop 4

; #define LAS __attribute__((address_space(3)))
; #define XSEG(W, ldw, c0, K, ncols, WT, d0, mode, sel) { const int ni_ = ((K) / 64) * ((ncols) / 32); if (r_ < ni_) { xpose_item(W, ldw, c0, K, ncols, WT, d0, mode, sel, scr, r_, lane); continue; } r_ -= ni_; }
; __device__ __forceinline__ void xpose_item(const float* W, int ldw, int c0, int K, int ncols, bf16* WT, int d0, int mode, int sel, LAS float* scr, int item, int lane) {
;     const int nblk = ncols >> 5, kb = item / nblk, nb = item - kb * nblk, k0 = 64 * kb, n0 = 32 * nb;
;     const int drow = mode ? d0 + 256 * (n0 >> 7) + 128 * sel + (n0 & 127) : d0 + n0;
;     f32x4 tv[8];
; #pragma unroll
;     for (int i = 0; i < 8; ++i) tv[i] = __builtin_nontemporal_load((const f32x4*)(W + (size_t)(k0 + 8 * i + (lane >> 3)) * ldw + c0 + n0 + 4 * (lane & 7)));
; #pragma unroll
;     for (int i = 0; i < 8; ++i) { LAS float* d = scr + (8 * i + (lane >> 3)) * 33 + 4 * (lane & 7); d[0] = tv[i][0]; d[1] = tv[i][1]; d[2] = tv[i][2]; d[3] = tv[i][3]; }
;     asm volatile("s_waitcnt lgkmcnt(0)" ::: "memory");
;     const int c = lane & 7;
; #pragma unroll
;     for (int j = 0; j < 4; ++j) { const int n = (lane >> 3) + 8 * j; const LAS float* s = scr + (8 * c) * 33 + n;
;         u32x4 o; o.x = cvt_pk_bf16(s[0 * 33], s[1 * 33]); o.y = cvt_pk_bf16(s[2 * 33], s[3 * 33]); o.z = cvt_pk_bf16(s[4 * 33], s[5 * 33]); o.w = cvt_pk_bf16(s[6 * 33], s[7 * 33]);
;         *(u32x4*)(WT + (size_t)(drow + n) * K + k0 + 8 * c) = o; }
;     asm volatile("s_waitcnt lgkmcnt(0)" ::: "memory");
; }
; __global__ void __launch_bounds__(NWAVES * 64, 2) mega_fwd(Args args) {
;     ...
;                 XSEG(w_in, INW, 0, 1024, 3072, WQKV, 0, 0, 0)
.LBB0_139:
	s_cmpk_gt_i32 s3, 0x5ff
	s_cselect_b64 s[20:21], -1, 0
	s_mov_b64 s[0:1], -1
	s_and_b64 vcc, exec, s[20:21]
	s_cbranch_vccnz .LBB0_142
	s_mul_hi_i32 s22, s3, 0x2aaaaaab
	s_lshr_b32 s23, s22, 31
	s_ashr_i32 s22, s22, 4
	s_add_i32 s23, s22, s23
	s_mul_i32 s22, s23, 0xfffff400
	s_add_i32 s22, s27, s22
	s_lshl_b32 s24, s23, 6
	s_ashr_i32 s23, s22, 31
	v_or_b32_e32 v39, s24, v1
	v_lshl_add_u64 v[18:19], s[22:23], 2, v[4:5]
	s_mov_b64 s[0:1], s[56:57]
	v_mad_i64_i32 v[48:49], s[30:31], v39, s29, v[18:19]
	v_or_b32_e32 v40, 8, v39
	v_mad_i64_i32 v[50:51], s[30:31], v40, s29, v[18:19]
	global_load_dwordx4 v[40:43], v[48:49], off nt
	global_load_dwordx4 v[44:47], v[50:51], off nt
	v_or_b32_e32 v48, 16, v39
	v_mad_i64_i32 v[56:57], s[30:31], v48, s29, v[18:19]
	v_or_b32_e32 v48, 24, v39
	v_mad_i64_i32 v[58:59], s[30:31], v48, s29, v[18:19]
	global_load_dwordx4 v[48:51], v[56:57], off nt
	global_load_dwordx4 v[52:55], v[58:59], off nt
	v_or_b32_e32 v56, 32, v39
	v_mad_i64_i32 v[64:65], s[30:31], v56, s29, v[18:19]
	v_or_b32_e32 v56, 40, v39
	v_mad_i64_i32 v[66:67], s[30:31], v56, s29, v[18:19]
	global_load_dwordx4 v[56:59], v[64:65], off nt
	global_load_dwordx4 v[60:63], v[66:67], off nt
	v_or_b32_e32 v64, 48, v39
	v_mad_i64_i32 v[64:65], s[30:31], v64, s29, v[18:19]
	global_load_dwordx4 v[64:67], v[64:65], off nt
	v_or_b32_e32 v39, 56, v39
	v_mad_i64_i32 v[18:19], s[30:31], v39, s29, v[18:19]
	global_load_dwordx4 v[68:71], v[18:19], off nt
	s_mov_b64 s[0:1], s[86:87]
	s_nop 4
	s_ashr_i32 s25, s24, 31
	s_lshl_b64 s[24:25], s[24:25], 1
	v_add_u32_e32 v18, s22, v1
	v_ashrrev_i32_e32 v19, 31, v18
	s_waitcnt lgkmcnt(0)
	s_add_u32 s0, s0, s24
	s_addc_u32 s1, s1, s25
	v_lshl_add_u64 v[76:77], s[0:1], 0, v[2:3]
	v_lshlrev_b64 v[74:75], 11, v[18:19]
	v_lshl_add_u64 v[76:77], v[76:77], 0, s[6:7]
	v_add_u32_e32 v72, 8, v18
	v_lshl_add_u64 v[74:75], v[76:77], 0, v[74:75]
	v_ashrrev_i32_e32 v73, 31, v72
	v_lshlrev_b64 v[72:73], 11, v[72:73]
	v_lshl_add_u64 v[72:73], v[76:77], 0, v[72:73]
	s_waitcnt vmcnt(0)
	ds_write2_b32 v24, v40, v41 offset1:1
	ds_write2_b32 v24, v42, v43 offset0:2 offset1:3
	ds_write2_b32 v25, v44, v45 offset1:1
	ds_write2_b32 v26, v46, v47 offset1:1
	ds_write2_b32 v27, v48, v49 offset1:1
	ds_write2_b32 v28, v50, v51 offset1:1
	ds_write2_b32 v29, v52, v53 offset1:1
	ds_write2_b32 v30, v54, v55 offset1:1
	ds_write2_b32 v31, v56, v57 offset1:1
	ds_write2_b32 v32, v58, v59 offset1:1
	ds_write2_b32 v33, v60, v61 offset1:1
	ds_write2_b32 v34, v62, v63 offset1:1
	ds_write2_b32 v35, v64, v65 offset1:1
	ds_write2_b32 v36, v66, v67 offset1:1
	ds_write2_b32 v37, v68, v69 offset1:1
	ds_write2_b32 v38, v70, v71 offset1:1
	s_waitcnt lgkmcnt(0)
	ds_read2_b32 v[44:45], v23 offset0:33 offset1:41
	ds_read2_b32 v[46:47], v23 offset1:8
	ds_read2_b32 v[48:49], v23 offset0:66 offset1:74
	ds_read2_b32 v[50:51], v23 offset0:99 offset1:107
	ds_read2_b32 v[52:53], v23 offset0:132 offset1:140
	ds_read2_b32 v[54:55], v23 offset0:165 offset1:173
	ds_read2_b32 v[56:57], v23 offset0:198 offset1:206
	ds_read2_b32 v[58:59], v23 offset0:231 offset1:239
	ds_read2_b32 v[60:61], v23 offset0:49 offset1:57
	ds_read2_b32 v[62:63], v23 offset0:16 offset1:24
	ds_read2_b32 v[64:65], v23 offset0:82 offset1:90
	ds_read2_b32 v[66:67], v23 offset0:115 offset1:123
	ds_read2_b32 v[68:69], v23 offset0:148 offset1:156
	s_waitcnt lgkmcnt(11)
	v_cvt_pk_bf16_f32 v40, v46, v44
	s_waitcnt lgkmcnt(9)
	v_cvt_pk_bf16_f32 v41, v48, v50
	s_waitcnt lgkmcnt(7)
	v_cvt_pk_bf16_f32 v42, v52, v54
	s_waitcnt lgkmcnt(5)
	v_cvt_pk_bf16_f32 v43, v56, v58
	global_store_dwordx4 v[74:75], v[40:43], off
	v_cvt_pk_bf16_f32 v44, v47, v45
	v_cvt_pk_bf16_f32 v45, v49, v51
	v_cvt_pk_bf16_f32 v46, v53, v55
	ds_read2_b32 v[48:49], v23 offset0:181 offset1:189
	ds_read2_b32 v[50:51], v23 offset0:214 offset1:222
	ds_read2_b32 v[52:53], v23 offset0:247 offset1:255
	v_cvt_pk_bf16_f32 v47, v57, v59
	global_store_dwordx4 v[72:73], v[44:47], off
	s_waitcnt lgkmcnt(6)
	v_cvt_pk_bf16_f32 v40, v62, v60
	s_waitcnt lgkmcnt(4)
	v_cvt_pk_bf16_f32 v41, v64, v66
	v_add_u32_e32 v44, 16, v18
	v_ashrrev_i32_e32 v45, 31, v44
	v_add_u32_e32 v18, 24, v18
	v_lshlrev_b64 v[44:45], 11, v[44:45]
	v_ashrrev_i32_e32 v19, 31, v18
	s_waitcnt lgkmcnt(2)
	v_cvt_pk_bf16_f32 v42, v68, v48
	s_waitcnt lgkmcnt(0)
	v_cvt_pk_bf16_f32 v43, v50, v52
	v_lshl_add_u64 v[44:45], v[76:77], 0, v[44:45]
	v_lshlrev_b64 v[18:19], 11, v[18:19]
	global_store_dwordx4 v[44:45], v[40:43], off
	v_lshl_add_u64 v[18:19], v[76:77], 0, v[18:19]
	s_nop 0
	v_cvt_pk_bf16_f32 v40, v63, v61
	v_cvt_pk_bf16_f32 v41, v65, v67
	v_cvt_pk_bf16_f32 v42, v69, v49
	v_cvt_pk_bf16_f32 v43, v51, v53
	global_store_dwordx4 v[18:19], v[40:43], off
	s_waitcnt lgkmcnt(0)
	s_mov_b32 s30, s3
	s_cbranch_execz .LBB0_143

; #define LAS __attribute__((address_space(3)))
; #define XSEG(W, ldw, c0, K, ncols, WT, d0, mode, sel) { const int ni_ = ((K) / 64) * ((ncols) / 32); if (r_ < ni_) { xpose_item(W, ldw, c0, K, ncols, WT, d0, mode, sel, scr, r_, lane); continue; } r_ -= ni_; }
; __device__ __forceinline__ void xpose_item(const float* W, int ldw, int c0, int K, int ncols, bf16* WT, int d0, int mode, int sel, LAS float* scr, int item, int lane) {
;     const int nblk = ncols >> 5, kb = item / nblk, nb = item - kb * nblk, k0 = 64 * kb, n0 = 32 * nb;
;     const int drow = mode ? d0 + 256 * (n0 >> 7) + 128 * sel + (n0 & 127) : d0 + n0;
;     f32x4 tv[8];
; #pragma unroll
;     for (int i = 0; i < 8; ++i) tv[i] = __builtin_nontemporal_load((const f32x4*)(W + (size_t)(k0 + 8 * i + (lane >> 3)) * ldw + c0 + n0 + 4 * (lane & 7)));
; #pragma unroll
;     for (int i = 0; i < 8; ++i) { LAS float* d = scr + (8 * i + (lane >> 3)) * 33 + 4 * (lane & 7); d[0] = tv[i][0]; d[1] = tv[i][1]; d[2] = tv[i][2]; d[3] = tv[i][3]; }
;     asm volatile("s_waitcnt lgkmcnt(0)" ::: "memory");
;     const int c = lane & 7;
; #pragma unroll
;     for (int j = 0; j < 4; ++j) { const int n = (lane >> 3) + 8 * j; const LAS float* s = scr + (8 * c) * 33 + n;
;         u32x4 o; o.x = cvt_pk_bf16(s[0 * 33], s[1 * 33]); o.y = cvt_pk_bf16(s[2 * 33], s[3 * 33]); o.z = cvt_pk_bf16(s[4 * 33], s[5 * 33]); o.w = cvt_pk_bf16(s[6 * 33], s[7 * 33]);
;         *(u32x4*)(WT + (size_t)(drow + n) * K + k0 + 8 * c) = o; }
;     asm volatile("s_waitcnt lgkmcnt(0)" ::: "memory");
; }
; __global__ void __launch_bounds__(NWAVES * 64, 2) mega_fwd(Args args) {
;     ...
;                 XSEG(w_in, INW, 3072, 1024, 1024, WINB, 0, 0, 0)
.LBB0_144:
	s_cmpk_gt_i32 s30, 0x1ff
	s_cselect_b64 s[20:21], -1, 0
	s_mov_b64 s[0:1], -1
	s_and_b64 vcc, exec, s[20:21]
	s_cbranch_vccnz .LBB0_147
	s_ashr_i32 s22, s30, 31
	s_lshr_b32 s22, s22, 27
	s_add_i32 s22, s30, s22
	s_ashr_i32 s23, s22, 5
	s_lshl_b32 s22, s23, 10
	s_lshl_b32 s24, s30, 5
	s_sub_i32 s22, s24, s22
	s_lshl_b32 s24, s23, 6
	s_ashr_i32 s23, s22, 31
	v_or_b32_e32 v39, s24, v1
	v_lshl_add_u64 v[18:19], s[22:23], 2, v[6:7]
	s_mov_b64 s[0:1], s[56:57]
	v_mad_i64_i32 v[48:49], s[34:35], v39, s29, v[18:19]
	v_or_b32_e32 v40, 8, v39
	v_mad_i64_i32 v[50:51], s[34:35], v40, s29, v[18:19]
	global_load_dwordx4 v[40:43], v[48:49], off nt
	global_load_dwordx4 v[44:47], v[50:51], off nt
	v_or_b32_e32 v48, 16, v39
	v_mad_i64_i32 v[56:57], s[34:35], v48, s29, v[18:19]
	v_or_b32_e32 v48, 24, v39
	v_mad_i64_i32 v[58:59], s[34:35], v48, s29, v[18:19]
	global_load_dwordx4 v[48:51], v[56:57], off nt
	global_load_dwordx4 v[52:55], v[58:59], off nt
	v_or_b32_e32 v56, 32, v39
	v_mad_i64_i32 v[64:65], s[34:35], v56, s29, v[18:19]
	v_or_b32_e32 v56, 40, v39
	v_mad_i64_i32 v[66:67], s[34:35], v56, s29, v[18:19]
	global_load_dwordx4 v[56:59], v[64:65], off nt
	global_load_dwordx4 v[60:63], v[66:67], off nt
	v_or_b32_e32 v64, 48, v39
	v_mad_i64_i32 v[64:65], s[34:35], v64, s29, v[18:19]
	global_load_dwordx4 v[64:67], v[64:65], off nt
	v_or_b32_e32 v39, 56, v39
	v_mad_i64_i32 v[18:19], s[34:35], v39, s29, v[18:19]
	global_load_dwordx4 v[68:71], v[18:19], off nt
	s_mov_b64 s[0:1], s[86:87]
	s_nop 4
	s_ashr_i32 s25, s24, 31
	s_lshl_b64 s[24:25], s[24:25], 1
	v_or_b32_e32 v18, s22, v1
	v_ashrrev_i32_e32 v19, 31, v18
	s_waitcnt lgkmcnt(0)
	s_add_u32 s0, s0, s24
	s_addc_u32 s1, s1, s25
	v_lshl_add_u64 v[74:75], s[0:1], 0, v[2:3]
	v_lshlrev_b64 v[18:19], 11, v[18:19]
	v_lshl_add_u64 v[74:75], v[74:75], 0, s[8:9]
	v_or_b32_e32 v72, s22, v20
	v_lshl_add_u64 v[18:19], v[74:75], 0, v[18:19]
	v_ashrrev_i32_e32 v73, 31, v72
	v_lshlrev_b64 v[72:73], 11, v[72:73]
	v_lshl_add_u64 v[72:73], v[74:75], 0, v[72:73]
	s_waitcnt vmcnt(0)
	ds_write2_b32 v24, v40, v41 offset1:1
	ds_write2_b32 v24, v42, v43 offset0:2 offset1:3
	ds_write2_b32 v25, v44, v45 offset1:1
	ds_write2_b32 v26, v46, v47 offset1:1
	ds_write2_b32 v27, v48, v49 offset1:1
	ds_write2_b32 v28, v50, v51 offset1:1
	ds_write2_b32 v29, v52, v53 offset1:1
	ds_write2_b32 v30, v54, v55 offset1:1
	ds_write2_b32 v31, v56, v57 offset1:1
	ds_write2_b32 v32, v58, v59 offset1:1
	ds_write2_b32 v33, v60, v61 offset1:1
	ds_write2_b32 v34, v62, v63 offset1:1
	ds_write2_b32 v35, v64, v65 offset1:1
	ds_write2_b32 v36, v66, v67 offset1:1
	ds_write2_b32 v37, v68, v69 offset1:1
	ds_write2_b32 v38, v70, v71 offset1:1
	s_waitcnt lgkmcnt(0)
	ds_read2_b32 v[44:45], v23 offset0:33 offset1:41
	ds_read2_b32 v[46:47], v23 offset1:8
	ds_read2_b32 v[48:49], v23 offset0:66 offset1:74
	ds_read2_b32 v[50:51], v23 offset0:99 offset1:107
	ds_read2_b32 v[52:53], v23 offset0:132 offset1:140
	ds_read2_b32 v[54:55], v23 offset0:165 offset1:173
	ds_read2_b32 v[56:57], v23 offset0:198 offset1:206
	ds_read2_b32 v[58:59], v23 offset0:231 offset1:239
	ds_read2_b32 v[60:61], v23 offset0:49 offset1:57
	ds_read2_b32 v[62:63], v23 offset0:16 offset1:24
	ds_read2_b32 v[64:65], v23 offset0:82 offset1:90
	ds_read2_b32 v[66:67], v23 offset0:115 offset1:123
	ds_read2_b32 v[68:69], v23 offset0:148 offset1:156
	s_waitcnt lgkmcnt(11)
	v_cvt_pk_bf16_f32 v40, v46, v44
	s_waitcnt lgkmcnt(9)
	v_cvt_pk_bf16_f32 v41, v48, v50
	s_waitcnt lgkmcnt(7)
	v_cvt_pk_bf16_f32 v42, v52, v54
	s_waitcnt lgkmcnt(5)
	v_cvt_pk_bf16_f32 v43, v56, v58
	global_store_dwordx4 v[18:19], v[40:43], off
	v_cvt_pk_bf16_f32 v44, v47, v45
	v_cvt_pk_bf16_f32 v45, v49, v51
	ds_read2_b32 v[18:19], v23 offset0:181 offset1:189
	ds_read2_b32 v[48:49], v23 offset0:214 offset1:222
	ds_read2_b32 v[50:51], v23 offset0:247 offset1:255
	v_cvt_pk_bf16_f32 v46, v53, v55
	v_cvt_pk_bf16_f32 v47, v57, v59
	global_store_dwordx4 v[72:73], v[44:47], off
	s_waitcnt lgkmcnt(6)
	v_cvt_pk_bf16_f32 v40, v62, v60
	s_waitcnt lgkmcnt(4)
	v_cvt_pk_bf16_f32 v41, v64, v66
	v_or_b32_e32 v44, s22, v21
	v_ashrrev_i32_e32 v45, 31, v44
	v_lshlrev_b64 v[44:45], 11, v[44:45]
	s_waitcnt lgkmcnt(2)
	v_cvt_pk_bf16_f32 v42, v68, v18
	s_waitcnt lgkmcnt(0)
	v_cvt_pk_bf16_f32 v43, v48, v50
	v_lshl_add_u64 v[44:45], v[74:75], 0, v[44:45]
	v_or_b32_e32 v18, s22, v22
	global_store_dwordx4 v[44:45], v[40:43], off
	s_nop 1
	v_cvt_pk_bf16_f32 v42, v69, v19
	v_ashrrev_i32_e32 v19, 31, v18
	v_lshlrev_b64 v[18:19], 11, v[18:19]
	v_cvt_pk_bf16_f32 v40, v63, v61
	v_cvt_pk_bf16_f32 v41, v65, v67
	v_cvt_pk_bf16_f32 v43, v49, v51
	v_lshl_add_u64 v[18:19], v[74:75], 0, v[18:19]
	global_store_dwordx4 v[18:19], v[40:43], off
	s_waitcnt lgkmcnt(0)
	s_cbranch_execz .LBB0_148

; #define LAS __attribute__((address_space(3)))
; #define XSEG(W, ldw, c0, K, ncols, WT, d0, mode, sel) { const int ni_ = ((K) / 64) * ((ncols) / 32); if (r_ < ni_) { xpose_item(W, ldw, c0, K, ncols, WT, d0, mode, sel, scr, r_, lane); continue; } r_ -= ni_; }
; __device__ __forceinline__ void xpose_item(const float* W, int ldw, int c0, int K, int ncols, bf16* WT, int d0, int mode, int sel, LAS float* scr, int item, int lane) {
;     const int nblk = ncols >> 5, kb = item / nblk, nb = item - kb * nblk, k0 = 64 * kb, n0 = 32 * nb;
;     const int drow = mode ? d0 + 256 * (n0 >> 7) + 128 * sel + (n0 & 127) : d0 + n0;
;     f32x4 tv[8];
; #pragma unroll
;     for (int i = 0; i < 8; ++i) tv[i] = __builtin_nontemporal_load((const f32x4*)(W + (size_t)(k0 + 8 * i + (lane >> 3)) * ldw + c0 + n0 + 4 * (lane & 7)));
; #pragma unroll
;     for (int i = 0; i < 8; ++i) { LAS float* d = scr + (8 * i + (lane >> 3)) * 33 + 4 * (lane & 7); d[0] = tv[i][0]; d[1] = tv[i][1]; d[2] = tv[i][2]; d[3] = tv[i][3]; }
;     asm volatile("s_waitcnt lgkmcnt(0)" ::: "memory");
;     const int c = lane & 7;
; #pragma unroll
;     for (int j = 0; j < 4; ++j) { const int n = (lane >> 3) + 8 * j; const LAS float* s = scr + (8 * c) * 33 + n;
;         u32x4 o; o.x = cvt_pk_bf16(s[0 * 33], s[1 * 33]); o.y = cvt_pk_bf16(s[2 * 33], s[3 * 33]); o.z = cvt_pk_bf16(s[4 * 33], s[5 * 33]); o.w = cvt_pk_bf16(s[6 * 33], s[7 * 33]);
;         *(u32x4*)(WT + (size_t)(drow + n) * K + k0 + 8 * c) = o; }
;     asm volatile("s_waitcnt lgkmcnt(0)" ::: "memory");
; }
; __global__ void __launch_bounds__(NWAVES * 64, 2) mega_fwd(Args args) {
;     ...
;                 XSEG(w_in, INW, 5136, 1024, 1024, WINB, 1024, 1, 0)
.LBB0_149:
	s_cmpk_gt_i32 s30, 0x1ff
	s_cselect_b64 s[20:21], -1, 0
	s_mov_b64 s[0:1], -1
	s_and_b64 vcc, exec, s[20:21]
	s_cbranch_vccnz .LBB0_152
	s_ashr_i32 s22, s30, 31
	s_lshr_b32 s22, s22, 27
	s_add_i32 s23, s30, s22
	s_and_b32 s22, s23, 0xffffffe0
	s_sub_i32 s25, s30, s22
	s_lshl_b32 s22, s25, 5
	s_lshl_b32 s23, s23, 1
	s_and_b32 s24, s23, 0xffffffc0
	s_ashr_i32 s23, s22, 31
	v_or_b32_e32 v39, s24, v1
	v_lshl_add_u64 v[18:19], s[22:23], 2, v[8:9]
	s_mov_b64 s[0:1], s[56:57]
	v_mad_i64_i32 v[48:49], s[34:35], v39, s29, v[18:19]
	v_or_b32_e32 v40, 8, v39
	v_mad_i64_i32 v[50:51], s[34:35], v40, s29, v[18:19]
	global_load_dwordx4 v[40:43], v[48:49], off nt
	global_load_dwordx4 v[44:47], v[50:51], off nt
	v_or_b32_e32 v48, 16, v39
	v_mad_i64_i32 v[56:57], s[34:35], v48, s29, v[18:19]
	v_or_b32_e32 v48, 24, v39
	v_mad_i64_i32 v[58:59], s[34:35], v48, s29, v[18:19]
	global_load_dwordx4 v[48:51], v[56:57], off nt
	global_load_dwordx4 v[52:55], v[58:59], off nt
	v_or_b32_e32 v56, 32, v39
	v_mad_i64_i32 v[64:65], s[34:35], v56, s29, v[18:19]
	v_or_b32_e32 v56, 40, v39
	v_mad_i64_i32 v[66:67], s[34:35], v56, s29, v[18:19]
	global_load_dwordx4 v[56:59], v[64:65], off nt
	global_load_dwordx4 v[60:63], v[66:67], off nt
	v_or_b32_e32 v64, 48, v39
	v_mad_i64_i32 v[64:65], s[34:35], v64, s29, v[18:19]
	global_load_dwordx4 v[64:67], v[64:65], off nt
	v_or_b32_e32 v39, 56, v39
	v_mad_i64_i32 v[18:19], s[34:35], v39, s29, v[18:19]
	global_load_dwordx4 v[68:71], v[18:19], off nt
	s_mov_b64 s[0:1], s[86:87]
	s_nop 4
	s_lshl_b32 s23, s25, 6
	s_ashr_i32 s25, s24, 31
	s_and_b32 s31, s23, 0xffffff00
	s_and_b32 s34, s22, 0x60
	s_lshl_b64 s[22:23], s[24:25], 1
	s_or_b32 s24, s31, s34
	s_addk_i32 s24, 0x400
	s_waitcnt lgkmcnt(0)
	s_add_u32 s0, s0, s22
	v_or_b32_e32 v18, s24, v1
	s_addc_u32 s1, s1, s23
	v_ashrrev_i32_e32 v19, 31, v18
	v_lshl_add_u64 v[74:75], s[0:1], 0, v[2:3]
	v_lshlrev_b64 v[18:19], 11, v[18:19]
	v_lshl_add_u64 v[74:75], v[74:75], 0, s[8:9]
	v_or_b32_e32 v72, s24, v20
	v_lshl_add_u64 v[18:19], v[74:75], 0, v[18:19]
	v_ashrrev_i32_e32 v73, 31, v72
	v_lshlrev_b64 v[72:73], 11, v[72:73]
	s_waitcnt vmcnt(0)
	ds_write2_b32 v24, v40, v41 offset1:1
	ds_write2_b32 v24, v42, v43 offset0:2 offset1:3
	ds_write2_b32 v25, v44, v45 offset1:1
	ds_write2_b32 v26, v46, v47 offset1:1
	ds_write2_b32 v27, v48, v49 offset1:1
	ds_write2_b32 v28, v50, v51 offset1:1
	ds_write2_b32 v29, v52, v53 offset1:1
	ds_write2_b32 v30, v54, v55 offset1:1
	ds_write2_b32 v31, v56, v57 offset1:1
	ds_write2_b32 v32, v58, v59 offset1:1
	ds_write2_b32 v33, v60, v61 offset1:1
	ds_write2_b32 v34, v62, v63 offset1:1
	ds_write2_b32 v35, v64, v65 offset1:1
	ds_write2_b32 v36, v66, v67 offset1:1
	ds_write2_b32 v37, v68, v69 offset1:1
	ds_write2_b32 v38, v70, v71 offset1:1
	s_waitcnt lgkmcnt(0)
	ds_read2_b32 v[44:45], v23 offset0:33 offset1:41
	ds_read2_b32 v[46:47], v23 offset1:8
	ds_read2_b32 v[48:49], v23 offset0:66 offset1:74
	ds_read2_b32 v[50:51], v23 offset0:99 offset1:107
	ds_read2_b32 v[52:53], v23 offset0:132 offset1:140
	ds_read2_b32 v[54:55], v23 offset0:165 offset1:173
	ds_read2_b32 v[56:57], v23 offset0:198 offset1:206
	ds_read2_b32 v[58:59], v23 offset0:231 offset1:239
	s_waitcnt lgkmcnt(6)
	v_cvt_pk_bf16_f32 v40, v46, v44
	s_waitcnt lgkmcnt(4)
	v_cvt_pk_bf16_f32 v41, v48, v50
	s_waitcnt lgkmcnt(2)
	v_cvt_pk_bf16_f32 v42, v52, v54
	v_cvt_pk_bf16_f32 v44, v47, v45
	s_waitcnt lgkmcnt(0)
	v_cvt_pk_bf16_f32 v43, v56, v58
	global_store_dwordx4 v[18:19], v[40:43], off
	v_cvt_pk_bf16_f32 v45, v49, v51
	v_cvt_pk_bf16_f32 v46, v53, v55
	v_cvt_pk_bf16_f32 v47, v57, v59
	ds_read2_b32 v[18:19], v23 offset0:49 offset1:57
	ds_read2_b32 v[48:49], v23 offset0:16 offset1:24
	ds_read2_b32 v[50:51], v23 offset0:82 offset1:90
	ds_read2_b32 v[52:53], v23 offset0:115 offset1:123
	ds_read2_b32 v[54:55], v23 offset0:148 offset1:156
	ds_read2_b32 v[56:57], v23 offset0:181 offset1:189
	ds_read2_b32 v[58:59], v23 offset0:214 offset1:222
	ds_read2_b32 v[62:63], v23 offset0:247 offset1:255
	v_lshl_add_u64 v[60:61], v[74:75], 0, v[72:73]
	global_store_dwordx4 v[60:61], v[44:47], off
	s_waitcnt lgkmcnt(6)
	v_cvt_pk_bf16_f32 v40, v48, v18
	s_waitcnt lgkmcnt(4)
	v_cvt_pk_bf16_f32 v41, v50, v52
	v_or_b32_e32 v44, s24, v21
	v_ashrrev_i32_e32 v45, 31, v44
	v_lshlrev_b64 v[44:45], 11, v[44:45]
	s_waitcnt lgkmcnt(2)
	v_cvt_pk_bf16_f32 v42, v54, v56
	s_waitcnt lgkmcnt(0)
	v_cvt_pk_bf16_f32 v43, v58, v62
	v_lshl_add_u64 v[44:45], v[74:75], 0, v[44:45]
	v_or_b32_e32 v18, s24, v22
	global_store_dwordx4 v[44:45], v[40:43], off
	s_nop 1
	v_cvt_pk_bf16_f32 v40, v49, v19
	v_ashrrev_i32_e32 v19, 31, v18
	v_lshlrev_b64 v[18:19], 11, v[18:19]
	v_cvt_pk_bf16_f32 v41, v51, v53
	v_cvt_pk_bf16_f32 v42, v55, v57
	v_cvt_pk_bf16_f32 v43, v59, v63
	v_lshl_add_u64 v[18:19], v[74:75], 0, v[18:19]
	global_store_dwordx4 v[18:19], v[40:43], off
	s_waitcnt lgkmcnt(0)
	s_cbranch_execz .LBB0_153

; #define LAS __attribute__((address_space(3)))
; __device__ __forceinline__ const float* arg_in(int k) { return (const float*)(const __attribute__((address_space(1))) float*)arg_q(k); }
; __device__ __forceinline__ void xpose_item(const float* W, int ldw, int c0, int K, int ncols, bf16* WT, int d0, int mode, int sel, LAS float* scr, int item, int lane) {
;     const int nblk = ncols >> 5, kb = item / nblk, nb = item - kb * nblk, k0 = 64 * kb, n0 = 32 * nb;
;     const int drow = mode ? d0 + 256 * (n0 >> 7) + 128 * sel + (n0 & 127) : d0 + n0;
;     f32x4 tv[8];
; #pragma unroll
;     for (int i = 0; i < 8; ++i) tv[i] = __builtin_nontemporal_load((const f32x4*)(W + (size_t)(k0 + 8 * i + (lane >> 3)) * ldw + c0 + n0 + 4 * (lane & 7)));
; #pragma unroll
;     for (int i = 0; i < 8; ++i) { LAS float* d = scr + (8 * i + (lane >> 3)) * 33 + 4 * (lane & 7); d[0] = tv[i][0]; d[1] = tv[i][1]; d[2] = tv[i][2]; d[3] = tv[i][3]; }
;     asm volatile("s_waitcnt lgkmcnt(0)" ::: "memory");
;     const int c = lane & 7;
; #pragma unroll
;     for (int j = 0; j < 4; ++j) { const int n = (lane >> 3) + 8 * j; const LAS float* s = scr + (8 * c) * 33 + n;
;         u32x4 o; o.x = cvt_pk_bf16(s[0 * 33], s[1 * 33]); o.y = cvt_pk_bf16(s[2 * 33], s[3 * 33]); o.z = cvt_pk_bf16(s[4 * 33], s[5 * 33]); o.w = cvt_pk_bf16(s[6 * 33], s[7 * 33]);
;         *(u32x4*)(WT + (size_t)(drow + n) * K + k0 + 8 * c) = o; }
;     asm volatile("s_waitcnt lgkmcnt(0)" ::: "memory");
; }
; __global__ void __launch_bounds__(NWAVES * 64, 2) mega_fwd(Args args) {
;     ...
;                 XSEG(w_in, INW, 0, 1024, 3072, WQKV, 0, 0, 0)
;                 XSEG(w_in, INW, 3072, 1024, 1024, WINB, 0, 0, 0)
;                 XSEG(w_in, INW, 5136, 1024, 1024, WINB, 1024, 1, 0)
;                 XSEG(w_in, INW, 6160, 1024, 1024, WINB, 1024, 1, 1)
;                 XSEG(w_in, INW, 4112, 1024, 1024, WINB, 3072, 0, 0)
;                 XSEG(w_in, INW, 7184, 1024, 1024, WINB, 4096, 0, 0)
;                 XSEG(w_in, INW, 8208, 1024, 1024, WINB, 5120, 0, 0)
;                 XSEG(arg_in(17), D, 0, 1024, 1024, WPG, 0, 0, 0)
;                 XSEG(arg_in(19), D, 0, 1024, 1024, WPS, 0, 0, 0)
;                 XSEG(arg_in(20), D, 0, 1024, 1024, WO, 0, 0, 0)
;                 XSEG(arg_in(28), D, 0, 1024, 1024, WPLEG, 0, 0, 0)
;                 XSEG(arg_in(29), D, 0, 256, 1024, WPLEP, 0, 0, 0)
;             }
.LBB0_154:
	s_cmpk_gt_i32 s30, 0x1ff
	s_cselect_b64 s[20:21], -1, 0
	s_mov_b64 s[0:1], -1
	s_and_b64 vcc, exec, s[20:21]
	s_cbranch_vccnz .LBB0_157
	s_ashr_i32 s22, s30, 31
	s_lshr_b32 s22, s22, 27
	s_add_i32 s23, s30, s22
	s_and_b32 s22, s23, 0xffffffe0
	s_sub_i32 s25, s30, s22
	s_lshl_b32 s22, s25, 5
	s_lshl_b32 s23, s23, 1
	s_and_b32 s24, s23, 0xffffffc0
	s_ashr_i32 s23, s22, 31
	v_or_b32_e32 v39, s24, v1
	v_lshl_add_u64 v[18:19], s[22:23], 2, v[10:11]
	s_mov_b64 s[0:1], s[56:57]
	v_mad_i64_i32 v[48:49], s[34:35], v39, s29, v[18:19]
	v_or_b32_e32 v40, 8, v39
	v_mad_i64_i32 v[50:51], s[34:35], v40, s29, v[18:19]
	global_load_dwordx4 v[40:43], v[48:49], off nt
	global_load_dwordx4 v[44:47], v[50:51], off nt
	v_or_b32_e32 v48, 16, v39
	v_mad_i64_i32 v[56:57], s[34:35], v48, s29, v[18:19]
	v_or_b32_e32 v48, 24, v39
	v_mad_i64_i32 v[58:59], s[34:35], v48, s29, v[18:19]
	global_load_dwordx4 v[48:51], v[56:57], off nt
	global_load_dwordx4 v[52:55], v[58:59], off nt
	v_or_b32_e32 v56, 32, v39
	v_mad_i64_i32 v[64:65], s[34:35], v56, s29, v[18:19]
	v_or_b32_e32 v56, 40, v39
	v_mad_i64_i32 v[66:67], s[34:35], v56, s29, v[18:19]
	global_load_dwordx4 v[56:59], v[64:65], off nt
	global_load_dwordx4 v[60:63], v[66:67], off nt
	v_or_b32_e32 v64, 48, v39
	v_mad_i64_i32 v[64:65], s[34:35], v64, s29, v[18:19]
	global_load_dwordx4 v[64:67], v[64:65], off nt
	v_or_b32_e32 v39, 56, v39
	v_mad_i64_i32 v[18:19], s[34:35], v39, s29, v[18:19]
	global_load_dwordx4 v[68:71], v[18:19], off nt
	s_mov_b64 s[0:1], s[86:87]
	s_nop 4
	s_lshl_b32 s23, s25, 6
	s_ashr_i32 s25, s24, 31
	s_and_b32 s31, s23, 0xffffff00
	s_and_b32 s34, s22, 0x60
	s_lshl_b64 s[22:23], s[24:25], 1
	s_or_b32 s24, s31, s34
	s_addk_i32 s24, 0x480
	s_waitcnt lgkmcnt(0)
	s_add_u32 s0, s0, s22
	v_or_b32_e32 v18, s24, v1
	s_addc_u32 s1, s1, s23
	v_ashrrev_i32_e32 v19, 31, v18
	v_lshl_add_u64 v[74:75], s[0:1], 0, v[2:3]
	v_lshlrev_b64 v[18:19], 11, v[18:19]
	v_lshl_add_u64 v[74:75], v[74:75], 0, s[8:9]
	v_or_b32_e32 v72, s24, v20
	v_lshl_add_u64 v[18:19], v[74:75], 0, v[18:19]
	v_ashrrev_i32_e32 v73, 31, v72
	v_lshlrev_b64 v[72:73], 11, v[72:73]
	s_waitcnt vmcnt(0)
	ds_write2_b32 v24, v40, v41 offset1:1
	ds_write2_b32 v24, v42, v43 offset0:2 offset1:3
	ds_write2_b32 v25, v44, v45 offset1:1
	ds_write2_b32 v26, v46, v47 offset1:1
	ds_write2_b32 v27, v48, v49 offset1:1
	ds_write2_b32 v28, v50, v51 offset1:1
	ds_write2_b32 v29, v52, v53 offset1:1
	ds_write2_b32 v30, v54, v55 offset1:1
	ds_write2_b32 v31, v56, v57 offset1:1
	ds_write2_b32 v32, v58, v59 offset1:1
	ds_write2_b32 v33, v60, v61 offset1:1
	ds_write2_b32 v34, v62, v63 offset1:1
	ds_write2_b32 v35, v64, v65 offset1:1
	ds_write2_b32 v36, v66, v67 offset1:1
	ds_write2_b32 v37, v68, v69 offset1:1
	ds_write2_b32 v38, v70, v71 offset1:1
	s_waitcnt lgkmcnt(0)
	ds_read2_b32 v[44:45], v23 offset0:33 offset1:41
	ds_read2_b32 v[46:47], v23 offset1:8
	ds_read2_b32 v[48:49], v23 offset0:66 offset1:74
	ds_read2_b32 v[50:51], v23 offset0:99 offset1:107
	ds_read2_b32 v[52:53], v23 offset0:132 offset1:140
	ds_read2_b32 v[54:55], v23 offset0:165 offset1:173
	ds_read2_b32 v[56:57], v23 offset0:198 offset1:206
	ds_read2_b32 v[58:59], v23 offset0:231 offset1:239
	s_waitcnt lgkmcnt(6)
	v_cvt_pk_bf16_f32 v40, v46, v44
	s_waitcnt lgkmcnt(4)
	v_cvt_pk_bf16_f32 v41, v48, v50
	s_waitcnt lgkmcnt(2)
	v_cvt_pk_bf16_f32 v42, v52, v54
	v_cvt_pk_bf16_f32 v44, v47, v45
	s_waitcnt lgkmcnt(0)
	v_cvt_pk_bf16_f32 v43, v56, v58
	global_store_dwordx4 v[18:19], v[40:43], off
	v_cvt_pk_bf16_f32 v45, v49, v51
	v_cvt_pk_bf16_f32 v46, v53, v55
	v_cvt_pk_bf16_f32 v47, v57, v59
	ds_read2_b32 v[18:19], v23 offset0:49 offset1:57
	ds_read2_b32 v[48:49], v23 offset0:16 offset1:24
	ds_read2_b32 v[50:51], v23 offset0:82 offset1:90
	ds_read2_b32 v[52:53], v23 offset0:115 offset1:123
	ds_read2_b32 v[54:55], v23 offset0:148 offset1:156
	ds_read2_b32 v[56:57], v23 offset0:181 offset1:189
	ds_read2_b32 v[58:59], v23 offset0:214 offset1:222
	ds_read2_b32 v[62:63], v23 offset0:247 offset1:255
	v_lshl_add_u64 v[60:61], v[74:75], 0, v[72:73]
	global_store_dwordx4 v[60:61], v[44:47], off
	s_waitcnt lgkmcnt(6)
	v_cvt_pk_bf16_f32 v40, v48, v18
	s_waitcnt lgkmcnt(4)
	v_cvt_pk_bf16_f32 v41, v50, v52
	v_or_b32_e32 v44, s24, v21
	v_ashrrev_i32_e32 v45, 31, v44
	v_lshlrev_b64 v[44:45], 11, v[44:45]
	s_waitcnt lgkmcnt(2)
	v_cvt_pk_bf16_f32 v42, v54, v56
	s_waitcnt lgkmcnt(0)
	v_cvt_pk_bf16_f32 v43, v58, v62
	v_lshl_add_u64 v[44:45], v[74:75], 0, v[44:45]
	v_or_b32_e32 v18, s24, v22
	global_store_dwordx4 v[44:45], v[40:43], off
	s_nop 1
	v_cvt_pk_bf16_f32 v40, v49, v19
	v_ashrrev_i32_e32 v19, 31, v18
	v_lshlrev_b64 v[18:19], 11, v[18:19]
	v_cvt_pk_bf16_f32 v41, v51, v53
	v_cvt_pk_bf16_f32 v42, v55, v57
	v_cvt_pk_bf16_f32 v43, v59, v63
	v_lshl_add_u64 v[18:19], v[74:75], 0, v[18:19]
	global_store_dwordx4 v[18:19], v[40:43], off
	s_waitcnt lgkmcnt(0)
	s_cbranch_execz .LBB0_158

; #define LAS __attribute__((address_space(3)))
; __device__ __forceinline__ const float* arg_in(int k) { return (const float*)(const __attribute__((address_space(1))) float*)arg_q(k); }
; __device__ __forceinline__ void xpose_item(const float* W, int ldw, int c0, int K, int ncols, bf16* WT, int d0, int mode, int sel, LAS float* scr, int item, int lane) {
;     const int nblk = ncols >> 5, kb = item / nblk, nb = item - kb * nblk, k0 = 64 * kb, n0 = 32 * nb;
;     const int drow = mode ? d0 + 256 * (n0 >> 7) + 128 * sel + (n0 & 127) : d0 + n0;
;     f32x4 tv[8];
; #pragma unroll
;     for (int i = 0; i < 8; ++i) tv[i] = __builtin_nontemporal_load((const f32x4*)(W + (size_t)(k0 + 8 * i + (lane >> 3)) * ldw + c0 + n0 + 4 * (lane & 7)));
; #pragma unroll
;     for (int i = 0; i < 8; ++i) { LAS float* d = scr + (8 * i + (lane >> 3)) * 33 + 4 * (lane & 7); d[0] = tv[i][0]; d[1] = tv[i][1]; d[2] = tv[i][2]; d[3] = tv[i][3]; }
;     asm volatile("s_waitcnt lgkmcnt(0)" ::: "memory");
;     const int c = lane & 7;
; #pragma unroll
;     for (int j = 0; j < 4; ++j) { const int n = (lane >> 3) + 8 * j; const LAS float* s = scr + (8 * c) * 33 + n;
;         u32x4 o; o.x = cvt_pk_bf16(s[0 * 33], s[1 * 33]); o.y = cvt_pk_bf16(s[2 * 33], s[3 * 33]); o.z = cvt_pk_bf16(s[4 * 33], s[5 * 33]); o.w = cvt_pk_bf16(s[6 * 33], s[7 * 33]);
;         *(u32x4*)(WT + (size_t)(drow + n) * K + k0 + 8 * c) = o; }
;     asm volatile("s_waitcnt lgkmcnt(0)" ::: "memory");
; }
; __global__ void __launch_bounds__(NWAVES * 64, 2) mega_fwd(Args args) {
;     ...
;                 XSEG(w_in, INW, 0, 1024, 3072, WQKV, 0, 0, 0)
;                 XSEG(w_in, INW, 3072, 1024, 1024, WINB, 0, 0, 0)
;                 XSEG(w_in, INW, 5136, 1024, 1024, WINB, 1024, 1, 0)
;                 XSEG(w_in, INW, 6160, 1024, 1024, WINB, 1024, 1, 1)
;                 XSEG(w_in, INW, 4112, 1024, 1024, WINB, 3072, 0, 0)
;                 XSEG(w_in, INW, 7184, 1024, 1024, WINB, 4096, 0, 0)
;                 XSEG(w_in, INW, 8208, 1024, 1024, WINB, 5120, 0, 0)
;                 XSEG(arg_in(17), D, 0, 1024, 1024, WPG, 0, 0, 0)
;                 XSEG(arg_in(19), D, 0, 1024, 1024, WPS, 0, 0, 0)
;                 XSEG(arg_in(20), D, 0, 1024, 1024, WO, 0, 0, 0)
;                 XSEG(arg_in(28), D, 0, 1024, 1024, WPLEG, 0, 0, 0)
;                 XSEG(arg_in(29), D, 0, 256, 1024, WPLEP, 0, 0, 0)
;             }
.LBB0_159:
	s_cmpk_gt_i32 s30, 0x1ff
	s_cselect_b64 s[20:21], -1, 0
	s_mov_b64 s[0:1], -1
	s_and_b64 vcc, exec, s[20:21]
	s_cbranch_vccnz .LBB0_162
	s_ashr_i32 s22, s30, 31
	s_lshr_b32 s22, s22, 27
	s_add_i32 s22, s30, s22
	s_ashr_i32 s23, s22, 5
	s_lshl_b32 s22, s23, 10
	s_lshl_b32 s24, s30, 5
	s_sub_i32 s22, s24, s22
	s_lshl_b32 s24, s23, 6
	s_ashr_i32 s23, s22, 31
	v_or_b32_e32 v39, s24, v1
	v_lshl_add_u64 v[18:19], s[22:23], 2, v[12:13]
	s_mov_b64 s[0:1], s[56:57]
	v_mad_i64_i32 v[48:49], s[34:35], v39, s29, v[18:19]
	v_or_b32_e32 v40, 8, v39
	v_mad_i64_i32 v[50:51], s[34:35], v40, s29, v[18:19]
	global_load_dwordx4 v[40:43], v[48:49], off nt
	global_load_dwordx4 v[44:47], v[50:51], off nt
	v_or_b32_e32 v48, 16, v39
	v_mad_i64_i32 v[56:57], s[34:35], v48, s29, v[18:19]
	v_or_b32_e32 v48, 24, v39
	v_mad_i64_i32 v[58:59], s[34:35], v48, s29, v[18:19]
	global_load_dwordx4 v[48:51], v[56:57], off nt
	global_load_dwordx4 v[52:55], v[58:59], off nt
	v_or_b32_e32 v56, 32, v39
	v_mad_i64_i32 v[64:65], s[34:35], v56, s29, v[18:19]
	v_or_b32_e32 v56, 40, v39
	v_mad_i64_i32 v[66:67], s[34:35], v56, s29, v[18:19]
	global_load_dwordx4 v[56:59], v[64:65], off nt
	global_load_dwordx4 v[60:63], v[66:67], off nt
	v_or_b32_e32 v64, 48, v39
	v_mad_i64_i32 v[64:65], s[34:35], v64, s29, v[18:19]
	global_load_dwordx4 v[64:67], v[64:65], off nt
	v_or_b32_e32 v39, 56, v39
	v_mad_i64_i32 v[18:19], s[34:35], v39, s29, v[18:19]
	global_load_dwordx4 v[68:71], v[18:19], off nt
	s_mov_b64 s[0:1], s[86:87]
	s_nop 4
	s_ashr_i32 s25, s24, 31
	s_add_i32 s31, s22, 0xc00
	s_lshl_b64 s[22:23], s[24:25], 1
	v_or_b32_e32 v18, s31, v1
	s_waitcnt lgkmcnt(0)
	s_add_u32 s0, s0, s22
	s_addc_u32 s1, s1, s23
	v_ashrrev_i32_e32 v19, 31, v18
	v_lshl_add_u64 v[74:75], s[0:1], 0, v[2:3]
	v_lshlrev_b64 v[18:19], 11, v[18:19]
	v_lshl_add_u64 v[74:75], v[74:75], 0, s[8:9]
	v_or_b32_e32 v72, s31, v20
	v_lshl_add_u64 v[18:19], v[74:75], 0, v[18:19]
	v_ashrrev_i32_e32 v73, 31, v72
	v_lshlrev_b64 v[72:73], 11, v[72:73]
	v_lshl_add_u64 v[72:73], v[74:75], 0, v[72:73]
	s_waitcnt vmcnt(0)
	ds_write2_b32 v24, v40, v41 offset1:1
	ds_write2_b32 v24, v42, v43 offset0:2 offset1:3
	ds_write2_b32 v25, v44, v45 offset1:1
	ds_write2_b32 v26, v46, v47 offset1:1
	ds_write2_b32 v27, v48, v49 offset1:1
	ds_write2_b32 v28, v50, v51 offset1:1
	ds_write2_b32 v29, v52, v53 offset1:1
	ds_write2_b32 v30, v54, v55 offset1:1
	ds_write2_b32 v31, v56, v57 offset1:1
	ds_write2_b32 v32, v58, v59 offset1:1
	ds_write2_b32 v33, v60, v61 offset1:1
	ds_write2_b32 v34, v62, v63 offset1:1
	ds_write2_b32 v35, v64, v65 offset1:1
	ds_write2_b32 v36, v66, v67 offset1:1
	ds_write2_b32 v37, v68, v69 offset1:1
	ds_write2_b32 v38, v70, v71 offset1:1
	s_waitcnt lgkmcnt(0)
	ds_read2_b32 v[44:45], v23 offset0:33 offset1:41
	ds_read2_b32 v[46:47], v23 offset1:8
	ds_read2_b32 v[48:49], v23 offset0:66 offset1:74
	ds_read2_b32 v[50:51], v23 offset0:99 offset1:107
	ds_read2_b32 v[52:53], v23 offset0:132 offset1:140
	ds_read2_b32 v[54:55], v23 offset0:165 offset1:173
	ds_read2_b32 v[56:57], v23 offset0:198 offset1:206
	ds_read2_b32 v[58:59], v23 offset0:231 offset1:239
	ds_read2_b32 v[60:61], v23 offset0:49 offset1:57
	ds_read2_b32 v[62:63], v23 offset0:16 offset1:24
	ds_read2_b32 v[64:65], v23 offset0:82 offset1:90
	ds_read2_b32 v[66:67], v23 offset0:115 offset1:123
	s_waitcnt lgkmcnt(10)
	v_cvt_pk_bf16_f32 v40, v46, v44
	s_waitcnt lgkmcnt(8)
	v_cvt_pk_bf16_f32 v41, v48, v50
	s_waitcnt lgkmcnt(6)
	v_cvt_pk_bf16_f32 v42, v52, v54
	s_waitcnt lgkmcnt(4)
	v_cvt_pk_bf16_f32 v43, v56, v58
	global_store_dwordx4 v[18:19], v[40:43], off
	v_cvt_pk_bf16_f32 v44, v47, v45
	v_cvt_pk_bf16_f32 v45, v49, v51
	v_cvt_pk_bf16_f32 v46, v53, v55
	ds_read2_b32 v[18:19], v23 offset0:148 offset1:156
	ds_read2_b32 v[48:49], v23 offset0:181 offset1:189
	ds_read2_b32 v[50:51], v23 offset0:214 offset1:222
	ds_read2_b32 v[52:53], v23 offset0:247 offset1:255
	v_cvt_pk_bf16_f32 v47, v57, v59
	global_store_dwordx4 v[72:73], v[44:47], off
	s_waitcnt lgkmcnt(6)
	v_cvt_pk_bf16_f32 v40, v62, v60
	s_waitcnt lgkmcnt(4)
	v_cvt_pk_bf16_f32 v41, v64, v66
	v_or_b32_e32 v44, s31, v21
	v_ashrrev_i32_e32 v45, 31, v44
	v_lshlrev_b64 v[44:45], 11, v[44:45]
	s_waitcnt lgkmcnt(2)
	v_cvt_pk_bf16_f32 v42, v18, v48
	s_waitcnt lgkmcnt(0)
	v_cvt_pk_bf16_f32 v43, v50, v52
	v_lshl_add_u64 v[44:45], v[74:75], 0, v[44:45]
	v_or_b32_e32 v18, s31, v22
	global_store_dwordx4 v[44:45], v[40:43], off
	s_nop 1
	v_cvt_pk_bf16_f32 v42, v19, v49
	v_ashrrev_i32_e32 v19, 31, v18
	v_lshlrev_b64 v[18:19], 11, v[18:19]
	v_cvt_pk_bf16_f32 v40, v63, v61
	v_cvt_pk_bf16_f32 v41, v65, v67
	v_cvt_pk_bf16_f32 v43, v51, v53
	v_lshl_add_u64 v[18:19], v[74:75], 0, v[18:19]
	global_store_dwordx4 v[18:19], v[40:43], off
	s_waitcnt lgkmcnt(0)
	s_cbranch_execz .LBB0_163

; #define LAS __attribute__((address_space(3)))
; __device__ __forceinline__ const float* arg_in(int k) { return (const float*)(const __attribute__((address_space(1))) float*)arg_q(k); }
; __device__ __forceinline__ void xpose_item(const float* W, int ldw, int c0, int K, int ncols, bf16* WT, int d0, int mode, int sel, LAS float* scr, int item, int lane) {
;     const int nblk = ncols >> 5, kb = item / nblk, nb = item - kb * nblk, k0 = 64 * kb, n0 = 32 * nb;
;     const int drow = mode ? d0 + 256 * (n0 >> 7) + 128 * sel + (n0 & 127) : d0 + n0;
;     f32x4 tv[8];
; #pragma unroll
;     for (int i = 0; i < 8; ++i) tv[i] = __builtin_nontemporal_load((const f32x4*)(W + (size_t)(k0 + 8 * i + (lane >> 3)) * ldw + c0 + n0 + 4 * (lane & 7)));
; #pragma unroll
;     for (int i = 0; i < 8; ++i) { LAS float* d = scr + (8 * i + (lane >> 3)) * 33 + 4 * (lane & 7); d[0] = tv[i][0]; d[1] = tv[i][1]; d[2] = tv[i][2]; d[3] = tv[i][3]; }
;     asm volatile("s_waitcnt lgkmcnt(0)" ::: "memory");
;     const int c = lane & 7;
; #pragma unroll
;     for (int j = 0; j < 4; ++j) { const int n = (lane >> 3) + 8 * j; const LAS float* s = scr + (8 * c) * 33 + n;
;         u32x4 o; o.x = cvt_pk_bf16(s[0 * 33], s[1 * 33]); o.y = cvt_pk_bf16(s[2 * 33], s[3 * 33]); o.z = cvt_pk_bf16(s[4 * 33], s[5 * 33]); o.w = cvt_pk_bf16(s[6 * 33], s[7 * 33]);
;         *(u32x4*)(WT + (size_t)(drow + n) * K + k0 + 8 * c) = o; }
;     asm volatile("s_waitcnt lgkmcnt(0)" ::: "memory");
; }
; __global__ void __launch_bounds__(NWAVES * 64, 2) mega_fwd(Args args) {
;     ...
;                 XSEG(w_in, INW, 0, 1024, 3072, WQKV, 0, 0, 0)
;                 XSEG(w_in, INW, 3072, 1024, 1024, WINB, 0, 0, 0)
;                 XSEG(w_in, INW, 5136, 1024, 1024, WINB, 1024, 1, 0)
;                 XSEG(w_in, INW, 6160, 1024, 1024, WINB, 1024, 1, 1)
;                 XSEG(w_in, INW, 4112, 1024, 1024, WINB, 3072, 0, 0)
;                 XSEG(w_in, INW, 7184, 1024, 1024, WINB, 4096, 0, 0)
;                 XSEG(w_in, INW, 8208, 1024, 1024, WINB, 5120, 0, 0)
;                 XSEG(arg_in(17), D, 0, 1024, 1024, WPG, 0, 0, 0)
;                 XSEG(arg_in(19), D, 0, 1024, 1024, WPS, 0, 0, 0)
;                 XSEG(arg_in(20), D, 0, 1024, 1024, WO, 0, 0, 0)
;                 XSEG(arg_in(28), D, 0, 1024, 1024, WPLEG, 0, 0, 0)
;                 XSEG(arg_in(29), D, 0, 256, 1024, WPLEP, 0, 0, 0)
;             }
.LBB0_164:
	s_cmpk_gt_i32 s30, 0x1ff
	s_cselect_b64 s[20:21], -1, 0
	s_mov_b64 s[0:1], -1
	s_and_b64 vcc, exec, s[20:21]
	s_cbranch_vccnz .LBB0_167
	s_ashr_i32 s22, s30, 31
	s_lshr_b32 s22, s22, 27
	s_add_i32 s22, s30, s22
	s_ashr_i32 s23, s22, 5
	s_lshl_b32 s22, s23, 10
	s_lshl_b32 s24, s30, 5
	s_sub_i32 s22, s24, s22
	s_lshl_b32 s24, s23, 6
	s_ashr_i32 s23, s22, 31
	v_or_b32_e32 v39, s24, v1
	v_lshl_add_u64 v[18:19], s[22:23], 2, v[14:15]
	s_mov_b64 s[0:1], s[56:57]
	v_mad_i64_i32 v[48:49], s[34:35], v39, s29, v[18:19]
	v_or_b32_e32 v40, 8, v39
	v_mad_i64_i32 v[50:51], s[34:35], v40, s29, v[18:19]
	global_load_dwordx4 v[40:43], v[48:49], off nt
	global_load_dwordx4 v[44:47], v[50:51], off nt
	v_or_b32_e32 v48, 16, v39
	v_mad_i64_i32 v[56:57], s[34:35], v48, s29, v[18:19]
	v_or_b32_e32 v48, 24, v39
	v_mad_i64_i32 v[58:59], s[34:35], v48, s29, v[18:19]
	global_load_dwordx4 v[48:51], v[56:57], off nt
	global_load_dwordx4 v[52:55], v[58:59], off nt
	v_or_b32_e32 v56, 32, v39
	v_mad_i64_i32 v[64:65], s[34:35], v56, s29, v[18:19]
	v_or_b32_e32 v56, 40, v39
	v_mad_i64_i32 v[66:67], s[34:35], v56, s29, v[18:19]
	global_load_dwordx4 v[56:59], v[64:65], off nt
	global_load_dwordx4 v[60:63], v[66:67], off nt
	v_or_b32_e32 v64, 48, v39
	v_mad_i64_i32 v[64:65], s[34:35], v64, s29, v[18:19]
	global_load_dwordx4 v[64:67], v[64:65], off nt
	v_or_b32_e32 v39, 56, v39
	v_mad_i64_i32 v[18:19], s[34:35], v39, s29, v[18:19]
	global_load_dwordx4 v[68:71], v[18:19], off nt
	s_mov_b64 s[0:1], s[86:87]
	s_nop 4
	s_ashr_i32 s25, s24, 31
	s_add_i32 s31, s22, 0x1000
	s_lshl_b64 s[22:23], s[24:25], 1
	v_or_b32_e32 v18, s31, v1
	s_waitcnt lgkmcnt(0)
	s_add_u32 s0, s0, s22
	s_addc_u32 s1, s1, s23
	v_ashrrev_i32_e32 v19, 31, v18
	v_lshl_add_u64 v[74:75], s[0:1], 0, v[2:3]
	v_lshlrev_b64 v[18:19], 11, v[18:19]
	v_lshl_add_u64 v[74:75], v[74:75], 0, s[8:9]
	v_or_b32_e32 v72, s31, v20
	v_lshl_add_u64 v[18:19], v[74:75], 0, v[18:19]
	v_ashrrev_i32_e32 v73, 31, v72
	v_lshlrev_b64 v[72:73], 11, v[72:73]
	v_lshl_add_u64 v[72:73], v[74:75], 0, v[72:73]
	s_waitcnt vmcnt(0)
	ds_write2_b32 v24, v40, v41 offset1:1
	ds_write2_b32 v24, v42, v43 offset0:2 offset1:3
	ds_write2_b32 v25, v44, v45 offset1:1
	ds_write2_b32 v26, v46, v47 offset1:1
	ds_write2_b32 v27, v48, v49 offset1:1
	ds_write2_b32 v28, v50, v51 offset1:1
	ds_write2_b32 v29, v52, v53 offset1:1
	ds_write2_b32 v30, v54, v55 offset1:1
	ds_write2_b32 v31, v56, v57 offset1:1
	ds_write2_b32 v32, v58, v59 offset1:1
	ds_write2_b32 v33, v60, v61 offset1:1
	ds_write2_b32 v34, v62, v63 offset1:1
	ds_write2_b32 v35, v64, v65 offset1:1
	ds_write2_b32 v36, v66, v67 offset1:1
	ds_write2_b32 v37, v68, v69 offset1:1
	ds_write2_b32 v38, v70, v71 offset1:1
	s_waitcnt lgkmcnt(0)
	ds_read2_b32 v[44:45], v23 offset0:33 offset1:41
	ds_read2_b32 v[46:47], v23 offset1:8
	ds_read2_b32 v[48:49], v23 offset0:66 offset1:74
	ds_read2_b32 v[50:51], v23 offset0:99 offset1:107
	ds_read2_b32 v[52:53], v23 offset0:132 offset1:140
	ds_read2_b32 v[54:55], v23 offset0:165 offset1:173
	ds_read2_b32 v[56:57], v23 offset0:198 offset1:206
	ds_read2_b32 v[58:59], v23 offset0:231 offset1:239
	ds_read2_b32 v[60:61], v23 offset0:49 offset1:57
	ds_read2_b32 v[62:63], v23 offset0:16 offset1:24
	ds_read2_b32 v[64:65], v23 offset0:82 offset1:90
	ds_read2_b32 v[66:67], v23 offset0:115 offset1:123
	s_waitcnt lgkmcnt(10)
	v_cvt_pk_bf16_f32 v40, v46, v44
	s_waitcnt lgkmcnt(8)
	v_cvt_pk_bf16_f32 v41, v48, v50
	s_waitcnt lgkmcnt(6)
	v_cvt_pk_bf16_f32 v42, v52, v54
	s_waitcnt lgkmcnt(4)
	v_cvt_pk_bf16_f32 v43, v56, v58
	global_store_dwordx4 v[18:19], v[40:43], off
	v_cvt_pk_bf16_f32 v44, v47, v45
	v_cvt_pk_bf16_f32 v45, v49, v51
	v_cvt_pk_bf16_f32 v46, v53, v55
	ds_read2_b32 v[18:19], v23 offset0:148 offset1:156
	ds_read2_b32 v[48:49], v23 offset0:181 offset1:189
	ds_read2_b32 v[50:51], v23 offset0:214 offset1:222
	ds_read2_b32 v[52:53], v23 offset0:247 offset1:255
	v_cvt_pk_bf16_f32 v47, v57, v59
	global_store_dwordx4 v[72:73], v[44:47], off
	s_waitcnt lgkmcnt(6)
	v_cvt_pk_bf16_f32 v40, v62, v60
	s_waitcnt lgkmcnt(4)
	v_cvt_pk_bf16_f32 v41, v64, v66
	v_or_b32_e32 v44, s31, v21
	v_ashrrev_i32_e32 v45, 31, v44
	v_lshlrev_b64 v[44:45], 11, v[44:45]
	s_waitcnt lgkmcnt(2)
	v_cvt_pk_bf16_f32 v42, v18, v48
	s_waitcnt lgkmcnt(0)
	v_cvt_pk_bf16_f32 v43, v50, v52
	v_lshl_add_u64 v[44:45], v[74:75], 0, v[44:45]
	v_or_b32_e32 v18, s31, v22
	global_store_dwordx4 v[44:45], v[40:43], off
	s_nop 1
	v_cvt_pk_bf16_f32 v42, v19, v49
	v_ashrrev_i32_e32 v19, 31, v18
	v_lshlrev_b64 v[18:19], 11, v[18:19]
	v_cvt_pk_bf16_f32 v40, v63, v61
	v_cvt_pk_bf16_f32 v41, v65, v67
	v_cvt_pk_bf16_f32 v43, v51, v53
	v_lshl_add_u64 v[18:19], v[74:75], 0, v[18:19]
	global_store_dwordx4 v[18:19], v[40:43], off
	s_waitcnt lgkmcnt(0)
	s_cbranch_execz .LBB0_168

; #define LAS __attribute__((address_space(3)))
; __device__ __forceinline__ const float* arg_in(int k) { return (const float*)(const __attribute__((address_space(1))) float*)arg_q(k); }
; __device__ __forceinline__ void xpose_item(const float* W, int ldw, int c0, int K, int ncols, bf16* WT, int d0, int mode, int sel, LAS float* scr, int item, int lane) {
;     const int nblk = ncols >> 5, kb = item / nblk, nb = item - kb * nblk, k0 = 64 * kb, n0 = 32 * nb;
;     const int drow = mode ? d0 + 256 * (n0 >> 7) + 128 * sel + (n0 & 127) : d0 + n0;
;     f32x4 tv[8];
; #pragma unroll
;     for (int i = 0; i < 8; ++i) tv[i] = __builtin_nontemporal_load((const f32x4*)(W + (size_t)(k0 + 8 * i + (lane >> 3)) * ldw + c0 + n0 + 4 * (lane & 7)));
; #pragma unroll
;     for (int i = 0; i < 8; ++i) { LAS float* d = scr + (8 * i + (lane >> 3)) * 33 + 4 * (lane & 7); d[0] = tv[i][0]; d[1] = tv[i][1]; d[2] = tv[i][2]; d[3] = tv[i][3]; }
;     asm volatile("s_waitcnt lgkmcnt(0)" ::: "memory");
;     const int c = lane & 7;
; #pragma unroll
;     for (int j = 0; j < 4; ++j) { const int n = (lane >> 3) + 8 * j; const LAS float* s = scr + (8 * c) * 33 + n;
;         u32x4 o; o.x = cvt_pk_bf16(s[0 * 33], s[1 * 33]); o.y = cvt_pk_bf16(s[2 * 33], s[3 * 33]); o.z = cvt_pk_bf16(s[4 * 33], s[5 * 33]); o.w = cvt_pk_bf16(s[6 * 33], s[7 * 33]);
;         *(u32x4*)(WT + (size_t)(drow + n) * K + k0 + 8 * c) = o; }
;     asm volatile("s_waitcnt lgkmcnt(0)" ::: "memory");
; }
; __global__ void __launch_bounds__(NWAVES * 64, 2) mega_fwd(Args args) {
;     ...
;                 XSEG(w_in, INW, 0, 1024, 3072, WQKV, 0, 0, 0)
;                 XSEG(w_in, INW, 3072, 1024, 1024, WINB, 0, 0, 0)
;                 XSEG(w_in, INW, 5136, 1024, 1024, WINB, 1024, 1, 0)
;                 XSEG(w_in, INW, 6160, 1024, 1024, WINB, 1024, 1, 1)
;                 XSEG(w_in, INW, 4112, 1024, 1024, WINB, 3072, 0, 0)
;                 XSEG(w_in, INW, 7184, 1024, 1024, WINB, 4096, 0, 0)
;                 XSEG(w_in, INW, 8208, 1024, 1024, WINB, 5120, 0, 0)
;                 XSEG(arg_in(17), D, 0, 1024, 1024, WPG, 0, 0, 0)
;                 XSEG(arg_in(19), D, 0, 1024, 1024, WPS, 0, 0, 0)
;                 XSEG(arg_in(20), D, 0, 1024, 1024, WO, 0, 0, 0)
;                 XSEG(arg_in(28), D, 0, 1024, 1024, WPLEG, 0, 0, 0)
;                 XSEG(arg_in(29), D, 0, 256, 1024, WPLEP, 0, 0, 0)
;             }
.LBB0_169:
	s_cmpk_gt_i32 s30, 0x1ff
	s_cselect_b64 s[20:21], -1, 0
	s_mov_b64 s[0:1], -1
	s_and_b64 vcc, exec, s[20:21]
	s_cbranch_vccnz .LBB0_172
	s_ashr_i32 s22, s30, 31
	s_lshr_b32 s22, s22, 27
	s_add_i32 s22, s30, s22
	s_ashr_i32 s23, s22, 5
	s_lshl_b32 s22, s23, 10
	s_lshl_b32 s24, s30, 5
	s_sub_i32 s22, s24, s22
	s_lshl_b32 s24, s23, 6
	s_ashr_i32 s23, s22, 31
	v_or_b32_e32 v39, s24, v1
	v_lshl_add_u64 v[18:19], s[22:23], 2, v[16:17]
	s_mov_b64 s[0:1], s[56:57]
	v_mad_i64_i32 v[48:49], s[34:35], v39, s29, v[18:19]
	v_or_b32_e32 v40, 8, v39
	v_mad_i64_i32 v[50:51], s[34:35], v40, s29, v[18:19]
	global_load_dwordx4 v[40:43], v[48:49], off nt
	global_load_dwordx4 v[44:47], v[50:51], off nt
	v_or_b32_e32 v48, 16, v39
	v_mad_i64_i32 v[56:57], s[34:35], v48, s29, v[18:19]
	v_or_b32_e32 v48, 24, v39
	v_mad_i64_i32 v[58:59], s[34:35], v48, s29, v[18:19]
	global_load_dwordx4 v[48:51], v[56:57], off nt
	global_load_dwordx4 v[52:55], v[58:59], off nt
	v_or_b32_e32 v56, 32, v39
	v_mad_i64_i32 v[64:65], s[34:35], v56, s29, v[18:19]
	v_or_b32_e32 v56, 40, v39
	v_mad_i64_i32 v[66:67], s[34:35], v56, s29, v[18:19]
	global_load_dwordx4 v[56:59], v[64:65], off nt
	global_load_dwordx4 v[60:63], v[66:67], off nt
	v_or_b32_e32 v64, 48, v39
	v_mad_i64_i32 v[64:65], s[34:35], v64, s29, v[18:19]
	global_load_dwordx4 v[64:67], v[64:65], off nt
	v_or_b32_e32 v39, 56, v39
	v_mad_i64_i32 v[18:19], s[34:35], v39, s29, v[18:19]
	global_load_dwordx4 v[68:71], v[18:19], off nt
	s_mov_b64 s[0:1], s[86:87]
	s_nop 4
	s_ashr_i32 s25, s24, 31
	s_add_i32 s31, s22, 0x1400
	s_lshl_b64 s[22:23], s[24:25], 1
	v_or_b32_e32 v18, s31, v1
	s_waitcnt lgkmcnt(0)
	s_add_u32 s0, s0, s22
	s_addc_u32 s1, s1, s23
	v_ashrrev_i32_e32 v19, 31, v18
	v_lshl_add_u64 v[74:75], s[0:1], 0, v[2:3]
	v_lshlrev_b64 v[18:19], 11, v[18:19]
	v_lshl_add_u64 v[74:75], v[74:75], 0, s[8:9]
	v_or_b32_e32 v72, s31, v20
	v_lshl_add_u64 v[18:19], v[74:75], 0, v[18:19]
	v_ashrrev_i32_e32 v73, 31, v72
	v_lshlrev_b64 v[72:73], 11, v[72:73]
	v_lshl_add_u64 v[72:73], v[74:75], 0, v[72:73]
	s_waitcnt vmcnt(0)
	ds_write2_b32 v24, v40, v41 offset1:1
	ds_write2_b32 v24, v42, v43 offset0:2 offset1:3
	ds_write2_b32 v25, v44, v45 offset1:1
	ds_write2_b32 v26, v46, v47 offset1:1
	ds_write2_b32 v27, v48, v49 offset1:1
	ds_write2_b32 v28, v50, v51 offset1:1
	ds_write2_b32 v29, v52, v53 offset1:1
	ds_write2_b32 v30, v54, v55 offset1:1
	ds_write2_b32 v31, v56, v57 offset1:1
	ds_write2_b32 v32, v58, v59 offset1:1
	ds_write2_b32 v33, v60, v61 offset1:1
	ds_write2_b32 v34, v62, v63 offset1:1
	ds_write2_b32 v35, v64, v65 offset1:1
	ds_write2_b32 v36, v66, v67 offset1:1
	ds_write2_b32 v37, v68, v69 offset1:1
	ds_write2_b32 v38, v70, v71 offset1:1
	s_waitcnt lgkmcnt(0)
	ds_read2_b32 v[44:45], v23 offset0:33 offset1:41
	ds_read2_b32 v[46:47], v23 offset1:8
	ds_read2_b32 v[48:49], v23 offset0:66 offset1:74
	ds_read2_b32 v[50:51], v23 offset0:99 offset1:107
	ds_read2_b32 v[52:53], v23 offset0:132 offset1:140
	ds_read2_b32 v[54:55], v23 offset0:165 offset1:173
	ds_read2_b32 v[56:57], v23 offset0:198 offset1:206
	ds_read2_b32 v[58:59], v23 offset0:231 offset1:239
	ds_read2_b32 v[60:61], v23 offset0:49 offset1:57
	ds_read2_b32 v[62:63], v23 offset0:16 offset1:24
	ds_read2_b32 v[64:65], v23 offset0:82 offset1:90
	ds_read2_b32 v[66:67], v23 offset0:115 offset1:123
	s_waitcnt lgkmcnt(10)
	v_cvt_pk_bf16_f32 v40, v46, v44
	s_waitcnt lgkmcnt(8)
	v_cvt_pk_bf16_f32 v41, v48, v50
	s_waitcnt lgkmcnt(6)
	v_cvt_pk_bf16_f32 v42, v52, v54
	s_waitcnt lgkmcnt(4)
	v_cvt_pk_bf16_f32 v43, v56, v58
	global_store_dwordx4 v[18:19], v[40:43], off
	v_cvt_pk_bf16_f32 v44, v47, v45
	v_cvt_pk_bf16_f32 v45, v49, v51
	v_cvt_pk_bf16_f32 v46, v53, v55
	ds_read2_b32 v[18:19], v23 offset0:148 offset1:156
	ds_read2_b32 v[48:49], v23 offset0:181 offset1:189
	ds_read2_b32 v[50:51], v23 offset0:214 offset1:222
	ds_read2_b32 v[52:53], v23 offset0:247 offset1:255
	v_cvt_pk_bf16_f32 v47, v57, v59
	global_store_dwordx4 v[72:73], v[44:47], off
	s_waitcnt lgkmcnt(6)
	v_cvt_pk_bf16_f32 v40, v62, v60
	s_waitcnt lgkmcnt(4)
	v_cvt_pk_bf16_f32 v41, v64, v66
	v_or_b32_e32 v44, s31, v21
	v_ashrrev_i32_e32 v45, 31, v44
	v_lshlrev_b64 v[44:45], 11, v[44:45]
	s_waitcnt lgkmcnt(2)
	v_cvt_pk_bf16_f32 v42, v18, v48
	s_waitcnt lgkmcnt(0)
	v_cvt_pk_bf16_f32 v43, v50, v52
	v_lshl_add_u64 v[44:45], v[74:75], 0, v[44:45]
	v_or_b32_e32 v18, s31, v22
	global_store_dwordx4 v[44:45], v[40:43], off
	s_nop 1
	v_cvt_pk_bf16_f32 v42, v19, v49
	v_ashrrev_i32_e32 v19, 31, v18
	v_lshlrev_b64 v[18:19], 11, v[18:19]
	v_cvt_pk_bf16_f32 v40, v63, v61
	v_cvt_pk_bf16_f32 v41, v65, v67
	v_cvt_pk_bf16_f32 v43, v51, v53
	v_lshl_add_u64 v[18:19], v[74:75], 0, v[18:19]
	global_store_dwordx4 v[18:19], v[40:43], off
	s_waitcnt lgkmcnt(0)
	s_cbranch_execz .LBB0_173

; #define LAS __attribute__((address_space(3)))
; #define XSEG(W, ldw, c0, K, ncols, WT, d0, mode, sel) { const int ni_ = ((K) / 64) * ((ncols) / 32); if (r_ < ni_) { xpose_item(W, ldw, c0, K, ncols, WT, d0, mode, sel, scr, r_, lane); continue; } r_ -= ni_; }
; __device__ __forceinline__ const float* arg_in(int k) { return (const float*)(const __attribute__((address_space(1))) float*)arg_q(k); }
; __device__ __forceinline__ void xpose_item(const float* W, int ldw, int c0, int K, int ncols, bf16* WT, int d0, int mode, int sel, LAS float* scr, int item, int lane) {
;     const int nblk = ncols >> 5, kb = item / nblk, nb = item - kb * nblk, k0 = 64 * kb, n0 = 32 * nb;
;     const int drow = mode ? d0 + 256 * (n0 >> 7) + 128 * sel + (n0 & 127) : d0 + n0;
;     f32x4 tv[8];
; #pragma unroll
;     for (int i = 0; i < 8; ++i) tv[i] = __builtin_nontemporal_load((const f32x4*)(W + (size_t)(k0 + 8 * i + (lane >> 3)) * ldw + c0 + n0 + 4 * (lane & 7)));
; #pragma unroll
;     for (int i = 0; i < 8; ++i) { LAS float* d = scr + (8 * i + (lane >> 3)) * 33 + 4 * (lane & 7); d[0] = tv[i][0]; d[1] = tv[i][1]; d[2] = tv[i][2]; d[3] = tv[i][3]; }
;     asm volatile("s_waitcnt lgkmcnt(0)" ::: "memory");
;     const int c = lane & 7;
; #pragma unroll
;     for (int j = 0; j < 4; ++j) { const int n = (lane >> 3) + 8 * j; const LAS float* s = scr + (8 * c) * 33 + n;
;         u32x4 o; o.x = cvt_pk_bf16(s[0 * 33], s[1 * 33]); o.y = cvt_pk_bf16(s[2 * 33], s[3 * 33]); o.z = cvt_pk_bf16(s[4 * 33], s[5 * 33]); o.w = cvt_pk_bf16(s[6 * 33], s[7 * 33]);
;         *(u32x4*)(WT + (size_t)(drow + n) * K + k0 + 8 * c) = o; }
;     asm volatile("s_waitcnt lgkmcnt(0)" ::: "memory");
; }
; __global__ void __launch_bounds__(NWAVES * 64, 2) mega_fwd(Args args) {
;     ...
;                 XSEG(arg_in(17), D, 0, 1024, 1024, WPG, 0, 0, 0)
.LBB0_174:
	s_cmpk_gt_i32 s30, 0x1ff
	s_cselect_b64 s[20:21], -1, 0
	s_mov_b64 s[0:1], -1
	s_and_b64 vcc, exec, s[20:21]
	s_cbranch_vccnz .LBB0_177
	s_ashr_i32 s22, s30, 31
	s_mov_b64 s[0:1], s[56:57]
	s_lshr_b32 s22, s22, 27
	s_add_i32 s22, s30, s22
	s_load_dwordx2 s[0:1], s[0:1], 0x88
	s_ashr_i32 s23, s22, 5
	s_lshl_b32 s22, s23, 10
	s_lshl_b32 s24, s30, 5
	s_sub_i32 s22, s24, s22
	s_lshl_b32 s24, s23, 6
	s_ashr_i32 s23, s22, 31
	v_or_b32_e32 v18, s24, v1
	s_lshl_b64 s[36:37], s[22:23], 2
	s_waitcnt lgkmcnt(0)
	s_add_u32 s0, s0, s36
	v_or_b32_e32 v48, 16, v18
	s_addc_u32 s1, s1, s37
	v_lshlrev_b32_e32 v40, 2, v0
	v_mov_b32_e32 v41, v3
	v_ashrrev_i32_e32 v49, 31, v48
	v_lshl_add_u64 v[68:69], s[0:1], 0, v[40:41]
	v_or_b32_e32 v42, 8, v18
	v_lshlrev_b64 v[48:49], 12, v[48:49]
	v_ashrrev_i32_e32 v19, 31, v18
	v_ashrrev_i32_e32 v43, 31, v42
	v_lshl_add_u64 v[56:57], v[68:69], 0, v[48:49]
	v_or_b32_e32 v48, 24, v18
	v_lshlrev_b64 v[40:41], 12, v[18:19]
	v_lshlrev_b64 v[42:43], 12, v[42:43]
	v_ashrrev_i32_e32 v49, 31, v48
	s_mov_b64 s[34:35], s[56:57]
	v_lshl_add_u64 v[40:41], v[68:69], 0, v[40:41]
	v_lshl_add_u64 v[44:45], v[68:69], 0, v[42:43]
	v_lshlrev_b64 v[48:49], 12, v[48:49]
	global_load_dwordx4 v[40:43], v[40:41], off nt
	s_nop 0
	global_load_dwordx4 v[44:47], v[44:45], off nt
	v_lshl_add_u64 v[58:59], v[68:69], 0, v[48:49]
	global_load_dwordx4 v[48:51], v[56:57], off nt
	global_load_dwordx4 v[52:55], v[58:59], off nt
	v_or_b32_e32 v56, 32, v18
	v_ashrrev_i32_e32 v57, 31, v56
	v_lshlrev_b64 v[56:57], 12, v[56:57]
	v_lshl_add_u64 v[64:65], v[68:69], 0, v[56:57]
	v_or_b32_e32 v56, 40, v18
	v_ashrrev_i32_e32 v57, 31, v56
	v_lshlrev_b64 v[56:57], 12, v[56:57]
	v_lshl_add_u64 v[66:67], v[68:69], 0, v[56:57]
	global_load_dwordx4 v[56:59], v[64:65], off nt
	global_load_dwordx4 v[60:63], v[66:67], off nt
	v_or_b32_e32 v64, 48, v18
	v_ashrrev_i32_e32 v65, 31, v64
	v_lshlrev_b64 v[64:65], 12, v[64:65]
	v_or_b32_e32 v18, 56, v18
	v_lshl_add_u64 v[64:65], v[68:69], 0, v[64:65]
	v_ashrrev_i32_e32 v19, 31, v18
	global_load_dwordx4 v[64:67], v[64:65], off nt
	v_lshlrev_b64 v[18:19], 12, v[18:19]
	v_lshl_add_u64 v[18:19], v[68:69], 0, v[18:19]
	global_load_dwordx4 v[68:71], v[18:19], off nt
	s_mov_b64 s[0:1], s[86:87]
	s_nop 4
	s_ashr_i32 s25, s24, 31
	s_lshl_b64 s[24:25], s[24:25], 1
	v_or_b32_e32 v18, s22, v1
	v_ashrrev_i32_e32 v19, 31, v18
	s_waitcnt lgkmcnt(0)
	s_add_u32 s0, s0, s24
	s_addc_u32 s1, s1, s25
	v_lshl_add_u64 v[72:73], s[0:1], 0, v[2:3]
	v_lshlrev_b64 v[18:19], 11, v[18:19]
	v_lshl_add_u64 v[72:73], v[72:73], 0, s[10:11]
	v_lshl_add_u64 v[18:19], v[72:73], 0, v[18:19]
	s_waitcnt vmcnt(0)
	ds_write2_b32 v24, v40, v41 offset1:1
	ds_write2_b32 v24, v42, v43 offset0:2 offset1:3
	ds_write2_b32 v25, v44, v45 offset1:1
	ds_write2_b32 v26, v46, v47 offset1:1
	ds_write2_b32 v27, v48, v49 offset1:1
	ds_write2_b32 v28, v50, v51 offset1:1
	ds_write2_b32 v29, v52, v53 offset1:1
	ds_write2_b32 v30, v54, v55 offset1:1
	ds_write2_b32 v31, v56, v57 offset1:1
	ds_write2_b32 v32, v58, v59 offset1:1
	ds_write2_b32 v33, v60, v61 offset1:1
	ds_write2_b32 v34, v62, v63 offset1:1
	ds_write2_b32 v35, v64, v65 offset1:1
	ds_write2_b32 v36, v66, v67 offset1:1
	ds_write2_b32 v37, v68, v69 offset1:1
	ds_write2_b32 v38, v70, v71 offset1:1
	s_waitcnt lgkmcnt(0)
	ds_read2_b32 v[44:45], v23 offset0:33 offset1:41
	ds_read2_b32 v[46:47], v23 offset1:8
	ds_read2_b32 v[48:49], v23 offset0:66 offset1:74
	ds_read2_b32 v[50:51], v23 offset0:99 offset1:107
	ds_read2_b32 v[52:53], v23 offset0:132 offset1:140
	ds_read2_b32 v[54:55], v23 offset0:165 offset1:173
	ds_read2_b32 v[56:57], v23 offset0:198 offset1:206
	ds_read2_b32 v[58:59], v23 offset0:231 offset1:239
	s_waitcnt lgkmcnt(6)
	v_cvt_pk_bf16_f32 v40, v46, v44
	s_waitcnt lgkmcnt(4)
	v_cvt_pk_bf16_f32 v41, v48, v50
	s_waitcnt lgkmcnt(2)
	v_cvt_pk_bf16_f32 v42, v52, v54
	s_waitcnt lgkmcnt(0)
	v_cvt_pk_bf16_f32 v43, v56, v58
	global_store_dwordx4 v[18:19], v[40:43], off
	v_or_b32_e32 v18, s22, v20
	v_ashrrev_i32_e32 v19, 31, v18
	v_cvt_pk_bf16_f32 v40, v47, v45
	v_cvt_pk_bf16_f32 v41, v49, v51
	v_cvt_pk_bf16_f32 v42, v53, v55
	v_cvt_pk_bf16_f32 v43, v57, v59
	v_lshlrev_b64 v[18:19], 11, v[18:19]
	ds_read2_b32 v[44:45], v23 offset0:49 offset1:57
	ds_read2_b32 v[46:47], v23 offset0:16 offset1:24
	ds_read2_b32 v[48:49], v23 offset0:82 offset1:90
	ds_read2_b32 v[50:51], v23 offset0:115 offset1:123
	ds_read2_b32 v[52:53], v23 offset0:148 offset1:156
	ds_read2_b32 v[54:55], v23 offset0:181 offset1:189
	ds_read2_b32 v[56:57], v23 offset0:214 offset1:222
	ds_read2_b32 v[58:59], v23 offset0:247 offset1:255
	v_lshl_add_u64 v[18:19], v[72:73], 0, v[18:19]
	global_store_dwordx4 v[18:19], v[40:43], off
	v_or_b32_e32 v18, s22, v21
	v_ashrrev_i32_e32 v19, 31, v18
	v_lshlrev_b64 v[18:19], 11, v[18:19]
	s_waitcnt lgkmcnt(6)
	v_cvt_pk_bf16_f32 v40, v46, v44
	s_waitcnt lgkmcnt(4)
	v_cvt_pk_bf16_f32 v41, v48, v50
	s_waitcnt lgkmcnt(2)
	v_cvt_pk_bf16_f32 v42, v52, v54
	s_waitcnt lgkmcnt(0)
	v_cvt_pk_bf16_f32 v43, v56, v58
	v_lshl_add_u64 v[18:19], v[72:73], 0, v[18:19]
	global_store_dwordx4 v[18:19], v[40:43], off
	v_or_b32_e32 v18, s22, v22
	v_ashrrev_i32_e32 v19, 31, v18
	v_lshlrev_b64 v[18:19], 11, v[18:19]
	v_cvt_pk_bf16_f32 v40, v47, v45
	v_cvt_pk_bf16_f32 v41, v49, v51
	v_cvt_pk_bf16_f32 v42, v53, v55
	v_cvt_pk_bf16_f32 v43, v57, v59
	v_lshl_add_u64 v[18:19], v[72:73], 0, v[18:19]
	global_store_dwordx4 v[18:19], v[40:43], off
	s_waitcnt lgkmcnt(0)
	s_cbranch_execz .LBB0_178

; #define LAS __attribute__((address_space(3)))
; #define XSEG(W, ldw, c0, K, ncols, WT, d0, mode, sel) { const int ni_ = ((K) / 64) * ((ncols) / 32); if (r_ < ni_) { xpose_item(W, ldw, c0, K, ncols, WT, d0, mode, sel, scr, r_, lane); continue; } r_ -= ni_; }
; __device__ __forceinline__ const float* arg_in(int k) { return (const float*)(const __attribute__((address_space(1))) float*)arg_q(k); }
; __device__ __forceinline__ void xpose_item(const float* W, int ldw, int c0, int K, int ncols, bf16* WT, int d0, int mode, int sel, LAS float* scr, int item, int lane) {
;     const int nblk = ncols >> 5, kb = item / nblk, nb = item - kb * nblk, k0 = 64 * kb, n0 = 32 * nb;
;     const int drow = mode ? d0 + 256 * (n0 >> 7) + 128 * sel + (n0 & 127) : d0 + n0;
;     f32x4 tv[8];
; #pragma unroll
;     for (int i = 0; i < 8; ++i) tv[i] = __builtin_nontemporal_load((const f32x4*)(W + (size_t)(k0 + 8 * i + (lane >> 3)) * ldw + c0 + n0 + 4 * (lane & 7)));
; #pragma unroll
;     for (int i = 0; i < 8; ++i) { LAS float* d = scr + (8 * i + (lane >> 3)) * 33 + 4 * (lane & 7); d[0] = tv[i][0]; d[1] = tv[i][1]; d[2] = tv[i][2]; d[3] = tv[i][3]; }
;     asm volatile("s_waitcnt lgkmcnt(0)" ::: "memory");
;     const int c = lane & 7;
; #pragma unroll
;     for (int j = 0; j < 4; ++j) { const int n = (lane >> 3) + 8 * j; const LAS float* s = scr + (8 * c) * 33 + n;
;         u32x4 o; o.x = cvt_pk_bf16(s[0 * 33], s[1 * 33]); o.y = cvt_pk_bf16(s[2 * 33], s[3 * 33]); o.z = cvt_pk_bf16(s[4 * 33], s[5 * 33]); o.w = cvt_pk_bf16(s[6 * 33], s[7 * 33]);
;         *(u32x4*)(WT + (size_t)(drow + n) * K + k0 + 8 * c) = o; }
;     asm volatile("s_waitcnt lgkmcnt(0)" ::: "memory");
; }
; __global__ void __launch_bounds__(NWAVES * 64, 2) mega_fwd(Args args) {
;     ...
;                 XSEG(arg_in(19), D, 0, 1024, 1024, WPS, 0, 0, 0)
.LBB0_179:
	s_cmpk_gt_i32 s30, 0x1ff
	s_cselect_b64 s[20:21], -1, 0
	s_mov_b64 s[0:1], -1
	s_and_b64 vcc, exec, s[20:21]
	s_cbranch_vccnz .LBB0_182
	s_ashr_i32 s22, s30, 31
	s_mov_b64 s[0:1], s[56:57]
	s_lshr_b32 s22, s22, 27
	s_add_i32 s22, s30, s22
	s_load_dwordx2 s[0:1], s[0:1], 0x98
	s_ashr_i32 s23, s22, 5
	s_lshl_b32 s22, s23, 10
	s_lshl_b32 s24, s30, 5
	s_sub_i32 s22, s24, s22
	s_lshl_b32 s24, s23, 6
	s_ashr_i32 s23, s22, 31
	v_or_b32_e32 v18, s24, v1
	s_lshl_b64 s[36:37], s[22:23], 2
	s_waitcnt lgkmcnt(0)
	s_add_u32 s0, s0, s36
	v_or_b32_e32 v48, 16, v18
	s_addc_u32 s1, s1, s37
	v_lshlrev_b32_e32 v40, 2, v0
	v_mov_b32_e32 v41, v3
	v_ashrrev_i32_e32 v49, 31, v48
	v_lshl_add_u64 v[68:69], s[0:1], 0, v[40:41]
	v_or_b32_e32 v42, 8, v18
	v_lshlrev_b64 v[48:49], 12, v[48:49]
	v_ashrrev_i32_e32 v19, 31, v18
	v_ashrrev_i32_e32 v43, 31, v42
	v_lshl_add_u64 v[56:57], v[68:69], 0, v[48:49]
	v_or_b32_e32 v48, 24, v18
	v_lshlrev_b64 v[40:41], 12, v[18:19]
	v_lshlrev_b64 v[42:43], 12, v[42:43]
	v_ashrrev_i32_e32 v49, 31, v48
	s_mov_b64 s[34:35], s[56:57]
	v_lshl_add_u64 v[40:41], v[68:69], 0, v[40:41]
	v_lshl_add_u64 v[44:45], v[68:69], 0, v[42:43]
	v_lshlrev_b64 v[48:49], 12, v[48:49]
	global_load_dwordx4 v[40:43], v[40:41], off nt
	s_nop 0
	global_load_dwordx4 v[44:47], v[44:45], off nt
	v_lshl_add_u64 v[58:59], v[68:69], 0, v[48:49]
	global_load_dwordx4 v[48:51], v[56:57], off nt
	global_load_dwordx4 v[52:55], v[58:59], off nt
	v_or_b32_e32 v56, 32, v18
	v_ashrrev_i32_e32 v57, 31, v56
	v_lshlrev_b64 v[56:57], 12, v[56:57]
	v_lshl_add_u64 v[64:65], v[68:69], 0, v[56:57]
	v_or_b32_e32 v56, 40, v18
	v_ashrrev_i32_e32 v57, 31, v56
	v_lshlrev_b64 v[56:57], 12, v[56:57]
	v_lshl_add_u64 v[66:67], v[68:69], 0, v[56:57]
	global_load_dwordx4 v[56:59], v[64:65], off nt
	global_load_dwordx4 v[60:63], v[66:67], off nt
	v_or_b32_e32 v64, 48, v18
	v_ashrrev_i32_e32 v65, 31, v64
	v_lshlrev_b64 v[64:65], 12, v[64:65]
	v_or_b32_e32 v18, 56, v18
	v_lshl_add_u64 v[64:65], v[68:69], 0, v[64:65]
	v_ashrrev_i32_e32 v19, 31, v18
	global_load_dwordx4 v[64:67], v[64:65], off nt
	v_lshlrev_b64 v[18:19], 12, v[18:19]
	v_lshl_add_u64 v[18:19], v[68:69], 0, v[18:19]
	global_load_dwordx4 v[68:71], v[18:19], off nt
	s_mov_b64 s[0:1], s[86:87]
	s_nop 4
	s_ashr_i32 s25, s24, 31
	s_lshl_b64 s[24:25], s[24:25], 1
	v_or_b32_e32 v18, s22, v1
	v_ashrrev_i32_e32 v19, 31, v18
	s_waitcnt lgkmcnt(0)
	s_add_u32 s0, s0, s24
	s_addc_u32 s1, s1, s25
	v_lshl_add_u64 v[72:73], s[0:1], 0, v[2:3]
	v_lshlrev_b64 v[18:19], 11, v[18:19]
	v_lshl_add_u64 v[72:73], v[72:73], 0, s[12:13]
	v_lshl_add_u64 v[18:19], v[72:73], 0, v[18:19]
	s_waitcnt vmcnt(0)
	ds_write2_b32 v24, v40, v41 offset1:1
	ds_write2_b32 v24, v42, v43 offset0:2 offset1:3
	ds_write2_b32 v25, v44, v45 offset1:1
	ds_write2_b32 v26, v46, v47 offset1:1
	ds_write2_b32 v27, v48, v49 offset1:1
	ds_write2_b32 v28, v50, v51 offset1:1
	ds_write2_b32 v29, v52, v53 offset1:1
	ds_write2_b32 v30, v54, v55 offset1:1
	ds_write2_b32 v31, v56, v57 offset1:1
	ds_write2_b32 v32, v58, v59 offset1:1
	ds_write2_b32 v33, v60, v61 offset1:1
	ds_write2_b32 v34, v62, v63 offset1:1
	ds_write2_b32 v35, v64, v65 offset1:1
	ds_write2_b32 v36, v66, v67 offset1:1
	ds_write2_b32 v37, v68, v69 offset1:1
	ds_write2_b32 v38, v70, v71 offset1:1
	s_waitcnt lgkmcnt(0)
	ds_read2_b32 v[44:45], v23 offset0:33 offset1:41
	ds_read2_b32 v[46:47], v23 offset1:8
	ds_read2_b32 v[48:49], v23 offset0:66 offset1:74
	ds_read2_b32 v[50:51], v23 offset0:99 offset1:107
	ds_read2_b32 v[52:53], v23 offset0:132 offset1:140
	ds_read2_b32 v[54:55], v23 offset0:165 offset1:173
	ds_read2_b32 v[56:57], v23 offset0:198 offset1:206
	ds_read2_b32 v[58:59], v23 offset0:231 offset1:239
	s_waitcnt lgkmcnt(6)
	v_cvt_pk_bf16_f32 v40, v46, v44
	s_waitcnt lgkmcnt(4)
	v_cvt_pk_bf16_f32 v41, v48, v50
	s_waitcnt lgkmcnt(2)
	v_cvt_pk_bf16_f32 v42, v52, v54
	s_waitcnt lgkmcnt(0)
	v_cvt_pk_bf16_f32 v43, v56, v58
	global_store_dwordx4 v[18:19], v[40:43], off
	v_or_b32_e32 v18, s22, v20
	v_ashrrev_i32_e32 v19, 31, v18
	v_cvt_pk_bf16_f32 v40, v47, v45
	v_cvt_pk_bf16_f32 v41, v49, v51
	v_cvt_pk_bf16_f32 v42, v53, v55
	v_cvt_pk_bf16_f32 v43, v57, v59
	v_lshlrev_b64 v[18:19], 11, v[18:19]
	ds_read2_b32 v[44:45], v23 offset0:49 offset1:57
	ds_read2_b32 v[46:47], v23 offset0:16 offset1:24
	ds_read2_b32 v[48:49], v23 offset0:82 offset1:90
	ds_read2_b32 v[50:51], v23 offset0:115 offset1:123
	ds_read2_b32 v[52:53], v23 offset0:148 offset1:156
	ds_read2_b32 v[54:55], v23 offset0:181 offset1:189
	ds_read2_b32 v[56:57], v23 offset0:214 offset1:222
	ds_read2_b32 v[58:59], v23 offset0:247 offset1:255
	v_lshl_add_u64 v[18:19], v[72:73], 0, v[18:19]
	global_store_dwordx4 v[18:19], v[40:43], off
	v_or_b32_e32 v18, s22, v21
	v_ashrrev_i32_e32 v19, 31, v18
	v_lshlrev_b64 v[18:19], 11, v[18:19]
	s_waitcnt lgkmcnt(6)
	v_cvt_pk_bf16_f32 v40, v46, v44
	s_waitcnt lgkmcnt(4)
	v_cvt_pk_bf16_f32 v41, v48, v50
	s_waitcnt lgkmcnt(2)
	v_cvt_pk_bf16_f32 v42, v52, v54
	s_waitcnt lgkmcnt(0)
	v_cvt_pk_bf16_f32 v43, v56, v58
	v_lshl_add_u64 v[18:19], v[72:73], 0, v[18:19]
	global_store_dwordx4 v[18:19], v[40:43], off
	v_or_b32_e32 v18, s22, v22
	v_ashrrev_i32_e32 v19, 31, v18
	v_lshlrev_b64 v[18:19], 11, v[18:19]
	v_cvt_pk_bf16_f32 v40, v47, v45
	v_cvt_pk_bf16_f32 v41, v49, v51
	v_cvt_pk_bf16_f32 v42, v53, v55
	v_cvt_pk_bf16_f32 v43, v57, v59
	v_lshl_add_u64 v[18:19], v[72:73], 0, v[18:19]
	global_store_dwordx4 v[18:19], v[40:43], off
	s_waitcnt lgkmcnt(0)
	s_cbranch_execz .LBB0_183

; #define LAS __attribute__((address_space(3)))
; #define XSEG(W, ldw, c0, K, ncols, WT, d0, mode, sel) { const int ni_ = ((K) / 64) * ((ncols) / 32); if (r_ < ni_) { xpose_item(W, ldw, c0, K, ncols, WT, d0, mode, sel, scr, r_, lane); continue; } r_ -= ni_; }
; __device__ __forceinline__ const float* arg_in(int k) { return (const float*)(const __attribute__((address_space(1))) float*)arg_q(k); }
; __device__ __forceinline__ void xpose_item(const float* W, int ldw, int c0, int K, int ncols, bf16* WT, int d0, int mode, int sel, LAS float* scr, int item, int lane) {
;     const int nblk = ncols >> 5, kb = item / nblk, nb = item - kb * nblk, k0 = 64 * kb, n0 = 32 * nb;
;     const int drow = mode ? d0 + 256 * (n0 >> 7) + 128 * sel + (n0 & 127) : d0 + n0;
;     f32x4 tv[8];
; #pragma unroll
;     for (int i = 0; i < 8; ++i) tv[i] = __builtin_nontemporal_load((const f32x4*)(W + (size_t)(k0 + 8 * i + (lane >> 3)) * ldw + c0 + n0 + 4 * (lane & 7)));
; #pragma unroll
;     for (int i = 0; i < 8; ++i) { LAS float* d = scr + (8 * i + (lane >> 3)) * 33 + 4 * (lane & 7); d[0] = tv[i][0]; d[1] = tv[i][1]; d[2] = tv[i][2]; d[3] = tv[i][3]; }
;     asm volatile("s_waitcnt lgkmcnt(0)" ::: "memory");
;     const int c = lane & 7;
; #pragma unroll
;     for (int j = 0; j < 4; ++j) { const int n = (lane >> 3) + 8 * j; const LAS float* s = scr + (8 * c) * 33 + n;
;         u32x4 o; o.x = cvt_pk_bf16(s[0 * 33], s[1 * 33]); o.y = cvt_pk_bf16(s[2 * 33], s[3 * 33]); o.z = cvt_pk_bf16(s[4 * 33], s[5 * 33]); o.w = cvt_pk_bf16(s[6 * 33], s[7 * 33]);
;         *(u32x4*)(WT + (size_t)(drow + n) * K + k0 + 8 * c) = o; }
;     asm volatile("s_waitcnt lgkmcnt(0)" ::: "memory");
; }
; __global__ void __launch_bounds__(NWAVES * 64, 2) mega_fwd(Args args) {
;     ...
;                 XSEG(arg_in(20), D, 0, 1024, 1024, WO, 0, 0, 0)
.LBB0_184:
	s_cmpk_gt_i32 s30, 0x1ff
	s_cselect_b64 s[20:21], -1, 0
	s_mov_b64 s[0:1], -1
	s_and_b64 vcc, exec, s[20:21]
	v_lshlrev_b32_e32 v18, 2, v0
	s_cbranch_vccnz .LBB0_187
	s_ashr_i32 s22, s30, 31
	s_mov_b64 s[0:1], s[56:57]
	s_lshr_b32 s22, s22, 27
	s_add_i32 s22, s30, s22
	s_load_dwordx2 s[0:1], s[0:1], 0xa0
	s_ashr_i32 s23, s22, 5
	s_lshl_b32 s22, s23, 10
	s_lshl_b32 s24, s30, 5
	s_sub_i32 s22, s24, s22
	s_lshl_b32 s24, s23, 6
	s_ashr_i32 s23, s22, 31
	v_or_b32_e32 v68, s24, v1
	s_lshl_b64 s[36:37], s[22:23], 2
	s_waitcnt lgkmcnt(0)
	s_add_u32 s0, s0, s36
	v_or_b32_e32 v48, 16, v68
	s_addc_u32 s1, s1, s37
	v_mov_b32_e32 v19, v3
	v_ashrrev_i32_e32 v49, 31, v48
	v_lshl_add_u64 v[70:71], s[0:1], 0, v[18:19]
	v_or_b32_e32 v42, 8, v68
	v_lshlrev_b64 v[48:49], 12, v[48:49]
	v_ashrrev_i32_e32 v69, 31, v68
	v_ashrrev_i32_e32 v43, 31, v42
	v_lshl_add_u64 v[56:57], v[70:71], 0, v[48:49]
	v_or_b32_e32 v48, 24, v68
	v_lshlrev_b64 v[40:41], 12, v[68:69]
	v_lshlrev_b64 v[42:43], 12, v[42:43]
	v_ashrrev_i32_e32 v49, 31, v48
	s_mov_b64 s[34:35], s[56:57]
	v_lshl_add_u64 v[40:41], v[70:71], 0, v[40:41]
	v_lshl_add_u64 v[44:45], v[70:71], 0, v[42:43]
	v_lshlrev_b64 v[48:49], 12, v[48:49]
	global_load_dwordx4 v[40:43], v[40:41], off nt
	s_nop 0
	global_load_dwordx4 v[44:47], v[44:45], off nt
	v_lshl_add_u64 v[58:59], v[70:71], 0, v[48:49]
	global_load_dwordx4 v[48:51], v[56:57], off nt
	global_load_dwordx4 v[52:55], v[58:59], off nt
	v_or_b32_e32 v56, 32, v68
	v_ashrrev_i32_e32 v57, 31, v56
	v_lshlrev_b64 v[56:57], 12, v[56:57]
	v_lshl_add_u64 v[64:65], v[70:71], 0, v[56:57]
	v_or_b32_e32 v56, 40, v68
	v_ashrrev_i32_e32 v57, 31, v56
	v_lshlrev_b64 v[56:57], 12, v[56:57]
	v_lshl_add_u64 v[66:67], v[70:71], 0, v[56:57]
	global_load_dwordx4 v[56:59], v[64:65], off nt
	global_load_dwordx4 v[60:63], v[66:67], off nt
	v_or_b32_e32 v64, 48, v68
	v_ashrrev_i32_e32 v65, 31, v64
	v_lshlrev_b64 v[64:65], 12, v[64:65]
	v_or_b32_e32 v68, 56, v68
	v_lshl_add_u64 v[64:65], v[70:71], 0, v[64:65]
	v_ashrrev_i32_e32 v69, 31, v68
	global_load_dwordx4 v[64:67], v[64:65], off nt
	v_lshlrev_b64 v[68:69], 12, v[68:69]
	v_lshl_add_u64 v[68:69], v[70:71], 0, v[68:69]
	global_load_dwordx4 v[68:71], v[68:69], off nt
	s_mov_b64 s[0:1], s[86:87]
	s_nop 4
	s_ashr_i32 s25, s24, 31
	s_lshl_b64 s[24:25], s[24:25], 1
	v_or_b32_e32 v72, s22, v1
	v_ashrrev_i32_e32 v73, 31, v72
	s_waitcnt lgkmcnt(0)
	s_add_u32 s0, s0, s24
	s_addc_u32 s1, s1, s25
	v_lshl_add_u64 v[74:75], s[0:1], 0, v[2:3]
	v_lshlrev_b64 v[72:73], 11, v[72:73]
	v_lshl_add_u64 v[74:75], v[74:75], 0, s[14:15]
	s_waitcnt vmcnt(0)
	ds_write2_b32 v24, v40, v41 offset1:1
	ds_write2_b32 v24, v42, v43 offset0:2 offset1:3
	ds_write2_b32 v25, v44, v45 offset1:1
	ds_write2_b32 v26, v46, v47 offset1:1
	ds_write2_b32 v27, v48, v49 offset1:1
	ds_write2_b32 v28, v50, v51 offset1:1
	ds_write2_b32 v29, v52, v53 offset1:1
	ds_write2_b32 v30, v54, v55 offset1:1
	ds_write2_b32 v31, v56, v57 offset1:1
	ds_write2_b32 v32, v58, v59 offset1:1
	ds_write2_b32 v33, v60, v61 offset1:1
	ds_write2_b32 v34, v62, v63 offset1:1
	ds_write2_b32 v35, v64, v65 offset1:1
	ds_write2_b32 v36, v66, v67 offset1:1
	ds_write2_b32 v37, v68, v69 offset1:1
	ds_write2_b32 v38, v70, v71 offset1:1
	s_waitcnt lgkmcnt(0)
	ds_read2_b32 v[44:45], v23 offset0:33 offset1:41
	ds_read2_b32 v[46:47], v23 offset1:8
	ds_read2_b32 v[48:49], v23 offset0:66 offset1:74
	ds_read2_b32 v[50:51], v23 offset0:99 offset1:107
	ds_read2_b32 v[52:53], v23 offset0:132 offset1:140
	ds_read2_b32 v[54:55], v23 offset0:165 offset1:173
	ds_read2_b32 v[56:57], v23 offset0:198 offset1:206
	ds_read2_b32 v[58:59], v23 offset0:231 offset1:239
	v_lshl_add_u64 v[60:61], v[74:75], 0, v[72:73]
	s_waitcnt lgkmcnt(6)
	v_cvt_pk_bf16_f32 v40, v46, v44
	s_waitcnt lgkmcnt(4)
	v_cvt_pk_bf16_f32 v41, v48, v50
	s_waitcnt lgkmcnt(2)
	v_cvt_pk_bf16_f32 v42, v52, v54
	s_waitcnt lgkmcnt(0)
	v_cvt_pk_bf16_f32 v43, v56, v58
	global_store_dwordx4 v[60:61], v[40:43], off
	v_cvt_pk_bf16_f32 v44, v47, v45
	v_cvt_pk_bf16_f32 v45, v49, v51
	v_or_b32_e32 v40, s22, v20
	v_ashrrev_i32_e32 v41, 31, v40
	v_cvt_pk_bf16_f32 v46, v53, v55
	v_cvt_pk_bf16_f32 v47, v57, v59
	v_lshlrev_b64 v[40:41], 11, v[40:41]
	ds_read2_b32 v[48:49], v23 offset0:49 offset1:57
	ds_read2_b32 v[50:51], v23 offset0:16 offset1:24
	ds_read2_b32 v[52:53], v23 offset0:82 offset1:90
	ds_read2_b32 v[54:55], v23 offset0:115 offset1:123
	ds_read2_b32 v[56:57], v23 offset0:148 offset1:156
	ds_read2_b32 v[58:59], v23 offset0:181 offset1:189
	ds_read2_b32 v[60:61], v23 offset0:214 offset1:222
	ds_read2_b32 v[62:63], v23 offset0:247 offset1:255
	v_lshl_add_u64 v[40:41], v[74:75], 0, v[40:41]
	global_store_dwordx4 v[40:41], v[44:47], off
	s_waitcnt lgkmcnt(6)
	v_cvt_pk_bf16_f32 v40, v50, v48
	s_waitcnt lgkmcnt(4)
	v_cvt_pk_bf16_f32 v41, v52, v54
	v_or_b32_e32 v44, s22, v21
	v_ashrrev_i32_e32 v45, 31, v44
	v_lshlrev_b64 v[44:45], 11, v[44:45]
	s_waitcnt lgkmcnt(2)
	v_cvt_pk_bf16_f32 v42, v56, v58
	s_waitcnt lgkmcnt(0)
	v_cvt_pk_bf16_f32 v43, v60, v62
	v_lshl_add_u64 v[44:45], v[74:75], 0, v[44:45]
	global_store_dwordx4 v[44:45], v[40:43], off
	v_or_b32_e32 v44, s22, v22
	v_ashrrev_i32_e32 v45, 31, v44
	v_lshlrev_b64 v[44:45], 11, v[44:45]
	v_cvt_pk_bf16_f32 v40, v51, v49
	v_cvt_pk_bf16_f32 v41, v53, v55
	v_cvt_pk_bf16_f32 v42, v57, v59
	v_cvt_pk_bf16_f32 v43, v61, v63
	v_lshl_add_u64 v[44:45], v[74:75], 0, v[44:45]
	global_store_dwordx4 v[44:45], v[40:43], off
	s_waitcnt lgkmcnt(0)
	s_cbranch_execz .LBB0_188

; #define LAS __attribute__((address_space(3)))
; #define XSEG(W, ldw, c0, K, ncols, WT, d0, mode, sel) { const int ni_ = ((K) / 64) * ((ncols) / 32); if (r_ < ni_) { xpose_item(W, ldw, c0, K, ncols, WT, d0, mode, sel, scr, r_, lane); continue; } r_ -= ni_; }
; __device__ __forceinline__ const float* arg_in(int k) { return (const float*)(const __attribute__((address_space(1))) float*)arg_q(k); }
; __device__ __forceinline__ void xpose_item(const float* W, int ldw, int c0, int K, int ncols, bf16* WT, int d0, int mode, int sel, LAS float* scr, int item, int lane) {
;     const int nblk = ncols >> 5, kb = item / nblk, nb = item - kb * nblk, k0 = 64 * kb, n0 = 32 * nb;
;     const int drow = mode ? d0 + 256 * (n0 >> 7) + 128 * sel + (n0 & 127) : d0 + n0;
;     f32x4 tv[8];
; #pragma unroll
;     for (int i = 0; i < 8; ++i) tv[i] = __builtin_nontemporal_load((const f32x4*)(W + (size_t)(k0 + 8 * i + (lane >> 3)) * ldw + c0 + n0 + 4 * (lane & 7)));
; #pragma unroll
;     for (int i = 0; i < 8; ++i) { LAS float* d = scr + (8 * i + (lane >> 3)) * 33 + 4 * (lane & 7); d[0] = tv[i][0]; d[1] = tv[i][1]; d[2] = tv[i][2]; d[3] = tv[i][3]; }
;     asm volatile("s_waitcnt lgkmcnt(0)" ::: "memory");
;     const int c = lane & 7;
; #pragma unroll
;     for (int j = 0; j < 4; ++j) { const int n = (lane >> 3) + 8 * j; const LAS float* s = scr + (8 * c) * 33 + n;
;         u32x4 o; o.x = cvt_pk_bf16(s[0 * 33], s[1 * 33]); o.y = cvt_pk_bf16(s[2 * 33], s[3 * 33]); o.z = cvt_pk_bf16(s[4 * 33], s[5 * 33]); o.w = cvt_pk_bf16(s[6 * 33], s[7 * 33]);
;         *(u32x4*)(WT + (size_t)(drow + n) * K + k0 + 8 * c) = o; }
;     asm volatile("s_waitcnt lgkmcnt(0)" ::: "memory");
; }
; __global__ void __launch_bounds__(NWAVES * 64, 2) mega_fwd(Args args) {
;     ...
;                 XSEG(arg_in(28), D, 0, 1024, 1024, WPLEG, 0, 0, 0)
.LBB0_189:
	s_cmpk_gt_i32 s30, 0x1ff
	s_cselect_b64 s[20:21], -1, 0
	s_mov_b64 s[0:1], -1
	s_and_b64 vcc, exec, s[20:21]
	s_cbranch_vccnz .LBB0_191
	s_ashr_i32 s22, s30, 31
	s_mov_b64 s[0:1], s[56:57]
	s_lshr_b32 s22, s22, 27
	s_add_i32 s22, s30, s22
	s_load_dwordx2 s[0:1], s[0:1], 0xe0
	s_ashr_i32 s23, s22, 5
	s_lshl_b32 s22, s23, 10
	s_lshl_b32 s24, s30, 5
	s_sub_i32 s22, s24, s22
	s_lshl_b32 s24, s23, 6
	s_ashr_i32 s23, s22, 31
	v_or_b32_e32 v68, s24, v1
	s_lshl_b64 s[36:37], s[22:23], 2
	s_waitcnt lgkmcnt(0)
	s_add_u32 s0, s0, s36
	v_or_b32_e32 v48, 16, v68
	s_addc_u32 s1, s1, s37
	v_mov_b32_e32 v19, v3
	v_ashrrev_i32_e32 v49, 31, v48
	v_lshl_add_u64 v[70:71], s[0:1], 0, v[18:19]
	v_or_b32_e32 v42, 8, v68
	v_lshlrev_b64 v[48:49], 12, v[48:49]
	v_ashrrev_i32_e32 v69, 31, v68
	v_ashrrev_i32_e32 v43, 31, v42
	v_lshl_add_u64 v[56:57], v[70:71], 0, v[48:49]
	v_or_b32_e32 v48, 24, v68
	v_lshlrev_b64 v[40:41], 12, v[68:69]
	v_lshlrev_b64 v[42:43], 12, v[42:43]
	v_ashrrev_i32_e32 v49, 31, v48
	s_mov_b64 s[34:35], s[56:57]
	v_lshl_add_u64 v[40:41], v[70:71], 0, v[40:41]
	v_lshl_add_u64 v[44:45], v[70:71], 0, v[42:43]
	v_lshlrev_b64 v[48:49], 12, v[48:49]
	global_load_dwordx4 v[40:43], v[40:41], off nt
	s_nop 0
	global_load_dwordx4 v[44:47], v[44:45], off nt
	v_lshl_add_u64 v[58:59], v[70:71], 0, v[48:49]
	global_load_dwordx4 v[48:51], v[56:57], off nt
	global_load_dwordx4 v[52:55], v[58:59], off nt
	v_or_b32_e32 v56, 32, v68
	v_ashrrev_i32_e32 v57, 31, v56
	v_lshlrev_b64 v[56:57], 12, v[56:57]
	v_lshl_add_u64 v[64:65], v[70:71], 0, v[56:57]
	v_or_b32_e32 v56, 40, v68
	v_ashrrev_i32_e32 v57, 31, v56
	v_lshlrev_b64 v[56:57], 12, v[56:57]
	v_lshl_add_u64 v[66:67], v[70:71], 0, v[56:57]
	global_load_dwordx4 v[56:59], v[64:65], off nt
	global_load_dwordx4 v[60:63], v[66:67], off nt
	v_or_b32_e32 v64, 48, v68
	v_ashrrev_i32_e32 v65, 31, v64
	v_lshlrev_b64 v[64:65], 12, v[64:65]
	v_or_b32_e32 v68, 56, v68
	v_lshl_add_u64 v[64:65], v[70:71], 0, v[64:65]
	v_ashrrev_i32_e32 v69, 31, v68
	global_load_dwordx4 v[64:67], v[64:65], off nt
	v_lshlrev_b64 v[68:69], 12, v[68:69]
	v_lshl_add_u64 v[68:69], v[70:71], 0, v[68:69]
	global_load_dwordx4 v[68:71], v[68:69], off nt
	s_mov_b64 s[0:1], s[86:87]
	s_nop 4
	s_ashr_i32 s25, s24, 31
	s_lshl_b64 s[24:25], s[24:25], 1
	v_or_b32_e32 v72, s22, v1
	v_ashrrev_i32_e32 v73, 31, v72
	s_waitcnt lgkmcnt(0)
	s_add_u32 s0, s0, s24
	s_addc_u32 s1, s1, s25
	v_lshl_add_u64 v[74:75], s[0:1], 0, v[2:3]
	v_lshlrev_b64 v[72:73], 11, v[72:73]
	v_lshl_add_u64 v[74:75], v[74:75], 0, s[16:17]
	s_mov_b64 s[0:1], 0
	s_waitcnt vmcnt(0)
	ds_write2_b32 v24, v40, v41 offset1:1
	ds_write2_b32 v24, v42, v43 offset0:2 offset1:3
	ds_write2_b32 v25, v44, v45 offset1:1
	ds_write2_b32 v26, v46, v47 offset1:1
	ds_write2_b32 v27, v48, v49 offset1:1
	ds_write2_b32 v28, v50, v51 offset1:1
	ds_write2_b32 v29, v52, v53 offset1:1
	ds_write2_b32 v30, v54, v55 offset1:1
	ds_write2_b32 v31, v56, v57 offset1:1
	ds_write2_b32 v32, v58, v59 offset1:1
	ds_write2_b32 v33, v60, v61 offset1:1
	ds_write2_b32 v34, v62, v63 offset1:1
	ds_write2_b32 v35, v64, v65 offset1:1
	ds_write2_b32 v36, v66, v67 offset1:1
	ds_write2_b32 v37, v68, v69 offset1:1
	ds_write2_b32 v38, v70, v71 offset1:1
	s_waitcnt lgkmcnt(0)
	ds_read2_b32 v[44:45], v23 offset0:33 offset1:41
	ds_read2_b32 v[46:47], v23 offset1:8
	ds_read2_b32 v[48:49], v23 offset0:66 offset1:74
	ds_read2_b32 v[50:51], v23 offset0:99 offset1:107
	ds_read2_b32 v[52:53], v23 offset0:132 offset1:140
	ds_read2_b32 v[54:55], v23 offset0:165 offset1:173
	ds_read2_b32 v[56:57], v23 offset0:198 offset1:206
	ds_read2_b32 v[58:59], v23 offset0:231 offset1:239
	v_lshl_add_u64 v[60:61], v[74:75], 0, v[72:73]
	s_waitcnt lgkmcnt(6)
	v_cvt_pk_bf16_f32 v40, v46, v44
	s_waitcnt lgkmcnt(4)
	v_cvt_pk_bf16_f32 v41, v48, v50
	s_waitcnt lgkmcnt(2)
	v_cvt_pk_bf16_f32 v42, v52, v54
	s_waitcnt lgkmcnt(0)
	v_cvt_pk_bf16_f32 v43, v56, v58
	global_store_dwordx4 v[60:61], v[40:43], off
	v_cvt_pk_bf16_f32 v44, v47, v45
	v_cvt_pk_bf16_f32 v45, v49, v51
	v_or_b32_e32 v40, s22, v20
	v_ashrrev_i32_e32 v41, 31, v40
	v_cvt_pk_bf16_f32 v46, v53, v55
	v_cvt_pk_bf16_f32 v47, v57, v59
	v_lshlrev_b64 v[40:41], 11, v[40:41]
	ds_read2_b32 v[48:49], v23 offset0:49 offset1:57
	ds_read2_b32 v[50:51], v23 offset0:16 offset1:24
	ds_read2_b32 v[52:53], v23 offset0:82 offset1:90
	ds_read2_b32 v[54:55], v23 offset0:115 offset1:123
	ds_read2_b32 v[56:57], v23 offset0:148 offset1:156
	ds_read2_b32 v[58:59], v23 offset0:181 offset1:189
	ds_read2_b32 v[60:61], v23 offset0:214 offset1:222
	ds_read2_b32 v[62:63], v23 offset0:247 offset1:255
	v_lshl_add_u64 v[40:41], v[74:75], 0, v[40:41]
	global_store_dwordx4 v[40:41], v[44:47], off
	s_waitcnt lgkmcnt(6)
	v_cvt_pk_bf16_f32 v40, v50, v48
	s_waitcnt lgkmcnt(4)
	v_cvt_pk_bf16_f32 v41, v52, v54
	v_or_b32_e32 v44, s22, v21
	v_ashrrev_i32_e32 v45, 31, v44
	v_lshlrev_b64 v[44:45], 11, v[44:45]
	s_waitcnt lgkmcnt(2)
	v_cvt_pk_bf16_f32 v42, v56, v58
	s_waitcnt lgkmcnt(0)
	v_cvt_pk_bf16_f32 v43, v60, v62
	v_lshl_add_u64 v[44:45], v[74:75], 0, v[44:45]
	global_store_dwordx4 v[44:45], v[40:43], off
	v_or_b32_e32 v44, s22, v22
	v_ashrrev_i32_e32 v45, 31, v44
	v_lshlrev_b64 v[44:45], 11, v[44:45]
	v_cvt_pk_bf16_f32 v40, v51, v49
	v_cvt_pk_bf16_f32 v41, v53, v55
	v_cvt_pk_bf16_f32 v42, v57, v59
	v_cvt_pk_bf16_f32 v43, v61, v63
	v_lshl_add_u64 v[44:45], v[74:75], 0, v[44:45]
	global_store_dwordx4 v[44:45], v[40:43], off
	s_waitcnt lgkmcnt(0)

; #define LAS __attribute__((address_space(3)))
; #define XSEG(W, ldw, c0, K, ncols, WT, d0, mode, sel) { const int ni_ = ((K) / 64) * ((ncols) / 32); if (r_ < ni_) { xpose_item(W, ldw, c0, K, ncols, WT, d0, mode, sel, scr, r_, lane); continue; } r_ -= ni_; }
; __device__ __forceinline__ const float* arg_in(int k) { return (const float*)(const __attribute__((address_space(1))) float*)arg_q(k); }
; __device__ __forceinline__ void xpose_item(const float* W, int ldw, int c0, int K, int ncols, bf16* WT, int d0, int mode, int sel, LAS float* scr, int item, int lane) {
;     const int nblk = ncols >> 5, kb = item / nblk, nb = item - kb * nblk, k0 = 64 * kb, n0 = 32 * nb;
;     const int drow = mode ? d0 + 256 * (n0 >> 7) + 128 * sel + (n0 & 127) : d0 + n0;
;     f32x4 tv[8];
; #pragma unroll
;     for (int i = 0; i < 8; ++i) tv[i] = __builtin_nontemporal_load((const f32x4*)(W + (size_t)(k0 + 8 * i + (lane >> 3)) * ldw + c0 + n0 + 4 * (lane & 7)));
; #pragma unroll
;     for (int i = 0; i < 8; ++i) { LAS float* d = scr + (8 * i + (lane >> 3)) * 33 + 4 * (lane & 7); d[0] = tv[i][0]; d[1] = tv[i][1]; d[2] = tv[i][2]; d[3] = tv[i][3]; }
;     asm volatile("s_waitcnt lgkmcnt(0)" ::: "memory");
;     const int c = lane & 7;
; #pragma unroll
;     for (int j = 0; j < 4; ++j) { const int n = (lane >> 3) + 8 * j; const LAS float* s = scr + (8 * c) * 33 + n;
;         u32x4 o; o.x = cvt_pk_bf16(s[0 * 33], s[1 * 33]); o.y = cvt_pk_bf16(s[2 * 33], s[3 * 33]); o.z = cvt_pk_bf16(s[4 * 33], s[5 * 33]); o.w = cvt_pk_bf16(s[6 * 33], s[7 * 33]);
;         *(u32x4*)(WT + (size_t)(drow + n) * K + k0 + 8 * c) = o; }
;     asm volatile("s_waitcnt lgkmcnt(0)" ::: "memory");
; }
; __global__ void __launch_bounds__(NWAVES * 64, 2) mega_fwd(Args args) {
;     ...
;                 XSEG(arg_in(29), D, 0, 256, 1024, WPLEP, 0, 0, 0)
;             }
.LBB0_193:
	s_cmpk_lt_i32 s30, 0x80
	s_cselect_b64 s[0:1], -1, 0
	s_and_b64 s[0:1], s[20:21], s[0:1]
	s_andn2_b64 vcc, exec, s[0:1]
	s_cbranch_vccnz .LBB0_138
	s_ashr_i32 s20, s30, 31
	s_mov_b64 s[0:1], s[56:57]
	s_lshr_b32 s20, s20, 27
	s_add_i32 s20, s30, s20
	s_load_dwordx2 s[0:1], s[0:1], 0xe8
	s_ashr_i32 s21, s20, 5
	s_lshl_b32 s20, s21, 10
	s_lshl_b32 s22, s30, 5
	s_sub_i32 s20, s22, s20
	s_lshl_b32 s22, s21, 6
	s_ashr_i32 s21, s20, 31
	s_lshl_b64 s[30:31], s[20:21], 2
	v_or_b32_e32 v68, s22, v1
	s_waitcnt lgkmcnt(0)
	s_add_u32 s0, s0, s30
	s_addc_u32 s1, s1, s31
	v_mov_b32_e32 v19, v3
	v_ashrrev_i32_e32 v69, 31, v68
	v_lshl_add_u64 v[18:19], s[0:1], 0, v[18:19]
	v_lshlrev_b64 v[40:41], 12, v[68:69]
	v_lshl_add_u64 v[48:49], v[18:19], 0, v[40:41]
	v_or_b32_e32 v40, 8, v68
	v_ashrrev_i32_e32 v41, 31, v40
	s_mov_b64 s[24:25], s[56:57]
	v_lshlrev_b64 v[40:41], 12, v[40:41]
	v_lshl_add_u64 v[50:51], v[18:19], 0, v[40:41]
	global_load_dwordx4 v[40:43], v[48:49], off nt
	global_load_dwordx4 v[44:47], v[50:51], off nt
	v_or_b32_e32 v48, 16, v68
	v_ashrrev_i32_e32 v49, 31, v48
	v_lshlrev_b64 v[48:49], 12, v[48:49]
	v_lshl_add_u64 v[56:57], v[18:19], 0, v[48:49]
	v_or_b32_e32 v48, 24, v68
	v_ashrrev_i32_e32 v49, 31, v48
	v_lshlrev_b64 v[48:49], 12, v[48:49]
	v_lshl_add_u64 v[58:59], v[18:19], 0, v[48:49]
	global_load_dwordx4 v[48:51], v[56:57], off nt
	global_load_dwordx4 v[52:55], v[58:59], off nt
	v_or_b32_e32 v56, 32, v68
	v_ashrrev_i32_e32 v57, 31, v56
	v_lshlrev_b64 v[56:57], 12, v[56:57]
	v_lshl_add_u64 v[64:65], v[18:19], 0, v[56:57]
	v_or_b32_e32 v56, 40, v68
	v_ashrrev_i32_e32 v57, 31, v56
	v_lshlrev_b64 v[56:57], 12, v[56:57]
	v_lshl_add_u64 v[66:67], v[18:19], 0, v[56:57]
	global_load_dwordx4 v[56:59], v[64:65], off nt
	global_load_dwordx4 v[60:63], v[66:67], off nt
	v_or_b32_e32 v64, 48, v68
	v_ashrrev_i32_e32 v65, 31, v64
	v_lshlrev_b64 v[64:65], 12, v[64:65]
	v_or_b32_e32 v68, 56, v68
	v_lshl_add_u64 v[64:65], v[18:19], 0, v[64:65]
	v_ashrrev_i32_e32 v69, 31, v68
	global_load_dwordx4 v[64:67], v[64:65], off nt
	v_lshlrev_b64 v[68:69], 12, v[68:69]
	v_lshl_add_u64 v[18:19], v[18:19], 0, v[68:69]
	global_load_dwordx4 v[68:71], v[18:19], off nt
	s_mov_b64 s[0:1], s[86:87]
	s_nop 4
	s_ashr_i32 s23, s22, 31
	s_lshl_b64 s[22:23], s[22:23], 1
	v_or_b32_e32 v18, s20, v1
	v_ashrrev_i32_e32 v19, 31, v18
	s_waitcnt lgkmcnt(0)
	s_add_u32 s0, s0, s22
	s_addc_u32 s1, s1, s23
	v_lshl_add_u64 v[72:73], s[0:1], 0, v[2:3]
	v_lshlrev_b64 v[18:19], 9, v[18:19]
	v_lshl_add_u64 v[72:73], v[72:73], 0, s[18:19]
	v_lshl_add_u64 v[18:19], v[72:73], 0, v[18:19]
	s_waitcnt vmcnt(0)
	ds_write2_b32 v24, v40, v41 offset1:1
	ds_write2_b32 v24, v42, v43 offset0:2 offset1:3
	ds_write2_b32 v25, v44, v45 offset1:1
	ds_write2_b32 v26, v46, v47 offset1:1
	ds_write2_b32 v27, v48, v49 offset1:1
	ds_write2_b32 v28, v50, v51 offset1:1
	ds_write2_b32 v29, v52, v53 offset1:1
	ds_write2_b32 v30, v54, v55 offset1:1
	ds_write2_b32 v31, v56, v57 offset1:1
	ds_write2_b32 v32, v58, v59 offset1:1
	ds_write2_b32 v33, v60, v61 offset1:1
	ds_write2_b32 v34, v62, v63 offset1:1
	ds_write2_b32 v35, v64, v65 offset1:1
	ds_write2_b32 v36, v66, v67 offset1:1
	ds_write2_b32 v37, v68, v69 offset1:1
	ds_write2_b32 v38, v70, v71 offset1:1
	s_waitcnt lgkmcnt(0)
	ds_read2_b32 v[44:45], v23 offset0:33 offset1:41
	ds_read2_b32 v[46:47], v23 offset1:8
	ds_read2_b32 v[48:49], v23 offset0:66 offset1:74
	ds_read2_b32 v[50:51], v23 offset0:99 offset1:107
	ds_read2_b32 v[52:53], v23 offset0:132 offset1:140
	ds_read2_b32 v[54:55], v23 offset0:165 offset1:173
	ds_read2_b32 v[56:57], v23 offset0:198 offset1:206
	ds_read2_b32 v[58:59], v23 offset0:231 offset1:239
	s_waitcnt lgkmcnt(6)
	v_cvt_pk_bf16_f32 v40, v46, v44
	s_waitcnt lgkmcnt(4)
	v_cvt_pk_bf16_f32 v41, v48, v50
	s_waitcnt lgkmcnt(2)
	v_cvt_pk_bf16_f32 v42, v52, v54
	v_cvt_pk_bf16_f32 v44, v47, v45
	s_waitcnt lgkmcnt(0)
	v_cvt_pk_bf16_f32 v43, v56, v58
	global_store_dwordx4 v[18:19], v[40:43], off
	v_or_b32_e32 v18, s20, v20
	v_ashrrev_i32_e32 v19, 31, v18
	v_cvt_pk_bf16_f32 v45, v49, v51
	v_cvt_pk_bf16_f32 v46, v53, v55
	v_cvt_pk_bf16_f32 v47, v57, v59
	v_lshlrev_b64 v[18:19], 9, v[18:19]
	ds_read2_b32 v[48:49], v23 offset0:49 offset1:57
	ds_read2_b32 v[50:51], v23 offset0:16 offset1:24
	ds_read2_b32 v[52:53], v23 offset0:82 offset1:90
	ds_read2_b32 v[54:55], v23 offset0:115 offset1:123
	ds_read2_b32 v[56:57], v23 offset0:148 offset1:156
	ds_read2_b32 v[58:59], v23 offset0:181 offset1:189
	ds_read2_b32 v[60:61], v23 offset0:214 offset1:222
	ds_read2_b32 v[62:63], v23 offset0:247 offset1:255
	v_lshl_add_u64 v[18:19], v[72:73], 0, v[18:19]
	global_store_dwordx4 v[18:19], v[44:47], off
	v_or_b32_e32 v18, s20, v21
	v_ashrrev_i32_e32 v19, 31, v18
	v_lshlrev_b64 v[18:19], 9, v[18:19]
	s_waitcnt lgkmcnt(6)
	v_cvt_pk_bf16_f32 v40, v50, v48
	s_waitcnt lgkmcnt(4)
	v_cvt_pk_bf16_f32 v41, v52, v54
	s_waitcnt lgkmcnt(2)
	v_cvt_pk_bf16_f32 v42, v56, v58
	s_waitcnt lgkmcnt(0)
	v_cvt_pk_bf16_f32 v43, v60, v62
	v_lshl_add_u64 v[18:19], v[72:73], 0, v[18:19]
	global_store_dwordx4 v[18:19], v[40:43], off
	v_or_b32_e32 v18, s20, v22
	v_ashrrev_i32_e32 v19, 31, v18
	v_lshlrev_b64 v[18:19], 9, v[18:19]
	v_cvt_pk_bf16_f32 v40, v51, v49
	v_cvt_pk_bf16_f32 v41, v53, v55
	v_cvt_pk_bf16_f32 v42, v57, v59
	v_cvt_pk_bf16_f32 v43, v61, v63
	v_lshl_add_u64 v[18:19], v[72:73], 0, v[18:19]
	global_store_dwordx4 v[18:19], v[40:43], off
	s_waitcnt lgkmcnt(0)
	s_branch .LBB0_138

; #define LAS __attribute__((address_space(3)))
; __device__ __forceinline__ const float* arg_in(int k) { return (const float*)(const __attribute__((address_space(1))) float*)arg_q(k); }
; template <class EpiS>
; __device__ __forceinline__ void sgemm_phase(LAS unsigned char* lds, const bf16* A, const bf16* Bt, int N, int K, const EpiS& E, int bidx, int nb) {
;     const int tid = threadIdx.x, lane = tid & 63, wave = __builtin_amdgcn_readfirstlane(tid >> 6), li = lane & 15, lq = lane >> 4;
;     const int ntask = (N >> 4) * 4, kper = K >> 3;
;     LAS float* red = (LAS float*)lds;
;     for (int task = bidx; task < ntask; task += nb) {
;         const int ct = task >> 2, rt = task & 3;
;         const bf16* ap0 = A + (size_t)(rt * 32 + li) * K + wave * kper + 8 * lq; const bf16* ap1 = ap0 + (size_t)16 * K;
;         const bf16* bp = Bt + (size_t)(ct * 16 + li) * K + wave * kper + 8 * lq;
;         f32x4 acc0 = (f32x4){0.f, 0.f, 0.f, 0.f}, acc1 = acc0;
; __global__ void __launch_bounds__(NWAVES * 64, 2) mega_fwd(Args args) {
;     ...
;     if (IN(2)) { { SRes ES{arg_in(1), RES + SOFF, ALPHA, 0.5f}; sgemm_phase(lds, R0 + (size_t)MPROMPT * FF, WD, 1024, FF, ES, (int)blockIdx.x, G); }
.LBB0_249:
	s_cmp_lt_i32 s64, 3
	s_cselect_b64 s[0:1], -1, 0
	s_and_b64 s[4:5], s[0:1], s[6:7]
	s_andn2_b64 vcc, exec, s[4:5]
	v_and_b32_e32 v156, 15, v154
	s_cbranch_vccnz .LBB0_320
	s_cmpk_lt_i32 s2, 0x100
	s_mov_b64 s[0:1], s[56:57]
	s_mov_b64 s[10:11], s[56:57]
	s_mov_b64 s[14:15], s[56:57]
	s_mov_b64 s[12:13], s[56:57]
	s_cselect_b64 s[8:9], -1, 0
	s_cmpk_gt_i32 s2, 0xff
	v_readfirstlane_b32 s3, v154
	s_cbranch_scc1 .LBB0_253
	s_load_dwordx2 s[16:17], s[10:11], 0x100
	s_load_dwordx2 s[6:7], s[0:1], 0x8
	s_mov_b64 s[18:19], s[86:87]
	s_nop 4
	v_bfe_u32 v7, v154, 4, 2
	s_mov_b64 s[0:1], s[86:87]
	s_nop 4
	s_waitcnt lgkmcnt(0)
	s_add_u32 s10, s16, 0x4000000
	s_addc_u32 s11, s17, 0
	s_lshr_b32 s3, s3, 6
	s_mul_i32 s12, s3, 0x160
	s_mov_b32 s13, 0
	s_lshl_b64 s[12:13], s[12:13], 1
	s_add_u32 s14, s18, s12
	s_addc_u32 s15, s19, s13
	s_add_u32 s0, s0, s12
	v_lshlrev_b32_e32 v0, 4, v7
	v_mov_b32_e32 v1, 0
	s_addc_u32 s1, s1, s13
	v_lshl_add_u64 v[4:5], s[0:1], 0, v[0:1]
	s_mov_b64 s[0:1], 0xb20000
	v_lshl_add_u64 v[4:5], v[4:5], 0, s[0:1]
	s_lshl_b32 s0, s3, 11
	v_lshl_add_u64 v[2:3], s[14:15], 0, v[0:1]
	s_add_i32 s0, s0, 0
	v_lshlrev_b32_e32 v0, 8, v7
	v_lshlrev_b32_e32 v8, 2, v156
	s_mov_b64 s[14:15], 0xa3b0000
	v_add3_u32 v8, s0, v0, v8
	s_mov_b32 s12, 0x3f9837f0
	v_lshrrev_b32_e32 v6, 4, v154
	v_lshl_add_u64 v[2:3], v[2:3], 0, s[14:15]
	v_lshl_add_u32 v7, v154, 2, 0
	s_lshl_b32 s0, s2, 2
	s_lshl_b32 s1, s88, 2
	s_lshl_b32 s3, s2, 5
	s_lshl_b32 s14, s88, 5
	s_movk_i32 s15, 0x1600
	s_mov_b32 s13, 0.5
	v_add_u32_e32 v9, 0x400, v8
	s_mov_b32 s16, s2

;     __host__ __device__ bool next(int i, Unit& u) const {
;         const long L = (long)i * G + c; if (L >= nwg) return false;
;         int wgid = (int)L; { const int q = nwg / NXCD, r = nwg % NXCD, xcd = wgid % NXCD, off = wgid / NXCD; wgid = (xcd < r ? xcd * (q + 1) : r * (q + 1) + (xcd - r) * q) + off; }
;         const int nig = WGM * nN, gid = wgid / nig, fm = gid * WGM, gsz = (nM - fm) < WGM ? (nM - fm) : WGM;
;         u.pm = fm + ((wgid % nig) % gsz); u.pn = (wgid % nig) / gsz; return true;
; template <class Epi, class Sched, bool ALIGN_EPI = false, bool SP2 = false>
; __device__ __forceinline__ void gemm_phase(PG8_LAS unsigned char* lds, const Gemm g, const Sched& S, const Epi& E) {
;     const int tid = threadIdx.x, wid = __builtin_amdgcn_readfirstlane(tid >> 6), lane = tid & 63, wr = wid >> 2, wc = wid & 3, fr = lane & 15, fq = lane >> 4;
;     const int K = g.K, nt = K / BK;
;     unsigned voffA[2], voffB[2];
; #pragma unroll
;     for (int i = 0; i < 2; ++i) { int R, C; stage_rc(tid * 16 + i * 8192, R, C); const int Rb = Epi::PERM ? ((R & ~31) + perm32(R & 31)) : R;
;         voffA[i] = (unsigned)(R * K + C) * 2u; voffB[i] = (unsigned)(Rb * K + C) * 2u; }
.LBB0_253:
	s_mov_b64 s[10:11], s[56:57]
	s_mov_b64 s[12:13], s[56:57]
	s_mov_b64 s[14:15], s[56:57]
	s_mov_b64 s[24:25], s[56:57]
	s_mov_b64 s[16:17], s[56:57]
	s_mov_b64 s[18:19], s[56:57]
	s_mov_b64 s[26:27], s[56:57]
	s_movk_i32 s6, 0xb00
	s_mov_b64 s[20:21], s[56:57]
	s_mov_b64 s[22:23], s[56:57]
	s_andn2_b64 vcc, exec, s[8:9]
	v_readfirstlane_b32 s3, v154
	s_cbranch_vccnz .LBB0_320
	s_ashr_i32 s51, s2, 31
	s_mov_b64 s[8:9], s[86:87]
	s_nop 4
	s_mov_b64 s[0:1], s[86:87]
	s_nop 4
	s_lshr_b32 s7, s51, 29
	s_add_i32 s7, s2, s7
	s_and_b32 s20, s7, -8
	s_sub_i32 s23, s2, s20
	s_cmp_gt_i32 s23, -1
	s_cbranch_scc0 .LBB0_256
	s_lshl_b32 s22, s23, 5
	s_cbranch_execz .LBB0_257
	s_branch .LBB0_258

; #define PG8_STAGE(bufoff, gbase, voff) do { _Pragma("unroll") for (int _i = 0; _i < 2; ++_i) \
;         __builtin_amdgcn_global_load_lds((const unsigned*)((const char*)(gbase) + (voff)[_i]), (PG8_LAS unsigned*)(lds + (bufoff) + ldsw + _i * 8192), 16, 0, 0); } while (0)
; #define PG8_WAIT_V(n) asm volatile("s_waitcnt vmcnt(" #n ")" ::: "memory")
; #define PG8_BAR __builtin_amdgcn_s_barrier()
; template <class Epi, class Sched, bool ALIGN_EPI = false, bool SP2 = false>
; __device__ __forceinline__ void gemm_phase(PG8_LAS unsigned char* lds, const Gemm g, const Sched& S, const Epi& E) {
;     ...
;     const char* cA = (const char*)g.A + (size_t)cur.pm * tstep; const char* cB = (const char*)g.Bt + (size_t)cur.pn * tstep;
;     S.a_ready(cur);
;     if constexpr (SP2) {
;         PG8_STAGE(PG8_SB(0, 0), cB, voffB); PG8_STAGE(PG8_SB(0, 1), cB + hstep, voffB); PG8_STAGE(PG8_SA(0, 0), cA, voffA); PG8_STAGE(PG8_SA(0, 1), cA + hstep, voffA);
;         if (wr == 1) PG8_BAR;
;         PG8_WAIT_V(2); PG8_BAR;
;         PG8_STAGE(PG8_SB(1, 0), cB + kstep, voffB); PG8_STAGE(PG8_SA(1, 0), cA + kstep, voffA); PG8_STAGE(PG8_SB(1, 1), cB + hstep + kstep, voffB);
;         PG8_WAIT_V(6); PG8_BAR;
.LBB0_258:
	s_ashr_i32 s20, s7, 3
	s_waitcnt lgkmcnt(0)
	s_add_u32 s52, s8, 0x4bb0000
	v_lshrrev_b32_e32 v148, 1, v154
	v_lshrrev_b32_e32 v4, 5, v154
	s_addc_u32 s53, s9, 0
	v_lshlrev_b32_e32 v0, 4, v154
	v_and_b32_e32 v1, 32, v154
	v_and_b32_e32 v3, 24, v148
	v_and_b32_e32 v4, 4, v4
	v_bfe_u32 v5, v154, 2, 2
	s_add_u32 s54, s0, 0xb20000
	v_bitop3_b32 v1, v0, v1, 48 bitop3:0x6c
	v_or3_b32 v3, v4, v5, v3
	v_lshrrev_b32_e32 v4, 3, v154
	s_movk_i32 s0, 0x60
	v_add_u32_e32 v0, 0x2000, v0
	v_and_b32_e32 v16, 0x70, v4
	v_and_or_b32 v4, v4, s0, v3
	v_lshrrev_b32_e32 v0, 7, v0
	s_movk_i32 s0, 0xe0
	s_addc_u32 s55, s1, 0
	v_and_b32_e32 v17, 0xf0, v0
	v_and_or_b32 v0, v0, s0, v3
	s_add_i32 s0, s22, s20
	s_ashr_i32 s1, s0, 31
	s_lshr_b32 s1, s1, 27
	s_add_i32 s1, s0, s1
	s_ashr_i32 s8, s1, 5
	s_andn2_b32 s1, s1, 31
	s_sub_i32 s0, s0, s1
	s_bfe_i32 s1, s0, 0x80000
	s_bfe_u32 s1, s1, 0x3000c
	s_add_i32 s1, s0, s1
	s_lshl_b32 s9, s8, 3
	s_bfe_i32 s8, s1, 0x80000
	s_and_b32 s1, s1, 0xf8
	s_sub_i32 s0, s0, s1
	s_sext_i32_i8 s0, s0
	s_ashr_i32 s7, s6, 31
	s_add_i32 s48, s9, s0
	s_lshl_b64 s[30:31], s[6:7], 9
	s_ashr_i32 s0, s48, 31
	s_mul_i32 s0, s30, s0
	s_mul_hi_u32 s1, s30, s48
	s_add_i32 s9, s1, s0
	s_lshr_b64 s[0:1], s[6:7], 23
	s_sext_i32_i16 s22, s8
	s_mul_i32 s1, s0, s48
	s_lshr_b32 s8, s22, 3
	s_add_i32 s9, s9, s1
	s_bfe_i64 s[20:21], s[8:9], 0x100000
	s_ashr_i32 s1, s22, 3
	s_mul_hi_u32 s20, s30, s1
	s_mul_i32 s21, s30, s21
	s_lshr_b32 s49, s3, 6
	s_add_i32 s20, s20, s21
	s_mul_i32 s0, s0, s1
	s_lshr_b32 s50, s3, 8
	v_and_b32_e32 v14, 64, v154
	s_lshl_b64 s[28:29], s[6:7], 8
	s_lshl_b32 s58, s49, 10
	s_add_i32 s20, s20, s0
	s_mul_i32 s0, s30, s1
	v_or_b32_e32 v2, v1, v14
	s_add_u32 s34, s54, s0
	v_lshrrev_b32_e32 v2, 1, v2
	v_mul_lo_u32 v4, s6, v4
	s_addc_u32 s35, s55, s20
	s_add_i32 s59, s58, 0
	v_add_lshl_u32 v134, v4, v2, 1
	s_add_i32 m0, s59, 0x10000
	v_mul_lo_u32 v0, s6, v0
	global_load_lds_dwordx4 v134, s[34:35]
	s_add_i32 m0, s59, 0x12000
	v_add_lshl_u32 v138, v0, v2, 1
	s_add_u32 s0, s34, s28
	global_load_lds_dwordx4 v138, s[34:35]
	s_addc_u32 s1, s35, s29
	s_add_i32 m0, s59, 0x14000
	v_bfe_u32 v15, v154, 2, 4
	s_mul_i32 s23, s30, s48
	global_load_lds_dwordx4 v134, s[0:1]
	s_add_i32 m0, s59, 0x16000
	v_or_b32_e32 v5, v16, v15
	s_add_u32 s36, s52, s23
	v_mul_lo_u32 v5, s6, v5
	v_or_b32_e32 v4, v17, v15
	s_addc_u32 s37, s53, s9
	s_add_i32 s60, s59, 0x2000
	v_add_lshl_u32 v132, v5, v2, 1
	v_mul_lo_u32 v3, s6, v4
	global_load_lds_dwordx4 v138, s[0:1]
	s_mov_b32 m0, s59
	s_add_u32 s20, s36, s28
	v_add_lshl_u32 v136, v3, v2, 1
	global_load_lds_dwordx4 v132, s[36:37]
	s_mov_b32 m0, s60
	s_addc_u32 s21, s37, s29
	s_add_i32 s61, s59, 0x4000
	global_load_lds_dwordx4 v136, s[36:37]
	s_mov_b32 m0, s61
	s_add_i32 s62, s59, 0x6000
	global_load_lds_dwordx4 v132, s[20:21]
	s_mov_b32 m0, s62
	v_mov_b32_e32 v0, 0
	global_load_lds_dwordx4 v136, s[20:21]
	s_mov_b64 s[12:13], s[86:87]
	s_nop 4
	s_nop 0
	s_mov_b64 s[22:23], s[86:87]
	s_nop 4
	s_mov_b64 s[20:21], s[86:87]
	s_nop 4
	s_nop 0
	s_mov_b64 s[18:19], s[86:87]
	s_nop 4
	s_nop 0
	s_load_dwordx2 s[26:27], s[10:11], 0x0
	s_load_dwordx2 s[16:17], s[14:15], 0x50
	s_nop 0
	s_load_dwordx2 s[14:15], s[24:25], 0x58
	v_mov_b32_e32 v135, v0
	v_mov_b32_e32 v139, v0
	v_mov_b32_e32 v133, v0
	v_mov_b32_e32 v137, v0
	v_lshl_add_u64 v[12:13], s[34:35], 0, v[134:135]
	v_lshl_add_u64 v[8:9], s[34:35], 0, v[138:139]
	v_lshl_add_u64 v[4:5], s[0:1], 0, v[134:135]
	v_lshl_add_u64 v[2:3], s[0:1], 0, v[138:139]
	v_lshl_add_u64 v[10:11], s[36:37], 0, v[132:133]
	s_cmp_lg_u32 s50, 1
	v_lshl_add_u64 v[6:7], s[36:37], 0, v[136:137]
	s_cbranch_scc1 .LBB0_260
	s_barrier

; __device__ __forceinline__ float sigm(float x) { return __builtin_amdgcn_rcpf(1.f + __expf(-x)); }
; __device__ __forceinline__ void ba_phase(const bf16* XBp, const bf16* WBAb, const float* A_log, const float* dt_bias, float* BETA, float* GG, int gw, int NGW, int lane) {
;     const int li = lane & 15, lq = lane >> 4;
;     for (int t = gw; t < MPROMPT / 16; t += NGW) {
;         const bf16* ap = XBp + (size_t)(16 * t + li) * D + 8 * lq; const bf16* bp = WBAb + (size_t)li * D + 8 * lq;
;         f32x4 acc = (f32x4){0.f, 0.f, 0.f, 0.f};
; #pragma unroll 8
;         for (int k = 0; k < D; k += 32) acc = __builtin_amdgcn_mfma_f32_16x16x32_bf16(*(const bf16x8*)(ap + k), *(const bf16x8*)(bp + k), acc, 0, 0, 0);
;         float al = 0.f, db = 0.f; if (li >= 8) { al = expf(A_log[li - 8]); db = dt_bias[li - 8]; }
; #pragma unroll
;         for (int r = 0; r < 4; ++r) { const size_t m = (size_t)(16 * t + 4 * lq + r); const float v = acc[r];
;             if (li < 8) BETA[m * 8 + li] = sigm(v);
;             else { const float xx = v + db; const float sp = xx > 20.f ? xx : log1pf(expf(xx)); GG[m * 8 + (li - 8)] = -al * sp; } }
;     }
; }
.LBB0_374:
	s_cmp_lt_i32 s64, 4
	s_cselect_b64 s[0:1], -1, 0
	s_and_b64 s[4:5], s[0:1], s[6:7]
	s_andn2_b64 vcc, exec, s[4:5]
	s_cbranch_vccnz .LBB0_425
	s_mov_b64 s[0:1], s[56:57]
	s_mov_b64 s[6:7], s[56:57]
	s_mov_b64 s[12:13], s[56:57]
	s_mov_b64 s[10:11], s[56:57]
	s_mov_b64 s[14:15], s[56:57]
	s_mov_b64 s[16:17], s[56:57]
	s_sub_i32 s3, s94, 0x80
	s_cmpk_gt_u32 s3, 0x3ff
	s_cbranch_scc1 .LBB0_406
	s_mov_b64 s[8:9], s[86:87]
	s_nop 4
	s_mov_b64 s[18:19], s[86:87]
	s_nop 4
	s_load_dwordx2 s[20:21], s[12:13], 0x70
	s_load_dwordx2 s[22:23], s[10:11], 0x78
	s_mov_b64 s[24:25], s[86:87]
	s_nop 4
	s_mov_b64 s[26:27], s[86:87]
	s_nop 4
	v_mov_b32_e32 v5, 0
	v_subrev_co_u32_e32 v4, vcc, 8, v156
	v_lshlrev_b64 v[2:3], 2, v[4:5]
	s_waitcnt lgkmcnt(0)
	v_lshl_add_u64 v[6:7], s[22:23], 0, v[2:3]
	v_lshl_add_u64 v[8:9], s[20:21], 0, v[2:3]
	v_lshrrev_b32_e32 v2, 2, v152
	v_lshlrev_b32_e32 v4, 2, v156
	v_and_b32_e32 v24, 12, v2
	v_lshl_add_u64 v[2:3], s[26:27], 0, v[4:5]
	s_mov_b64 s[0:1], 0xeeb2000
	v_lshl_add_u64 v[10:11], v[2:3], 0, s[0:1]
	v_lshl_add_u64 v[2:3], s[24:25], 0, v[4:5]
	s_mov_b64 s[0:1], 0xee30000
	v_lshl_add_u64 v[12:13], v[2:3], 0, s[0:1]
	s_lshl_b32 s0, s2, 7
	s_lshl_b32 s1, s95, 4
	v_lshlrev_b32_e32 v0, 11, v156
	v_mov_b32_e32 v1, v5
	s_add_i32 s0, s0, s1
	s_sub_i32 s0, s0, 0x800
	v_cmp_lt_u32_e64 s[6:7], 7, v156
	s_xor_b64 s[10:11], vcc, -1
	v_and_b32_e32 v4, 48, v154
	v_or_b32_e32 v14, s0, v156
	s_lshl_b32 s3, s88, 7
	v_lshl_add_u64 v[16:17], s[18:19], 0, v[0:1]
	s_mov_b64 s[12:13], 0x200
	s_mov_b32 s18, 0x3fb8aa3b
	s_mov_b32 s19, 0xc2ce8ed0
	s_mov_b32 s20, 0x42b17218
	s_mov_b32 s21, 0x7f800000
	s_mov_b32 s22, 0x41a00000
	s_mov_b32 s23, 0x3f2aaaab
	v_mov_b32_e32 v25, 0x3ecc95a3
	s_mov_b32 s24, 0x3f317218
	s_mov_b32 s25, 0x33800000
	v_mov_b32_e32 v26, 0x7f800000
	v_mov_b32_e32 v18, 0x3f317218
	s_sub_i32 s26, s94, 0x80
	s_branch .LBB0_378

; #define LAS __attribute__((address_space(3)))
; __device__ __forceinline__ const float* arg_in(int k) { return (const float*)(const __attribute__((address_space(1))) float*)arg_q(k); }
; template <bool WRITE_BF16, bool DO_BA, bool WRITE_F32>
; __device__ __forceinline__ void ln_phase(int m_lo, float* RES, const float* g, const float* b, bf16* XB, const LAS float* wba, const float* A_log, const float* dt_bias, float* BETA, float* GG, int gw, int NGW, int lane) {
;     f32x4 gv[4], bv[4];
; #pragma unroll
;     for (int j = 0; j < 4; ++j) { gv[j] = *((const f32x4*)g + 64 * j + lane); bv[j] = *((const f32x4*)b + 64 * j + lane); }
;     for (int m = m_lo + gw; m < MREAL; m += NGW) {
; __global__ void __launch_bounds__(NWAVES * 64, 2) mega_fwd(Args args) {
;     ...
;         if ((int)blockIdx.x * NWAVES < MS) {
;             for (int e = tid; e < 16 * 1024 / 4; e += 512) ((LAS f32x4*)lds)[e] = ((const f32x4*)WBA)[e];
;             __syncthreads();
;             ln_phase<true, true, false>(MPROMPT, RES, arg_in(10), arg_in(11), XB, (const LAS float*)lds, arg_in(14), arg_in(15), BETA, GG, gw, NGW, lane);
.LBB0_406:
	s_cmp_gt_i32 s2, 15
	s_cbranch_scc1 .LBB0_425
	v_lshlrev_b32_e32 v3, 4, v154
	s_mov_b64 s[8:9], s[56:57]
	s_mov_b64 s[8:9], s[86:87]
	s_nop 4
	v_or_b32_e32 v0, 0x2b20000, v3
	v_mov_b32_e32 v1, 0
	s_mov_b64 s[6:7], 0x2000
	s_mov_b64 s[0:1], 0
	s_waitcnt lgkmcnt(0)
	v_lshl_add_u64 v[0:1], s[8:9], 0, v[0:1]
	global_load_dwordx4 v[4:7], v[0:1], off
	v_lshl_add_u64 v[0:1], v[0:1], 0, s[6:7]
	global_load_dwordx4 v[8:11], v[0:1], off
	v_lshl_add_u64 v[0:1], v[0:1], 0, s[6:7]
	global_load_dwordx4 v[12:15], v[0:1], off
	v_lshl_add_u64 v[0:1], v[0:1], 0, s[6:7]
	global_load_dwordx4 v[16:19], v[0:1], off
	v_lshl_add_u64 v[0:1], v[0:1], 0, s[6:7]
	global_load_dwordx4 v[20:23], v[0:1], off
	v_lshl_add_u64 v[0:1], v[0:1], 0, s[6:7]
	global_load_dwordx4 v[24:27], v[0:1], off
	v_lshl_add_u64 v[0:1], v[0:1], 0, s[6:7]
	global_load_dwordx4 v[28:31], v[0:1], off
	v_lshl_add_u64 v[0:1], v[0:1], 0, s[6:7]
	global_load_dwordx4 v[32:35], v[0:1], off
	s_waitcnt vmcnt(7)
	ds_write_b128 v3, v[4:7]
	s_waitcnt vmcnt(6)
	ds_write_b128 v3, v[8:11] offset:8192
	s_waitcnt vmcnt(5)
	ds_write_b128 v3, v[12:15] offset:16384
	s_waitcnt vmcnt(4)
	ds_write_b128 v3, v[16:19] offset:24576
	s_waitcnt vmcnt(3)
	ds_write_b128 v3, v[20:23] offset:32768
	s_waitcnt vmcnt(2)
	ds_write_b128 v3, v[24:27] offset:40960
	s_waitcnt vmcnt(1)
	ds_write_b128 v3, v[28:31] offset:49152
	s_waitcnt vmcnt(0)
	ds_write_b128 v3, v[32:35] offset:57344
	s_or_b64 exec, exec, s[0:1]
	s_mov_b64 s[0:1], s[56:57]
	s_mov_b64 s[16:17], s[56:57]
	s_mov_b64 s[18:19], s[56:57]
	s_mov_b64 s[6:7], s[56:57]
	s_mov_b64 s[8:9], s[56:57]
	s_mov_b64 s[10:11], s[56:57]
	s_mov_b64 s[14:15], s[56:57]
	s_mov_b64 s[12:13], s[56:57]
	s_cmpk_gt_i32 s94, 0x7f
	s_waitcnt lgkmcnt(0)
	s_barrier
	s_cbranch_scc1 .LBB0_424
	s_load_dwordx2 s[20:21], s[16:17], 0x50
	s_load_dwordx2 s[22:23], s[18:19], 0x58
	v_lshlrev_b32_e32 v32, 4, v152
	v_mbcnt_lo_u32_b32 v34, -1, 0
	v_mbcnt_hi_u32_b32 v34, -1, v34
	v_and_b32_e32 v35, 64, v34
	s_waitcnt lgkmcnt(0)
	global_load_dwordx4 v[0:3], v32, s[20:21]
	global_load_dwordx4 v[4:7], v32, s[20:21] offset:1024
	global_load_dwordx4 v[8:11], v32, s[22:23]
	global_load_dwordx4 v[12:15], v32, s[22:23] offset:1024
	global_load_dwordx4 v[16:19], v32, s[20:21] offset:2048
	global_load_dwordx4 v[20:23], v32, s[20:21] offset:3072
	global_load_dwordx4 v[24:27], v32, s[22:23] offset:2048
	global_load_dwordx4 v[28:31], v32, s[22:23] offset:3072
	v_add_u32_e32 v35, 64, v35
	v_xor_b32_e32 v36, 1, v34
	v_cmp_lt_i32_e32 vcc, v36, v35
	s_load_dwordx2 s[16:17], s[0:1], 0x100
	s_mov_b64 s[18:19], s[86:87]
	s_nop 4
	s_load_dwordx2 s[20:21], s[8:9], 0x70
	s_load_dwordx2 s[22:23], s[10:11], 0x78
	s_mov_b64 s[24:25], s[86:87]
	s_nop 4
	v_cndmask_b32_e32 v36, v34, v36, vcc
	v_lshlrev_b32_e32 v62, 2, v36
	v_xor_b32_e32 v36, 2, v34
	v_cmp_lt_i32_e32 vcc, v36, v35
	s_mov_b64 s[0:1], s[86:87]
	s_nop 4
	v_mov_b32_e32 v33, 0
	v_cndmask_b32_e32 v36, v34, v36, vcc
	v_lshlrev_b32_e32 v63, 2, v36
	v_xor_b32_e32 v36, 4, v34
	v_cmp_lt_i32_e32 vcc, v36, v35
	s_waitcnt lgkmcnt(0)
	v_lshl_add_u64 v[48:49], s[16:17], 0, v[32:33]
	s_mov_b64 s[6:7], 0x2b30000
	v_cndmask_b32_e32 v36, v34, v36, vcc
	v_lshlrev_b32_e32 v64, 2, v36
	v_xor_b32_e32 v36, 8, v34
	v_cmp_lt_i32_e32 vcc, v36, v35
	v_add_u32_e32 v68, 0, v32
	s_add_i32 s10, s94, 0x4000
	v_cndmask_b32_e32 v36, v34, v36, vcc
	v_lshlrev_b32_e32 v65, 2, v36
	v_xor_b32_e32 v36, 16, v34
	v_cmp_lt_i32_e32 vcc, v36, v35
	v_lshlrev_b32_e32 v69, 12, v152
	v_mov_b32_e32 v70, 0x3727c5ac
	v_cndmask_b32_e32 v36, v34, v36, vcc
	v_lshlrev_b32_e32 v66, 2, v36
	v_xor_b32_e32 v36, 32, v34
	v_cmp_lt_i32_e32 vcc, v36, v35
	v_mov_b32_e32 v35, v33
	s_mov_b32 s3, 0xf800000
	v_cndmask_b32_e32 v34, v34, v36, vcc
	v_lshlrev_b32_e32 v67, 2, v34
	v_lshlrev_b32_e32 v34, 3, v152
	v_lshl_add_u64 v[34:35], s[18:19], 0, v[34:35]
	v_subrev_co_u32_e32 v32, vcc, 8, v152
	v_lshl_add_u64 v[50:51], v[34:35], 0, s[6:7]
	v_lshlrev_b64 v[34:35], 2, v[32:33]
	v_lshl_add_u64 v[52:53], s[22:23], 0, v[34:35]
	v_lshl_add_u64 v[54:55], s[20:21], 0, v[34:35]
	v_lshl_add_u64 v[34:35], s[0:1], 0, v[34:35]
	s_mov_b64 s[0:1], 0xeeb2000
	v_lshlrev_b32_e32 v32, 2, v152
	v_lshl_add_u64 v[56:57], v[34:35], 0, s[0:1]
	v_lshl_add_u64 v[32:33], s[24:25], 0, v[32:33]
	s_mov_b64 s[0:1], 0xee30000
	s_xor_b64 s[12:13], vcc, -1
	v_cmp_gt_u32_e64 s[6:7], 16, v152
	v_lshl_add_u64 v[58:59], v[32:33], 0, s[0:1]
	v_mov_b32_e32 v71, 0x260
	s_mov_b32 s18, 0x41a00000
	s_mov_b32 s19, 0x3fb8aa3b
	s_mov_b32 s20, 0xc2ce8ed0
	s_mov_b32 s21, 0x42b17218
	s_mov_b32 s22, 0x7f800000
	s_mov_b32 s23, 0x3f2aaaab
	v_mov_b32_e32 v72, 0x3ecc95a3
	s_mov_b32 s24, 0x3f317218
	s_mov_b32 s25, 0x33800000
	v_mov_b32_e32 v73, 0x7f800000
	v_mov_b32_e32 v60, 0x3f317218
	s_branch .LBB0_412

; #define LAS __attribute__((address_space(3)))
; template <class RowMap, class EpiT>
; __device__ __forceinline__ void sgemm128_phase(LAS unsigned char* lds, const bf16* A, const bf16* Bt, int ntile, int K, const RowMap& RM, const EpiT& E, int bidx, int nb) {
;     const int tid = threadIdx.x, lane = tid & 63, wave = __builtin_amdgcn_readfirstlane(tid >> 6), li = lane & 15, lq = lane >> 4;
;     const int kper = K >> 3;
;     LAS float* red = (LAS float*)lds; LAS float* tile = red + 8 * 2048;
;     for (int ct = bidx; ct < ntile; ct += nb) {
;         const bf16* bp = Bt + (size_t)RM(ct, li) * K + wave * kper + 8 * lq; const bf16* ap = A + (size_t)li * K + wave * kper + 8 * lq;
; __global__ void __launch_bounds__(NWAVES * 64, 2) mega_fwd(Args args) {
;     ...
;     if (IN(4)) { EpiQKV E{R0, HALO, out + O_SPQ, out + O_SSQ}; { SQkv ES{out + O_SSQ}; RMPlain RM; sgemm128_phase(lds, XB + SOFF, WQKV, 192, 1024, RM, ES, (int)blockIdx.x, G); }
.LBB0_479:
	s_cmp_lt_i32 s64, 5
	s_cselect_b64 s[0:1], -1, 0
	s_and_b64 s[4:5], s[0:1], s[6:7]
	s_andn2_b64 vcc, exec, s[4:5]
	s_cbranch_vccnz .LBB0_580
	s_mov_b64 s[0:1], s[56:57]
	s_mov_b64 s[6:7], s[86:87]
	s_nop 4
	s_mov_b64 s[0:1], s[56:57]
	s_mov_b64 s[8:9], s[86:87]
	s_nop 4
	s_mov_b64 s[0:1], s[56:57]
	s_load_dwordx2 s[10:11], s[0:1], 0x100
	s_mov_b64 s[0:1], s[56:57]
	s_load_dwordx2 s[12:13], s[0:1], 0x100
	s_mov_b64 s[0:1], s[56:57]
	s_mov_b64 s[14:15], s[56:57]
	s_mov_b64 s[16:17], s[56:57]
	s_cmpk_gt_i32 s2, 0xbf
	v_readfirstlane_b32 s3, v154
	s_cbranch_scc1 .LBB0_485
	s_load_dwordx2 s[18:19], s[0:1], 0x100
	s_mov_b64 s[20:21], s[86:87]
	s_nop 4
	s_mov_b64 s[22:23], s[86:87]
	s_nop 4
	v_lshlrev_b32_e32 v0, 2, v156
	v_lshrrev_b32_e32 v1, 4, v154
	s_waitcnt lgkmcnt(0)
	s_add_u32 s14, s18, 0x84d8000
	s_addc_u32 s15, s19, 0
	s_lshr_b32 s3, s3, 6
	s_lshl_b32 s0, s3, 7
	s_lshl_b32 s3, s3, 13
	s_add_i32 s3, s3, 0
	v_add_u32_e32 v6, s3, v0
	s_add_i32 s3, 0, 0x10000
	v_lshlrev_b32_e32 v2, 2, v154
	v_mul_u32_u24_e32 v32, 0x9000, v1
	v_mov_b32_e32 v33, 0
	v_lshlrev_b32_e32 v8, 6, v1
	v_add_u32_e32 v52, 0, v2
	v_add_u32_e32 v53, s3, v2
	v_lshl_add_u64 v[2:3], s[14:15], 0, v[32:33]
	v_mov_b32_e32 v1, v33
	v_add_u32_e32 v9, 0x200, v154
	v_lshl_add_u64 v[2:3], v[2:3], 0, v[0:1]
	s_mov_b64 s[16:17], 0x6000
	v_lshl_add_u64 v[34:35], v[2:3], 0, s[16:17]
	v_lshrrev_b32_e32 v2, 4, v9
	v_mul_u32_u24_e32 v32, 0x9000, v2
	v_lshl_add_u32 v54, v9, 2, s3
	v_lshlrev_b32_e32 v9, 6, v2
	v_lshl_add_u64 v[2:3], s[14:15], 0, v[32:33]
	v_or_b32_e32 v10, 0x400, v154
	v_lshl_add_u64 v[2:3], v[2:3], 0, v[0:1]
	v_lshl_add_u64 v[36:37], v[2:3], 0, s[16:17]
	v_lshrrev_b32_e32 v2, 4, v10
	v_mul_u32_u24_e32 v32, 0x9000, v2
	v_lshl_add_u32 v55, v10, 2, s3
	v_lshlrev_b32_e32 v10, 6, v2
	v_lshl_add_u64 v[2:3], s[14:15], 0, v[32:33]
	v_add_u32_e32 v11, 0x600, v154
	v_lshl_add_u64 v[2:3], v[2:3], 0, v[0:1]
	v_lshl_add_u64 v[38:39], v[2:3], 0, s[16:17]
	v_lshrrev_b32_e32 v2, 4, v11
	v_bfe_u32 v4, v154, 4, 2
	v_mul_u32_u24_e32 v32, 0x9000, v2
	v_lshl_add_u32 v56, v11, 2, s3
	v_lshlrev_b32_e32 v11, 6, v2
	v_lshl_add_u64 v[2:3], s[14:15], 0, v[32:33]
	v_lshlrev_b32_e32 v32, 4, v4
	s_mov_b32 s1, 0
	v_lshlrev_b32_e32 v5, 8, v4
	v_add_u32_e32 v7, s3, v0
	v_lshl_add_u64 v[0:1], v[2:3], 0, v[0:1]
	v_lshl_add_u64 v[42:43], s[22:23], 0, v[32:33]
	v_lshl_or_b32 v32, v156, 11, v32
	v_lshl_add_u64 v[40:41], v[0:1], 0, s[16:17]
	s_lshl_b64 s[14:15], s[0:1], 1
	v_lshl_or_b32 v44, s2, 4, v156
	s_lshl_b32 s0, s88, 4
	v_lshl_add_u64 v[46:47], s[20:21], 0, v[32:33]
	s_mov_b32 s1, 0x10a0000
	s_mov_b32 s3, 0x4b30000
	s_mov_b32 s18, 0x4b38000
	s_mov_b32 s19, 0x4b40000
	s_mov_b32 s20, 0x4b48000
	s_mov_b32 s21, 0x4b50000
	s_mov_b32 s22, 0x4b58000
	s_mov_b32 s23, 0x4b60000
	s_mov_b32 s24, 0x4b68000
	s_mov_b64 s[16:17], 0x80
	v_add_u32_e32 v32, v6, v5
	v_add_u32_e32 v57, v7, v8
	v_add_u32_e32 v58, v7, v9
	v_add_u32_e32 v59, v7, v10
	v_add_u32_e32 v60, v7, v11
	s_mov_b32 s25, s2

; #define PG8_STAGE(bufoff, gbase, voff) do { _Pragma("unroll") for (int _i = 0; _i < 2; ++_i) \
;         __builtin_amdgcn_global_load_lds((const unsigned*)((const char*)(gbase) + (voff)[_i]), (PG8_LAS unsigned*)(lds + (bufoff) + ldsw + _i * 8192), 16, 0, 0); } while (0)
; #define PG8_WAIT_V(n) asm volatile("s_waitcnt vmcnt(" #n ")" ::: "memory")
; #define PG8_BAR __builtin_amdgcn_s_barrier()
; #define GEMM(EpiT, E, Aop, Bop, M_, N_, K_) do { int k_ = K_; asm volatile("" : "+s"(k_)); pg8::Gemm g_{Aop, Bop, M_, N_, k_}; pg8::StaticOrder S_; S_.init(M_, N_, G, (int)blockIdx.x); \
;         pg8::gemm_phase<EpiT, pg8::StaticOrder, true, true>(lds, g_, S_, E); } while (0)
; template <class Epi, class Sched, bool ALIGN_EPI = false, bool SP2 = false>
; __device__ __forceinline__ void gemm_phase(PG8_LAS unsigned char* lds, const Gemm g, const Sched& S, const Epi& E) {
;     ...
;     const char* cA = (const char*)g.A + (size_t)cur.pm * tstep; const char* cB = (const char*)g.Bt + (size_t)cur.pn * tstep;
;     S.a_ready(cur);
;     if constexpr (SP2) {
;         PG8_STAGE(PG8_SB(0, 0), cB, voffB); PG8_STAGE(PG8_SB(0, 1), cB + hstep, voffB); PG8_STAGE(PG8_SA(0, 0), cA, voffA); PG8_STAGE(PG8_SA(0, 1), cA + hstep, voffA);
;         if (wr == 1) PG8_BAR;
;         PG8_WAIT_V(2); PG8_BAR;
;         PG8_STAGE(PG8_SB(1, 0), cB + kstep, voffB); PG8_STAGE(PG8_SA(1, 0), cA + kstep, voffA); PG8_STAGE(PG8_SB(1, 1), cB + hstep + kstep, voffB);
;         PG8_WAIT_V(6); PG8_BAR;
; __global__ void __launch_bounds__(NWAVES * 64, 2) mega_fwd(Args args) {
;     ...
;         GEMM(EpiQKV, E, XB, WQKV, MPROMPT, 3072, 1024); }
.LBB0_487:
	s_andn2_b64 vcc, exec, s[16:17]
	s_cbranch_vccnz .LBB0_580
	s_mov_b64 s[16:17], s[86:87]
	s_nop 4
	s_mov_b64 s[18:19], s[86:87]
	s_nop 4
	v_lshrrev_b32_e32 v2, 1, v154
	v_and_b32_e32 v17, 24, v2
	v_lshrrev_b32_e32 v2, 5, v154
	s_waitcnt lgkmcnt(0)
	s_add_u32 s3, s16, 0x2b30000
	s_addc_u32 s52, s17, 0
	s_add_u32 s53, s18, 0x10a0000
	s_addc_u32 s54, s19, 0
	s_ashr_i32 s35, s34, 31
	s_lshl_b64 s[16:17], s[34:35], 9
	s_ashr_i32 s18, s48, 31
	s_mul_i32 s18, s16, s18
	s_mul_hi_u32 s19, s16, s48
	s_add_i32 s20, s19, s18
	s_lshr_b64 s[18:19], s[34:35], 23
	s_mul_i32 s19, s18, s48
	v_lshlrev_b32_e32 v0, 4, v154
	v_and_b32_e32 v1, 32, v154
	v_and_b32_e32 v2, 4, v2
	v_bfe_u32 v3, v154, 2, 2
	s_add_i32 s20, s20, s19
	s_ashr_i32 s19, s49, 31
	v_bitop3_b32 v12, v0, v1, 48 bitop3:0x6c
	v_or3_b32 v2, v2, v3, v17
	v_lshrrev_b32_e32 v3, 3, v154
	s_movk_i32 s1, 0x60
	v_add_u32_e32 v0, 0x2000, v0
	s_mul_i32 s19, s16, s19
	s_mul_hi_u32 s22, s16, s49
	s_lshr_b32 s0, s30, 6
	v_and_b32_e32 v15, 0x70, v3
	v_and_or_b32 v3, v3, s1, v2
	v_lshrrev_b32_e32 v0, 7, v0
	s_movk_i32 s1, 0xe0
	s_add_i32 s19, s22, s19
	s_mul_i32 s18, s18, s49
	v_and_b32_e32 v13, 64, v154
	v_and_b32_e32 v16, 0xf0, v0
	v_and_or_b32 v0, v0, s1, v2
	s_lshr_b32 s1, s30, 8
	s_lshl_b64 s[14:15], s[34:35], 8
	s_lshl_b32 s55, s0, 10
	s_add_i32 s19, s19, s18
	s_mul_i32 s18, s16, s49
	v_or_b32_e32 v1, v12, v13
	s_add_u32 s44, s53, s18
	v_lshrrev_b32_e32 v1, 1, v1
	v_mul_lo_u32 v3, s34, v3
	s_addc_u32 s45, s54, s19
	s_add_i32 s58, s55, 0
	v_add_lshl_u32 v130, v3, v1, 1
	s_add_i32 m0, s58, 0x10000
	v_mul_lo_u32 v0, s34, v0
	global_load_lds_dwordx4 v130, s[44:45]
	s_add_i32 m0, s58, 0x12000
	v_add_lshl_u32 v134, v0, v1, 1
	s_add_u32 s18, s44, s14
	global_load_lds_dwordx4 v134, s[44:45]
	s_addc_u32 s19, s45, s15
	s_add_i32 m0, s58, 0x14000
	v_bfe_u32 v14, v154, 2, 4
	s_mul_i32 s21, s16, s48
	global_load_lds_dwordx4 v130, s[18:19]
	s_add_i32 m0, s58, 0x16000
	v_or_b32_e32 v4, v15, v14
	s_add_u32 s46, s3, s21
	v_mul_lo_u32 v4, s34, v4
	v_or_b32_e32 v3, v16, v14
	s_addc_u32 s47, s52, s20
	s_add_i32 s59, s58, 0x2000
	v_add_lshl_u32 v128, v4, v1, 1
	v_mul_lo_u32 v2, s34, v3
	global_load_lds_dwordx4 v134, s[18:19]
	s_mov_b32 m0, s58
	s_add_u32 s20, s46, s14
	v_add_lshl_u32 v132, v2, v1, 1
	global_load_lds_dwordx4 v128, s[46:47]
	s_mov_b32 m0, s59
	s_addc_u32 s21, s47, s15
	s_add_i32 s60, s58, 0x4000
	global_load_lds_dwordx4 v132, s[46:47]
	s_mov_b32 m0, s60
	s_add_i32 s61, s58, 0x6000
	global_load_lds_dwordx4 v128, s[20:21]
	s_mov_b32 m0, s61
	v_mov_b32_e32 v137, 0
	global_load_lds_dwordx4 v132, s[20:21]
	v_mov_b32_e32 v131, v137
	v_mov_b32_e32 v135, v137
	v_mov_b32_e32 v129, v137
	v_mov_b32_e32 v133, v137
	s_cmp_eq_u32 s1, 1
	s_mov_b64 s[96:97], s[80:81]
	s_mov_b32 s62, 0
	v_lshl_add_u64 v[8:9], s[44:45], 0, v[130:131]
	v_lshl_add_u64 v[4:5], s[44:45], 0, v[134:135]
	v_lshl_add_u64 v[2:3], s[18:19], 0, v[130:131]
	v_lshl_add_u64 v[0:1], s[18:19], 0, v[134:135]
	v_lshl_add_u64 v[6:7], s[46:47], 0, v[128:129]
	s_cselect_b64 s[18:19], -1, 0
	s_cmp_lg_u32 s1, 1
	v_lshl_add_u64 v[10:11], s[46:47], 0, v[132:133]
	s_cbranch_scc1 .LBB0_490
	s_barrier

; #define LAS __attribute__((address_space(3)))
; __device__ __forceinline__ void prep_unit(const int PREP_STEPS, LAS unsigned char* lds, int uidx, bf16* Qg, bf16* Kg, bf16* Vg, bf16* KT, bf16* QK, const bf16* HALO, const float* wconv, const float* BETA, const float* GG, float* GC) {
;     const int tid = threadIdx.x, hb = tid >> 8, tl = tid & 255, lane = tid & 63, wq = (tid >> 6) & 3;
;     const int b = uidx >> 7, rem = uidx & 127, h = rem >> 4, cp = rem & 15, n = 2 * cp + hb;
;     const int gcid = b * 32 + n, m0 = b * 2048 + n * 64;
;     LAS unsigned char* L = lds + hb * PREP_HALF;
;     LAS bf16* Qs = (LAS bf16*)L; LAS bf16* Ks = Qs + 64 * 136; LAS bf16* Vs = Ks + 64 * 136;
;     LAS float* Af = (LAS float*)(L + 3 * 17408); LAS float* gcs = Af + 64 * 68; LAS float* betas = gcs + 64; LAS float* egcs = betas + 64;
;     if (PREP_STEPS & 1) {
;         const int c8 = tl & 15, rg = tl >> 4, colh = h * 128 + 8 * c8;
; #pragma unroll
;         for (int mat = 0; mat < 3; ++mat) {
;             const bf16* src = (mat == 0 ? Qg : (mat == 1 ? Kg : Vg));
;             float xin[7][8];
; #pragma unroll
;             for (int i = 0; i < 7; ++i) { const int rr = 4 * rg - 3 + i; u32x4 w = (u32x4){0u, 0u, 0u, 0u};
;                 if (rr >= 0) w = *(const u32x4*)(src + (size_t)(m0 + rr) * D + colh);
;                 else if (n > 0) w = *(const u32x4*)(HALO + ((size_t)(gcid - 1) * 3 + (3 + rr)) * 3072 + mat * 1024 + colh);
;                 unpack8(w, xin[i]); }
.LBB0_638:
	s_mov_b64 s[0:1], s[56:57]
	s_mov_b64 s[0:1], s[86:87]
	s_nop 4
	s_mov_b64 s[6:7], s[56:57]
	s_mov_b64 s[6:7], s[86:87]
	s_nop 4
	s_mov_b64 s[8:9], s[56:57]
	s_mov_b64 s[10:11], s[86:87]
	s_nop 4
	s_waitcnt lgkmcnt(0)
	s_add_u32 s16, s0, 0x4bb0000
	s_addc_u32 s17, s1, 0
	s_add_u32 s8, s6, 0x6c30000
	s_mov_b64 s[0:1], s[56:57]
	s_addc_u32 s9, s7, 0
	s_add_u32 s10, s10, 0x8cb0000
	s_mov_b64 s[14:15], s[86:87]
	s_nop 4
	s_mov_b64 s[0:1], s[56:57]
	s_addc_u32 s11, s11, 0
	s_mov_b64 s[12:13], s[86:87]
	s_nop 4
	s_lshl_b32 s25, s3, 1
	s_and_b32 s25, s25, 30
	s_ashr_i32 s24, s3, 7
	v_add_u32_e32 v1, s25, v57
	v_lshl_add_u32 v59, s24, 5, v1
	s_lshl_b32 s24, s24, 11
	s_mov_b64 s[6:7], s[56:57]
	s_mov_b64 s[80:81], s[56:57]
	s_mov_b64 s[90:91], s[56:57]
	s_mov_b64 s[0:1], s[56:57]
	s_mov_b64 s[54:55], s[56:57]
	s_bfe_u32 s82, s3, 0x30004
	s_andn2_b64 vcc, exec, s[92:93]
	v_lshl_add_u32 v70, v1, 6, s24
	s_cbranch_vccnz .LBB0_696
	v_lshl_or_b32 v0, s82, 7, v113
	v_lshlrev_b32_e32 v54, 1, v0
	v_cmp_ne_u32_e64 s[76:77], 0, v1
	v_lshl_add_u64 v[82:83], s[16:17], 0, v[54:55]
	s_and_saveexec_b64 s[96:97], s[94:95]
	s_xor_b64 s[96:97], exec, s[96:97]
	s_cbranch_execz .LBB0_641
	v_add_u32_e32 v2, v70, v115
	v_ashrrev_i32_e32 v3, 31, v2
	v_lshlrev_b64 v[2:3], 11, v[2:3]
	v_lshl_add_u64 v[2:3], v[82:83], 0, v[2:3]
	global_load_dwordx4 v[40:43], v[2:3], off
.LBB0_641:
	s_or_saveexec_b64 vcc, s[96:97]
	s_mov_b64 s[24:25], s[86:87]
	s_nop 4
	s_load_dwordx2 s[96:97], s[80:81], 0x68
	s_nop 0
	s_mov_b64 s[6:7], s[86:87]
	s_nop 4
	s_nop 0
	s_mov_b64 s[90:91], s[86:87]
	s_nop 4
	s_mov_b64 s[80:81], s[86:87]
	s_nop 4
	s_waitcnt lgkmcnt(0)
	v_lshl_add_u64 v[2:3], s[24:25], 0, v[54:55]
	s_mov_b64 s[0:1], 0xf3c6000
	v_add_u32_e32 v63, -1, v59
	v_lshl_add_u64 v[48:49], v[2:3], 0, s[0:1]
	s_xor_b64 exec, exec, vcc
	s_cbranch_execz .LBB0_645
	s_waitcnt vmcnt(0)
	v_mov_b32_e32 v43, 0
	v_mov_b32_e32 v42, 0
	v_mov_b32_e32 v41, 0
	v_mov_b32_e32 v40, 0
	s_and_saveexec_b64 s[0:1], s[76:77]
	s_cbranch_execz .LBB0_644
	s_movk_i32 s24, 0x4800
	v_mad_i64_i32 v[2:3], s[24:25], v63, s24, v[48:49]
	global_load_dwordx4 v[40:43], v[2:3], off

; __device__ __forceinline__ const float* arg_in(int k) { return (const float*)(const __attribute__((address_space(1))) float*)arg_q(k); }
; __device__ __forceinline__ void prep_sample(const float* st_qkv, float* ss_qkv, const float* wconv, float* SQKV, int G) {
;     const int tid = threadIdx.x, c8 = tid & 15;
;     for (int g = blockIdx.x * 32 + (tid >> 4); g < 128 * 24; g += G * 32) {
;         const int bs = g / 24, mh = g - bs * 24, mat = mh >> 3, gcol = mh * 128 + 8 * c8;
;         float y[8];
; #pragma unroll
;         for (int e = 0; e < 8; ++e) y[e] = 0.f;
; #pragma unroll
;         for (int j = 0; j < 4; ++j) {
;             const float* xp = (j < 3) ? st_qkv + ((size_t)bs * 3 + j) * 3072 + gcol : ss_qkv + ((size_t)bs * 3 + 2) * 3072 + gcol;
;             const f32x4 x0 = *(const f32x4*)xp, x1 = *(const f32x4*)(xp + 4);
;             const float* wp = wconv + (size_t)j * 3072 + gcol; const f32x4 w0 = *(const f32x4*)wp, w1 = *(const f32x4*)(wp + 4);
; #pragma unroll
;             for (int e = 0; e < 4; ++e) { y[e] += w0[e] * x0[e]; y[4 + e] += w1[e] * x1[e]; }
;             if (j >= 1 && j < 3) { float* o = ss_qkv + ((size_t)bs * 3 + (j - 1)) * 3072 + gcol; *(f32x4*)o = x0; *(f32x4*)(o + 4) = x1; }
; __global__ void __launch_bounds__(NWAVES * 64, 2) mega_fwd(Args args) {
;     ...
;         prep_sample(arg_in(5), out + O_SSQ, arg_in(13), SQKV, G);
.LBB0_768:
	v_lshrrev_b32_e32 v0, 4, v154
	v_lshl_add_u32 v6, s2, 5, v0
	s_movk_i32 s3, 0xc00
	s_mov_b64 s[0:1], s[56:57]
	s_mov_b64 s[10:11], s[56:57]
	s_waitcnt lgkmcnt(0)
	s_mov_b64 s[12:13], s[56:57]
	s_mov_b64 s[14:15], s[56:57]
	v_cmp_gt_i32_e32 vcc, s3, v6
	s_and_saveexec_b64 s[4:5], vcc
	s_load_dwordx4 s[64:67], s[56:57], 0x110
	s_load_dword s92, s[56:57], 0x128
	v_readlane_b32 s94, v244, 5
	v_readlane_b32 s95, v244, 6
	v_readlane_b32 s80, v244, 3
	v_readlane_b32 s81, v244, 4
	v_readlane_b32 s95, v244, 2
	s_cbranch_execz .LBB0_773
	s_load_dwordx2 s[16:17], s[10:11], 0x100
	s_load_dwordx2 s[6:7], s[0:1], 0x28
	s_mov_b64 s[18:19], s[86:87]
	s_nop 4
	s_load_dwordx2 s[8:9], s[12:13], 0x68
	v_lshlrev_b32_e32 v0, 7, v0
	s_waitcnt lgkmcnt(0)
	s_add_u32 s10, s16, 0x84d8000
	s_addc_u32 s11, s17, 0
	v_lshlrev_b32_e32 v1, 3, v154
	s_add_u32 s12, s18, 0xf846000
	v_lshl_add_u32 v0, s2, 12, v0
	s_movk_i32 s0, 0x78
	s_addc_u32 s13, s19, 0
	s_lshl_b32 s3, s88, 5
	v_and_or_b32 v8, v1, s0, v0
	s_lshl_b32 s22, s88, 12
	s_mov_b64 s[14:15], 0
	s_mov_b32 s23, 0x2aaaaaab
	s_movk_i32 s24, 0xffe8
	s_movk_i32 s25, 0xf400
	s_movk_i32 s26, 0x3000
	v_mov_b64_e32 v[10:11], s[10:11]
	s_mov_b64 s[16:17], 0x3000
	s_mov_b64 s[18:19], 0x6000
	s_movk_i32 s27, 0x6000
	s_mov_b64 s[20:21], 0x9000
	s_mov_b32 s28, 0x9000
	s_movk_i32 s29, 0xbff
	v_mov_b32_e32 v7, 0x3db504f3
	s_branch .LBB0_771

; #define LAS __attribute__((address_space(3)))
; __device__ __forceinline__ float bf2f(unsigned short b) { return __uint_as_float((unsigned)b << 16); }
; __device__ __forceinline__ void scan_load(ScanFrag& f, int n, int b, int h, int ti, int s, int li, int lq, int ucol, const bf16* Qg, const bf16* Kg, const bf16* Vg, const bf16* KT, const bf16* QK, const float* GC) {
;     const int gcid = b * 32 + n, m0 = b * 2048 + n * 64;
;     const bf16* wrow = Kg + (size_t)(m0 + 16 * ti + li) * D + h * 128 + 8 * lq; const bf16* qrow = Qg + (size_t)(m0 + 16 * ti + li) * D + h * 128 + 8 * lq;
; #pragma unroll
;     for (int ks = 0; ks < 4; ++ks) { f.wA[ks] = *(const bf16x8*)(wrow + 32 * ks); f.qA[ks] = *(const bf16x8*)(qrow + 32 * ks); }
;     const bf16* qkrow = QK + ((size_t)(gcid * 8 + h) * 64 + 16 * ti + li) * 64 + 8 * lq; const bf16* ktrow = KT + ((size_t)(gcid * 8 + h) * 128 + 16 * s + li) * 64 + 8 * lq;
; #pragma unroll
;     for (int k2 = 0; k2 < 2; ++k2) { f.qkA[k2] = *(const bf16x8*)(qkrow + 32 * k2); f.kA[k2] = *(const bf16x8*)(ktrow + 32 * k2); }
;     const int rowb = m0 + 16 * ti + 4 * lq;
; #pragma unroll
;     for (int r = 0; r < 4; ++r) { f.uval[r] = bf2f(Vg[(size_t)(rowb + r) * D + ucol]); f.gcr[r] = GC[(size_t)(rowb + r) * 8 + h]; }
;     f.gl = GC[(size_t)(m0 + 63) * 8 + h];
; }
; __device__ __forceinline__ void scan_unit(LAS unsigned char* lds, int uidx, const bf16* Qg, const bf16* Kg, bf16* Vg, const bf16* KT, const bf16* QK, const float* GC, float* SSQ, float* sp_gdn) {
;     const int tid = threadIdx.x, lane = tid & 63, s = __builtin_amdgcn_readfirstlane(tid >> 6);
;     const int xc = uidx & 7, yy = uidx >> 3, slab = yy & 3, bh = xc * 8 + (yy >> 2), b = bh >> 3, h = bh & 7;
;     LAS bf16* St = (LAS bf16*)lds; LAS bf16* Vt = St + 2 * 32 * 136; LAS bf16* Vts = Vt + 32 * 72;
;     const int ti = s >> 1, c = s & 1, li = lane & 15, lq = lane >> 4;
;     f32x4 S0 = (f32x4){0.f, 0.f, 0.f, 0.f}, S1 = S0;
;     const int ucol = h * 128 + slab * 32 + 16 * c + li;
;     ScanFrag cur, nxt;
;     scan_load(cur, 0, b, h, ti, s, li, lq, ucol, Qg, Kg, Vg, KT, QK, GC);
.LBB0_832:
	s_mov_b64 s[0:1], s[56:57]
	s_mov_b64 s[0:1], s[86:87]
	s_nop 4
	s_mov_b64 s[6:7], s[56:57]
	s_mov_b64 s[6:7], s[86:87]
	s_nop 4
	s_mov_b64 s[14:15], s[56:57]
	s_waitcnt lgkmcnt(0)
	s_add_u32 s18, s0, 0x4bb0000
	s_addc_u32 s19, s1, 0
	s_mov_b64 s[0:1], s[56:57]
	s_add_u32 s22, s6, 0x6c30000
	s_mov_b64 s[20:21], s[86:87]
	s_nop 4
	s_addc_u32 s23, s7, 0
	s_mov_b64 s[0:1], s[86:87]
	s_nop 4
	s_mov_b64 s[6:7], s[56:57]
	s_mov_b64 s[6:7], s[86:87]
	s_nop 4
	s_mov_b64 s[14:15], s[56:57]
	s_mov_b64 s[24:25], s[86:87]
	s_nop 4
	s_waitcnt lgkmcnt(0)
	s_add_u32 s28, s0, 0xad30000
	s_addc_u32 s29, s1, 0
	s_add_u32 s30, s6, 0xcdb0000
	s_addc_u32 s31, s7, 0
	s_add_u32 s39, s24, 0xef34000
	s_mov_b64 s[0:1], s[56:57]
	s_addc_u32 s42, s25, 0
	s_lshl_b32 s6, s36, 3
	s_ashr_i32 s7, s36, 5
	s_mov_b64 s[26:27], s[86:87]
	s_nop 4
	v_readfirstlane_b32 s0, v154
	s_bfe_u32 s1, s36, 0x20003
	s_and_b32 s6, s6, 56
	s_and_b32 s38, s7, 7
	s_add_i32 s6, s6, s7
	s_bfe_u32 s17, s0, 0x10006
	s_lshl_b32 s7, s38, 7
	s_lshl_b32 s37, s1, 5
	s_lshr_b32 s40, s0, 6
	s_ashr_i32 s34, s6, 3
	v_lshl_or_b32 v34, s17, 4, v156
	s_or_b32 s7, s7, s37
	s_lshr_b32 s0, s0, 3
	v_or_b32_e32 v4, s7, v34
	s_lshl_b32 s16, s34, 11
	s_and_b32 s7, s0, 0x1ffffff0
	s_add_i32 s0, s7, s16
	v_or_b32_e32 v76, s0, v70
	v_lshlrev_b32_e32 v68, 1, v4
	v_or_b32_e32 v6, 1, v76
	v_lshl_add_u64 v[4:5], s[20:21], 0, v[68:69]
	v_ashrrev_i32_e32 v77, 31, v76
	v_ashrrev_i32_e32 v7, 31, v6
	v_or_b32_e32 v0, s0, v156
	v_lshl_add_u64 v[74:75], v[4:5], 0, s[10:11]
	v_lshlrev_b64 v[4:5], 11, v[76:77]
	v_lshlrev_b64 v[8:9], 11, v[6:7]
	s_lshl_b32 s20, s34, 8
	s_mov_b64 s[14:15], s[56:57]
	v_ashrrev_i32_e32 v1, 31, v0
	v_lshl_add_u64 v[4:5], v[74:75], 0, v[4:5]
	v_lshl_add_u64 v[8:9], v[74:75], 0, v[8:9]
	s_or_b32 s34, s20, s38
	v_lshlrev_b64 v[0:1], 11, v[0:1]
	v_or_b32_e32 v4, 2, v76
	v_or_b32_e32 v32, 3, v76
	s_ashr_i32 s35, s34, 31
	v_lshl_add_u64 v[2:3], s[22:23], 0, v[0:1]
	s_lshl_b32 s8, s38, 8
	v_lshl_add_u64 v[0:1], s[18:19], 0, v[0:1]
	v_ashrrev_i32_e32 v5, 31, v4
	v_ashrrev_i32_e32 v33, 31, v32
	s_lshl_b64 s[20:21], s[34:35], 6
	v_lshl_add_u64 v[0:1], v[0:1], 0, s[8:9]
	v_lshlrev_b64 v[8:9], 11, v[4:5]
	v_lshlrev_b64 v[10:11], 11, v[32:33]
	s_add_u32 s20, s20, s7
	v_lshl_add_u64 v[2:3], v[2:3], 0, s[8:9]
	v_lshl_add_u64 v[0:1], v[0:1], 0, v[72:73]
	v_lshl_add_u64 v[8:9], v[74:75], 0, v[8:9]
	v_lshl_add_u64 v[10:11], v[74:75], 0, v[10:11]
	s_addc_u32 s21, s21, 0
	v_lshl_add_u64 v[2:3], v[2:3], 0, v[72:73]
	v_mov_b32_e32 v1, s21
	v_or_b32_e32 v0, s20, v156
	s_lshl_b64 s[20:21], s[34:35], 7
	s_lshl_b32 s35, s40, 4
	s_add_u32 s20, s20, s35
	s_addc_u32 s21, s21, 0
	v_lshlrev_b64 v[0:1], 7, v[0:1]
	v_mov_b32_e32 v3, s21
	v_or_b32_e32 v2, s20, v156
	v_lshl_add_u64 v[0:1], s[30:31], 0, v[0:1]
	v_lshlrev_b64 v[2:3], 7, v[2:3]
	s_lshl_b32 s43, s38, 2
	v_lshl_add_u64 v[0:1], v[0:1], 0, v[72:73]
	v_lshl_add_u64 v[2:3], s[28:29], 0, v[2:3]
	s_add_u32 s20, s39, s43
	v_lshl_add_u64 v[2:3], v[2:3], 0, v[72:73]
	s_addc_u32 s21, s42, 0
	v_lshlrev_b64 v[0:1], 5, v[76:77]
	v_lshl_add_u64 v[0:1], s[20:21], 0, v[0:1]
	v_lshlrev_b64 v[0:1], 5, v[6:7]
	v_lshl_add_u64 v[0:1], s[20:21], 0, v[0:1]
	v_lshlrev_b64 v[0:1], 5, v[4:5]
	s_or_b32 s40, s16, 63
	v_lshl_add_u64 v[0:1], s[20:21], 0, v[0:1]
	s_ashr_i32 s41, s40, 31
	v_lshlrev_b64 v[0:1], 5, v[32:33]
	s_lshl_b64 s[40:41], s[40:41], 5
	v_lshl_add_u64 v[0:1], s[20:21], 0, v[0:1]
	s_add_u32 s40, s39, s40
	s_addc_u32 s41, s42, s41
	v_mov_b32_e32 v2, s43
	s_add_u32 s22, s22, s8
	s_addc_u32 s23, s23, 0
	v_mul_u32_u24_e32 v32, 0x48, v34
	s_add_u32 s18, s18, s8
	v_lshlrev_b32_e32 v32, 1, v32
	s_addc_u32 s19, s19, 0
	s_lshl_b32 s8, s7, 1
	v_add_u32_e32 v106, 0, v32
	v_add3_u32 v101, v106, s8, v98
	v_add3_u32 v100, v92, s8, v32
	s_lshl_b32 s8, s38, 5
	s_waitcnt lgkmcnt(0)
; #define LAS __attribute__((address_space(3)))
; __device__ __forceinline__ float bf2f(unsigned short b) { return __uint_as_float((unsigned)b << 16); }
; __device__ __forceinline__ void scan_load(ScanFrag& f, int n, int b, int h, int ti, int s, int li, int lq, int ucol, const bf16* Qg, const bf16* Kg, const bf16* Vg, const bf16* KT, const bf16* QK, const float* GC) {
;     const int gcid = b * 32 + n, m0 = b * 2048 + n * 64;
;     const bf16* wrow = Kg + (size_t)(m0 + 16 * ti + li) * D + h * 128 + 8 * lq; const bf16* qrow = Qg + (size_t)(m0 + 16 * ti + li) * D + h * 128 + 8 * lq;
; #pragma unroll
;     for (int ks = 0; ks < 4; ++ks) { f.wA[ks] = *(const bf16x8*)(wrow + 32 * ks); f.qA[ks] = *(const bf16x8*)(qrow + 32 * ks); }
;     const bf16* qkrow = QK + ((size_t)(gcid * 8 + h) * 64 + 16 * ti + li) * 64 + 8 * lq; const bf16* ktrow = KT + ((size_t)(gcid * 8 + h) * 128 + 16 * s + li) * 64 + 8 * lq;
; #pragma unroll
;     for (int k2 = 0; k2 < 2; ++k2) { f.qkA[k2] = *(const bf16x8*)(qkrow + 32 * k2); f.kA[k2] = *(const bf16x8*)(ktrow + 32 * k2); }
;     const int rowb = m0 + 16 * ti + 4 * lq;
; #pragma unroll
;     for (int r = 0; r < 4; ++r) { f.uval[r] = bf2f(Vg[(size_t)(rowb + r) * D + ucol]); f.gcr[r] = GC[(size_t)(rowb + r) * 8 + h]; }
;     f.gl = GC[(size_t)(m0 + 63) * 8 + h];
; }
; __device__ __forceinline__ void scan_unit(LAS unsigned char* lds, int uidx, const bf16* Qg, const bf16* Kg, bf16* Vg, const bf16* KT, const bf16* QK, const float* GC, float* SSQ, float* sp_gdn) {
;     const int tid = threadIdx.x, lane = tid & 63, s = __builtin_amdgcn_readfirstlane(tid >> 6);
;     const int xc = uidx & 7, yy = uidx >> 3, slab = yy & 3, bh = xc * 8 + (yy >> 2), b = bh >> 3, h = bh & 7;
;     LAS bf16* St = (LAS bf16*)lds; LAS bf16* Vt = St + 2 * 32 * 136; LAS bf16* Vts = Vt + 32 * 72;
;     const int ti = s >> 1, c = s & 1, li = lane & 15, lq = lane >> 4;
;     f32x4 S0 = (f32x4){0.f, 0.f, 0.f, 0.f}, S1 = S0;
;     const int ucol = h * 128 + slab * 32 + 16 * c + li;
;     ScanFrag cur, nxt;
;     scan_load(cur, 0, b, h, ti, s, li, lq, ucol, Qg, Kg, Vg, KT, QK, GC);
;     for (int n = 0; n < 32; ++n) {
;         const int m0 = b * 2048 + n * 64, rowb = m0 + 16 * ti + 4 * lq;
;         __builtin_amdgcn_sched_barrier(0);
;         if (n + 1 < 32) scan_load(nxt, n + 1, b, h, ti, s, li, lq, ucol, Qg, Kg, Vg, KT, QK, GC);
	s_add_u32 s8, s26, s8
	v_lshl_add_u64 v[80:81], s[18:19], 0, v[72:73]
	s_addc_u32 s18, s27, 0
	s_lshl_b32 s1, s1, 3
	s_add_u32 s1, s8, s1
	s_addc_u32 s8, s18, 0
	s_lshl_b32 s17, s17, 2
	s_add_u32 s1, s1, s17
	s_addc_u32 s8, s8, 0
	s_add_u32 s18, s1, 0xefb6000
	s_addc_u32 s19, s8, 0
	s_ashr_i32 s17, s16, 31
	s_lshl_b64 s[26:27], s[16:17], 5
	s_load_dwordx2 s[14:15], s[14:15], 0x100
	v_lshl_add_u64 v[78:79], s[22:23], 0, v[72:73]
	s_or_b32 s22, s34, 8
	s_or_b32 s1, s26, s43
	v_or_b32_e32 v0, s7, v156
	v_mov_b32_e32 v1, v71
	s_add_u32 s1, s24, s1
	v_lshl_add_u64 v[2:3], s[30:31], 0, v[72:73]
	v_or_b32_e32 v4, s35, v156
	v_mov_b32_e32 v5, v71
	v_lshlrev_b64 v[0:1], 7, v[0:1]
	s_addc_u32 s8, s25, s27
	v_lshl_add_u64 v[6:7], s[28:29], 0, v[72:73]
	v_lshl_add_u64 v[82:83], v[2:3], 0, v[0:1]
	v_lshlrev_b64 v[0:1], 7, v[4:5]
	s_add_u32 s24, s1, 0xef34fe0
	v_mul_u32_u24_e32 v105, 0x110, v34
	v_lshl_add_u64 v[84:85], v[6:7], 0, v[0:1]
	s_addc_u32 s25, s8, 0
	v_add_u32_e32 v107, s0, v97
	s_mov_b32 s8, 0
	s_mov_b32 s17, 0
	v_mov_b32_e32 v4, 0
	v_mov_b32_e32 v5, v69
	v_mov_b32_e32 v6, v69
	v_mov_b32_e32 v7, v69
	v_mov_b32_e32 v0, 0
	v_mov_b32_e32 v1, v69
	v_mov_b32_e32 v2, v69
	v_mov_b32_e32 v3, v69
	s_and_b32 s0, s36, 7
	s_bfe_u32 s1, s36, 0x30005
	s_bfe_u32 s22, s36, 0x20003
	s_lshl_b32 s38, s0, 22
	s_lshl_b32 s39, s1, 8
	s_add_u32 s38, s38, s39
	s_add_u32 s24, s86, 0x6c30000
	s_addc_u32 s25, s87, 0
	s_add_u32 s24, s24, s38
	s_addc_u32 s25, s25, 0
	s_add_u32 s26, s86, 0x4bb0000
	s_addc_u32 s27, s87, 0
	s_add_u32 s26, s26, s38
	s_addc_u32 s27, s27, 0
	s_lshl_b32 s39, s22, 6
	s_add_u32 s98, s86, 0x8cb0000
	s_addc_u32 s99, s87, 0
	s_add_u32 s98, s98, s38
	s_addc_u32 s99, s99, 0
	s_add_u32 s98, s98, s39
	s_addc_u32 s99, s99, 0
	s_lshl_b32 s39, s0, 8
	s_add_u32 s39, s39, s1
	s_lshl_b32 s40, s39, 14
	s_add_u32 s28, s86, 0xad30000
	s_addc_u32 s29, s87, 0
	s_add_u32 s28, s28, s40
	s_addc_u32 s29, s29, 0
	s_lshl_b32 s40, s39, 13
	s_add_u32 s30, s86, 0xcdb0000
	s_addc_u32 s31, s87, 0
	s_add_u32 s30, s30, s40
	s_addc_u32 s31, s31, 0
	s_lshl_b32 s40, s0, 16
	s_lshl_b32 s41, s1, 2
	s_add_u32 s40, s40, s41
	s_add_u32 s100, s86, 0xef34000
	s_addc_u32 s101, s87, 0
	s_add_u32 s100, s100, s40
	s_addc_u32 s101, s101, 0
	v_lshrrev_b32_e32 v176, 4, v154
	v_and_b32_e32 v177, 15, v154
	v_lshlrev_b32_e32 v177, 4, v177
	v_lshl_add_u32 v41, v176, 11, v177
	v_add_u32_e32 v42, 0x10000, v41
	v_mul_u32_u24_e32 v47, 0x110, v176
	v_add_u32_e32 v47, v47, v177
	v_add_u32_e32 v47, 0x6800, v47
	v_lshlrev_b32_e32 v43, 4, v154
	v_add_u32_e32 v44, 0x2000, v43
	v_lshrrev_b32_e32 v176, 3, v154
	v_and_b32_e32 v177, 7, v154
	v_lshlrev_b32_e32 v177, 4, v177
	v_mul_u32_u24_e32 v48, 0x90, v176
	v_add_u32_e32 v48, v48, v177
	v_add_u32_e32 v48, 0xf000, v48
	v_add_u32_e32 v47, 0x4800, v48
	v_and_b32_e32 v176, 0x7f, v154
	v_lshrrev_b32_e32 v177, 7, v154
	v_lshlrev_b32_e32 v177, 4, v177
	v_mul_u32_u24_e32 v48, 0x90, v176
	v_add_u32_e32 v48, v48, v177
	v_add_u32_e32 v48, 0xf000, v48
	v_bfe_u32 v176, v154, 2, 6
	v_and_b32_e32 v177, 3, v154
	v_lshlrev_b32_e32 v177, 4, v177
	v_lshl_add_u32 v45, v176, 11, v177
	v_mul_u32_u24_e32 v49, 0x50, v176
	v_add_u32_e32 v49, v49, v177
	v_add_u32_e32 v49, 0x15c00, v49
	v_and_b32_e32 v176, 63, v154
	v_lshlrev_b32_e32 v46, 5, v176
	v_lshlrev_b32_e32 v50, 2, v176
	v_add_u32_e32 v50, 0x17000, v50
	v_lshrrev_b32_e32 v176, 7, v154
	v_and_b32_e32 v177, 15, v154
	v_lshl_add_u32 v176, v176, 4, v177
	v_bfe_u32 v178, v154, 4, 2
	v_lshlrev_b32_e32 v179, 4, v178
	v_mul_u32_u24_e32 v51, 0x110, v176
	v_add_u32_e32 v51, v51, v179
	v_add_u32_e32 v51, 0x6800, v51
	v_mul_u32_u24_e32 v52, 0x90, v176
	v_add_u32_e32 v52, v52, v179
	v_add_u32_e32 v52, 0x13800, v52
	v_lshrrev_b32_e32 v180, 6, v154
	v_lshl_add_u32 v180, v180, 4, v177
	v_mul_u32_u24_e32 v53, 0x90, v180
	v_add_u32_e32 v53, v53, v179
	v_add_u32_e32 v53, 0xf000, v53
	v_lshrrev_b32_e32 v180, 7, v154
	v_lshlrev_b32_e32 v180, 4, v180
	v_lshl_add_u32 v180, v178, 2, v180
	v_mul_u32_u24_e32 v54, 0x50, v180
	v_bfe_u32 v181, v154, 6, 1
	v_lshl_add_u32 v181, v181, 4, v177
	v_lshl_add_u32 v54, v181, 1, v54
	v_add_u32_e32 v54, 0x15c00, v54
	v_lshlrev_b32_e32 v55, 2, v180
	v_add_u32_e32 v55, 0x17000, v55
	v_mov_b32_e32 v174, 0x170fc
	v_lshrrev_b32_e32 v176, 7, v154
	v_bfe_u32 v178, v154, 4, 2
	v_lshl_add_u32 v176, v176, 4, v178
	v_and_b32_e32 v177, 15, v154
	v_lshlrev_b32_e32 v177, 4, v177
	v_lshl_add_u32 v236, v176, 11, v177
	v_add_u32_e32 v237, 0x2000, v236
	v_add_u32_e32 v238, 0x4000, v236
	v_add_u32_e32 v239, 0x6000, v236
	v_and_b32_e32 v241, 1, v156
	v_mov_b32_e32 v240, 0x5040100
	v_mov_b32_e32 v242, 0x3020706
	v_cmp_eq_u32_e64 s[96:97], 1, v241
	v_and_b32_e32 v241, 3, v156
	s_nop 0
	v_cndmask_b32_e64 v240, v240, v242, s[96:97]
	v_lshlrev_b32_e32 v242, 1, v241
	v_sub_co_u32_e64 v242, s[96:97], v74, v242
	s_nop 1
	v_subb_co_u32_e64 v243, s[96:97], v75, 0, s[96:97]
	global_load_dwordx4 v[8:11], v236, s[24:25]
	global_load_dwordx4 v[12:15], v237, s[24:25]
	global_load_dwordx4 v[16:19], v238, s[24:25]
	global_load_dwordx4 v[20:23], v239, s[24:25]
	global_load_dwordx4 v[130:133], v236, s[26:27]
	global_load_dwordx4 v[134:137], v237, s[26:27]
	global_load_dwordx4 v[138:141], v238, s[26:27]
	global_load_dwordx4 v[142:145], v239, s[26:27]
	s_add_u32 s24, s24, 0x20000
	s_addc_u32 s25, s25, 0
	s_add_u32 s26, s26, 0x20000
	s_addc_u32 s27, s27, 0
	global_load_dwordx4 v[24:27], v43, s[28:29]
	global_load_dwordx4 v[28:31], v44, s[28:29]
	global_load_dwordx4 v[32:35], v43, s[30:31]
	s_cmp_gt_u32 s95, 3
	s_cbranch_scc1 .Lscan_sl1u
	global_load_dwordx4 v[36:39], v45, s[98:99]

; #define LAS __attribute__((address_space(3)))
; #define LDS_BARRIER() do { asm volatile("s_waitcnt lgkmcnt(0)" ::: "memory"); __builtin_amdgcn_s_barrier(); asm volatile("" ::: "memory"); } while (0)
; __device__ __forceinline__ void gdn_sample_unit(LAS unsigned char* lds, int su, int su_next, f32x4 (&Spre)[8], const float* state, float* ss_gdn, const float* SQKV, const float* BETA, const float* GG, bf16* Vg, float* SSQ) {
;     const int tid = threadIdx.x, bs = su >> 3, h = su & 7, kq = tid >> 5, vq = tid & 31, m = MPROMPT + bs;
;     const float* Sin = state + (size_t)su * 16384; float* Sout = ss_gdn + (size_t)su * 16384;
;     f32x4 Sv[8];
; #pragma unroll
;     for (int i = 0; i < 8; ++i) Sv[i] = Spre[i];
;     if (su_next < 1024) {
; #pragma unroll
;         for (int i = 0; i < 8; ++i) Spre[i] = __builtin_nontemporal_load((const f32x4*)(state + (size_t)su_next * 16384 + (size_t)(8 * kq + i) * 128 + 4 * vq)); }
;     const float* qv = SQKV + (size_t)bs * 3072 + h * 128; const float* kv = qv + 1024; const float* vv = qv + 2048;
;     float kk[8], qq[8];
; #pragma unroll
;     for (int i = 0; i < 8; ++i) { kk[i] = kv[8 * kq + i]; qq[i] = qv[8 * kq + i]; }
;     const float a = expf(GG[(size_t)m * 8 + h]), be = BETA[(size_t)m * 8 + h];
;     f32x4 p = (f32x4){0.f, 0.f, 0.f, 0.f};
; #pragma unroll
;     for (int i = 0; i < 8; ++i) { Sv[i] = Sv[i] * a; p += Sv[i] * kk[i]; }
;     LAS f32x4* red = (LAS f32x4*)lds;
;     red[kq * 32 + vq] = p; LDS_BARRIER();
.LBB0_854:
	s_mov_b64 s[0:1], s[56:57]
	s_mov_b64 s[18:19], s[56:57]
	s_load_dwordx2 s[28:29], s[18:19], 0x100
	s_mov_b64 s[18:19], s[56:57]
	s_mov_b64 s[20:21], s[86:87]
	s_nop 4
	s_mov_b64 s[18:19], s[56:57]
	s_mov_b64 s[30:31], s[86:87]
	s_nop 4
	s_mov_b64 s[18:19], s[56:57]
	s_mov_b64 s[26:27], s[86:87]
	s_nop 4
	s_add_i32 s16, s24, s88
	s_cmpk_gt_i32 s16, 0x3ff
	s_cselect_b64 s[18:19], -1, 0
	s_mov_b64 s[22:23], s[56:57]
	s_mov_b64 s[36:37], s[56:57]
	s_and_b64 vcc, exec, s[18:19]
	s_waitcnt vmcnt(0)
	v_mov_b32_e32 v0, v32
	v_mov_b32_e32 v1, v33
	v_mov_b32_e32 v2, v34
	v_mov_b32_e32 v3, v35
	v_mov_b32_e32 v4, v36
	v_mov_b32_e32 v5, v37
	v_mov_b32_e32 v6, v38
	v_mov_b32_e32 v7, v39
	v_mov_b32_e32 v8, v40
	v_mov_b32_e32 v9, v41
	v_mov_b32_e32 v10, v42
	v_mov_b32_e32 v11, v43
	v_mov_b32_e32 v12, v44
	v_mov_b32_e32 v13, v45
	v_mov_b32_e32 v14, v46
	v_mov_b32_e32 v15, v47
	v_mov_b32_e32 v16, v48
	v_mov_b32_e32 v17, v49
	v_mov_b32_e32 v18, v50
	v_mov_b32_e32 v19, v51
	v_mov_b32_e32 v20, v52
	v_mov_b32_e32 v21, v53
	v_mov_b32_e32 v22, v54
	v_mov_b32_e32 v23, v55
	v_mov_b32_e32 v24, v56
	v_mov_b32_e32 v25, v57
	v_mov_b32_e32 v26, v58
	v_mov_b32_e32 v27, v59
	v_mov_b32_e32 v28, v60
	v_mov_b32_e32 v29, v61
	v_mov_b32_e32 v30, v62
	v_mov_b32_e32 v31, v63
	s_cbranch_vccnz .LBB0_856
	s_load_dwordx2 s[0:1], s[0:1], 0x20
	s_ashr_i32 s17, s16, 31
	s_lshl_b64 s[34:35], s[16:17], 16
	v_mov_b32_e32 v79, v73
	v_mov_b32_e32 v77, v73
	s_waitcnt lgkmcnt(0)
	s_add_u32 s0, s0, s34
	s_addc_u32 s1, s1, s35
	v_lshl_add_u64 v[0:1], s[0:1], 0, v[78:79]
	v_lshl_add_u64 v[64:65], v[0:1], 0, v[76:77]
	global_load_dwordx4 v[0:3], v[64:65], off nt
	global_load_dwordx4 v[4:7], v[64:65], off offset:512 nt
	global_load_dwordx4 v[8:11], v[64:65], off offset:1024 nt
	global_load_dwordx4 v[12:15], v[64:65], off offset:1536 nt
	global_load_dwordx4 v[16:19], v[64:65], off offset:2048 nt
	global_load_dwordx4 v[20:23], v[64:65], off offset:2560 nt
	global_load_dwordx4 v[24:27], v[64:65], off offset:3072 nt
	global_load_dwordx4 v[28:31], v[64:65], off offset:3584 nt
.LBB0_856:
	s_ashr_i32 s1, s24, 3
	s_and_b32 s0, s24, 7
	s_add_i32 s24, s1, 0x4000
	s_mul_hi_i32 s17, s1, 0x3000
	s_mulk_i32 s1, 0x3000
	s_waitcnt lgkmcnt(0)
	s_add_u32 s1, s20, s1
	s_addc_u32 s17, s21, s17
	s_lshl_b32 s20, s0, 9
	s_add_u32 s1, s1, s20
	s_addc_u32 s17, s17, 0
	s_add_u32 s34, s1, 0xf846000
	s_addc_u32 s35, s17, 0
	s_ashr_i32 s25, s24, 31
	s_lshl_b64 s[20:21], s[24:25], 3
	s_or_b32 s20, s20, s0
	s_lshl_b64 s[38:39], s[20:21], 2
	s_add_u32 s26, s26, s38
	s_addc_u32 s27, s27, s39
	global_load_dword v77, v86, s[26:27]
	v_lshl_add_u64 v[64:65], s[34:35], 0, v[72:73]
	v_lshl_add_u64 v[66:67], v[64:65], 0, s[14:15]
	v_add_co_u32_e32 v64, vcc, s3, v64
	v_mov_b32_e32 v79, v73
	s_nop 0
	v_addc_co_u32_e32 v65, vcc, 0, v65, vcc
	global_load_dwordx4 v[68:71], v[64:65], off
	s_nop 0
	global_load_dwordx4 v[64:67], v[66:67], off offset:16
	v_lshl_add_u64 v[98:99], s[34:35], 0, v[78:79]
	v_add_co_u32_e32 v98, vcc, s43, v98
	s_add_u32 s30, s30, s38
	s_nop 0
	v_addc_co_u32_e32 v99, vcc, 0, v99, vcc
	s_mov_b64 s[26:27], s[86:87]
	s_nop 4
	s_nop 0
	s_mov_b64 s[22:23], s[86:87]
	s_nop 4
	global_load_dwordx4 v[90:93], v72, s[34:35] offset:16
	global_load_dwordx4 v[94:97], v72, s[34:35]
	s_addc_u32 s31, s31, s39
	global_load_dword v134, v87, s[30:31]
	v_lshl_add_u64 v[178:179], s[28:29], 0, v[74:75]
	s_waitcnt vmcnt(5)
	v_mul_f32_e32 v79, 0x3fb8aa3b, v77
	v_fma_f32 v81, v77, s40, -v79
	v_rndne_f32_e32 v83, v79
	v_fmac_f32_e32 v81, 0x32a5705f, v77
	v_sub_f32_e32 v79, v79, v83
	v_add_f32_e32 v79, v79, v81
	v_cvt_i32_f32_e32 v83, v83
	v_exp_f32_e32 v79, v79
	v_cmp_ngt_f32_e32 vcc, s41, v77
	s_waitcnt vmcnt(4)
	v_mov_b32_e32 v136, v71
	s_waitcnt vmcnt(3)
	v_mov_b32_e32 v138, v67
	v_ldexp_f32 v79, v79, v83
	v_cndmask_b32_e32 v79, 0, v79, vcc
	v_cmp_nlt_f32_e32 vcc, s42, v77
	s_waitcnt vmcnt(2)
	v_mov_b32_e32 v182, v93
	v_cndmask_b32_e32 v100, v88, v79, vcc
	v_pk_mul_f32 v[140:141], v[34:35], v[100:101] op_sel_hi:[1,0]
	v_pk_mul_f32 v[142:143], v[32:33], v[100:101] op_sel_hi:[1,0]
	v_pk_mul_f32 v[144:145], v[36:37], v[100:101] op_sel_hi:[1,0]
	v_pk_mul_f32 v[146:147], v[38:39], v[100:101] op_sel_hi:[1,0]
	v_pk_fma_f32 v[32:33], v[68:69], v[142:143], 0 op_sel_hi:[0,1,0]
	v_pk_fma_f32 v[34:35], v[68:69], v[140:141], 0 op_sel_hi:[0,1,0]
	v_pk_mul_f32 v[148:149], v[42:43], v[100:101] op_sel_hi:[1,0]
	v_pk_mul_f32 v[150:151], v[40:41], v[100:101] op_sel_hi:[1,0]
	v_pk_fma_f32 v[34:35], v[68:69], v[146:147], v[34:35] op_sel:[1,0,0]
	v_pk_fma_f32 v[32:33], v[68:69], v[144:145], v[32:33] op_sel:[1,0,0]
	v_pk_mul_f32 v[158:159], v[44:45], v[100:101] op_sel_hi:[1,0]
	v_pk_mul_f32 v[160:161], v[46:47], v[100:101] op_sel_hi:[1,0]
	v_pk_fma_f32 v[32:33], v[70:71], v[150:151], v[32:33] op_sel_hi:[0,1,1]
	v_pk_fma_f32 v[34:35], v[70:71], v[148:149], v[34:35] op_sel_hi:[0,1,1]
	v_pk_mul_f32 v[162:163], v[50:51], v[100:101] op_sel_hi:[1,0]
	v_pk_mul_f32 v[164:165], v[48:49], v[100:101] op_sel_hi:[1,0]
	v_pk_fma_f32 v[34:35], v[136:137], v[160:161], v[34:35] op_sel_hi:[0,1,1]
	v_pk_fma_f32 v[32:33], v[136:137], v[158:159], v[32:33] op_sel_hi:[0,1,1]
	v_pk_mul_f32 v[166:167], v[52:53], v[100:101] op_sel_hi:[1,0]
	v_pk_mul_f32 v[168:169], v[54:55], v[100:101] op_sel_hi:[1,0]
	v_pk_fma_f32 v[32:33], v[64:65], v[164:165], v[32:33] op_sel_hi:[0,1,1]
	v_pk_fma_f32 v[34:35], v[64:65], v[162:163], v[34:35] op_sel_hi:[0,1,1]
	v_pk_mul_f32 v[170:171], v[58:59], v[100:101] op_sel_hi:[1,0]
	v_pk_mul_f32 v[172:173], v[56:57], v[100:101] op_sel_hi:[1,0]
	v_pk_fma_f32 v[34:35], v[64:65], v[168:169], v[34:35] op_sel:[1,0,0]
	v_pk_fma_f32 v[32:33], v[64:65], v[166:167], v[32:33] op_sel:[1,0,0]
	v_pk_mul_f32 v[174:175], v[60:61], v[100:101] op_sel_hi:[1,0]
	v_pk_mul_f32 v[176:177], v[62:63], v[100:101] op_sel_hi:[1,0]
	v_pk_fma_f32 v[32:33], v[66:67], v[172:173], v[32:33] op_sel_hi:[0,1,1]
	v_pk_fma_f32 v[34:35], v[66:67], v[170:171], v[34:35] op_sel_hi:[0,1,1]
	v_pk_fma_f32 v[34:35], v[138:139], v[176:177], v[34:35] op_sel_hi:[0,1,1]
	v_pk_fma_f32 v[32:33], v[138:139], v[174:175], v[32:33] op_sel_hi:[0,1,1]
	ds_write_b128 v84, v[32:35]
	s_waitcnt lgkmcnt(0)
	s_barrier
; #define LDS_BARRIER() do { asm volatile("s_waitcnt lgkmcnt(0)" ::: "memory"); __builtin_amdgcn_s_barrier(); asm volatile("" ::: "memory"); } while (0)
; __device__ __forceinline__ void gdn_sample_unit(LAS unsigned char* lds, int su, int su_next, f32x4 (&Spre)[8], const float* state, float* ss_gdn, const float* SQKV, const float* BETA, const float* GG, bf16* Vg, float* SSQ) {
;     ...
;     f32x4 kvs = (f32x4){0.f, 0.f, 0.f, 0.f};
; #pragma unroll
;     for (int g = 0; g < 16; ++g) kvs += red[g * 32 + vq];
;     const f32x4 dd = (*(const f32x4*)(vv + 4 * vq) - kvs) * be;
;     f32x4 po = (f32x4){0.f, 0.f, 0.f, 0.f};
; #pragma unroll
;     for (int i = 0; i < 8; ++i) { Sv[i] += dd * kk[i]; po += Sv[i] * qq[i]; __builtin_nontemporal_store(Sv[i], (f32x4*)(Sout + (size_t)(8 * kq + i) * 128 + 4 * vq)); }
;     LDS_BARRIER();
	global_load_dwordx4 v[32:35], v[98:99], off
	ds_read_b128 v[36:39], v85
	ds_read_b128 v[40:43], v85 offset:512
	ds_read_b128 v[44:47], v85 offset:1024
	ds_read_b128 v[48:51], v85 offset:1536
	ds_read_b128 v[52:55], v85 offset:2048
	ds_read_b128 v[56:59], v85 offset:2560
	ds_read_b128 v[60:63], v85 offset:3072
	ds_read_b128 v[98:101], v85 offset:3584
	ds_read_b128 v[102:105], v85 offset:4096
	ds_read_b128 v[106:109], v85 offset:4608
	ds_read_b128 v[110:113], v85 offset:5120
	ds_read_b128 v[114:117], v85 offset:5632
	ds_read_b128 v[118:121], v85 offset:6144
	ds_read_b128 v[122:125], v85 offset:6656
	ds_read_b128 v[126:129], v85 offset:7168
	ds_read_b128 v[130:133], v85 offset:7680
	s_waitcnt lgkmcnt(0)
	v_pk_add_f32 v[38:39], v[38:39], 0 op_sel_hi:[1,0]
	v_pk_add_f32 v[36:37], v[36:37], 0 op_sel_hi:[1,0]
	v_pk_add_f32 v[38:39], v[38:39], v[42:43]
	v_pk_add_f32 v[36:37], v[36:37], v[40:41]
	v_pk_add_f32 v[38:39], v[38:39], v[46:47]
	v_pk_add_f32 v[36:37], v[36:37], v[44:45]
	v_pk_add_f32 v[38:39], v[38:39], v[50:51]
	v_pk_add_f32 v[36:37], v[36:37], v[48:49]
	v_pk_add_f32 v[38:39], v[38:39], v[54:55]
	v_pk_add_f32 v[36:37], v[36:37], v[52:53]
	v_pk_add_f32 v[38:39], v[38:39], v[58:59]
	v_pk_add_f32 v[36:37], v[36:37], v[56:57]
	v_pk_add_f32 v[38:39], v[38:39], v[62:63]
	v_pk_add_f32 v[36:37], v[36:37], v[60:61]
	v_pk_add_f32 v[38:39], v[38:39], v[100:101]
	v_pk_add_f32 v[36:37], v[36:37], v[98:99]
	v_pk_add_f32 v[38:39], v[38:39], v[104:105]
	v_pk_add_f32 v[36:37], v[36:37], v[102:103]
	v_pk_add_f32 v[38:39], v[38:39], v[108:109]
	v_pk_add_f32 v[36:37], v[36:37], v[106:107]
	v_pk_add_f32 v[38:39], v[38:39], v[112:113]
	v_pk_add_f32 v[36:37], v[36:37], v[110:111]
	v_pk_add_f32 v[38:39], v[38:39], v[116:117]
	v_pk_add_f32 v[36:37], v[36:37], v[114:115]
	v_pk_add_f32 v[38:39], v[38:39], v[120:121]
	v_pk_add_f32 v[36:37], v[36:37], v[118:119]
	v_pk_add_f32 v[38:39], v[38:39], v[124:125]
	v_pk_add_f32 v[36:37], v[36:37], v[122:123]
	v_pk_add_f32 v[38:39], v[38:39], v[128:129]
	v_pk_add_f32 v[36:37], v[36:37], v[126:127]
	v_pk_add_f32 v[38:39], v[38:39], v[132:133]
	v_pk_add_f32 v[36:37], v[36:37], v[130:131]
	s_waitcnt vmcnt(2)
	v_mov_b32_e32 v180, v97
	s_waitcnt vmcnt(0)
	v_sub_f32_e32 v33, v33, v37
	v_sub_f32_e32 v32, v32, v36
	v_sub_f32_e32 v35, v35, v39
	v_sub_f32_e32 v34, v34, v38
	v_pk_mul_f32 v[62:63], v[134:135], v[34:35] op_sel_hi:[0,1]
	v_pk_mul_f32 v[60:61], v[134:135], v[32:33] op_sel_hi:[0,1]
	v_pk_fma_f32 v[32:33], v[68:69], v[60:61], v[142:143] op_sel_hi:[0,1,1]
	v_pk_fma_f32 v[34:35], v[68:69], v[62:63], v[140:141] op_sel_hi:[0,1,1]
	v_pk_fma_f32 v[36:37], v[68:69], v[60:61], v[144:145] op_sel:[1,0,0]
	v_pk_fma_f32 v[38:39], v[68:69], v[62:63], v[146:147] op_sel:[1,0,0]
	v_pk_fma_f32 v[48:49], v[64:65], v[60:61], v[164:165] op_sel_hi:[0,1,1]
	v_pk_fma_f32 v[50:51], v[64:65], v[62:63], v[162:163] op_sel_hi:[0,1,1]
	v_pk_fma_f32 v[52:53], v[64:65], v[60:61], v[166:167] op_sel:[1,0,0]
	v_pk_fma_f32 v[54:55], v[64:65], v[62:63], v[168:169] op_sel:[1,0,0]
	v_pk_fma_f32 v[56:57], v[66:67], v[60:61], v[172:173] op_sel_hi:[0,1,1]
	v_pk_fma_f32 v[58:59], v[66:67], v[62:63], v[170:171] op_sel_hi:[0,1,1]
	v_pk_fma_f32 v[64:65], v[94:95], v[34:35], 0 op_sel_hi:[0,1,0]
	v_pk_fma_f32 v[66:67], v[94:95], v[32:33], 0 op_sel_hi:[0,1,0]
	v_pk_fma_f32 v[40:41], v[70:71], v[60:61], v[150:151] op_sel_hi:[0,1,1]
	v_pk_fma_f32 v[42:43], v[70:71], v[62:63], v[148:149] op_sel_hi:[0,1,1]
	v_pk_fma_f32 v[44:45], v[136:137], v[60:61], v[158:159] op_sel_hi:[0,1,1]
	v_pk_fma_f32 v[46:47], v[136:137], v[62:63], v[160:161] op_sel_hi:[0,1,1]
	v_pk_fma_f32 v[60:61], v[138:139], v[60:61], v[174:175] op_sel_hi:[0,1,1]
	v_pk_fma_f32 v[62:63], v[138:139], v[62:63], v[176:177] op_sel_hi:[0,1,1]
	global_store_dwordx4 v[178:179], v[32:35], off offset:-3584 nt
	global_store_dwordx4 v[178:179], v[36:39], off offset:-3072 nt
	global_store_dwordx4 v[178:179], v[40:43], off offset:-2560 nt
	global_store_dwordx4 v[178:179], v[44:47], off offset:-2048 nt
	global_store_dwordx4 v[178:179], v[48:51], off offset:-1536 nt
	global_store_dwordx4 v[178:179], v[52:55], off offset:-1024 nt
	global_store_dwordx4 v[178:179], v[56:59], off offset:-512 nt
	global_store_dwordx4 v[178:179], v[60:63], off nt
	v_pk_fma_f32 v[32:33], v[94:95], v[36:37], v[66:67] op_sel:[1,0,0]
	v_pk_fma_f32 v[34:35], v[94:95], v[38:39], v[64:65] op_sel:[1,0,0]
	v_pk_fma_f32 v[32:33], v[96:97], v[40:41], v[32:33] op_sel_hi:[0,1,1]
	v_pk_fma_f32 v[34:35], v[96:97], v[42:43], v[34:35] op_sel_hi:[0,1,1]
	v_pk_fma_f32 v[32:33], v[180:181], v[44:45], v[32:33] op_sel_hi:[0,1,1]
	v_pk_fma_f32 v[34:35], v[180:181], v[46:47], v[34:35] op_sel_hi:[0,1,1]
	v_pk_fma_f32 v[34:35], v[90:91], v[50:51], v[34:35] op_sel_hi:[0,1,1]
	v_pk_fma_f32 v[32:33], v[90:91], v[48:49], v[32:33] op_sel_hi:[0,1,1]
	v_pk_fma_f32 v[32:33], v[90:91], v[52:53], v[32:33] op_sel:[1,0,0]
	v_pk_fma_f32 v[34:35], v[90:91], v[54:55], v[34:35] op_sel:[1,0,0]
	v_pk_fma_f32 v[32:33], v[92:93], v[56:57], v[32:33] op_sel_hi:[0,1,1]
	v_pk_fma_f32 v[34:35], v[92:93], v[58:59], v[34:35] op_sel_hi:[0,1,1]
	v_pk_fma_f32 v[32:33], v[182:183], v[60:61], v[32:33] op_sel_hi:[0,1,1]
	v_pk_fma_f32 v[34:35], v[182:183], v[62:63], v[34:35] op_sel_hi:[0,1,1]
	s_waitcnt lgkmcnt(0)
	s_barrier
; #define LDS_BARRIER() do { asm volatile("s_waitcnt lgkmcnt(0)" ::: "memory"); __builtin_amdgcn_s_barrier(); asm volatile("" ::: "memory"); } while (0)
; __device__ __forceinline__ void gdn_sample_unit(LAS unsigned char* lds, int su, int su_next, f32x4 (&Spre)[8], const float* state, float* ss_gdn, const float* SQKV, const float* BETA, const float* GG, bf16* Vg, float* SSQ) {
;     ...
;     red[kq * 32 + vq] = po; LDS_BARRIER();
;     if (tid < 64) {
;         float ssum = 0.f;
;         if (tid < 32) { f32x4 o = (f32x4){0.f, 0.f, 0.f, 0.f};
; #pragma unroll
;             for (int g = 0; g < 16; ++g) o += red[g * 32 + tid];
;             u32x2 w; w.x = cvt_pk_bf16(o[0], o[1]); w.y = cvt_pk_bf16(o[2], o[3]); *(u32x2*)(Vg + (size_t)m * D + h * 128 + 4 * tid) = w;
;             ssum = (o[0] * o[0] + o[1] * o[1]) + (o[2] * o[2] + o[3] * o[3]); }
;         ssum = wave_sum(ssum);
	ds_write_b128 v84, v[32:35]
	s_waitcnt lgkmcnt(0)
	s_barrier
	s_and_saveexec_b64 s[28:29], s[6:7]
	s_cbranch_execz .LBB0_853
	v_mov_b32_e32 v32, 0
	s_and_saveexec_b64 s[30:31], s[8:9]
	s_cbranch_execz .LBB0_859
	ds_read_b128 v[32:35], v84
	ds_read_b128 v[36:39], v84 offset:512
	ds_read_b128 v[40:43], v84 offset:1024
	s_lshl_b32 s17, s0, 7
	s_lshl_b64 s[0:1], s[24:25], 11
	s_waitcnt lgkmcnt(2)
	v_pk_add_f32 v[34:35], v[34:35], 0 op_sel_hi:[1,0]
	v_pk_add_f32 v[44:45], v[32:33], 0 op_sel_hi:[1,0]
	s_waitcnt lgkmcnt(1)
	v_pk_add_f32 v[38:39], v[34:35], v[38:39]
	ds_read_b128 v[32:35], v84 offset:1536
	v_pk_add_f32 v[44:45], v[44:45], v[36:37]
	s_waitcnt lgkmcnt(1)
	v_pk_add_f32 v[42:43], v[38:39], v[42:43]
	ds_read_b128 v[36:39], v84 offset:2048
	v_pk_add_f32 v[44:45], v[44:45], v[40:41]
	s_waitcnt lgkmcnt(1)
	v_pk_add_f32 v[34:35], v[42:43], v[34:35]
	ds_read_b128 v[40:43], v84 offset:2560
	v_pk_add_f32 v[44:45], v[44:45], v[32:33]
	s_waitcnt lgkmcnt(1)
	v_pk_add_f32 v[38:39], v[34:35], v[38:39]
	ds_read_b128 v[32:35], v84 offset:3072
	v_pk_add_f32 v[44:45], v[44:45], v[36:37]
	s_waitcnt lgkmcnt(1)
	v_pk_add_f32 v[42:43], v[38:39], v[42:43]
	ds_read_b128 v[36:39], v84 offset:3584
	v_pk_add_f32 v[44:45], v[44:45], v[40:41]
	s_waitcnt lgkmcnt(1)
	v_pk_add_f32 v[34:35], v[42:43], v[34:35]
	ds_read_b128 v[40:43], v84 offset:4096
	v_pk_add_f32 v[44:45], v[44:45], v[32:33]
	s_waitcnt lgkmcnt(1)
	v_pk_add_f32 v[38:39], v[34:35], v[38:39]
	ds_read_b128 v[32:35], v84 offset:4608
	v_pk_add_f32 v[44:45], v[44:45], v[36:37]
	s_waitcnt lgkmcnt(1)
	v_pk_add_f32 v[42:43], v[38:39], v[42:43]
	ds_read_b128 v[36:39], v84 offset:5120
	v_pk_add_f32 v[44:45], v[44:45], v[40:41]
	s_waitcnt lgkmcnt(1)
	v_pk_add_f32 v[34:35], v[42:43], v[34:35]
	ds_read_b128 v[40:43], v84 offset:5632
	v_pk_add_f32 v[44:45], v[44:45], v[32:33]
	s_waitcnt lgkmcnt(1)
	v_pk_add_f32 v[38:39], v[34:35], v[38:39]
	ds_read_b128 v[32:35], v84 offset:6144
	v_pk_add_f32 v[36:37], v[44:45], v[36:37]
	s_waitcnt lgkmcnt(1)
	v_pk_add_f32 v[42:43], v[38:39], v[42:43]
	v_pk_add_f32 v[44:45], v[36:37], v[40:41]
	ds_read_b128 v[36:39], v84 offset:6656
	s_waitcnt lgkmcnt(1)
	v_pk_add_f32 v[46:47], v[42:43], v[34:35]
	ds_read_b128 v[40:43], v84 offset:7168
	v_pk_add_f32 v[44:45], v[44:45], v[32:33]
	ds_read_b128 v[32:35], v84 offset:7680
	s_add_u32 s0, s26, s0
	s_addc_u32 s1, s27, s1
	s_lshl_b32 s17, s17, 1
	s_waitcnt lgkmcnt(2)
	v_pk_add_f32 v[38:39], v[46:47], v[38:39]
	s_add_u32 s0, s0, s17
	v_pk_add_f32 v[36:37], v[44:45], v[36:37]
	s_waitcnt lgkmcnt(1)
	v_pk_add_f32 v[38:39], v[38:39], v[42:43]
	s_addc_u32 s1, s1, 0
	v_mov_b32_e32 v81, v73
	v_pk_add_f32 v[36:37], v[36:37], v[40:41]
	s_waitcnt lgkmcnt(0)
	v_pk_add_f32 v[34:35], v[38:39], v[34:35]
	v_lshl_add_u64 v[38:39], s[0:1], 0, v[80:81]
	v_pk_add_f32 v[32:33], v[36:37], v[32:33]
	v_add_co_u32_e32 v38, vcc, 0x8cb0000, v38
	v_cvt_pk_bf16_f32 v36, v32, v33
	v_cvt_pk_bf16_f32 v37, v34, v35
	v_addc_co_u32_e32 v39, vcc, 0, v39, vcc
	v_pk_mul_f32 v[34:35], v[34:35], v[34:35]
	v_pk_mul_f32 v[32:33], v[32:33], v[32:33]
	global_store_dwordx2 v[38:39], v[36:37], off
	v_pk_mov_b32 v[36:37], v[32:33], v[34:35] op_sel:[1,0]
	v_mov_b32_e32 v33, v35
	v_pk_add_f32 v[32:33], v[36:37], v[32:33]
	s_nop 0
	v_add_f32_e32 v32, v32, v33

; #define LAS __attribute__((address_space(3)))
; __device__ __forceinline__ const float* arg_in(int k) { return (const float*)(const __attribute__((address_space(1))) float*)arg_q(k); }
; template <class RowMap, class EpiT>
; __device__ __forceinline__ void sgemm128_phase(LAS unsigned char* lds, const bf16* A, const bf16* Bt, int ntile, int K, const RowMap& RM, const EpiT& E, int bidx, int nb) {
;     const int tid = threadIdx.x, lane = tid & 63, wave = __builtin_amdgcn_readfirstlane(tid >> 6), li = lane & 15, lq = lane >> 4;
;     const int kper = K >> 3;
;     LAS float* red = (LAS float*)lds; LAS float* tile = red + 8 * 2048;
;     for (int ct = bidx; ct < ntile; ct += nb) {
;         const bf16* bp = Bt + (size_t)RM(ct, li) * K + wave * kper + 8 * lq; const bf16* ap = A + (size_t)li * K + wave * kper + 8 * lq;
;         f32x4 acc[8];
; #pragma unroll
;         for (int mt = 0; mt < 8; ++mt) acc[mt] = (f32x4){0.f, 0.f, 0.f, 0.f};
; #pragma unroll 2
;         for (int k = 0; k < kper; k += 32) { const bf16x8 bfr = *(const bf16x8*)(bp + k);
; #pragma unroll
;             for (int mt = 0; mt < 8; ++mt) acc[mt] = __builtin_amdgcn_mfma_f32_16x16x32_bf16(*(const bf16x8*)(ap + (size_t)mt * 16 * K + k), bfr, acc[mt], 0, 0, 0); }
; __global__ void __launch_bounds__(NWAVES * 64, 2) mega_fwd(Args args) {
;     ...
;     if (IN(7)) { EpiB E{R0, SSQ, arg_in(16), out + O_SPC, out + O_SSC}; { SPartB ES{R0 + SOFF, SSQ + (size_t)MPROMPT * 64, arg_in(16), out + O_SSC}; RMPartB RM; sgemm128_phase(lds, XB + SOFF, WINB, 384, 1024, RM, ES, (int)blockIdx.x, G); }
.LBB0_915:
	s_cmp_lt_i32 s64, 8
	s_cselect_b64 s[0:1], -1, 0
	s_and_b64 s[4:5], s[0:1], s[6:7]
	s_mov_b64 s[96:97], s[80:81]
	s_andn2_b64 vcc, exec, s[4:5]
	s_cbranch_vccnz .LBB0_1064
	s_mov_b64 s[0:1], s[56:57]
	s_mov_b64 s[30:31], s[86:87]
	s_nop 4
	s_mov_b64 s[0:1], s[56:57]
	s_mov_b64 s[18:19], s[86:87]
	s_nop 4
	s_mov_b64 s[0:1], s[56:57]
	s_load_dwordx2 s[34:35], s[0:1], 0x80
	s_mov_b64 s[0:1], s[56:57]
	s_load_dwordx2 s[20:21], s[0:1], 0x100
	s_mov_b64 s[0:1], s[56:57]
	s_load_dwordx2 s[22:23], s[0:1], 0x100
	s_mov_b64 s[0:1], s[56:57]
	s_mov_b64 s[8:9], s[56:57]
	s_mov_b64 s[10:11], s[56:57]
	s_mov_b64 s[14:15], s[56:57]
	s_mov_b64 s[16:17], s[56:57]
	s_mov_b64 s[6:7], s[56:57]
	s_cmpk_gt_i32 s2, 0x17f
	v_readfirstlane_b32 s24, v154
	s_cbranch_scc1 .LBB0_969
	s_mov_b64 s[26:27], s[86:87]
	s_nop 4
	s_mov_b64 s[28:29], s[86:87]
	s_nop 4
	s_load_dwordx2 s[12:13], s[10:11], 0x80
	s_load_dwordx2 s[36:37], s[14:15], 0x100
	s_nop 0
	s_mov_b64 s[8:9], s[86:87]
	s_nop 4
	s_waitcnt lgkmcnt(0)
	s_add_u32 s14, s26, 0x6bb0000
	s_addc_u32 s15, s27, 0
	s_add_u32 s3, s28, 0xf3b6000
	s_addc_u32 s40, s29, 0
	s_add_u32 s0, s36, 0x8958000
	s_addc_u32 s1, s37, 0
	s_lshr_b32 s16, s24, 6
	s_lshl_b32 s24, s16, 7
	s_lshl_b32 s16, s16, 13
	v_lshlrev_b32_e32 v0, 2, v156
	s_add_i32 s16, s16, 0
	v_add_u32_e32 v10, s16, v0
	s_add_i32 s16, 0, 0x10000
	v_add_u32_e32 v11, s16, v0
	v_lshlrev_b32_e32 v0, 2, v154
	s_mov_b64 s[10:11], s[86:87]
	s_nop 4
	v_add_u32_e32 v67, 0, v0
	v_add_u32_e32 v68, s16, v0
	v_add_u32_e32 v0, 0x200, v154
	v_lshrrev_b32_e32 v1, 4, v154
	v_or_b32_e32 v2, 0x400, v154
	v_add_u32_e32 v4, 0x600, v154
	v_mov_b32_e32 v35, 0
	v_lshrrev_b32_e32 v3, 4, v0
	v_lshl_add_u32 v69, v0, 2, s16
	v_lshl_add_u32 v70, v2, 2, s16
	v_lshl_add_u32 v71, v4, 2, s16
	v_lshlrev_b32_e32 v12, 6, v1
	v_lshlrev_b32_e32 v32, 11, v1
	v_lshlrev_b32_e32 v34, 13, v1
	v_lshlrev_b32_e32 v36, 8, v1
	v_lshlrev_b32_e32 v0, 13, v3
	v_mov_b32_e32 v1, v35
	v_lshrrev_b32_e32 v5, 4, v2
	s_add_u32 s16, s26, 0xacb0000
	v_bfe_u32 v8, v154, 4, 2
	v_lshlrev_b32_e32 v13, 6, v3
	v_lshlrev_b32_e32 v38, 11, v3
	v_lshlrev_b32_e32 v40, 8, v3
	v_lshlrev_b32_e32 v2, 13, v5
	v_mov_b32_e32 v3, v35
	v_lshrrev_b32_e32 v6, 4, v4
	s_addc_u32 s17, s27, 0
	s_mov_b64 s[26:27], 0x1000
	v_lshl_add_u64 v[0:1], s[0:1], 0, v[0:1]
	v_lshlrev_b32_e32 v14, 6, v5
	v_lshlrev_b32_e32 v42, 11, v5
	v_lshlrev_b32_e32 v44, 8, v5
	v_lshlrev_b32_e32 v15, 6, v6
	v_lshlrev_b32_e32 v46, 11, v6
	v_lshlrev_b32_e32 v4, 13, v6
	v_mov_b32_e32 v5, v35
	v_lshlrev_b32_e32 v48, 8, v6
	v_lshl_add_u64 v[6:7], s[0:1], 0, v[34:35]
	v_lshl_add_u64 v[52:53], v[0:1], 0, s[26:27]
	v_lshl_add_u64 v[0:1], s[0:1], 0, v[2:3]
	v_lshlrev_b32_e32 v34, 4, v8
	s_mov_b32 s25, 0
	v_lshlrev_b32_e32 v9, 8, v8
	v_lshl_add_u64 v[54:55], v[0:1], 0, s[26:27]
	v_lshl_add_u64 v[0:1], s[0:1], 0, v[4:5]
	s_waitcnt lgkmcnt(0)
	v_lshl_add_u64 v[58:59], s[10:11], 0, v[34:35]
	v_lshl_or_b32 v34, v156, 11, v34
	v_cmp_gt_u32_e64 s[6:7], 8, v156
	v_add_u32_e32 v66, 0x78, v156
	v_mov_b32_e32 v33, v35
	v_mov_b32_e32 v37, v35
	v_mov_b32_e32 v39, v35
	v_mov_b32_e32 v41, v35
	v_mov_b32_e32 v43, v35
	v_mov_b32_e32 v45, v35
	v_mov_b32_e32 v47, v35
	v_mov_b32_e32 v49, v35
	v_lshl_add_u64 v[50:51], v[6:7], 0, s[26:27]
	v_lshl_add_u64 v[56:57], v[0:1], 0, s[26:27]
	s_lshl_b64 s[24:25], s[24:25], 1
	v_lshl_add_u64 v[60:61], s[8:9], 0, v[34:35]
	s_mov_b32 s41, 0x16a0000
	s_mov_b32 s42, 0x4b30000
	s_mov_b32 s43, 0x4b38000
	s_mov_b32 s44, 0x4b40000
	s_mov_b32 s45, 0x4b48000
	s_mov_b32 s46, 0x4b50000
	s_mov_b32 s47, 0x4b58000
	s_mov_b32 s48, 0x4b60000
	s_mov_b32 s49, 0x4b68000
	s_mov_b64 s[26:27], 0x80
	v_add_u32_e32 v72, v10, v9
	v_mov_b32_e32 v73, 0x358637bd
	v_mov_b32_e32 v74, 0xc0
	v_add_u32_e32 v75, v11, v12
	v_mov_b32_e32 v76, 0x7f
	v_add_u32_e32 v77, v11, v13
	v_add_u32_e32 v78, v11, v14
	v_add_u32_e32 v79, v11, v15
	s_mov_b32 s50, s2
	s_branch .LBB0_919

; #define PG8_STAGE(bufoff, gbase, voff) do { _Pragma("unroll") for (int _i = 0; _i < 2; ++_i) \
;         __builtin_amdgcn_global_load_lds((const unsigned*)((const char*)(gbase) + (voff)[_i]), (PG8_LAS unsigned*)(lds + (bufoff) + ldsw + _i * 8192), 16, 0, 0); } while (0)
; #define PG8_WAIT_V(n) asm volatile("s_waitcnt vmcnt(" #n ")" ::: "memory")
; #define PG8_BAR __builtin_amdgcn_s_barrier()
; #define GEMM(EpiT, E, Aop, Bop, M_, N_, K_) do { int k_ = K_; asm volatile("" : "+s"(k_)); pg8::Gemm g_{Aop, Bop, M_, N_, k_}; pg8::StaticOrder S_; S_.init(M_, N_, G, (int)blockIdx.x); \
;         pg8::gemm_phase<EpiT, pg8::StaticOrder, true, true>(lds, g_, S_, E); } while (0)
; template <class Epi, class Sched, bool ALIGN_EPI = false, bool SP2 = false>
; __device__ __forceinline__ void gemm_phase(PG8_LAS unsigned char* lds, const Gemm g, const Sched& S, const Epi& E) {
;     ...
;     const char* cA = (const char*)g.A + (size_t)cur.pm * tstep; const char* cB = (const char*)g.Bt + (size_t)cur.pn * tstep;
;     S.a_ready(cur);
;     if constexpr (SP2) {
;         PG8_STAGE(PG8_SB(0, 0), cB, voffB); PG8_STAGE(PG8_SB(0, 1), cB + hstep, voffB); PG8_STAGE(PG8_SA(0, 0), cA, voffA); PG8_STAGE(PG8_SA(0, 1), cA + hstep, voffA);
;         if (wr == 1) PG8_BAR;
;         PG8_WAIT_V(2); PG8_BAR;
;         PG8_STAGE(PG8_SB(1, 0), cB + kstep, voffB); PG8_STAGE(PG8_SA(1, 0), cA + kstep, voffA); PG8_STAGE(PG8_SB(1, 1), cB + hstep + kstep, voffB);
;         PG8_WAIT_V(6); PG8_BAR;
; __global__ void __launch_bounds__(NWAVES * 64, 2) mega_fwd(Args args) {
;     ...
;         GEMM(EpiB, E, XB, WINB, MPROMPT, 6144, 1024); }
.LBB0_971:
	s_andn2_b64 vcc, exec, s[10:11]
	s_cbranch_vccnz .LBB0_1064
	s_mov_b64 s[10:11], s[86:87]
	s_nop 4
	s_mov_b64 s[12:13], s[86:87]
	s_nop 4
	v_lshrrev_b32_e32 v2, 1, v154
	v_and_b32_e32 v17, 24, v2
	v_lshrrev_b32_e32 v2, 5, v154
	s_waitcnt lgkmcnt(0)
	s_add_u32 s3, s10, 0x2b30000
	s_addc_u32 s54, s11, 0
	s_add_u32 s55, s12, 0x16a0000
	s_addc_u32 s58, s13, 0
	s_ashr_i32 s7, s6, 31
	s_lshl_b64 s[12:13], s[6:7], 9
	s_ashr_i32 s8, s84, 31
	s_mul_i32 s8, s12, s8
	s_mul_hi_u32 s9, s12, s84
	s_add_i32 s14, s9, s8
	s_lshr_b64 s[8:9], s[6:7], 23
	s_mul_i32 s9, s8, s84
	v_lshlrev_b32_e32 v0, 4, v154
	v_and_b32_e32 v1, 32, v154
	v_and_b32_e32 v2, 4, v2
	v_bfe_u32 v3, v154, 2, 2
	s_add_i32 s14, s14, s9
	s_ashr_i32 s9, s83, 31
	v_bitop3_b32 v12, v0, v1, 48 bitop3:0x6c
	v_or3_b32 v2, v2, v3, v17
	v_lshrrev_b32_e32 v3, 3, v154
	s_movk_i32 s1, 0x60
	v_add_u32_e32 v0, 0x2000, v0
	s_mul_i32 s9, s12, s9
	s_mul_hi_u32 s16, s12, s83
	s_lshr_b32 s0, s28, 6
	v_and_b32_e32 v15, 0x70, v3
	v_and_or_b32 v3, v3, s1, v2
	v_lshrrev_b32_e32 v0, 7, v0
	s_movk_i32 s1, 0xe0
	s_add_i32 s9, s16, s9
	s_mul_i32 s8, s8, s83
	v_and_b32_e32 v13, 64, v154
	v_and_b32_e32 v16, 0xf0, v0
	v_and_or_b32 v0, v0, s1, v2
	s_lshr_b32 s1, s28, 8
	s_lshl_b64 s[10:11], s[6:7], 8
	s_lshl_b32 s59, s0, 10
	s_add_i32 s9, s9, s8
	s_mul_i32 s8, s12, s83
	v_or_b32_e32 v1, v12, v13
	s_add_u32 s50, s55, s8
	v_lshrrev_b32_e32 v1, 1, v1
	v_mul_lo_u32 v3, s6, v3
	s_addc_u32 s51, s58, s9
	s_add_i32 s60, s59, 0
	v_add_lshl_u32 v138, v3, v1, 1
	s_add_i32 m0, s60, 0x10000
	v_mul_lo_u32 v0, s6, v0
	global_load_lds_dwordx4 v138, s[50:51]
	s_add_i32 m0, s60, 0x12000
	v_add_lshl_u32 v142, v0, v1, 1
	s_add_u32 s8, s50, s10
	global_load_lds_dwordx4 v142, s[50:51]
	s_addc_u32 s9, s51, s11
	s_add_i32 m0, s60, 0x14000
	v_bfe_u32 v14, v154, 2, 4
	s_mul_i32 s15, s12, s84
	global_load_lds_dwordx4 v138, s[8:9]
	s_add_i32 m0, s60, 0x16000
	v_or_b32_e32 v4, v15, v14
	s_add_u32 s52, s3, s15
	v_mul_lo_u32 v4, s6, v4
	v_or_b32_e32 v3, v16, v14
	s_addc_u32 s53, s54, s14
	s_add_i32 s61, s60, 0x2000
	v_add_lshl_u32 v136, v4, v1, 1
	v_mul_lo_u32 v2, s6, v3
	global_load_lds_dwordx4 v142, s[8:9]
	s_mov_b32 m0, s60
	s_add_u32 s14, s52, s10
	v_add_lshl_u32 v140, v2, v1, 1
	global_load_lds_dwordx4 v136, s[52:53]
	s_mov_b32 m0, s61
	s_addc_u32 s15, s53, s11
	s_add_i32 s62, s60, 0x4000
	global_load_lds_dwordx4 v140, s[52:53]
	s_mov_b32 m0, s62
	s_add_i32 s63, s60, 0x6000
	global_load_lds_dwordx4 v136, s[14:15]
	s_mov_b32 m0, s63
	v_mov_b32_e32 v145, 0
	global_load_lds_dwordx4 v140, s[14:15]
	v_mov_b32_e32 v139, v145
	v_mov_b32_e32 v143, v145
	v_mov_b32_e32 v137, v145
	v_mov_b32_e32 v141, v145
	s_cmp_eq_u32 s1, 1
	s_mov_b32 s64, 0
	v_lshl_add_u64 v[8:9], s[50:51], 0, v[138:139]
	v_lshl_add_u64 v[4:5], s[50:51], 0, v[142:143]
	v_lshl_add_u64 v[2:3], s[8:9], 0, v[138:139]
	v_lshl_add_u64 v[0:1], s[8:9], 0, v[142:143]
	v_lshl_add_u64 v[6:7], s[52:53], 0, v[136:137]
	s_cselect_b64 s[14:15], -1, 0
	s_cmp_lg_u32 s1, 1
	v_lshl_add_u64 v[10:11], s[52:53], 0, v[140:141]
	s_cbranch_scc1 .LBB0_974
	s_barrier

; __device__ __forceinline__ void conv3_phase(const bf16* CH, bf16* Bg, const float* wsc, const float* st_sc, float* ss_sc, int G) {
;     const size_t total = (size_t)MREAL * 128;
;     for (size_t it = (size_t)blockIdx.x * 512 + threadIdx.x; it < total; it += (size_t)G * 512) {
;         const int m = (int)(it >> 7), c = (int)(it & 127) * 8;
;         float x0[8], x1[8], x2[8], bg[8], w0[8], w1[8], w2[8];
;         unpack8(*(const u32x4*)(CH + (size_t)m * D + c), x2); unpack8(*(const u32x4*)(Bg + (size_t)m * D + c), bg);
; #pragma unroll
;         for (int e = 0; e < 8; ++e) { w0[e] = wsc[c + e]; w1[e] = wsc[1024 + c + e]; w2[e] = wsc[2048 + c + e]; x0[e] = 0.f; x1[e] = 0.f; }
;         if (m < MPROMPT) { const int t = m & 2047;
;             if (t >= 1) unpack8(*(const u32x4*)(CH + (size_t)(m - 1) * D + c), x1);
;             if (t >= 2) unpack8(*(const u32x4*)(CH + (size_t)(m - 2) * D + c), x0);
;         } else { const int bs = m - MPROMPT; const float* s0 = st_sc + ((size_t)bs * 2) * 1024 + c; float* o = ss_sc + ((size_t)bs * 2) * 1024 + c;
; #pragma unroll
;             for (int e = 0; e < 8; ++e) { x0[e] = s0[e]; x1[e] = s0[1024 + e]; o[e] = s0[1024 + e]; } }
.LBB0_1118:
	s_cmp_lt_i32 s64, 9
	s_cselect_b64 s[0:1], -1, 0
	s_and_b64 s[4:5], s[0:1], s[6:7]
	s_andn2_b64 vcc, exec, s[4:5]
	s_cbranch_vccnz .LBB0_1144
	s_mov_b32 s3, 0
	v_mov_b32_e32 v41, 0
	s_lshl_b64 s[6:7], s[2:3], 9
	v_mov_b32_e32 v155, v41
	v_lshl_add_u64 v[42:43], s[6:7], 0, v[154:155]
	s_mov_b64 s[6:7], 0x204000
	s_mov_b64 s[0:1], s[56:57]
	s_mov_b64 s[12:13], s[56:57]
	s_mov_b64 s[16:17], s[56:57]
	s_mov_b64 s[14:15], s[56:57]
	s_mov_b64 s[18:19], s[56:57]
	v_cmp_gt_u64_e32 vcc, s[6:7], v[42:43]
	s_and_saveexec_b64 s[6:7], vcc
	s_cbranch_execz .LBB0_1130
	s_mov_b64 s[20:21], s[86:87]
	s_nop 4
	s_mov_b64 s[22:23], s[86:87]
	s_nop 4
	s_load_dwordx2 s[8:9], s[16:17], 0x90
	s_load_dwordx2 s[10:11], s[14:15], 0x30
	s_load_dwordx2 s[24:25], s[18:19], 0x100
	s_waitcnt lgkmcnt(0)
	s_add_u32 s12, s20, 0x4bb0000
	s_addc_u32 s13, s21, 0
	s_add_u32 s14, s22, 0x6c30000
	s_addc_u32 s15, s23, 0
	s_add_u32 s16, s24, 0x8958000
	s_addc_u32 s17, s25, 0
	s_ashr_i32 s1, s88, 31
	s_mov_b32 s0, s88
	s_lshl_b64 s[20:21], s[2:3], 12
	v_lshlrev_b32_e32 v40, 3, v154
	s_mov_b32 s30, 0xfe000000
	s_lshl_b64 s[18:19], s[0:1], 9
	v_lshl_add_u64 v[44:45], s[20:21], 0, v[40:41]
	s_lshl_b64 s[20:21], s[0:1], 12
	s_mov_b64 s[22:23], 0
	s_mov_b64 s[24:25], 0x1000
	s_mov_b64 s[26:27], 0x2000
	s_mov_b64 s[28:29], 0x1fffff
	s_movk_i32 s31, 0x7ff
	s_mov_b64 s[34:35], 0x203fff
	s_branch .LBB0_1123

; #define LAS __attribute__((address_space(3)))
; #define XSEG(W, ldw, c0, K, ncols, WT, d0, mode, sel) { const int ni_ = ((K) / 64) * ((ncols) / 32); if (r_ < ni_) { xpose_item(W, ldw, c0, K, ncols, WT, d0, mode, sel, scr, r_, lane); continue; } r_ -= ni_; }
; __device__ __forceinline__ const float* arg_in(int k) { return (const float*)(const __attribute__((address_space(1))) float*)arg_q(k); }
; __device__ __forceinline__ void xpose_item(const float* W, int ldw, int c0, int K, int ncols, bf16* WT, int d0, int mode, int sel, LAS float* scr, int item, int lane) {
;     const int nblk = ncols >> 5, kb = item / nblk, nb = item - kb * nblk, k0 = 64 * kb, n0 = 32 * nb;
;     const int drow = mode ? d0 + 256 * (n0 >> 7) + 128 * sel + (n0 & 127) : d0 + n0;
;     f32x4 tv[8];
; #pragma unroll
;     for (int i = 0; i < 8; ++i) tv[i] = __builtin_nontemporal_load((const f32x4*)(W + (size_t)(k0 + 8 * i + (lane >> 3)) * ldw + c0 + n0 + 4 * (lane & 7)));
; #pragma unroll
;     for (int i = 0; i < 8; ++i) { LAS float* d = scr + (8 * i + (lane >> 3)) * 33 + 4 * (lane & 7); d[0] = tv[i][0]; d[1] = tv[i][1]; d[2] = tv[i][2]; d[3] = tv[i][3]; }
;     asm volatile("s_waitcnt lgkmcnt(0)" ::: "memory");
;     const int c = lane & 7;
; #pragma unroll
;     for (int j = 0; j < 4; ++j) { const int n = (lane >> 3) + 8 * j; const LAS float* s = scr + (8 * c) * 33 + n;
;         u32x4 o; o.x = cvt_pk_bf16(s[0 * 33], s[1 * 33]); o.y = cvt_pk_bf16(s[2 * 33], s[3 * 33]); o.z = cvt_pk_bf16(s[4 * 33], s[5 * 33]); o.w = cvt_pk_bf16(s[6 * 33], s[7 * 33]);
;         *(u32x4*)(WT + (size_t)(drow + n) * K + k0 + 8 * c) = o; }
;     asm volatile("s_waitcnt lgkmcnt(0)" ::: "memory");
; }
; __global__ void __launch_bounds__(NWAVES * 64, 2) mega_fwd(Args args) {
;     ...
;             XSEG(arg_in(23), FF, 0, 1024, FF, WGU, 0, 1, 0)
.LBB0_1133:
	s_cmpk_gt_i32 s19, 0x57f
	s_cselect_b64 s[10:11], -1, 0
	s_mov_b64 s[0:1], -1
	s_and_b64 vcc, exec, s[10:11]
	s_cbranch_vccnz .LBB0_1136
	s_mul_hi_i32 s20, s19, 0x2e8ba2e9
	s_mov_b64 s[0:1], s[56:57]
	s_lshr_b32 s21, s20, 31
	s_ashr_i32 s20, s20, 4
	s_add_i32 s21, s20, s21
	s_load_dwordx2 s[0:1], s[0:1], 0xb8
	s_mul_i32 s20, s21, 0xfffff500
	s_mul_i32 s22, s21, 0xffffea00
	s_add_i32 s20, s3, s20
	s_add_i32 s22, s15, s22
	s_and_b32 s22, s22, 0xffffff00
	s_and_b32 s23, s20, 0x60
	s_or_b32 s24, s22, s23
	s_lshl_b32 s22, s21, 6
	s_ashr_i32 s21, s20, 31
	s_lshl_b64 s[20:21], s[20:21], 2
	s_waitcnt lgkmcnt(0)
	s_add_u32 s0, s0, s20
	s_addc_u32 s1, s1, s21
	v_or_b32_e32 v3, s22, v4
	v_lshl_add_u64 v[52:53], s[0:1], 0, v[0:1]
	s_mov_b64 s[12:13], s[56:57]
	v_mad_i64_i32 v[32:33], s[0:1], v3, s17, v[52:53]
	v_or_b32_e32 v24, 8, v3
	v_mad_i64_i32 v[34:35], s[0:1], v24, s17, v[52:53]
	global_load_dwordx4 v[24:27], v[32:33], off nt
	global_load_dwordx4 v[28:31], v[34:35], off nt
	v_or_b32_e32 v32, 16, v3
	v_mad_i64_i32 v[40:41], s[0:1], v32, s17, v[52:53]
	v_or_b32_e32 v32, 24, v3
	v_mad_i64_i32 v[42:43], s[0:1], v32, s17, v[52:53]
	global_load_dwordx4 v[32:35], v[40:41], off nt
	global_load_dwordx4 v[36:39], v[42:43], off nt
	v_or_b32_e32 v40, 32, v3
	v_mad_i64_i32 v[48:49], s[0:1], v40, s17, v[52:53]
	v_or_b32_e32 v40, 40, v3
	v_mad_i64_i32 v[50:51], s[0:1], v40, s17, v[52:53]
	global_load_dwordx4 v[40:43], v[48:49], off nt
	global_load_dwordx4 v[44:47], v[50:51], off nt
	v_or_b32_e32 v48, 48, v3
	v_mad_i64_i32 v[48:49], s[0:1], v48, s17, v[52:53]
	global_load_dwordx4 v[48:51], v[48:49], off nt
	v_or_b32_e32 v3, 56, v3
	v_mad_i64_i32 v[52:53], s[0:1], v3, s17, v[52:53]
	global_load_dwordx4 v[52:55], v[52:53], off nt
	s_mov_b64 s[0:1], s[86:87]
	s_nop 4
	s_ashr_i32 s23, s22, 31
	s_lshl_b64 s[12:13], s[22:23], 1
	v_mov_b32_e32 v3, v1
	v_or_b32_e32 v56, s24, v4
	s_waitcnt lgkmcnt(0)
	s_add_u32 s0, s0, s12
	s_addc_u32 s1, s1, s13
	v_ashrrev_i32_e32 v57, 31, v56
	v_lshl_add_u64 v[58:59], s[0:1], 0, v[2:3]
	v_lshlrev_b64 v[56:57], 11, v[56:57]
	v_lshl_add_u64 v[58:59], v[58:59], 0, s[6:7]
	s_waitcnt vmcnt(0)
	ds_write2_b32 v9, v24, v25 offset1:1
	ds_write2_b32 v9, v26, v27 offset0:2 offset1:3
	ds_write2_b32 v10, v28, v29 offset1:1
	ds_write2_b32 v11, v30, v31 offset1:1
	ds_write2_b32 v12, v32, v33 offset1:1
	ds_write2_b32 v13, v34, v35 offset1:1
	ds_write2_b32 v14, v36, v37 offset1:1
	ds_write2_b32 v15, v38, v39 offset1:1
	ds_write2_b32 v16, v40, v41 offset1:1
	ds_write2_b32 v17, v42, v43 offset1:1
	ds_write2_b32 v18, v44, v45 offset1:1
	ds_write2_b32 v19, v46, v47 offset1:1
	ds_write2_b32 v20, v48, v49 offset1:1
	ds_write2_b32 v21, v50, v51 offset1:1
	ds_write2_b32 v22, v52, v53 offset1:1
	ds_write2_b32 v23, v54, v55 offset1:1
	s_waitcnt lgkmcnt(0)
	ds_read2_b32 v[28:29], v8 offset0:33 offset1:41
	ds_read2_b32 v[30:31], v8 offset1:8
	ds_read2_b32 v[32:33], v8 offset0:66 offset1:74
	ds_read2_b32 v[34:35], v8 offset0:99 offset1:107
	ds_read2_b32 v[36:37], v8 offset0:132 offset1:140
	ds_read2_b32 v[38:39], v8 offset0:165 offset1:173
	ds_read2_b32 v[40:41], v8 offset0:198 offset1:206
	ds_read2_b32 v[42:43], v8 offset0:231 offset1:239
	v_lshl_add_u64 v[44:45], v[58:59], 0, v[56:57]
	s_waitcnt lgkmcnt(6)
	v_cvt_pk_bf16_f32 v24, v30, v28
	s_waitcnt lgkmcnt(4)
	v_cvt_pk_bf16_f32 v25, v32, v34
	s_waitcnt lgkmcnt(2)
	v_cvt_pk_bf16_f32 v26, v36, v38
	s_waitcnt lgkmcnt(0)
	v_cvt_pk_bf16_f32 v27, v40, v42
	global_store_dwordx4 v[44:45], v[24:27], off
	v_cvt_pk_bf16_f32 v28, v31, v29
	v_cvt_pk_bf16_f32 v29, v33, v35
	v_or_b32_e32 v24, s24, v5
	v_ashrrev_i32_e32 v25, 31, v24
	v_cvt_pk_bf16_f32 v30, v37, v39
	v_cvt_pk_bf16_f32 v31, v41, v43
	v_lshlrev_b64 v[24:25], 11, v[24:25]
	ds_read2_b32 v[32:33], v8 offset0:49 offset1:57
	ds_read2_b32 v[34:35], v8 offset0:16 offset1:24
	ds_read2_b32 v[36:37], v8 offset0:82 offset1:90
	ds_read2_b32 v[38:39], v8 offset0:115 offset1:123
	ds_read2_b32 v[40:41], v8 offset0:148 offset1:156
	ds_read2_b32 v[42:43], v8 offset0:181 offset1:189
	ds_read2_b32 v[44:45], v8 offset0:214 offset1:222
	ds_read2_b32 v[46:47], v8 offset0:247 offset1:255
	v_lshl_add_u64 v[24:25], v[58:59], 0, v[24:25]
	global_store_dwordx4 v[24:25], v[28:31], off
	s_waitcnt lgkmcnt(6)
	v_cvt_pk_bf16_f32 v24, v34, v32
	s_waitcnt lgkmcnt(4)
	v_cvt_pk_bf16_f32 v25, v36, v38
	v_or_b32_e32 v28, s24, v6
	v_ashrrev_i32_e32 v29, 31, v28
	v_lshlrev_b64 v[28:29], 11, v[28:29]
	s_waitcnt lgkmcnt(2)
	v_cvt_pk_bf16_f32 v26, v40, v42
	s_waitcnt lgkmcnt(0)
	v_cvt_pk_bf16_f32 v27, v44, v46
	v_lshl_add_u64 v[28:29], v[58:59], 0, v[28:29]
	global_store_dwordx4 v[28:29], v[24:27], off
	v_or_b32_e32 v28, s24, v7
	v_ashrrev_i32_e32 v29, 31, v28
	v_lshlrev_b64 v[28:29], 11, v[28:29]
	v_cvt_pk_bf16_f32 v24, v35, v33
	v_cvt_pk_bf16_f32 v25, v37, v39
	v_cvt_pk_bf16_f32 v26, v41, v43
	v_cvt_pk_bf16_f32 v27, v45, v47
	v_lshl_add_u64 v[28:29], v[58:59], 0, v[28:29]
	global_store_dwordx4 v[28:29], v[24:27], off
	s_waitcnt lgkmcnt(0)
	s_mov_b32 s20, s19
	s_cbranch_execz .LBB0_1137

; #define LAS __attribute__((address_space(3)))
; #define XSEG(W, ldw, c0, K, ncols, WT, d0, mode, sel) { const int ni_ = ((K) / 64) * ((ncols) / 32); if (r_ < ni_) { xpose_item(W, ldw, c0, K, ncols, WT, d0, mode, sel, scr, r_, lane); continue; } r_ -= ni_; }
; __device__ __forceinline__ const float* arg_in(int k) { return (const float*)(const __attribute__((address_space(1))) float*)arg_q(k); }
; __device__ __forceinline__ void xpose_item(const float* W, int ldw, int c0, int K, int ncols, bf16* WT, int d0, int mode, int sel, LAS float* scr, int item, int lane) {
;     const int nblk = ncols >> 5, kb = item / nblk, nb = item - kb * nblk, k0 = 64 * kb, n0 = 32 * nb;
;     const int drow = mode ? d0 + 256 * (n0 >> 7) + 128 * sel + (n0 & 127) : d0 + n0;
;     f32x4 tv[8];
; #pragma unroll
;     for (int i = 0; i < 8; ++i) tv[i] = __builtin_nontemporal_load((const f32x4*)(W + (size_t)(k0 + 8 * i + (lane >> 3)) * ldw + c0 + n0 + 4 * (lane & 7)));
; #pragma unroll
;     for (int i = 0; i < 8; ++i) { LAS float* d = scr + (8 * i + (lane >> 3)) * 33 + 4 * (lane & 7); d[0] = tv[i][0]; d[1] = tv[i][1]; d[2] = tv[i][2]; d[3] = tv[i][3]; }
;     asm volatile("s_waitcnt lgkmcnt(0)" ::: "memory");
;     const int c = lane & 7;
; #pragma unroll
;     for (int j = 0; j < 4; ++j) { const int n = (lane >> 3) + 8 * j; const LAS float* s = scr + (8 * c) * 33 + n;
;         u32x4 o; o.x = cvt_pk_bf16(s[0 * 33], s[1 * 33]); o.y = cvt_pk_bf16(s[2 * 33], s[3 * 33]); o.z = cvt_pk_bf16(s[4 * 33], s[5 * 33]); o.w = cvt_pk_bf16(s[6 * 33], s[7 * 33]);
;         *(u32x4*)(WT + (size_t)(drow + n) * K + k0 + 8 * c) = o; }
;     asm volatile("s_waitcnt lgkmcnt(0)" ::: "memory");
; }
; __global__ void __launch_bounds__(NWAVES * 64, 2) mega_fwd(Args args) {
;     ...
;             XSEG(arg_in(24), FF, 0, 1024, FF, WGU, 0, 1, 1)
.LBB0_1138:
	s_cmpk_gt_i32 s20, 0x57f
	s_cselect_b64 s[10:11], -1, 0
	s_mov_b64 s[0:1], -1
	s_and_b64 vcc, exec, s[10:11]
	s_cbranch_vccnz .LBB0_1141
	s_mul_hi_i32 s12, s20, 0x2e8ba2e9
	s_lshr_b32 s13, s12, 31
	s_ashr_i32 s12, s12, 4
	s_mov_b64 s[0:1], s[56:57]
	s_add_i32 s12, s12, s13
	s_mul_i32 s13, s12, 0xffffffa8
	s_load_dwordx2 s[0:1], s[0:1], 0xc0
	s_add_i32 s13, s13, s20
	s_lshl_b32 s24, s13, 5
	s_lshl_b32 s13, s13, 6
	s_and_b32 s13, s13, 0xffffff00
	s_and_b32 s21, s24, 0x60
	s_or_b32 s13, s21, s13
	s_ashr_i32 s25, s24, 31
	s_or_b32 s21, s13, 0x80
	s_lshl_b32 s12, s12, 6
	s_lshl_b64 s[24:25], s[24:25], 2
	s_waitcnt lgkmcnt(0)
	s_add_u32 s0, s0, s24
	s_addc_u32 s1, s1, s25
	v_or_b32_e32 v3, s12, v4
	v_lshl_add_u64 v[52:53], s[0:1], 0, v[0:1]
	s_mov_b64 s[22:23], s[56:57]
	v_mad_i64_i32 v[32:33], s[0:1], v3, s17, v[52:53]
	v_or_b32_e32 v24, 8, v3
	v_mad_i64_i32 v[34:35], s[0:1], v24, s17, v[52:53]
	global_load_dwordx4 v[24:27], v[32:33], off nt
	global_load_dwordx4 v[28:31], v[34:35], off nt
	v_or_b32_e32 v32, 16, v3
	v_mad_i64_i32 v[40:41], s[0:1], v32, s17, v[52:53]
	v_or_b32_e32 v32, 24, v3
	v_mad_i64_i32 v[42:43], s[0:1], v32, s17, v[52:53]
	global_load_dwordx4 v[32:35], v[40:41], off nt
	global_load_dwordx4 v[36:39], v[42:43], off nt
	v_or_b32_e32 v40, 32, v3
	v_mad_i64_i32 v[48:49], s[0:1], v40, s17, v[52:53]
	v_or_b32_e32 v40, 40, v3
	v_mad_i64_i32 v[50:51], s[0:1], v40, s17, v[52:53]
	global_load_dwordx4 v[40:43], v[48:49], off nt
	global_load_dwordx4 v[44:47], v[50:51], off nt
	v_or_b32_e32 v48, 48, v3
	v_mad_i64_i32 v[48:49], s[0:1], v48, s17, v[52:53]
	global_load_dwordx4 v[48:51], v[48:49], off nt
	v_or_b32_e32 v3, 56, v3
	v_mad_i64_i32 v[52:53], s[0:1], v3, s17, v[52:53]
	global_load_dwordx4 v[52:55], v[52:53], off nt
	s_mov_b64 s[0:1], s[86:87]
	s_nop 4
	s_ashr_i32 s13, s12, 31
	s_lshl_b64 s[12:13], s[12:13], 1
	v_mov_b32_e32 v3, v1
	v_or_b32_e32 v56, s21, v4
	s_waitcnt lgkmcnt(0)
	s_add_u32 s0, s0, s12
	s_addc_u32 s1, s1, s13
	v_ashrrev_i32_e32 v57, 31, v56
	v_lshl_add_u64 v[60:61], s[0:1], 0, v[2:3]
	v_lshlrev_b64 v[56:57], 11, v[56:57]
	v_lshl_add_u64 v[60:61], v[60:61], 0, s[6:7]
	v_or_b32_e32 v58, s21, v5
	v_ashrrev_i32_e32 v59, 31, v58
	s_waitcnt vmcnt(0)
	ds_write2_b32 v9, v24, v25 offset1:1
	ds_write2_b32 v9, v26, v27 offset0:2 offset1:3
	ds_write2_b32 v10, v28, v29 offset1:1
	ds_write2_b32 v11, v30, v31 offset1:1
	ds_write2_b32 v12, v32, v33 offset1:1
	ds_write2_b32 v13, v34, v35 offset1:1
	ds_write2_b32 v14, v36, v37 offset1:1
	ds_write2_b32 v15, v38, v39 offset1:1
	ds_write2_b32 v16, v40, v41 offset1:1
	ds_write2_b32 v17, v42, v43 offset1:1
	ds_write2_b32 v18, v44, v45 offset1:1
	ds_write2_b32 v19, v46, v47 offset1:1
	ds_write2_b32 v20, v48, v49 offset1:1
	ds_write2_b32 v21, v50, v51 offset1:1
	ds_write2_b32 v22, v52, v53 offset1:1
	ds_write2_b32 v23, v54, v55 offset1:1
	s_waitcnt lgkmcnt(0)
	ds_read2_b32 v[28:29], v8 offset0:33 offset1:41
	ds_read2_b32 v[30:31], v8 offset1:8
	ds_read2_b32 v[32:33], v8 offset0:66 offset1:74
	ds_read2_b32 v[34:35], v8 offset0:99 offset1:107
	ds_read2_b32 v[36:37], v8 offset0:132 offset1:140
	ds_read2_b32 v[38:39], v8 offset0:165 offset1:173
	ds_read2_b32 v[40:41], v8 offset0:198 offset1:206
	ds_read2_b32 v[42:43], v8 offset0:231 offset1:239
	v_lshl_add_u64 v[44:45], v[60:61], 0, v[56:57]
	s_waitcnt lgkmcnt(6)
	v_cvt_pk_bf16_f32 v24, v30, v28
	s_waitcnt lgkmcnt(4)
	v_cvt_pk_bf16_f32 v25, v32, v34
	s_waitcnt lgkmcnt(2)
	v_cvt_pk_bf16_f32 v26, v36, v38
	s_waitcnt lgkmcnt(0)
	v_cvt_pk_bf16_f32 v27, v40, v42
	global_store_dwordx4 v[44:45], v[24:27], off
	v_cvt_pk_bf16_f32 v28, v31, v29
	v_cvt_pk_bf16_f32 v29, v33, v35
	v_cvt_pk_bf16_f32 v30, v37, v39
	v_cvt_pk_bf16_f32 v31, v41, v43
	v_lshlrev_b64 v[24:25], 11, v[58:59]
	ds_read2_b32 v[32:33], v8 offset0:49 offset1:57
	ds_read2_b32 v[34:35], v8 offset0:16 offset1:24
	ds_read2_b32 v[36:37], v8 offset0:82 offset1:90
	ds_read2_b32 v[38:39], v8 offset0:115 offset1:123
	ds_read2_b32 v[40:41], v8 offset0:148 offset1:156
	ds_read2_b32 v[42:43], v8 offset0:181 offset1:189
	ds_read2_b32 v[44:45], v8 offset0:214 offset1:222
	ds_read2_b32 v[46:47], v8 offset0:247 offset1:255
	v_lshl_add_u64 v[24:25], v[60:61], 0, v[24:25]
	global_store_dwordx4 v[24:25], v[28:31], off
	s_waitcnt lgkmcnt(6)
	v_cvt_pk_bf16_f32 v24, v34, v32
	s_waitcnt lgkmcnt(4)
	v_cvt_pk_bf16_f32 v25, v36, v38
	v_or_b32_e32 v28, s21, v6
	v_ashrrev_i32_e32 v29, 31, v28
	v_lshlrev_b64 v[28:29], 11, v[28:29]
	s_waitcnt lgkmcnt(2)
	v_cvt_pk_bf16_f32 v26, v40, v42
	s_waitcnt lgkmcnt(0)
	v_cvt_pk_bf16_f32 v27, v44, v46
	v_lshl_add_u64 v[28:29], v[60:61], 0, v[28:29]
	global_store_dwordx4 v[28:29], v[24:27], off
	v_or_b32_e32 v28, s21, v7
	v_ashrrev_i32_e32 v29, 31, v28
	v_lshlrev_b64 v[28:29], 11, v[28:29]
	v_cvt_pk_bf16_f32 v24, v35, v33
	v_cvt_pk_bf16_f32 v25, v37, v39
	v_cvt_pk_bf16_f32 v26, v41, v43
	v_cvt_pk_bf16_f32 v27, v45, v47
	v_lshl_add_u64 v[28:29], v[60:61], 0, v[28:29]
	global_store_dwordx4 v[28:29], v[24:27], off
	s_waitcnt lgkmcnt(0)
	s_cbranch_execz .LBB0_1142

; #define LAS __attribute__((address_space(3)))
; #define XSEG(W, ldw, c0, K, ncols, WT, d0, mode, sel) { const int ni_ = ((K) / 64) * ((ncols) / 32); if (r_ < ni_) { xpose_item(W, ldw, c0, K, ncols, WT, d0, mode, sel, scr, r_, lane); continue; } r_ -= ni_; }
; __device__ __forceinline__ const float* arg_in(int k) { return (const float*)(const __attribute__((address_space(1))) float*)arg_q(k); }
; __device__ __forceinline__ void xpose_item(const float* W, int ldw, int c0, int K, int ncols, bf16* WT, int d0, int mode, int sel, LAS float* scr, int item, int lane) {
;     const int nblk = ncols >> 5, kb = item / nblk, nb = item - kb * nblk, k0 = 64 * kb, n0 = 32 * nb;
;     const int drow = mode ? d0 + 256 * (n0 >> 7) + 128 * sel + (n0 & 127) : d0 + n0;
;     f32x4 tv[8];
; #pragma unroll
;     for (int i = 0; i < 8; ++i) tv[i] = __builtin_nontemporal_load((const f32x4*)(W + (size_t)(k0 + 8 * i + (lane >> 3)) * ldw + c0 + n0 + 4 * (lane & 7)));
; #pragma unroll
;     for (int i = 0; i < 8; ++i) { LAS float* d = scr + (8 * i + (lane >> 3)) * 33 + 4 * (lane & 7); d[0] = tv[i][0]; d[1] = tv[i][1]; d[2] = tv[i][2]; d[3] = tv[i][3]; }
;     asm volatile("s_waitcnt lgkmcnt(0)" ::: "memory");
;     const int c = lane & 7;
; #pragma unroll
;     for (int j = 0; j < 4; ++j) { const int n = (lane >> 3) + 8 * j; const LAS float* s = scr + (8 * c) * 33 + n;
;         u32x4 o; o.x = cvt_pk_bf16(s[0 * 33], s[1 * 33]); o.y = cvt_pk_bf16(s[2 * 33], s[3 * 33]); o.z = cvt_pk_bf16(s[4 * 33], s[5 * 33]); o.w = cvt_pk_bf16(s[6 * 33], s[7 * 33]);
;         *(u32x4*)(WT + (size_t)(drow + n) * K + k0 + 8 * c) = o; }
;     asm volatile("s_waitcnt lgkmcnt(0)" ::: "memory");
; }
; __global__ void __launch_bounds__(NWAVES * 64, 2) mega_fwd(Args args) {
;     ...
;             XSEG(arg_in(25), D, 0, FF, D, WD, 0, 0, 0)
.LBB0_1143:
	s_ashr_i32 s10, s20, 31
	s_mov_b64 s[0:1], s[56:57]
	s_lshr_b32 s10, s10, 27
	s_add_i32 s10, s20, s10
	s_load_dwordx2 s[0:1], s[0:1], 0xc8
	s_ashr_i32 s11, s10, 5
	s_lshl_b32 s10, s11, 10
	s_lshl_b32 s12, s20, 5
	s_sub_i32 s10, s12, s10
	s_lshl_b32 s12, s11, 6
	s_ashr_i32 s11, s10, 31
	s_lshl_b64 s[20:21], s[10:11], 2
	v_or_b32_e32 v52, s12, v4
	s_waitcnt lgkmcnt(0)
	s_add_u32 s0, s0, s20
	s_addc_u32 s1, s1, s21
	v_ashrrev_i32_e32 v53, 31, v52
	v_lshl_add_u64 v[54:55], s[0:1], 0, v[0:1]
	v_lshlrev_b64 v[24:25], 12, v[52:53]
	v_lshl_add_u64 v[32:33], v[54:55], 0, v[24:25]
	v_or_b32_e32 v24, 8, v52
	v_ashrrev_i32_e32 v25, 31, v24
	s_mov_b64 s[22:23], s[56:57]
	v_lshlrev_b64 v[24:25], 12, v[24:25]
	v_lshl_add_u64 v[34:35], v[54:55], 0, v[24:25]
	global_load_dwordx4 v[24:27], v[32:33], off nt
	global_load_dwordx4 v[28:31], v[34:35], off nt
	v_or_b32_e32 v32, 16, v52
	v_ashrrev_i32_e32 v33, 31, v32
	v_lshlrev_b64 v[32:33], 12, v[32:33]
	v_lshl_add_u64 v[40:41], v[54:55], 0, v[32:33]
	v_or_b32_e32 v32, 24, v52
	v_ashrrev_i32_e32 v33, 31, v32
	v_lshlrev_b64 v[32:33], 12, v[32:33]
	v_lshl_add_u64 v[42:43], v[54:55], 0, v[32:33]
	global_load_dwordx4 v[32:35], v[40:41], off nt
	global_load_dwordx4 v[36:39], v[42:43], off nt
	v_or_b32_e32 v40, 32, v52
	v_ashrrev_i32_e32 v41, 31, v40
	v_lshlrev_b64 v[40:41], 12, v[40:41]
	v_lshl_add_u64 v[48:49], v[54:55], 0, v[40:41]
	v_or_b32_e32 v40, 40, v52
	v_ashrrev_i32_e32 v41, 31, v40
	v_lshlrev_b64 v[40:41], 12, v[40:41]
	v_lshl_add_u64 v[50:51], v[54:55], 0, v[40:41]
	global_load_dwordx4 v[40:43], v[48:49], off nt
	global_load_dwordx4 v[44:47], v[50:51], off nt
	v_or_b32_e32 v48, 48, v52
	v_ashrrev_i32_e32 v49, 31, v48
	v_lshlrev_b64 v[48:49], 12, v[48:49]
	v_or_b32_e32 v52, 56, v52
	v_lshl_add_u64 v[48:49], v[54:55], 0, v[48:49]
	v_ashrrev_i32_e32 v53, 31, v52
	global_load_dwordx4 v[48:51], v[48:49], off nt
	v_lshlrev_b64 v[52:53], 12, v[52:53]
	v_lshl_add_u64 v[52:53], v[54:55], 0, v[52:53]
	global_load_dwordx4 v[52:55], v[52:53], off nt
	s_mov_b64 s[0:1], s[86:87]
	s_nop 4
	s_ashr_i32 s13, s12, 31
	s_lshl_b64 s[12:13], s[12:13], 1
	v_mov_b32_e32 v3, v1
	v_or_b32_e32 v58, s10, v4
	s_waitcnt lgkmcnt(0)
	s_add_u32 s0, s0, s12
	s_addc_u32 s1, s1, s13
	v_lshl_add_u64 v[56:57], s[0:1], 0, v[2:3]
	v_lshl_add_u64 v[56:57], v[56:57], 0, s[8:9]
	v_or_b32_e32 v3, s10, v5
	s_waitcnt vmcnt(0)
	ds_write2_b32 v9, v24, v25 offset1:1
	ds_write2_b32 v9, v26, v27 offset0:2 offset1:3
	ds_write2_b32 v10, v28, v29 offset1:1
	ds_write2_b32 v11, v30, v31 offset1:1
	ds_write2_b32 v12, v32, v33 offset1:1
	ds_write2_b32 v13, v34, v35 offset1:1
	ds_write2_b32 v14, v36, v37 offset1:1
	ds_write2_b32 v15, v38, v39 offset1:1
	ds_write2_b32 v16, v40, v41 offset1:1
	ds_write2_b32 v17, v42, v43 offset1:1
	ds_write2_b32 v18, v44, v45 offset1:1
	ds_write2_b32 v19, v46, v47 offset1:1
	ds_write2_b32 v20, v48, v49 offset1:1
	ds_write2_b32 v21, v50, v51 offset1:1
	ds_write2_b32 v22, v52, v53 offset1:1
	ds_write2_b32 v23, v54, v55 offset1:1
	s_waitcnt lgkmcnt(0)
	ds_read2_b32 v[28:29], v8 offset0:33 offset1:41
	ds_read2_b32 v[30:31], v8 offset1:8
	ds_read2_b32 v[32:33], v8 offset0:66 offset1:74
	ds_read2_b32 v[34:35], v8 offset0:99 offset1:107
	ds_read2_b32 v[36:37], v8 offset0:132 offset1:140
	ds_read2_b32 v[38:39], v8 offset0:165 offset1:173
	ds_read2_b32 v[40:41], v8 offset0:198 offset1:206
	ds_read2_b32 v[42:43], v8 offset0:231 offset1:239
	v_mad_i64_i32 v[44:45], s[0:1], v58, s18, v[56:57]
	s_waitcnt lgkmcnt(6)
	v_cvt_pk_bf16_f32 v24, v30, v28
	s_waitcnt lgkmcnt(4)
	v_cvt_pk_bf16_f32 v25, v32, v34
	s_waitcnt lgkmcnt(2)
	v_cvt_pk_bf16_f32 v26, v36, v38
	s_waitcnt lgkmcnt(0)
	v_cvt_pk_bf16_f32 v27, v40, v42
	global_store_dwordx4 v[44:45], v[24:27], off
	v_cvt_pk_bf16_f32 v28, v31, v29
	v_cvt_pk_bf16_f32 v29, v33, v35
	v_cvt_pk_bf16_f32 v30, v37, v39
	v_cvt_pk_bf16_f32 v31, v41, v43
	ds_read2_b32 v[32:33], v8 offset0:49 offset1:57
	ds_read2_b32 v[34:35], v8 offset0:16 offset1:24
	ds_read2_b32 v[36:37], v8 offset0:82 offset1:90
	ds_read2_b32 v[38:39], v8 offset0:115 offset1:123
	ds_read2_b32 v[40:41], v8 offset0:148 offset1:156
	ds_read2_b32 v[42:43], v8 offset0:181 offset1:189
	ds_read2_b32 v[44:45], v8 offset0:214 offset1:222
	ds_read2_b32 v[46:47], v8 offset0:247 offset1:255
	v_mad_i64_i32 v[24:25], s[0:1], v3, s18, v[56:57]
	v_or_b32_e32 v3, s10, v6
	global_store_dwordx4 v[24:25], v[28:31], off
	s_waitcnt lgkmcnt(6)
	v_cvt_pk_bf16_f32 v24, v34, v32
	s_waitcnt lgkmcnt(4)
	v_cvt_pk_bf16_f32 v25, v36, v38
	s_waitcnt lgkmcnt(2)
	v_cvt_pk_bf16_f32 v26, v40, v42
	s_waitcnt lgkmcnt(0)
	v_cvt_pk_bf16_f32 v27, v44, v46
	v_mad_i64_i32 v[28:29], s[0:1], v3, s18, v[56:57]
	v_or_b32_e32 v3, s10, v7
	global_store_dwordx4 v[28:29], v[24:27], off
	v_mad_i64_i32 v[28:29], s[0:1], v3, s18, v[56:57]
	s_nop 0
	v_cvt_pk_bf16_f32 v24, v35, v33
	v_cvt_pk_bf16_f32 v25, v37, v39
	v_cvt_pk_bf16_f32 v26, v41, v43
	v_cvt_pk_bf16_f32 v27, v45, v47
	global_store_dwordx4 v[28:29], v[24:27], off
	s_waitcnt lgkmcnt(0)
	s_branch .LBB0_1132

; #define LAS __attribute__((address_space(3)))
; template <class EpiS>
; __device__ __forceinline__ void sgemm_phase(LAS unsigned char* lds, const bf16* A, const bf16* Bt, int N, int K, const EpiS& E, int bidx, int nb) {
;     const int tid = threadIdx.x, lane = tid & 63, wave = __builtin_amdgcn_readfirstlane(tid >> 6), li = lane & 15, lq = lane >> 4;
;     const int ntask = (N >> 4) * 4, kper = K >> 3;
;     LAS float* red = (LAS float*)lds;
;     for (int task = bidx; task < ntask; task += nb) {
;         const int ct = task >> 2, rt = task & 3;
;         const bf16* ap0 = A + (size_t)(rt * 32 + li) * K + wave * kper + 8 * lq; const bf16* ap1 = ap0 + (size_t)16 * K;
;         const bf16* bp = Bt + (size_t)(ct * 16 + li) * K + wave * kper + 8 * lq;
;         f32x4 acc0 = (f32x4){0.f, 0.f, 0.f, 0.f}, acc1 = acc0;
; __global__ void __launch_bounds__(NWAVES * 64, 2) mega_fwd(Args args) {
;     ...
;     if (IN(9)) { { SMul ES{R3 + SOFF}; sgemm_phase(lds, R2 + SOFF, WPG, 1024, 1024, ES, (int)blockIdx.x, G); }
.LBB0_1146:
	s_cmp_lt_i32 s64, 10
	s_cselect_b64 s[4:5], -1, 0
	s_and_b64 s[4:5], s[4:5], s[0:1]
	s_andn2_b64 vcc, exec, s[4:5]
	s_cbranch_vccnz .LBB0_1179
	s_cmpk_lt_i32 s2, 0x100
	s_mov_b64 s[0:1], s[56:57]
	s_mov_b64 s[6:7], s[56:57]
	s_mov_b64 s[10:11], s[56:57]
	s_cselect_b64 s[8:9], -1, 0
	s_cmpk_gt_i32 s2, 0xff
	v_readfirstlane_b32 s3, v154
	s_cbranch_scc1 .LBB0_1150
	s_mov_b64 s[12:13], s[86:87]
	s_nop 4
	s_mov_b64 s[14:15], s[86:87]
	s_nop 4
	v_bfe_u32 v7, v154, 4, 2
	s_mov_b64 s[0:1], s[86:87]
	s_nop 4
	v_lshlrev_b32_e32 v0, 4, v7
	s_waitcnt lgkmcnt(0)
	s_add_u32 s6, s12, 0xcd30000
	s_addc_u32 s7, s13, 0
	s_lshr_b32 s3, s3, 6
	s_lshl_b32 s12, s3, 8
	s_add_u32 s10, s14, s12
	s_addc_u32 s11, s15, 0
	s_add_u32 s0, s0, s12
	v_mov_b32_e32 v1, 0
	s_addc_u32 s1, s1, 0
	v_lshl_add_u64 v[4:5], s[0:1], 0, v[0:1]
	s_mov_b64 s[0:1], 0x22a0000
	v_lshl_add_u64 v[4:5], v[4:5], 0, s[0:1]
	s_lshl_b32 s0, s3, 11
	v_lshl_add_u64 v[2:3], s[10:11], 0, v[0:1]
	s_add_i32 s0, s0, 0
	v_lshlrev_b32_e32 v0, 8, v7
	v_lshlrev_b32_e32 v8, 2, v156
	s_mov_b64 s[10:11], 0xacb0000
	v_add3_u32 v8, s0, v0, v8
	v_lshrrev_b32_e32 v6, 4, v154
	v_lshl_add_u64 v[2:3], v[2:3], 0, s[10:11]
	v_lshl_add_u32 v7, v154, 2, 0
	s_lshl_b32 s0, s2, 2
	s_lshl_b32 s1, s88, 2
	s_lshl_b32 s3, s2, 5
	s_lshl_b32 s10, s88, 5
	v_add_u32_e32 v9, 0x400, v8
	s_mov_b32 s11, s2

;     __host__ __device__ bool next(int i, Unit& u) const {
;         const long L = (long)i * G + c; if (L >= nwg) return false;
;         int wgid = (int)L; { const int q = nwg / NXCD, r = nwg % NXCD, xcd = wgid % NXCD, off = wgid / NXCD; wgid = (xcd < r ? xcd * (q + 1) : r * (q + 1) + (xcd - r) * q) + off; }
;         const int nig = WGM * nN, gid = wgid / nig, fm = gid * WGM, gsz = (nM - fm) < WGM ? (nM - fm) : WGM;
;         u.pm = fm + ((wgid % nig) % gsz); u.pn = (wgid % nig) / gsz; return true;
; template <class Epi, class Sched, bool ALIGN_EPI = false, bool SP2 = false>
; __device__ __forceinline__ void gemm_phase(PG8_LAS unsigned char* lds, const Gemm g, const Sched& S, const Epi& E) {
;     const int tid = threadIdx.x, wid = __builtin_amdgcn_readfirstlane(tid >> 6), lane = tid & 63, wr = wid >> 2, wc = wid & 3, fr = lane & 15, fq = lane >> 4;
;     const int K = g.K, nt = K / BK;
;     unsigned voffA[2], voffB[2];
; #pragma unroll
;     for (int i = 0; i < 2; ++i) { int R, C; stage_rc(tid * 16 + i * 8192, R, C); const int Rb = Epi::PERM ? ((R & ~31) + perm32(R & 31)) : R;
;         voffA[i] = (unsigned)(R * K + C) * 2u; voffB[i] = (unsigned)(Rb * K + C) * 2u; }
.LBB0_1150:
	s_mov_b64 s[0:1], s[56:57]
	s_movk_i32 s6, 0x400
	s_mov_b64 s[14:15], s[56:57]
	s_mov_b64 s[16:17], s[56:57]
	s_andn2_b64 vcc, exec, s[8:9]
	v_readfirstlane_b32 s22, v154
	s_cbranch_vccnz .LBB0_1179
	s_ashr_i32 s3, s2, 31
	s_mov_b64 s[12:13], s[86:87]
	s_nop 4
	s_mov_b64 s[10:11], s[86:87]
	s_nop 4
	s_lshr_b32 s7, s3, 29
	s_add_i32 s7, s2, s7
	s_and_b32 s8, s7, -8
	s_sub_i32 s17, s2, s8
	s_cmp_gt_i32 s17, -1
	s_cbranch_scc0 .LBB0_1153
	s_lshl_b32 s16, s17, 5
	s_mov_b64 s[8:9], s[86:87]
	s_nop 4
	s_cbranch_execz .LBB0_1154
	s_branch .LBB0_1155

; #define LAS __attribute__((address_space(3)))
; template <class EpiS>
; __device__ __forceinline__ void sgemm_phase(LAS unsigned char* lds, const bf16* A, const bf16* Bt, int N, int K, const EpiS& E, int bidx, int nb) {
;     const int tid = threadIdx.x, lane = tid & 63, wave = __builtin_amdgcn_readfirstlane(tid >> 6), li = lane & 15, lq = lane >> 4;
;     const int ntask = (N >> 4) * 4, kper = K >> 3;
;     LAS float* red = (LAS float*)lds;
;     for (int task = bidx; task < ntask; task += nb) {
;         const int ct = task >> 2, rt = task & 3;
;         const bf16* ap0 = A + (size_t)(rt * 32 + li) * K + wave * kper + 8 * lq; const bf16* ap1 = ap0 + (size_t)16 * K;
;         const bf16* bp = Bt + (size_t)(ct * 16 + li) * K + wave * kper + 8 * lq;
;         f32x4 acc0 = (f32x4){0.f, 0.f, 0.f, 0.f}, acc1 = acc0;
; __global__ void __launch_bounds__(NWAVES * 64, 2) mega_fwd(Args args) {
;     ...
;     if (IN(10)) { { SMerge ES{R3 + SOFF, R4 + SOFF}; sgemm_phase(lds, R1 + SOFF, WPS, 1024, 1024, ES, (int)blockIdx.x, G); }
.LBB0_1233:
	s_cmp_lt_i32 s64, 11
	s_cselect_b64 s[0:1], -1, 0
	s_and_b64 s[4:5], s[0:1], s[6:7]
	s_andn2_b64 vcc, exec, s[4:5]
	s_cbranch_vccnz .LBB0_1266
	s_cmpk_lt_i32 s2, 0x100
	s_mov_b64 s[0:1], s[56:57]
	s_mov_b64 s[6:7], s[56:57]
	s_mov_b64 s[12:13], s[56:57]
	s_mov_b64 s[10:11], s[56:57]
	s_cselect_b64 s[8:9], -1, 0
	s_cmpk_gt_i32 s2, 0xff
	v_readfirstlane_b32 s3, v154
	s_cbranch_scc1 .LBB0_1237
	s_mov_b64 s[14:15], s[86:87]
	s_nop 4
	s_mov_b64 s[16:17], s[86:87]
	s_nop 4
	s_mov_b64 s[18:19], s[86:87]
	s_nop 4
	v_bfe_u32 v7, v154, 4, 2
	s_mov_b64 s[0:1], s[86:87]
	s_nop 4
	s_waitcnt lgkmcnt(0)
	s_add_u32 s6, s14, 0xcd30000
	s_addc_u32 s7, s15, 0
	s_add_u32 s10, s16, 0xedb0000
	s_addc_u32 s11, s17, 0
	s_lshr_b32 s3, s3, 6
	s_lshl_b32 s14, s3, 8
	s_add_u32 s12, s18, s14
	s_addc_u32 s13, s19, 0
	s_add_u32 s0, s0, s14
	v_lshlrev_b32_e32 v0, 4, v7
	v_mov_b32_e32 v1, 0
	s_addc_u32 s1, s1, 0
	v_lshl_add_u64 v[4:5], s[0:1], 0, v[0:1]
	s_mov_b64 s[0:1], 0x24a0000
	v_lshl_add_u64 v[4:5], v[4:5], 0, s[0:1]
	s_lshl_b32 s0, s3, 11
	v_lshl_add_u64 v[2:3], s[12:13], 0, v[0:1]
	s_add_i32 s0, s0, 0
	v_lshlrev_b32_e32 v0, 8, v7
	v_lshlrev_b32_e32 v8, 2, v156
	s_mov_b64 s[12:13], 0x8c30000
	v_add3_u32 v8, s0, v0, v8
	v_lshrrev_b32_e32 v6, 4, v154
	v_lshl_add_u64 v[2:3], v[2:3], 0, s[12:13]
	v_lshl_add_u32 v7, v154, 2, 0
	s_lshl_b32 s0, s2, 2
	s_lshl_b32 s1, s88, 2
	s_lshl_b32 s3, s2, 5
	s_lshl_b32 s12, s88, 5
	v_add_u32_e32 v9, 0x400, v8
	s_mov_b32 s13, s2

;     __host__ __device__ bool next(int i, Unit& u) const {
;         const long L = (long)i * G + c; if (L >= nwg) return false;
;         int wgid = (int)L; { const int q = nwg / NXCD, r = nwg % NXCD, xcd = wgid % NXCD, off = wgid / NXCD; wgid = (xcd < r ? xcd * (q + 1) : r * (q + 1) + (xcd - r) * q) + off; }
;         const int nig = WGM * nN, gid = wgid / nig, fm = gid * WGM, gsz = (nM - fm) < WGM ? (nM - fm) : WGM;
;         u.pm = fm + ((wgid % nig) % gsz); u.pn = (wgid % nig) / gsz; return true;
; template <class Epi, class Sched, bool ALIGN_EPI = false, bool SP2 = false>
; __device__ __forceinline__ void gemm_phase(PG8_LAS unsigned char* lds, const Gemm g, const Sched& S, const Epi& E) {
;     const int tid = threadIdx.x, wid = __builtin_amdgcn_readfirstlane(tid >> 6), lane = tid & 63, wr = wid >> 2, wc = wid & 3, fr = lane & 15, fq = lane >> 4;
;     const int K = g.K, nt = K / BK;
;     unsigned voffA[2], voffB[2];
; #pragma unroll
;     for (int i = 0; i < 2; ++i) { int R, C; stage_rc(tid * 16 + i * 8192, R, C); const int Rb = Epi::PERM ? ((R & ~31) + perm32(R & 31)) : R;
;         voffA[i] = (unsigned)(R * K + C) * 2u; voffB[i] = (unsigned)(Rb * K + C) * 2u; }
;     const size_t kstep = (size_t)(BK * 2);
;     const size_t hstep = (size_t)HALF * K * 2;
;     const size_t tstep = 2 * hstep;
;     const unsigned ldsw = (unsigned)wid * 1024u;
;     const int aoff = lds_byte(wr * 64 + fr, fq * 8), boff = lds_byte(wc * 32 + fr, fq * 8);
;     ...
;     Unit cur, nxt; int ui = 0;
;     if (!S.next(0, cur)) return;
.LBB0_1237:
	s_mov_b64 s[0:1], s[56:57]
	s_mov_b64 s[10:11], s[56:57]
	s_movk_i32 s6, 0x400
	s_mov_b64 s[16:17], s[56:57]
	s_mov_b64 s[18:19], s[56:57]
	s_andn2_b64 vcc, exec, s[8:9]
	v_readfirstlane_b32 s24, v154
	s_cbranch_vccnz .LBB0_1266
	s_ashr_i32 s3, s2, 31
	s_mov_b64 s[14:15], s[86:87]
	s_nop 4
	s_mov_b64 s[12:13], s[86:87]
	s_nop 4
	s_lshr_b32 s7, s3, 29
	s_add_i32 s7, s2, s7
	s_and_b32 s8, s7, -8
	s_sub_i32 s21, s2, s8
	s_cmp_gt_i32 s21, -1
	s_cbranch_scc0 .LBB0_1240
	s_lshl_b32 s20, s21, 5
	s_mov_b64 s[16:17], s[86:87]
	s_nop 4
	s_mov_b64 s[8:9], s[86:87]
	s_nop 4
	s_cbranch_execz .LBB0_1241
	s_branch .LBB0_1242
.LBB0_1240:
	s_mov_b64 s[16:17], s[86:87]
	s_nop 4
	s_mov_b64 s[8:9], s[86:87]
	s_nop 4

; #define LAS __attribute__((address_space(3)))
; template <class EpiS>
; __device__ __forceinline__ void sgemm_phase(LAS unsigned char* lds, const bf16* A, const bf16* Bt, int N, int K, const EpiS& E, int bidx, int nb) {
;     const int tid = threadIdx.x, lane = tid & 63, wave = __builtin_amdgcn_readfirstlane(tid >> 6), li = lane & 15, lq = lane >> 4;
;     const int ntask = (N >> 4) * 4, kper = K >> 3;
;     LAS float* red = (LAS float*)lds;
;     for (int task = bidx; task < ntask; task += nb) {
;         const int ct = task >> 2, rt = task & 3;
;         const bf16* ap0 = A + (size_t)(rt * 32 + li) * K + wave * kper + 8 * lq; const bf16* ap1 = ap0 + (size_t)16 * K;
;         const bf16* bp = Bt + (size_t)(ct * 16 + li) * K + wave * kper + 8 * lq;
; __global__ void __launch_bounds__(NWAVES * 64, 2) mega_fwd(Args args) {
;     ...
;     if (IN(11)) { { SResB ES{XB + SOFF, RES + SOFF, ALPHA, 1.0f}; sgemm_phase(lds, R4 + SOFF, WO, 1024, 1024, ES, (int)blockIdx.x, G); }
.LBB0_1320:
	s_cmp_lt_i32 s64, 12
	s_cselect_b64 s[0:1], -1, 0
	s_and_b64 s[4:5], s[0:1], s[6:7]
	s_andn2_b64 vcc, exec, s[4:5]
	s_cbranch_vccnz .LBB0_1391
	s_cmpk_lt_i32 s2, 0x100
	s_mov_b64 s[0:1], s[56:57]
	s_mov_b64 s[6:7], s[56:57]
	s_mov_b64 s[10:11], s[56:57]
	s_mov_b64 s[12:13], s[56:57]
	s_cselect_b64 s[8:9], -1, 0
	s_cmpk_gt_i32 s2, 0xff
	v_readfirstlane_b32 s3, v154
	s_cbranch_scc1 .LBB0_1324
	s_mov_b64 s[14:15], s[86:87]
	s_nop 4
	s_load_dwordx2 s[16:17], s[6:7], 0x100
	s_mov_b64 s[18:19], s[86:87]
	s_nop 4
	v_bfe_u32 v7, v154, 4, 2
	s_mov_b64 s[0:1], s[86:87]
	s_nop 4
	s_waitcnt lgkmcnt(0)
	s_add_u32 s6, s14, 0x4b30000
	s_addc_u32 s7, s15, 0
	s_add_u32 s10, s16, 0x4000000
	s_addc_u32 s11, s17, 0
	s_lshr_b32 s3, s3, 6
	s_lshl_b32 s14, s3, 8
	s_add_u32 s12, s18, s14
	s_addc_u32 s13, s19, 0
	s_add_u32 s0, s0, s14
	v_lshlrev_b32_e32 v0, 4, v7
	v_mov_b32_e32 v1, 0
	s_addc_u32 s1, s1, 0
	v_lshl_add_u64 v[4:5], s[0:1], 0, v[0:1]
	s_mov_b64 s[0:1], 0x26a0000
	v_lshl_add_u64 v[4:5], v[4:5], 0, s[0:1]
	s_lshl_b32 s0, s3, 11
	v_lshl_add_u64 v[2:3], s[12:13], 0, v[0:1]
	s_add_i32 s0, s0, 0
	v_lshlrev_b32_e32 v0, 8, v7
	v_lshlrev_b32_e32 v8, 2, v156
	s_mov_b64 s[12:13], 0xedb0000
	v_add3_u32 v8, s0, v0, v8
	v_lshrrev_b32_e32 v6, 4, v154
	v_lshl_add_u64 v[2:3], v[2:3], 0, s[12:13]
	v_lshl_add_u32 v7, v154, 2, 0
	s_lshl_b32 s0, s2, 2
	s_lshl_b32 s1, s88, 2
	s_lshl_b32 s3, s2, 5
	s_lshl_b32 s12, s88, 5
	v_add_u32_e32 v9, 0x400, v8
	s_mov_b32 s13, s2

;     __host__ __device__ bool next(int i, Unit& u) const {
;         const long L = (long)i * G + c; if (L >= nwg) return false;
;         int wgid = (int)L; { const int q = nwg / NXCD, r = nwg % NXCD, xcd = wgid % NXCD, off = wgid / NXCD; wgid = (xcd < r ? xcd * (q + 1) : r * (q + 1) + (xcd - r) * q) + off; }
;         const int nig = WGM * nN, gid = wgid / nig, fm = gid * WGM, gsz = (nM - fm) < WGM ? (nM - fm) : WGM;
;         u.pm = fm + ((wgid % nig) % gsz); u.pn = (wgid % nig) / gsz; return true;
; template <class Epi, class Sched, bool ALIGN_EPI = false, bool SP2 = false>
; __device__ __forceinline__ void gemm_phase(PG8_LAS unsigned char* lds, const Gemm g, const Sched& S, const Epi& E) {
;     const int tid = threadIdx.x, wid = __builtin_amdgcn_readfirstlane(tid >> 6), lane = tid & 63, wr = wid >> 2, wc = wid & 3, fr = lane & 15, fq = lane >> 4;
;     const int K = g.K, nt = K / BK;
;     unsigned voffA[2], voffB[2];
; #pragma unroll
;     for (int i = 0; i < 2; ++i) { int R, C; stage_rc(tid * 16 + i * 8192, R, C); const int Rb = Epi::PERM ? ((R & ~31) + perm32(R & 31)) : R;
;         voffA[i] = (unsigned)(R * K + C) * 2u; voffB[i] = (unsigned)(Rb * K + C) * 2u; }
;     const size_t kstep = (size_t)(BK * 2);
;     const size_t hstep = (size_t)HALF * K * 2;
;     const size_t tstep = 2 * hstep;
;     const unsigned ldsw = (unsigned)wid * 1024u;
;     const int aoff = lds_byte(wr * 64 + fr, fq * 8), boff = lds_byte(wc * 32 + fr, fq * 8);
;     ...
;     Unit cur, nxt; int ui = 0;
;     if (!S.next(0, cur)) return;
.LBB0_1324:
	s_mov_b64 s[12:13], s[56:57]
	s_mov_b64 s[10:11], s[56:57]
	s_mov_b64 s[22:23], s[56:57]
	s_mov_b64 s[14:15], s[56:57]
	s_mov_b64 s[16:17], s[56:57]
	s_mov_b64 s[36:37], s[56:57]
	s_movk_i32 s6, 0x400
	s_mov_b64 s[18:19], s[56:57]
	s_mov_b64 s[20:21], s[56:57]
	s_andn2_b64 vcc, exec, s[8:9]
	v_readfirstlane_b32 s3, v154
	s_cbranch_vccnz .LBB0_1391
	s_ashr_i32 s49, s2, 31
	s_mov_b64 s[8:9], s[86:87]
	s_nop 4
	s_mov_b64 s[0:1], s[86:87]
	s_nop 4
	s_lshr_b32 s7, s49, 29
	s_add_i32 s7, s2, s7
	s_and_b32 s18, s7, -8
	s_sub_i32 s21, s2, s18
	s_cmp_gt_i32 s21, -1
	s_cbranch_scc0 .LBB0_1327
	s_lshl_b32 s20, s21, 5
	s_cbranch_execz .LBB0_1328
	s_branch .LBB0_1329

; #define PG8_STAGE(bufoff, gbase, voff) do { _Pragma("unroll") for (int _i = 0; _i < 2; ++_i) \
;         __builtin_amdgcn_global_load_lds((const unsigned*)((const char*)(gbase) + (voff)[_i]), (PG8_LAS unsigned*)(lds + (bufoff) + ldsw + _i * 8192), 16, 0, 0); } while (0)
; #define PG8_WAIT_V(n) asm volatile("s_waitcnt vmcnt(" #n ")" ::: "memory")
; #define PG8_BAR __builtin_amdgcn_s_barrier()
; __device__ __forceinline__ const float* arg_in(int k) { return (const float*)(const __attribute__((address_space(1))) float*)arg_q(k); }
; #define GEMMF(EpiT, E, Aop, Bop, M_, N_, K_) do { int k_ = K_; asm volatile("" : "+s"(k_)); pg8::Gemm g_{Aop, Bop, M_, N_, k_}; pg8::StaticOrder S_; S_.init(M_, N_, G, (int)blockIdx.x); \
;         pg8::gemm_phase<EpiT, pg8::StaticOrder, false, true>(lds, g_, S_, E); } while (0)
; template <class Epi, class Sched, bool ALIGN_EPI = false, bool SP2 = false>
; __device__ __forceinline__ void gemm_phase(PG8_LAS unsigned char* lds, const Gemm g, const Sched& S, const Epi& E) {
;     ...
;     const char* cA = (const char*)g.A + (size_t)cur.pm * tstep; const char* cB = (const char*)g.Bt + (size_t)cur.pn * tstep;
;     S.a_ready(cur);
;     if constexpr (SP2) {
;         PG8_STAGE(PG8_SB(0, 0), cB, voffB); PG8_STAGE(PG8_SB(0, 1), cB + hstep, voffB); PG8_STAGE(PG8_SA(0, 0), cA, voffA); PG8_STAGE(PG8_SA(0, 1), cA + hstep, voffA);
;         if (wr == 1) PG8_BAR;
;         PG8_WAIT_V(2); PG8_BAR;
; __global__ void __launch_bounds__(NWAVES * 64, 2) mega_fwd(Args args) {
;     ...
;         EpiLn<1> E{nullptr, XB, nullptr, nullptr, arg_in(21), arg_in(22), 1.0f, PSTAT(1)}; GEMMF(EpiLn<1>, E, R4, WO, MPROMPT, 1024, 1024); }
.LBB0_1329:
	s_ashr_i32 s18, s7, 3
	s_waitcnt lgkmcnt(0)
	s_add_u32 s50, s8, 0xcdb0000
	v_lshrrev_b32_e32 v149, 1, v154
	v_lshrrev_b32_e32 v4, 5, v154
	s_addc_u32 s51, s9, 0
	v_lshlrev_b32_e32 v0, 4, v154
	v_and_b32_e32 v1, 32, v154
	v_and_b32_e32 v3, 24, v149
	v_and_b32_e32 v4, 4, v4
	v_bfe_u32 v5, v154, 2, 2
	s_add_u32 s52, s0, 0x26a0000
	v_bitop3_b32 v1, v0, v1, 48 bitop3:0x6c
	v_or3_b32 v3, v4, v5, v3
	v_lshrrev_b32_e32 v4, 3, v154
	s_movk_i32 s0, 0x60
	v_add_u32_e32 v0, 0x2000, v0
	v_and_b32_e32 v16, 0x70, v4
	v_and_or_b32 v4, v4, s0, v3
	v_lshrrev_b32_e32 v0, 7, v0
	s_movk_i32 s0, 0xe0
	s_addc_u32 s53, s1, 0
	v_and_b32_e32 v17, 0xf0, v0
	v_and_or_b32 v0, v0, s0, v3
	s_add_i32 s0, s20, s18
	s_ashr_i32 s1, s0, 31
	s_lshr_b32 s1, s1, 27
	s_add_i32 s1, s0, s1
	s_ashr_i32 s8, s1, 5
	s_andn2_b32 s1, s1, 31
	s_sub_i32 s0, s0, s1
	s_bfe_i32 s1, s0, 0x80000
	s_bfe_u32 s1, s1, 0x3000c
	s_add_i32 s1, s0, s1
	s_lshl_b32 s9, s8, 3
	s_bfe_i32 s8, s1, 0x80000
	s_and_b32 s1, s1, 0xf8
	s_sub_i32 s0, s0, s1
	s_sext_i32_i8 s0, s0
	s_ashr_i32 s7, s6, 31
	s_add_i32 s46, s9, s0
	s_lshl_b64 s[26:27], s[6:7], 9
	s_ashr_i32 s0, s46, 31
	s_mul_i32 s0, s26, s0
	s_mul_hi_u32 s1, s26, s46
	s_add_i32 s9, s1, s0
	s_lshr_b64 s[0:1], s[6:7], 23
	s_sext_i32_i16 s20, s8
	s_mul_i32 s1, s0, s46
	s_lshr_b32 s8, s20, 3
	s_add_i32 s9, s9, s1
	s_bfe_i64 s[18:19], s[8:9], 0x100000
	s_ashr_i32 s1, s20, 3
	s_mul_hi_u32 s18, s26, s1
	s_mul_i32 s19, s26, s19
	s_lshr_b32 s47, s3, 6
	s_add_i32 s18, s18, s19
	s_mul_i32 s0, s0, s1
	s_lshr_b32 s48, s3, 8
	v_and_b32_e32 v14, 64, v154
	s_lshl_b64 s[24:25], s[6:7], 8
	s_lshl_b32 s54, s47, 10
	s_add_i32 s18, s18, s0
	s_mul_i32 s0, s26, s1
	v_or_b32_e32 v2, v1, v14
	s_add_u32 s28, s52, s0
	v_lshrrev_b32_e32 v2, 1, v2
	v_mul_lo_u32 v4, s6, v4
	s_addc_u32 s29, s53, s18
	s_add_i32 s55, s54, 0
	v_add_lshl_u32 v134, v4, v2, 1
	s_add_i32 m0, s55, 0x10000
	v_mul_lo_u32 v0, s6, v0
	global_load_lds_dwordx4 v134, s[28:29]
	s_add_i32 m0, s55, 0x12000
	v_add_lshl_u32 v138, v0, v2, 1
	s_add_u32 s0, s28, s24
	global_load_lds_dwordx4 v138, s[28:29]
	s_addc_u32 s1, s29, s25
	s_add_i32 m0, s55, 0x14000
	v_bfe_u32 v15, v154, 2, 4
	s_mul_i32 s21, s26, s46
	global_load_lds_dwordx4 v134, s[0:1]
	s_add_i32 m0, s55, 0x16000
	v_or_b32_e32 v5, v16, v15
	s_add_u32 s34, s50, s21
	v_mul_lo_u32 v5, s6, v5
	v_or_b32_e32 v4, v17, v15
	s_addc_u32 s35, s51, s9
	s_add_i32 s58, s55, 0x2000
	v_add_lshl_u32 v132, v5, v2, 1
	v_mul_lo_u32 v3, s6, v4
	global_load_lds_dwordx4 v138, s[0:1]
	s_mov_b32 m0, s55
	s_add_u32 s18, s34, s24
	v_add_lshl_u32 v136, v3, v2, 1
	global_load_lds_dwordx4 v132, s[34:35]
	s_mov_b32 m0, s58
	s_addc_u32 s19, s35, s25
	s_add_i32 s59, s55, 0x4000
	global_load_lds_dwordx4 v136, s[34:35]
	s_mov_b32 m0, s59
	s_add_i32 s60, s55, 0x6000
	global_load_lds_dwordx4 v132, s[18:19]
	s_mov_b32 m0, s60
	v_mov_b32_e32 v0, 0
	global_load_lds_dwordx4 v136, s[18:19]
	s_mov_b64 s[30:31], s[86:87]
	s_nop 4
	s_mov_b64 s[20:21], s[86:87]
	s_nop 4
	s_mov_b64 s[18:19], s[86:87]
	s_nop 4
	s_nop 0
	s_mov_b64 s[16:17], s[86:87]
	s_nop 4
	s_load_dwordx2 s[14:15], s[10:11], 0xa8
	s_load_dwordx2 s[12:13], s[22:23], 0xb0
	v_mov_b32_e32 v135, v0
	v_mov_b32_e32 v139, v0
	v_mov_b32_e32 v133, v0
	v_mov_b32_e32 v137, v0
	v_lshl_add_u64 v[12:13], s[28:29], 0, v[134:135]
	v_lshl_add_u64 v[8:9], s[28:29], 0, v[138:139]
	v_lshl_add_u64 v[4:5], s[0:1], 0, v[134:135]
	v_lshl_add_u64 v[2:3], s[0:1], 0, v[138:139]
	v_lshl_add_u64 v[10:11], s[34:35], 0, v[132:133]
	s_cmp_lg_u32 s48, 1
	v_lshl_add_u64 v[6:7], s[34:35], 0, v[136:137]
	s_cbranch_scc1 .LBB0_1331
	s_barrier

; #define LAS __attribute__((address_space(3)))
; __device__ __forceinline__ const float* arg_in(int k) { return (const float*)(const __attribute__((address_space(1))) float*)arg_q(k); }
; template <bool WRITE_BF16, bool DO_BA, bool WRITE_F32>
; __device__ __forceinline__ void ln_phase(int m_lo, float* RES, const float* g, const float* b, bf16* XB, const LAS float* wba, const float* A_log, const float* dt_bias, float* BETA, float* GG, int gw, int NGW, int lane) {
;     f32x4 gv[4], bv[4];
; #pragma unroll
;     for (int j = 0; j < 4; ++j) { gv[j] = *((const f32x4*)g + 64 * j + lane); bv[j] = *((const f32x4*)b + 64 * j + lane); }
;     for (int m = m_lo + gw; m < MREAL; m += NGW) {
;         f32x4* xr = (f32x4*)(RES + (size_t)m * D) + lane;
;         f32x4 v[4]; float s = 0.f;
; #pragma unroll
;         for (int j = 0; j < 4; ++j) { v[j] = xr[64 * j]; s += (v[j][0] + v[j][1]) + (v[j][2] + v[j][3]); }
;         const float mean = wave_sum(s) * (1.f / D); float s2 = 0.f;
; #pragma unroll
;         for (int j = 0; j < 4; ++j) { v[j] = v[j] - mean; s2 += (v[j][0] * v[j][0] + v[j][1] * v[j][1]) + (v[j][2] * v[j][2] + v[j][3] * v[j][3]); }
;         const float rstd = 1.f / sqrtf(wave_sum(s2) * (1.f / D) + 1e-5f);
; #pragma unroll
;         for (int j = 0; j < 4; ++j) { v[j] = v[j] * rstd * gv[j] + bv[j]; if (WRITE_F32) xr[64 * j] = v[j]; }
;         if (WRITE_BF16) {
;             u32x2* o8 = (u32x2*)(XB + (size_t)m * D) + lane;
; #pragma unroll
;             for (int j = 0; j < 4; ++j) { u32x2 w; w.x = cvt_pk_bf16(v[j][0], v[j][1]); w.y = cvt_pk_bf16(v[j][2], v[j][3]); o8[64 * j] = w; }
;         }
; __global__ void __launch_bounds__(NWAVES * 64, 2) mega_fwd(Args args) {
;     ...
;     if (IN(12)) { ln_phase<true, false, false>(MPROMPT, RES, arg_in(21), arg_in(22), XB, nullptr, nullptr, nullptr, nullptr, nullptr, gw, NGW, lane);
.LBB0_1445:
	s_cmp_lt_i32 s64, 13
	s_cselect_b64 s[0:1], -1, 0
	s_and_b64 s[8:9], s[0:1], s[6:7]
	s_andn2_b64 vcc, exec, s[8:9]
	s_cbranch_vccnz .LBB0_1456
	s_mov_b64 s[0:1], s[56:57]
	s_mov_b64 s[6:7], s[56:57]
	s_mov_b64 s[10:11], s[56:57]
	s_mov_b64 s[4:5], s[56:57]
	s_cmpk_gt_i32 s94, 0x7f
	v_mov_b32_e32 v33, 0
	s_cbranch_scc1 .LBB0_1449
	s_load_dwordx2 s[12:13], s[10:11], 0xb0
	s_load_dwordx2 s[14:15], s[6:7], 0xa8
	v_lshlrev_b32_e32 v32, 4, v152
	v_mbcnt_lo_u32_b32 v34, -1, 0
	v_mbcnt_hi_u32_b32 v34, -1, v34
	v_and_b32_e32 v35, 64, v34
	s_waitcnt lgkmcnt(0)
	global_load_dwordx4 v[0:3], v32, s[12:13]
	global_load_dwordx4 v[4:7], v32, s[12:13] offset:1024
	global_load_dwordx4 v[8:11], v32, s[14:15] offset:2048
	global_load_dwordx4 v[12:15], v32, s[14:15] offset:3072
	global_load_dwordx4 v[16:19], v32, s[12:13] offset:2048
	global_load_dwordx4 v[20:23], v32, s[12:13] offset:3072
	global_load_dwordx4 v[24:27], v32, s[14:15] offset:1024
	global_load_dwordx4 v[28:31], v32, s[14:15]
	v_add_u32_e32 v35, 64, v35
	v_xor_b32_e32 v36, 1, v34
	v_cmp_lt_i32_e32 vcc, v36, v35
	s_load_dwordx2 s[6:7], s[0:1], 0x100
	s_mov_b64 s[10:11], s[86:87]
	s_nop 4
	v_cndmask_b32_e32 v36, v34, v36, vcc
	v_lshlrev_b32_e32 v52, 2, v36
	v_xor_b32_e32 v36, 2, v34
	v_cmp_lt_i32_e32 vcc, v36, v35
	s_add_i32 s4, s94, 0x4000
	s_ashr_i32 s5, s4, 31
	v_cndmask_b32_e32 v36, v34, v36, vcc
	v_lshlrev_b32_e32 v53, 2, v36
	v_xor_b32_e32 v36, 4, v34
	v_cmp_lt_i32_e32 vcc, v36, v35
	s_lshl_b64 s[0:1], s[4:5], 11
	s_waitcnt lgkmcnt(0)
	s_add_u32 s0, s10, s0
	v_cndmask_b32_e32 v36, v34, v36, vcc
	v_lshlrev_b32_e32 v54, 2, v36
	v_xor_b32_e32 v36, 8, v34
	v_cmp_lt_i32_e32 vcc, v36, v35
	s_addc_u32 s1, s11, s1
	s_ashr_i32 s79, s78, 31
	v_cndmask_b32_e32 v36, v34, v36, vcc
	v_lshlrev_b32_e32 v55, 2, v36
	v_xor_b32_e32 v36, 16, v34
	v_cmp_lt_i32_e32 vcc, v36, v35
	s_lshl_b64 s[10:11], s[78:79], 11
	v_mov_b32_e32 v58, 0x3727c5ac
	v_cndmask_b32_e32 v36, v34, v36, vcc
	v_lshlrev_b32_e32 v56, 2, v36
	v_xor_b32_e32 v36, 32, v34
	v_cmp_lt_i32_e32 vcc, v36, v35
	v_mov_b32_e32 v35, v33
	v_mov_b32_e32 v59, 0x260
	v_cndmask_b32_e32 v34, v34, v36, vcc
	v_lshlrev_b32_e32 v57, 2, v34
	v_lshlrev_b32_e32 v34, 3, v152
	v_lshl_add_u64 v[34:35], s[0:1], 0, v[34:35]
	s_mov_b64 s[0:1], 0x2b30000
	v_lshl_add_u64 v[48:49], v[34:35], 0, s[0:1]
	s_lshl_b64 s[0:1], s[4:5], 12
	s_add_u32 s0, s6, s0
	s_addc_u32 s1, s7, s1
	v_lshl_add_u64 v[32:33], s[0:1], 0, v[32:33]
	s_mov_b64 s[0:1], 0xc00
	v_lshl_add_u64 v[50:51], v[32:33], 0, s[0:1]
	s_lshl_b64 s[12:13], s[78:79], 12
	s_mov_b32 s0, 0xf800000

; __device__ __forceinline__ const float* arg_in(int k) { return (const float*)(const __attribute__((address_space(1))) float*)arg_q(k); }
; template <int W>
; __device__ __forceinline__ void cvt_rows(const float* srcP, const float* srcS, bf16* dst, int gw, int NGW, int lane) {
;     for (int m = gw; m < MP; m += NGW) {
;         const float* src = m < MPROMPT ? srcP + (size_t)m * W : srcS + (size_t)(m - MPROMPT) * W;
; #pragma unroll
;         for (int j = 0; j < W / 256; ++j) { f32x4 v = (f32x4){0.f, 0.f, 0.f, 0.f}; if (m < MREAL) v = __builtin_nontemporal_load((const f32x4*)src + 64 * j + lane);
;             u32x2 w; w.x = cvt_pk_bf16(v[0], v[1]); w.y = cvt_pk_bf16(v[2], v[3]); *((u32x2*)(dst + (size_t)m * W) + 64 * j + lane) = w; }
;     }
; __global__ void __launch_bounds__(NWAVES * 64, 2) mega_fwd(Args args) {
;     ...
;         cvt_rows<256>(arg_in(2), arg_in(3), PBUF, gw, NGW, lane); }
.LBB0_1449:
	s_mov_b64 s[0:1], s[56:57]
	s_mov_b64 s[6:7], s[56:57]
	s_mov_b64 s[10:11], s[56:57]
	s_cmpk_gt_i32 s94, 0x40ff
	s_cbranch_scc1 .LBB0_1456
	s_mov_b64 s[12:13], s[86:87]
	s_nop 4
	s_load_dwordx2 s[14:15], s[0:1], 0x10
	s_load_dwordx2 s[4:5], s[6:7], 0x18
	v_lshlrev_b32_e32 v0, 3, v152
	v_mov_b32_e32 v1, 0
	s_waitcnt lgkmcnt(0)
	v_lshl_add_u64 v[0:1], s[12:13], 0, v[0:1]
	s_mov_b64 s[0:1], 0xee30000
	s_ashr_i32 s95, s94, 31
	v_lshl_add_u64 v[4:5], v[0:1], 0, s[0:1]
	s_ashr_i32 s79, s78, 31
	s_lshl_b64 s[0:1], s[94:95], 10
	s_add_u32 s6, s14, s0
	s_addc_u32 s7, s15, s1
	s_lshl_b64 s[10:11], s[78:79], 10
	s_mov_b32 s13, 0
	v_lshlrev_b32_e32 v6, 4, v152
	s_mov_b64 s[14:15], s[94:95]
	s_branch .LBB0_1452

; #define GEMM(EpiT, E, Aop, Bop, M_, N_, K_) do { int k_ = K_; asm volatile("" : "+s"(k_)); pg8::Gemm g_{Aop, Bop, M_, N_, k_}; pg8::StaticOrder S_; S_.init(M_, N_, G, (int)blockIdx.x); \
;         pg8::gemm_phase<EpiT, pg8::StaticOrder, true, true>(lds, g_, S_, E); } while (0)
;     __host__ __device__ bool next(int i, Unit& u) const {
;         const long L = (long)i * G + c; if (L >= nwg) return false;
;         int wgid = (int)L; { const int q = nwg / NXCD, r = nwg % NXCD, xcd = wgid % NXCD, off = wgid / NXCD; wgid = (xcd < r ? xcd * (q + 1) : r * (q + 1) + (xcd - r) * q) + off; }
;         const int nig = WGM * nN, gid = wgid / nig, fm = gid * WGM, gsz = (nM - fm) < WGM ? (nM - fm) : WGM;
;         u.pm = fm + ((wgid % nig) % gsz); u.pn = (wgid % nig) / gsz; return true;
; __global__ void __launch_bounds__(NWAVES * 64, 2) mega_fwd(Args args) {
;     ...
;     if (IN(13)) { EpiGU E{R0}; GEMM(EpiGU, E, XB, WGU, MP, 5632, 1024);
.LBB0_1510:
	s_cmp_lt_i32 s64, 14
	s_cselect_b64 s[0:1], -1, 0
	s_and_b64 s[4:5], s[0:1], s[4:5]
	s_andn2_b64 vcc, exec, s[4:5]
	s_cbranch_vccnz .LBB0_1609
	v_lshlrev_b32_e32 v0, 4, v154
	v_and_b32_e32 v1, 32, v154
	v_bitop3_b32 v144, v0, v1, 48 bitop3:0x6c
	v_and_b32_e32 v145, 64, v154
	v_or_b32_e32 v1, v144, v145
	v_lshrrev_b32_e32 v153, 1, v1
	v_lshrrev_b32_e32 v1, 5, v154
	v_lshrrev_b32_e32 v3, 1, v154
	v_and_b32_e32 v1, 4, v1
	v_bfe_u32 v2, v154, 2, 2
	v_and_b32_e32 v147, 24, v3
	v_or3_b32 v1, v1, v2, v147
	v_lshrrev_b32_e32 v2, 3, v154
	s_movk_i32 s3, 0x60
	v_add_u32_e32 v0, 0x2000, v0
	v_and_or_b32 v157, v2, s3, v1
	v_lshrrev_b32_e32 v0, 7, v0
	s_movk_i32 s3, 0xe0
	v_and_b32_e32 v148, 0xf0, v0
	v_and_or_b32 v159, v0, s3, v1
	v_lshlrev_b32_e32 v0, 6, v154
	v_lshlrev_b32_e32 v1, 2, v154
	v_bfe_u32 v146, v154, 2, 4
	v_and_b32_e32 v149, 0x70, v2
	v_lshlrev_b32_e32 v150, 1, v147
	v_and_b32_e32 v0, 0x3c0, v0
	v_and_b32_e32 v1, 32, v1
	s_mov_b64 s[8:9], s[56:57]
	s_movk_i32 s6, 0x400
	s_mov_b64 s[0:1], s[56:57]
	s_mov_b64 s[12:13], s[56:57]
	v_readfirstlane_b32 s22, v154
	v_or_b32_e32 v155, v149, v146
	v_or_b32_e32 v158, v148, v146
	s_cmpk_gt_i32 s2, 0x595
	v_bitop3_b32 v151, v150, v1, v0 bitop3:0x36
	s_cbranch_scc1 .LBB0_1540
	s_ashr_i32 s3, s2, 31
	s_mov_b64 s[14:15], s[86:87]
	s_nop 4
	s_mov_b64 s[10:11], s[86:87]
	s_nop 4
	s_lshr_b32 s0, s3, 29
	s_add_i32 s7, s2, s0
	s_and_b32 s0, s7, -8
	s_sub_i32 s12, s2, s0
	s_cmp_gt_i32 s12, 5
	s_cbranch_scc0 .LBB0_1514
	s_mul_i32 s0, s12, 0xb2
	s_add_i32 s16, s0, 6
	s_mov_b64 s[8:9], s[86:87]
	s_nop 4
	s_cbranch_execz .LBB0_1515
	s_branch .LBB0_1516

; #define LAS __attribute__((address_space(3)))
; template <class EpiS>
; __device__ __forceinline__ void sgemm_phase(LAS unsigned char* lds, const bf16* A, const bf16* Bt, int N, int K, const EpiS& E, int bidx, int nb) {
;     const int tid = threadIdx.x, lane = tid & 63, wave = __builtin_amdgcn_readfirstlane(tid >> 6), li = lane & 15, lq = lane >> 4;
;     const int ntask = (N >> 4) * 4, kper = K >> 3;
;     LAS float* red = (LAS float*)lds;
;     for (int task = bidx; task < ntask; task += nb) {
;         const int ct = task >> 2, rt = task & 3;
;         const bf16* ap0 = A + (size_t)(rt * 32 + li) * K + wave * kper + 8 * lq; const bf16* ap1 = ap0 + (size_t)16 * K;
;         const bf16* bp = Bt + (size_t)(ct * 16 + li) * K + wave * kper + 8 * lq;
; __global__ void __launch_bounds__(NWAVES * 64, 2) mega_fwd(Args args) {
;     ...
;         const int nfull = (65 * 22) % G;
;         if (nfull && (int)blockIdx.x >= nfull) { const int bi = (int)blockIdx.x - nfull, nbi = G - nfull;
;             { SStore ES{R4 + SOFF}; sgemm_phase(lds, PBUF + (size_t)MPROMPT * 256, WPLEP, 1024, 256, ES, bi, nbi); }
.LBB0_1540:
	s_abs_i32 s0, s88
	v_cvt_f32_u32_e32 v0, s0
	s_sub_i32 s1, 0, s0
	v_rcp_iflag_f32_e32 v0, v0
	s_nop 0
	v_mul_f32_e32 v0, 0x4f7ffffe, v0
	v_cvt_u32_f32_e32 v0, v0
	s_nop 0
	v_readfirstlane_b32 s3, v0
	s_mul_i32 s1, s1, s3
	s_mul_hi_u32 s1, s3, s1
	s_add_i32 s3, s3, s1
	s_mul_hi_u32 s1, s3, 0x596
	s_mul_i32 s1, s1, s0
	s_sub_i32 s1, 0x596, s1
	s_sub_i32 s3, s1, s0
	s_cmp_ge_u32 s1, s0
	s_cselect_b32 s1, s3, s1
	s_sub_i32 s3, s1, s0
	s_cmp_ge_u32 s1, s0
	s_cselect_b32 s7, s3, s1
	s_cmp_eq_u32 s7, 0
	s_cbranch_scc1 .LBB0_1548
	s_cmp_lt_i32 s2, s7
	s_cbranch_scc1 .LBB0_1576
	s_sub_i32 s3, s2, s7
	s_sub_i32 s40, s88, s7
	s_cmpk_lt_i32 s3, 0x100
	s_mov_b64 s[0:1], s[56:57]
	s_mov_b64 s[10:11], s[56:57]
	s_mov_b64 s[12:13], s[56:57]
	v_readfirstlane_b32 s14, v154
	s_cselect_b64 s[8:9], -1, 0
	s_cmpk_gt_i32 s3, 0xff
	s_movk_i32 s6, 0x100
	s_cbranch_scc1 .LBB0_1545
	s_mov_b64 s[16:17], s[86:87]
	s_nop 4
	s_mov_b64 s[18:19], s[86:87]
	s_nop 4
	v_bfe_u32 v7, v154, 4, 2
	s_mov_b64 s[0:1], s[86:87]
	s_nop 4
	v_lshlrev_b32_e32 v0, 4, v7
	s_waitcnt lgkmcnt(0)
	s_add_u32 s10, s16, 0xedb0000
	s_addc_u32 s11, s17, 0
	s_and_b32 s15, s14, 0xffffffc0
	s_add_u32 s12, s18, s15
	s_addc_u32 s13, s19, 0
	s_add_u32 s0, s0, s15
	v_mov_b32_e32 v1, 0
	s_addc_u32 s1, s1, 0
	v_lshl_add_u64 v[4:5], s[0:1], 0, v[0:1]
	s_mov_b64 s[0:1], 0x2aa0000
	v_lshl_add_u64 v[4:5], v[4:5], 0, s[0:1]
	s_lshl_b32 s0, s14, 5
	s_and_b32 s0, s0, 0xfffff800
	v_lshl_add_u64 v[2:3], s[12:13], 0, v[0:1]
	s_mov_b64 s[12:13], 0xf630000
	s_add_i32 s0, s0, 0
	v_lshlrev_b32_e32 v0, 8, v7
	v_lshlrev_b32_e32 v8, 2, v156
	v_lshl_add_u64 v[2:3], v[2:3], 0, s[12:13]
	v_add3_u32 v8, s0, v0, v8
	s_lshl_b32 s0, s2, 2
	s_lshl_b32 s1, s7, 2
	s_lshl_b32 s12, s88, 2
	s_sub_i32 s0, s0, s1
	s_sub_i32 s1, s12, s1
	s_lshl_b32 s12, s2, 5
	s_lshl_b32 s13, s7, 5
	s_sub_i32 s7, s12, s13
	s_lshl_b32 s12, s88, 5
	v_lshrrev_b32_e32 v6, 4, v154
	v_lshl_add_u32 v7, v154, 2, 0
	s_sub_i32 s12, s12, s13
	v_add_u32_e32 v9, 0x400, v8
	s_mov_b32 s13, s3

;     __host__ __device__ bool next(int i, Unit& u) const {
;         const long L = (long)i * G + c; if (L >= nwg) return false;
;         int wgid = (int)L; { const int q = nwg / NXCD, r = nwg % NXCD, xcd = wgid % NXCD, off = wgid / NXCD; wgid = (xcd < r ? xcd * (q + 1) : r * (q + 1) + (xcd - r) * q) + off; }
;         const int nig = WGM * nN, gid = wgid / nig, fm = gid * WGM, gsz = (nM - fm) < WGM ? (nM - fm) : WGM;
;         u.pm = fm + ((wgid % nig) % gsz); u.pn = (wgid % nig) / gsz; return true;
; __global__ void __launch_bounds__(NWAVES * 64, 2) mega_fwd(Args args) {
;     ...
;             int k_ = 256; asm volatile("" : "+s"(k_)); pg8::Gemm g_{PBUF, WPLEP, MPROMPT, 1024, k_}; pg8::StaticOrder S_; S_.init(MPROMPT, 1024, nbi, bi);
;             EpiStore E2{R4}; pg8::gemm_phase<EpiStore, pg8::StaticOrder, true, true>(lds, g_, S_, E2); }
.LBB0_1545:
	s_mov_b64 s[14:15], s[56:57]
	s_mov_b64 s[16:17], s[56:57]
	s_mov_b64 s[12:13], s[56:57]
	s_andn2_b64 vcc, exec, s[8:9]
	v_readfirstlane_b32 s22, v154
	s_cbranch_vccnz .LBB0_1576
	s_sext_i32_i16 s7, s3
	s_bfe_u32 s7, s7, 0x3001c
	s_mov_b64 s[10:11], s[86:87]
	s_nop 4
	s_mov_b64 s[0:1], s[86:87]
	s_nop 4
	s_add_i32 s8, s3, s7
	s_and_b32 s7, s8, 0xfff8
	s_sub_i32 s7, s3, s7
	s_sext_i32_i16 s9, s7
	s_cmp_gt_i32 s9, -1
	s_sext_i32_i16 s17, s8
	s_cbranch_scc0 .LBB0_1549
	s_lshl_b32 s16, s7, 5
	s_mov_b64 s[14:15], 0
	s_branch .LBB0_1550

;     __host__ __device__ bool next(int i, Unit& u) const {
;         const long L = (long)i * G + c; if (L >= nwg) return false;
;         int wgid = (int)L; { const int q = nwg / NXCD, r = nwg % NXCD, xcd = wgid % NXCD, off = wgid / NXCD; wgid = (xcd < r ? xcd * (q + 1) : r * (q + 1) + (xcd - r) * q) + off; }
;         const int nig = WGM * nN, gid = wgid / nig, fm = gid * WGM, gsz = (nM - fm) < WGM ? (nM - fm) : WGM;
;         u.pm = fm + ((wgid % nig) % gsz); u.pn = (wgid % nig) / gsz; return true;
.LBB0_1550:
	s_mov_b64 s[8:9], s[86:87]
	s_nop 4
	s_andn2_b64 vcc, exec, s[14:15]
	s_lshr_b32 s14, s17, 3
	s_cbranch_vccnz .LBB0_1552
	s_mul_i32 s16, s7, 33

; #define LAS __attribute__((address_space(3)))
; template <class EpiS>
; __device__ __forceinline__ void sgemm_phase(LAS unsigned char* lds, const bf16* A, const bf16* Bt, int N, int K, const EpiS& E, int bidx, int nb) {
;     const int tid = threadIdx.x, lane = tid & 63, wave = __builtin_amdgcn_readfirstlane(tid >> 6), li = lane & 15, lq = lane >> 4;
;     const int ntask = (N >> 4) * 4, kper = K >> 3;
;     LAS float* red = (LAS float*)lds;
;     for (int task = bidx; task < ntask; task += nb) {
;         const int ct = task >> 2, rt = task & 3;
;         const bf16* ap0 = A + (size_t)(rt * 32 + li) * K + wave * kper + 8 * lq; const bf16* ap1 = ap0 + (size_t)16 * K;
;         const bf16* bp = Bt + (size_t)(ct * 16 + li) * K + wave * kper + 8 * lq;
; __global__ void __launch_bounds__(NWAVES * 64, 2) mega_fwd(Args args) {
;     ...
;         else if (!nfull) { { SStore ES{R4 + SOFF}; sgemm_phase(lds, PBUF + (size_t)MPROMPT * 256, WPLEP, 1024, 256, ES, (int)blockIdx.x, G); }
.LBB0_1577:
	s_cmpk_lt_i32 s2, 0x100
	s_mov_b64 s[0:1], s[56:57]
	s_mov_b64 s[10:11], s[56:57]
	s_mov_b64 s[12:13], s[56:57]
	v_readfirstlane_b32 s3, v154
	s_cselect_b64 s[8:9], -1, 0
	s_cmpk_gt_i32 s2, 0xff
	s_movk_i32 s6, 0x100
	s_cbranch_scc1 .LBB0_1580
	s_mov_b64 s[14:15], s[86:87]
	s_nop 4
	s_mov_b64 s[16:17], s[86:87]
	s_nop 4
	v_bfe_u32 v7, v154, 4, 2
	s_mov_b64 s[0:1], s[86:87]
	s_nop 4
	v_lshlrev_b32_e32 v0, 4, v7
	s_waitcnt lgkmcnt(0)
	s_add_u32 s10, s14, 0xedb0000
	s_addc_u32 s11, s15, 0
	s_and_b32 s7, s3, 0xffffffc0
	s_add_u32 s12, s16, s7
	s_addc_u32 s13, s17, 0
	s_add_u32 s0, s0, s7
	v_mov_b32_e32 v1, 0
	s_addc_u32 s1, s1, 0
	v_lshl_add_u64 v[4:5], s[0:1], 0, v[0:1]
	s_mov_b64 s[0:1], 0x2aa0000
	v_lshl_add_u64 v[4:5], v[4:5], 0, s[0:1]
	s_lshl_b32 s0, s3, 5
	s_and_b32 s0, s0, 0xfffff800
	v_lshl_add_u64 v[2:3], s[12:13], 0, v[0:1]
	s_add_i32 s0, s0, 0
	v_lshlrev_b32_e32 v0, 8, v7
	v_lshlrev_b32_e32 v8, 2, v156
	s_mov_b64 s[12:13], 0xf630000
	v_add3_u32 v8, s0, v0, v8
	v_lshrrev_b32_e32 v6, 4, v154
	v_lshl_add_u64 v[2:3], v[2:3], 0, s[12:13]
	v_lshl_add_u32 v7, v154, 2, 0
	s_lshl_b32 s0, s2, 2
	s_lshl_b32 s1, s88, 2
	s_lshl_b32 s3, s2, 5
	s_lshl_b32 s7, s88, 5
	v_add_u32_e32 v9, 0x400, v8
	s_mov_b32 s12, s2

; #define GEMM(EpiT, E, Aop, Bop, M_, N_, K_) do { int k_ = K_; asm volatile("" : "+s"(k_)); pg8::Gemm g_{Aop, Bop, M_, N_, k_}; pg8::StaticOrder S_; S_.init(M_, N_, G, (int)blockIdx.x); \
;         pg8::gemm_phase<EpiT, pg8::StaticOrder, true, true>(lds, g_, S_, E); } while (0)
;     __host__ __device__ bool next(int i, Unit& u) const {
;         const long L = (long)i * G + c; if (L >= nwg) return false;
;         int wgid = (int)L; { const int q = nwg / NXCD, r = nwg % NXCD, xcd = wgid % NXCD, off = wgid / NXCD; wgid = (xcd < r ? xcd * (q + 1) : r * (q + 1) + (xcd - r) * q) + off; }
;         const int nig = WGM * nN, gid = wgid / nig, fm = gid * WGM, gsz = (nM - fm) < WGM ? (nM - fm) : WGM;
;         u.pm = fm + ((wgid % nig) % gsz); u.pn = (wgid % nig) / gsz; return true;
; __global__ void __launch_bounds__(NWAVES * 64, 2) mega_fwd(Args args) {
;     ...
;             EpiStore E2{R4}; GEMM(EpiStore, E2, PBUF, WPLEP, MPROMPT, 1024, 256); } }
.LBB0_1580:
	s_mov_b64 s[0:1], s[56:57]
	s_mov_b64 s[14:15], s[56:57]
	s_mov_b64 s[16:17], s[56:57]
	s_andn2_b64 vcc, exec, s[8:9]
	v_readfirstlane_b32 s22, v154
	s_cbranch_vccnz .LBB0_1609
	s_ashr_i32 s3, s2, 31
	s_mov_b64 s[12:13], s[86:87]
	s_nop 4
	s_mov_b64 s[10:11], s[86:87]
	s_nop 4
	s_lshr_b32 s7, s3, 29
	s_add_i32 s7, s2, s7
	s_and_b32 s8, s7, -8
	s_sub_i32 s17, s2, s8
	s_cmp_gt_i32 s17, -1
	s_cbranch_scc0 .LBB0_1583
	s_lshl_b32 s16, s17, 5
	s_mov_b64 s[8:9], s[86:87]
	s_nop 4
	s_cbranch_execz .LBB0_1584
	s_branch .LBB0_1585

; #define LAS __attribute__((address_space(3)))
; template <class EpiS>
; __device__ __forceinline__ void sgemm_phase(LAS unsigned char* lds, const bf16* A, const bf16* Bt, int N, int K, const EpiS& E, int bidx, int nb) {
;     const int tid = threadIdx.x, lane = tid & 63, wave = __builtin_amdgcn_readfirstlane(tid >> 6), li = lane & 15, lq = lane >> 4;
;     const int ntask = (N >> 4) * 4, kper = K >> 3;
;     LAS float* red = (LAS float*)lds;
;     for (int task = bidx; task < ntask; task += nb) {
;         const int ct = task >> 2, rt = task & 3;
;         const bf16* ap0 = A + (size_t)(rt * 32 + li) * K + wave * kper + 8 * lq; const bf16* ap1 = ap0 + (size_t)16 * K;
;         const bf16* bp = Bt + (size_t)(ct * 16 + li) * K + wave * kper + 8 * lq;
; __global__ void __launch_bounds__(NWAVES * 64, 2) mega_fwd(Args args) {
;     ...
;     if (IN(14)) { { SResB ES{XB + SOFF, RES + SOFF, ALPHA, 0.5f}; sgemm_phase(lds, R0 + (size_t)MPROMPT * FF, WD, 1024, FF, ES, (int)blockIdx.x, G); }
.LBB0_1663:
	s_cmp_lt_i32 s64, 15
	s_cselect_b64 s[0:1], -1, 0
	s_and_b64 s[4:5], s[0:1], s[6:7]
	s_andn2_b64 vcc, exec, s[4:5]
	s_cbranch_vccnz .LBB0_1734
	s_cmpk_lt_i32 s2, 0x100
	s_mov_b64 s[0:1], s[56:57]
	s_mov_b64 s[6:7], s[56:57]
	s_mov_b64 s[12:13], s[56:57]
	s_mov_b64 s[10:11], s[56:57]
	s_cselect_b64 s[8:9], -1, 0
	s_cmpk_gt_i32 s2, 0xff
	v_readfirstlane_b32 s3, v154
	s_cbranch_scc1 .LBB0_1667
	s_mov_b64 s[14:15], s[86:87]
	s_nop 4
	s_load_dwordx2 s[16:17], s[6:7], 0x100
	s_mov_b64 s[18:19], s[86:87]
	s_nop 4
	s_mov_b32 s13, 0
	s_mov_b64 s[0:1], s[86:87]
	s_nop 4
	s_waitcnt lgkmcnt(0)
	s_add_u32 s6, s14, 0x4b30000
	s_addc_u32 s7, s15, 0
	s_add_u32 s10, s16, 0x4000000
	s_addc_u32 s11, s17, 0
	s_lshr_b32 s3, s3, 6
	s_mul_i32 s12, s3, 0x160
	s_lshl_b64 s[12:13], s[12:13], 1
	s_add_u32 s14, s18, s12
	s_addc_u32 s15, s19, s13
	v_bfe_u32 v7, v154, 4, 2
	s_add_u32 s0, s0, s12
	v_lshlrev_b32_e32 v0, 4, v7
	v_mov_b32_e32 v1, 0
	s_addc_u32 s1, s1, s13
	v_lshl_add_u64 v[4:5], s[0:1], 0, v[0:1]
	s_mov_b64 s[0:1], 0xb20000
	v_lshl_add_u64 v[4:5], v[4:5], 0, s[0:1]
	s_lshl_b32 s0, s3, 11
	v_lshl_add_u64 v[2:3], s[14:15], 0, v[0:1]
	s_add_i32 s0, s0, 0
	v_lshlrev_b32_e32 v0, 8, v7
	v_lshlrev_b32_e32 v8, 2, v156
	s_mov_b64 s[14:15], 0xa3b0000
	v_add3_u32 v8, s0, v0, v8
	s_mov_b32 s12, 0.5
	v_lshrrev_b32_e32 v6, 4, v154
	v_lshl_add_u64 v[2:3], v[2:3], 0, s[14:15]
	v_lshl_add_u32 v7, v154, 2, 0
	s_lshl_b32 s0, s2, 2
	s_lshl_b32 s1, s88, 2
	s_lshl_b32 s3, s2, 5
	s_lshl_b32 s14, s88, 5
	s_movk_i32 s15, 0x1600
	s_mov_b32 s13, 0x3f9837f0
	v_add_u32_e32 v9, 0x400, v8
	s_mov_b32 s16, s2

;     __host__ __device__ bool next(int i, Unit& u) const {
;         const long L = (long)i * G + c; if (L >= nwg) return false;
;         int wgid = (int)L; { const int q = nwg / NXCD, r = nwg % NXCD, xcd = wgid % NXCD, off = wgid / NXCD; wgid = (xcd < r ? xcd * (q + 1) : r * (q + 1) + (xcd - r) * q) + off; }
;         const int nig = WGM * nN, gid = wgid / nig, fm = gid * WGM, gsz = (nM - fm) < WGM ? (nM - fm) : WGM;
;         u.pm = fm + ((wgid % nig) % gsz); u.pn = (wgid % nig) / gsz; return true;
; template <class Epi, class Sched, bool ALIGN_EPI = false, bool SP2 = false>
; __device__ __forceinline__ void gemm_phase(PG8_LAS unsigned char* lds, const Gemm g, const Sched& S, const Epi& E) {
;     const int tid = threadIdx.x, wid = __builtin_amdgcn_readfirstlane(tid >> 6), lane = tid & 63, wr = wid >> 2, wc = wid & 3, fr = lane & 15, fq = lane >> 4;
;     const int K = g.K, nt = K / BK;
;     unsigned voffA[2], voffB[2];
; #pragma unroll
;     for (int i = 0; i < 2; ++i) { int R, C; stage_rc(tid * 16 + i * 8192, R, C); const int Rb = Epi::PERM ? ((R & ~31) + perm32(R & 31)) : R;
;         voffA[i] = (unsigned)(R * K + C) * 2u; voffB[i] = (unsigned)(Rb * K + C) * 2u; }
;     const size_t kstep = (size_t)(BK * 2);
;     const size_t hstep = (size_t)HALF * K * 2;
;     const size_t tstep = 2 * hstep;
;     const unsigned ldsw = (unsigned)wid * 1024u;
;     const int aoff = lds_byte(wr * 64 + fr, fq * 8), boff = lds_byte(wc * 32 + fr, fq * 8);
;     ...
;     Unit cur, nxt; int ui = 0;
;     if (!S.next(0, cur)) return;
.LBB0_1667:
	s_mov_b64 s[12:13], s[56:57]
	s_mov_b64 s[10:11], s[56:57]
	s_mov_b64 s[22:23], s[56:57]
	s_mov_b64 s[14:15], s[56:57]
	s_mov_b64 s[16:17], s[56:57]
	s_mov_b64 s[36:37], s[56:57]
	s_movk_i32 s6, 0xb00
	s_mov_b64 s[18:19], s[56:57]
	s_mov_b64 s[20:21], s[56:57]
	s_andn2_b64 vcc, exec, s[8:9]
	v_readfirstlane_b32 s3, v154
	s_cbranch_vccnz .LBB0_1734
	s_ashr_i32 s49, s2, 31
	s_mov_b64 s[8:9], s[86:87]
	s_nop 4
	s_mov_b64 s[0:1], s[86:87]
	s_nop 4
	s_lshr_b32 s7, s49, 29
	s_add_i32 s7, s2, s7
	s_and_b32 s18, s7, -8
	s_sub_i32 s21, s2, s18
	s_cmp_gt_i32 s21, -1
	s_cbranch_scc0 .LBB0_1670
	s_lshl_b32 s20, s21, 5
	s_cbranch_execz .LBB0_1671
	s_branch .LBB0_1672

; #define PG8_STAGE(bufoff, gbase, voff) do { _Pragma("unroll") for (int _i = 0; _i < 2; ++_i) \
;         __builtin_amdgcn_global_load_lds((const unsigned*)((const char*)(gbase) + (voff)[_i]), (PG8_LAS unsigned*)(lds + (bufoff) + ldsw + _i * 8192), 16, 0, 0); } while (0)
; #define PG8_WAIT_V(n) asm volatile("s_waitcnt vmcnt(" #n ")" ::: "memory")
; #define PG8_BAR __builtin_amdgcn_s_barrier()
; __device__ __forceinline__ const float* arg_in(int k) { return (const float*)(const __attribute__((address_space(1))) float*)arg_q(k); }
; #define GEMMF(EpiT, E, Aop, Bop, M_, N_, K_) do { int k_ = K_; asm volatile("" : "+s"(k_)); pg8::Gemm g_{Aop, Bop, M_, N_, k_}; pg8::StaticOrder S_; S_.init(M_, N_, G, (int)blockIdx.x); \
;         pg8::gemm_phase<EpiT, pg8::StaticOrder, false, true>(lds, g_, S_, E); } while (0)
; template <class Epi, class Sched, bool ALIGN_EPI = false, bool SP2 = false>
; __device__ __forceinline__ void gemm_phase(PG8_LAS unsigned char* lds, const Gemm g, const Sched& S, const Epi& E) {
;     ...
;     const char* cA = (const char*)g.A + (size_t)cur.pm * tstep; const char* cB = (const char*)g.Bt + (size_t)cur.pn * tstep;
;     S.a_ready(cur);
;     if constexpr (SP2) {
;         PG8_STAGE(PG8_SB(0, 0), cB, voffB); PG8_STAGE(PG8_SB(0, 1), cB + hstep, voffB); PG8_STAGE(PG8_SA(0, 0), cA, voffA); PG8_STAGE(PG8_SA(0, 1), cA + hstep, voffA);
;         if (wr == 1) PG8_BAR;
;         PG8_WAIT_V(2); PG8_BAR;
; __global__ void __launch_bounds__(NWAVES * 64, 2) mega_fwd(Args args) {
;     ...
;         EpiLn<1> E{nullptr, XB, nullptr, nullptr, arg_in(26), arg_in(27), 0.5f, PSTAT(2)}; GEMMF(EpiLn<1>, E, R0, WD, MPROMPT, 1024, FF); }
.LBB0_1672:
	s_ashr_i32 s18, s7, 3
	s_waitcnt lgkmcnt(0)
	s_add_u32 s50, s8, 0x4bb0000
	v_lshrrev_b32_e32 v149, 1, v154
	v_lshrrev_b32_e32 v4, 5, v154
	s_addc_u32 s51, s9, 0
	v_lshlrev_b32_e32 v0, 4, v154
	v_and_b32_e32 v1, 32, v154
	v_and_b32_e32 v3, 24, v149
	v_and_b32_e32 v4, 4, v4
	v_bfe_u32 v5, v154, 2, 2
	s_add_u32 s52, s0, 0xb20000
	v_bitop3_b32 v1, v0, v1, 48 bitop3:0x6c
	v_or3_b32 v3, v4, v5, v3
	v_lshrrev_b32_e32 v4, 3, v154
	s_movk_i32 s0, 0x60
	v_add_u32_e32 v0, 0x2000, v0
	v_and_b32_e32 v16, 0x70, v4
	v_and_or_b32 v4, v4, s0, v3
	v_lshrrev_b32_e32 v0, 7, v0
	s_movk_i32 s0, 0xe0
	s_addc_u32 s53, s1, 0
	v_and_b32_e32 v17, 0xf0, v0
	v_and_or_b32 v0, v0, s0, v3
	s_add_i32 s0, s20, s18
	s_ashr_i32 s1, s0, 31
	s_lshr_b32 s1, s1, 27
	s_add_i32 s1, s0, s1
	s_ashr_i32 s8, s1, 5
	s_andn2_b32 s1, s1, 31
	s_sub_i32 s0, s0, s1
	s_bfe_i32 s1, s0, 0x80000
	s_bfe_u32 s1, s1, 0x3000c
	s_add_i32 s1, s0, s1
	s_lshl_b32 s9, s8, 3
	s_bfe_i32 s8, s1, 0x80000
	s_and_b32 s1, s1, 0xf8
	s_sub_i32 s0, s0, s1
	s_sext_i32_i8 s0, s0
	s_ashr_i32 s7, s6, 31
	s_add_i32 s46, s9, s0
	s_lshl_b64 s[26:27], s[6:7], 9
	s_ashr_i32 s0, s46, 31
	s_mul_i32 s0, s26, s0
	s_mul_hi_u32 s1, s26, s46
	s_add_i32 s9, s1, s0
	s_lshr_b64 s[0:1], s[6:7], 23
	s_sext_i32_i16 s20, s8
	s_mul_i32 s1, s0, s46
	s_lshr_b32 s8, s20, 3
	s_add_i32 s9, s9, s1
	s_bfe_i64 s[18:19], s[8:9], 0x100000
	s_ashr_i32 s1, s20, 3
	s_mul_hi_u32 s18, s26, s1
	s_mul_i32 s19, s26, s19
	s_lshr_b32 s47, s3, 6
	s_add_i32 s18, s18, s19
	s_mul_i32 s0, s0, s1
	s_lshr_b32 s48, s3, 8
	v_and_b32_e32 v14, 64, v154
	s_lshl_b64 s[24:25], s[6:7], 8
	s_lshl_b32 s54, s47, 10
	s_add_i32 s18, s18, s0
	s_mul_i32 s0, s26, s1
	v_or_b32_e32 v2, v1, v14
	s_add_u32 s28, s52, s0
	v_lshrrev_b32_e32 v2, 1, v2
	v_mul_lo_u32 v4, s6, v4
	s_addc_u32 s29, s53, s18
	s_add_i32 s55, s54, 0
	v_add_lshl_u32 v134, v4, v2, 1
	s_add_i32 m0, s55, 0x10000
	v_mul_lo_u32 v0, s6, v0
	global_load_lds_dwordx4 v134, s[28:29]
	s_add_i32 m0, s55, 0x12000
	v_add_lshl_u32 v138, v0, v2, 1
	s_add_u32 s0, s28, s24
	global_load_lds_dwordx4 v138, s[28:29]
	s_addc_u32 s1, s29, s25
	s_add_i32 m0, s55, 0x14000
	v_bfe_u32 v15, v154, 2, 4
	s_mul_i32 s21, s26, s46
	global_load_lds_dwordx4 v134, s[0:1]
	s_add_i32 m0, s55, 0x16000
	v_or_b32_e32 v5, v16, v15
	s_add_u32 s34, s50, s21
	v_mul_lo_u32 v5, s6, v5
	v_or_b32_e32 v4, v17, v15
	s_addc_u32 s35, s51, s9
	s_add_i32 s58, s55, 0x2000
	v_add_lshl_u32 v132, v5, v2, 1
	v_mul_lo_u32 v3, s6, v4
	global_load_lds_dwordx4 v138, s[0:1]
	s_mov_b32 m0, s55
	s_add_u32 s18, s34, s24
	v_add_lshl_u32 v136, v3, v2, 1
	global_load_lds_dwordx4 v132, s[34:35]
	s_mov_b32 m0, s58
	s_addc_u32 s19, s35, s25
	s_add_i32 s59, s55, 0x4000
	global_load_lds_dwordx4 v136, s[34:35]
	s_mov_b32 m0, s59
	s_add_i32 s60, s55, 0x6000
	global_load_lds_dwordx4 v132, s[18:19]
	s_mov_b32 m0, s60
	v_mov_b32_e32 v0, 0
	global_load_lds_dwordx4 v136, s[18:19]
	s_mov_b64 s[30:31], s[86:87]
	s_nop 4
	s_mov_b64 s[20:21], s[86:87]
	s_nop 4
	s_mov_b64 s[18:19], s[86:87]
	s_nop 4
	s_nop 0
	s_mov_b64 s[16:17], s[86:87]
	s_nop 4
	s_load_dwordx2 s[14:15], s[10:11], 0xd0
	s_load_dwordx2 s[12:13], s[22:23], 0xd8
	v_mov_b32_e32 v135, v0
	v_mov_b32_e32 v139, v0
	v_mov_b32_e32 v133, v0
	v_mov_b32_e32 v137, v0
	v_lshl_add_u64 v[12:13], s[28:29], 0, v[134:135]
	v_lshl_add_u64 v[8:9], s[28:29], 0, v[138:139]
	v_lshl_add_u64 v[4:5], s[0:1], 0, v[134:135]
	v_lshl_add_u64 v[2:3], s[0:1], 0, v[138:139]
	v_lshl_add_u64 v[10:11], s[34:35], 0, v[132:133]
	s_cmp_lg_u32 s48, 1
	v_lshl_add_u64 v[6:7], s[34:35], 0, v[136:137]
	s_cbranch_scc1 .LBB0_1674
	s_barrier

; #define LAS __attribute__((address_space(3)))
; __device__ __forceinline__ const float* arg_in(int k) { return (const float*)(const __attribute__((address_space(1))) float*)arg_q(k); }
; template <bool WRITE_BF16, bool DO_BA, bool WRITE_F32>
; __device__ __forceinline__ void ln_phase(int m_lo, float* RES, const float* g, const float* b, bf16* XB, const LAS float* wba, const float* A_log, const float* dt_bias, float* BETA, float* GG, int gw, int NGW, int lane) {
;     f32x4 gv[4], bv[4];
; #pragma unroll
;     for (int j = 0; j < 4; ++j) { gv[j] = *((const f32x4*)g + 64 * j + lane); bv[j] = *((const f32x4*)b + 64 * j + lane); }
;     for (int m = m_lo + gw; m < MREAL; m += NGW) {
;         f32x4* xr = (f32x4*)(RES + (size_t)m * D) + lane;
;         f32x4 v[4]; float s = 0.f;
; #pragma unroll
;         for (int j = 0; j < 4; ++j) { v[j] = xr[64 * j]; s += (v[j][0] + v[j][1]) + (v[j][2] + v[j][3]); }
;         const float mean = wave_sum(s) * (1.f / D); float s2 = 0.f;
; #pragma unroll
;         for (int j = 0; j < 4; ++j) { v[j] = v[j] - mean; s2 += (v[j][0] * v[j][0] + v[j][1] * v[j][1]) + (v[j][2] * v[j][2] + v[j][3] * v[j][3]); }
;         const float rstd = 1.f / sqrtf(wave_sum(s2) * (1.f / D) + 1e-5f);
; #pragma unroll
;         for (int j = 0; j < 4; ++j) { v[j] = v[j] * rstd * gv[j] + bv[j]; if (WRITE_F32) xr[64 * j] = v[j]; }
;         if (WRITE_BF16) {
;             u32x2* o8 = (u32x2*)(XB + (size_t)m * D) + lane;
; #pragma unroll
;             for (int j = 0; j < 4; ++j) { u32x2 w; w.x = cvt_pk_bf16(v[j][0], v[j][1]); w.y = cvt_pk_bf16(v[j][2], v[j][3]); o8[64 * j] = w; }
;         }
; __global__ void __launch_bounds__(NWAVES * 64, 2) mega_fwd(Args args) {
;     ...
;     if (IN(15)) ln_phase<true, false, false>(MPROMPT, RES, arg_in(26), arg_in(27), XB, nullptr, nullptr, nullptr, nullptr, nullptr, gw, NGW, lane);
.LBB0_1788:
	s_cmp_lt_i32 s64, 16
	s_cselect_b64 s[0:1], -1, 0
	s_and_b64 s[4:5], s[0:1], s[6:7]
	s_andn2_b64 vcc, exec, s[4:5]
	s_cbranch_vccnz .LBB0_1792
	s_mov_b64 s[0:1], s[56:57]
	s_mov_b64 s[8:9], s[56:57]
	s_mov_b64 s[10:11], s[56:57]
	s_mov_b64 s[6:7], s[56:57]
	s_cmpk_gt_i32 s94, 0x7f
	s_cbranch_scc1 .LBB0_1792
	s_load_dwordx2 s[12:13], s[10:11], 0xd8
	s_load_dwordx2 s[14:15], s[8:9], 0xd0
	v_lshlrev_b32_e32 v32, 4, v152
	v_mbcnt_lo_u32_b32 v34, -1, 0
	v_mbcnt_hi_u32_b32 v34, -1, v34
	v_and_b32_e32 v35, 64, v34
	s_waitcnt lgkmcnt(0)
	global_load_dwordx4 v[0:3], v32, s[12:13]
	global_load_dwordx4 v[4:7], v32, s[12:13] offset:1024
	global_load_dwordx4 v[8:11], v32, s[14:15] offset:2048
	global_load_dwordx4 v[12:15], v32, s[14:15] offset:3072
	global_load_dwordx4 v[16:19], v32, s[12:13] offset:2048
	global_load_dwordx4 v[20:23], v32, s[12:13] offset:3072
	global_load_dwordx4 v[24:27], v32, s[14:15] offset:1024
	global_load_dwordx4 v[28:31], v32, s[14:15]
	v_add_u32_e32 v35, 64, v35
	v_xor_b32_e32 v36, 1, v34
	v_cmp_lt_i32_e32 vcc, v36, v35
	s_mov_b64 s[6:7], s[86:87]
	s_nop 4
	s_add_i32 s8, s94, 0x4000
	v_cndmask_b32_e32 v36, v34, v36, vcc
	v_lshlrev_b32_e32 v52, 2, v36
	v_xor_b32_e32 v36, 2, v34
	v_cmp_lt_i32_e32 vcc, v36, v35
	s_ashr_i32 s9, s8, 31
	s_load_dwordx2 s[0:1], s[0:1], 0x100
	v_cndmask_b32_e32 v36, v34, v36, vcc
	v_lshlrev_b32_e32 v53, 2, v36
	v_xor_b32_e32 v36, 4, v34
	v_cmp_lt_i32_e32 vcc, v36, v35
	s_lshl_b64 s[10:11], s[8:9], 11
	v_mov_b32_e32 v33, 0
	v_cndmask_b32_e32 v36, v34, v36, vcc
	v_lshlrev_b32_e32 v54, 2, v36
	v_xor_b32_e32 v36, 8, v34
	v_cmp_lt_i32_e32 vcc, v36, v35
	s_waitcnt lgkmcnt(0)
	s_add_u32 s6, s6, s10
	s_addc_u32 s7, s7, s11
	v_cndmask_b32_e32 v36, v34, v36, vcc
	v_lshlrev_b32_e32 v55, 2, v36
	v_xor_b32_e32 v36, 16, v34
	v_cmp_lt_i32_e32 vcc, v36, v35
	s_ashr_i32 s79, s78, 31
	s_lshl_b64 s[10:11], s[78:79], 11
	v_cndmask_b32_e32 v36, v34, v36, vcc
	v_lshlrev_b32_e32 v56, 2, v36
	v_xor_b32_e32 v36, 32, v34
	v_cmp_lt_i32_e32 vcc, v36, v35
	v_mov_b32_e32 v35, v33
	v_mov_b32_e32 v58, 0x3727c5ac
	v_cndmask_b32_e32 v34, v34, v36, vcc
	v_lshlrev_b32_e32 v57, 2, v34
	v_lshlrev_b32_e32 v34, 3, v152
	v_lshl_add_u64 v[34:35], s[6:7], 0, v[34:35]
	s_mov_b64 s[6:7], 0x2b30000
	v_lshl_add_u64 v[48:49], v[34:35], 0, s[6:7]
	s_lshl_b64 s[6:7], s[8:9], 12
	s_add_u32 s0, s0, s6
	s_addc_u32 s1, s1, s7
	v_lshl_add_u64 v[32:33], s[0:1], 0, v[32:33]
	s_mov_b64 s[0:1], 0xc00
	v_lshl_add_u64 v[50:51], v[32:33], 0, s[0:1]
	s_lshl_b64 s[12:13], s[78:79], 12
	s_mov_b32 s0, 0xf800000
	v_mov_b32_e32 v59, 0x260

; #define LAS __attribute__((address_space(3)))
; template <class EpiS>
; __device__ __forceinline__ void sgemm_phase(LAS unsigned char* lds, const bf16* A, const bf16* Bt, int N, int K, const EpiS& E, int bidx, int nb) {
;     const int tid = threadIdx.x, lane = tid & 63, wave = __builtin_amdgcn_readfirstlane(tid >> 6), li = lane & 15, lq = lane >> 4;
;     const int ntask = (N >> 4) * 4, kper = K >> 3;
;     LAS float* red = (LAS float*)lds;
;     for (int task = bidx; task < ntask; task += nb) {
;         const int ct = task >> 2, rt = task & 3;
;         const bf16* ap0 = A + (size_t)(rt * 32 + li) * K + wave * kper + 8 * lq; const bf16* ap1 = ap0 + (size_t)16 * K;
;         const bf16* bp = Bt + (size_t)(ct * 16 + li) * K + wave * kper + 8 * lq;
; __global__ void __launch_bounds__(NWAVES * 64, 2) mega_fwd(Args args) {
;     ...
;     if (IN(17)) { { SPle ES{RES + SOFF, R4 + SOFF, XB + SOFF}; sgemm_phase(lds, XB + SOFF, WPLEG, 1024, 1024, ES, (int)blockIdx.x, G); }
.LBB0_1846:
	s_cmp_lt_i32 s64, 18
	s_cselect_b64 s[0:1], -1, 0
	s_cmp_gt_i32 s65, 17
	s_cselect_b64 s[4:5], -1, 0
	s_and_b64 s[4:5], s[0:1], s[4:5]
	s_andn2_b64 vcc, exec, s[4:5]
	s_cbranch_vccnz .LBB0_1917
	s_cmpk_lt_i32 s2, 0x100
	s_mov_b64 s[6:7], s[56:57]
	s_mov_b64 s[10:11], s[56:57]
	s_mov_b64 s[12:13], s[56:57]
	s_mov_b64 s[0:1], s[56:57]
	s_mov_b64 s[14:15], s[56:57]
	s_cselect_b64 s[8:9], -1, 0
	s_cmpk_gt_i32 s2, 0xff
	v_readfirstlane_b32 s3, v154
	s_cbranch_scc1 .LBB0_1850
	s_load_dwordx2 s[16:17], s[6:7], 0x100
	s_mov_b64 s[18:19], s[86:87]
	s_nop 4
	s_mov_b64 s[20:21], s[86:87]
	s_nop 4
	v_bfe_u32 v6, v154, 4, 2
	s_mov_b64 s[0:1], s[86:87]
	s_nop 4
	s_waitcnt lgkmcnt(0)
	s_add_u32 s6, s16, 0x4000000
	s_addc_u32 s7, s17, 0
	s_add_u32 s10, s18, 0xedb0000
	s_addc_u32 s11, s19, 0
	s_add_u32 s12, s20, 0x4b30000
	s_mov_b64 s[14:15], s[86:87]
	s_nop 4
	s_addc_u32 s13, s21, 0
	s_lshr_b32 s3, s3, 6
	s_lshl_b32 s16, s3, 8
	s_add_u32 s0, s0, s16
	s_addc_u32 s1, s1, 0
	v_lshlrev_b32_e32 v0, 4, v6
	v_mov_b32_e32 v1, 0
	v_lshl_add_u64 v[2:3], s[0:1], 0, v[0:1]
	s_waitcnt lgkmcnt(0)
	s_add_u32 s0, s14, s16
	s_addc_u32 s1, s15, 0
	v_lshl_add_u64 v[4:5], s[0:1], 0, v[0:1]
	s_mov_b64 s[0:1], 0x28a0000
	v_lshl_add_u64 v[4:5], v[4:5], 0, s[0:1]
	s_lshl_b32 s0, s3, 11
	s_add_i32 s0, s0, 0
	v_lshlrev_b32_e32 v0, 8, v6
	v_lshlrev_b32_e32 v6, 2, v156
	s_mov_b64 s[22:23], 0x4b30000
	v_add3_u32 v10, s0, v0, v6
	v_lshrrev_b32_e32 v8, 4, v154
	v_lshl_add_u64 v[2:3], v[2:3], 0, s[22:23]
	v_lshl_add_u32 v9, v154, 2, 0
	s_lshl_b32 s0, s2, 2
	s_lshl_b32 s1, s88, 2
	s_lshl_b32 s3, s2, 5
	s_lshl_b32 s14, s88, 5
	v_mov_b32_e32 v6, 0x3f9837f0
	v_add_u32_e32 v11, 0x400, v10
	s_mov_b32 s15, s2

;     __host__ __device__ bool next(int i, Unit& u) const {
;         const long L = (long)i * G + c; if (L >= nwg) return false;
;         int wgid = (int)L; { const int q = nwg / NXCD, r = nwg % NXCD, xcd = wgid % NXCD, off = wgid / NXCD; wgid = (xcd < r ? xcd * (q + 1) : r * (q + 1) + (xcd - r) * q) + off; }
;         const int nig = WGM * nN, gid = wgid / nig, fm = gid * WGM, gsz = (nM - fm) < WGM ? (nM - fm) : WGM;
;         u.pm = fm + ((wgid % nig) % gsz); u.pn = (wgid % nig) / gsz; return true;
; template <class Epi, class Sched, bool ALIGN_EPI = false, bool SP2 = false>
; __device__ __forceinline__ void gemm_phase(PG8_LAS unsigned char* lds, const Gemm g, const Sched& S, const Epi& E) {
;     const int tid = threadIdx.x, wid = __builtin_amdgcn_readfirstlane(tid >> 6), lane = tid & 63, wr = wid >> 2, wc = wid & 3, fr = lane & 15, fq = lane >> 4;
;     const int K = g.K, nt = K / BK;
;     unsigned voffA[2], voffB[2];
; #pragma unroll
;     for (int i = 0; i < 2; ++i) { int R, C; stage_rc(tid * 16 + i * 8192, R, C); const int Rb = Epi::PERM ? ((R & ~31) + perm32(R & 31)) : R;
;         voffA[i] = (unsigned)(R * K + C) * 2u; voffB[i] = (unsigned)(Rb * K + C) * 2u; }
;     const size_t kstep = (size_t)(BK * 2);
;     const size_t hstep = (size_t)HALF * K * 2;
;     const size_t tstep = 2 * hstep;
;     const unsigned ldsw = (unsigned)wid * 1024u;
;     const int aoff = lds_byte(wr * 64 + fr, fq * 8), boff = lds_byte(wc * 32 + fr, fq * 8);
;     ...
;     Unit cur, nxt; int ui = 0;
;     if (!S.next(0, cur)) return;
.LBB0_1850:
	s_mov_b64 s[10:11], s[56:57]
	s_mov_b64 s[14:15], s[56:57]
	s_mov_b64 s[12:13], s[56:57]
	s_mov_b64 s[16:17], s[56:57]
	s_mov_b64 s[24:25], s[56:57]
	s_mov_b64 s[18:19], s[56:57]
	s_mov_b64 s[20:21], s[56:57]
	s_mov_b64 s[40:41], s[56:57]
	s_movk_i32 s6, 0x400
	s_mov_b64 s[22:23], s[56:57]
	s_mov_b64 s[26:27], s[56:57]
	s_andn2_b64 vcc, exec, s[8:9]
	v_readfirstlane_b32 s50, v154
	s_cbranch_vccnz .LBB0_1917
	s_ashr_i32 s53, s2, 31
	s_mov_b64 s[8:9], s[86:87]
	s_nop 4
	s_mov_b64 s[0:1], s[86:87]
	s_nop 4
	s_lshr_b32 s3, s53, 29
	s_add_i32 s7, s2, s3
	s_and_b32 s3, s7, -8
	s_sub_i32 s3, s2, s3
	s_cmp_gt_i32 s3, -1
	s_cbranch_scc0 .LBB0_1853
	s_lshl_b32 s30, s3, 5
	s_ashr_i32 s22, s7, 3
	s_cbranch_execz .LBB0_1854
	s_branch .LBB0_1855

; #define PG8_STAGE(bufoff, gbase, voff) do { _Pragma("unroll") for (int _i = 0; _i < 2; ++_i) \
;         __builtin_amdgcn_global_load_lds((const unsigned*)((const char*)(gbase) + (voff)[_i]), (PG8_LAS unsigned*)(lds + (bufoff) + ldsw + _i * 8192), 16, 0, 0); } while (0)
; #define PG8_WAIT_V(n) asm volatile("s_waitcnt vmcnt(" #n ")" ::: "memory")
; #define PG8_BAR __builtin_amdgcn_s_barrier()
; __device__ __forceinline__ const float* arg_in(int k) { return (const float*)(const __attribute__((address_space(1))) float*)arg_q(k); }
; #define GEMMF(EpiT, E, Aop, Bop, M_, N_, K_) do { int k_ = K_; asm volatile("" : "+s"(k_)); pg8::Gemm g_{Aop, Bop, M_, N_, k_}; pg8::StaticOrder S_; S_.init(M_, N_, G, (int)blockIdx.x); \
;         pg8::gemm_phase<EpiT, pg8::StaticOrder, false, true>(lds, g_, S_, E); } while (0)
; template <class Epi, class Sched, bool ALIGN_EPI = false, bool SP2 = false>
; __device__ __forceinline__ void gemm_phase(PG8_LAS unsigned char* lds, const Gemm g, const Sched& S, const Epi& E) {
;     ...
;     const char* cA = (const char*)g.A + (size_t)cur.pm * tstep; const char* cB = (const char*)g.Bt + (size_t)cur.pn * tstep;
;     S.a_ready(cur);
;     if constexpr (SP2) {
;         PG8_STAGE(PG8_SB(0, 0), cB, voffB); PG8_STAGE(PG8_SB(0, 1), cB + hstep, voffB); PG8_STAGE(PG8_SA(0, 0), cA, voffA); PG8_STAGE(PG8_SA(0, 1), cA + hstep, voffA);
;         if (wr == 1) PG8_BAR;
;         PG8_WAIT_V(2); PG8_BAR;
; __global__ void __launch_bounds__(NWAVES * 64, 2) mega_fwd(Args args) {
;     ...
;         EpiLn<2> E{nullptr, XB, R4, RES, arg_in(30), arg_in(31), 1.0f, PSTAT(3)}; GEMMF(EpiLn<2>, E, XB, WPLEG, MPROMPT, 1024, 1024); }
.LBB0_1855:
	s_waitcnt lgkmcnt(0)
	s_add_u32 s54, s8, 0x2b30000
	v_lshrrev_b32_e32 v149, 1, v154
	v_lshrrev_b32_e32 v4, 5, v154
	s_addc_u32 s55, s9, 0
	v_lshlrev_b32_e32 v0, 4, v154
	v_and_b32_e32 v1, 32, v154
	v_and_b32_e32 v3, 24, v149
	v_and_b32_e32 v4, 4, v4
	v_bfe_u32 v5, v154, 2, 2
	s_add_u32 s58, s0, 0x28a0000
	v_bitop3_b32 v1, v0, v1, 48 bitop3:0x6c
	v_or3_b32 v3, v4, v5, v3
	v_lshrrev_b32_e32 v4, 3, v154
	s_movk_i32 s0, 0x60
	v_add_u32_e32 v0, 0x2000, v0
	v_and_b32_e32 v16, 0x70, v4
	v_and_or_b32 v4, v4, s0, v3
	v_lshrrev_b32_e32 v0, 7, v0
	s_movk_i32 s0, 0xe0
	s_addc_u32 s59, s1, 0
	v_and_b32_e32 v17, 0xf0, v0
	v_and_or_b32 v0, v0, s0, v3
	s_add_i32 s0, s30, s22
	s_ashr_i32 s1, s0, 31
	s_lshr_b32 s1, s1, 27
	s_add_i32 s1, s0, s1
	s_ashr_i32 s8, s1, 5
	s_and_b32 s1, s1, 0xffe0
	s_sub_i32 s0, s0, s1
	s_bfe_i32 s1, s0, 0x80000
	s_bfe_u32 s1, s1, 0x3000c
	s_add_i32 s1, s0, s1
	s_lshl_b32 s9, s8, 3
	s_bfe_i32 s8, s1, 0x80000
	s_and_b32 s1, s1, 0xf8
	s_sub_i32 s0, s0, s1
	s_sext_i32_i8 s0, s0
	s_ashr_i32 s7, s6, 31
	s_add_i32 s51, s9, s0
	s_lshl_b64 s[28:29], s[6:7], 9
	s_ashr_i32 s0, s51, 31
	s_mul_i32 s0, s28, s0
	s_mul_hi_u32 s1, s28, s51
	s_add_i32 s9, s1, s0
	s_lshr_b64 s[0:1], s[6:7], 23
	s_sext_i32_i16 s30, s8
	s_mul_i32 s1, s0, s51
	s_lshr_b32 s8, s30, 3
	s_add_i32 s9, s9, s1
	s_bfe_i64 s[22:23], s[8:9], 0x100000
	s_ashr_i32 s1, s30, 3
	s_mul_hi_u32 s22, s28, s1
	s_mul_i32 s23, s28, s23
	s_lshr_b32 s3, s50, 6
	s_add_i32 s22, s22, s23
	s_mul_i32 s0, s0, s1
	s_lshr_b32 s52, s50, 8
	v_and_b32_e32 v14, 64, v154
	s_lshl_b64 s[26:27], s[6:7], 8
	s_lshl_b32 s60, s3, 10
	s_add_i32 s22, s22, s0
	s_mul_i32 s0, s28, s1
	v_or_b32_e32 v2, v1, v14
	s_add_u32 s30, s58, s0
	v_lshrrev_b32_e32 v2, 1, v2
	v_mul_lo_u32 v4, s6, v4
	s_addc_u32 s31, s59, s22
	s_add_i32 s61, s60, 0
	v_add_lshl_u32 v134, v4, v2, 1
	s_add_i32 m0, s61, 0x10000
	v_mul_lo_u32 v0, s6, v0
	global_load_lds_dwordx4 v134, s[30:31]
	s_add_i32 m0, s61, 0x12000
	v_add_lshl_u32 v138, v0, v2, 1
	s_add_u32 s0, s30, s26
	global_load_lds_dwordx4 v138, s[30:31]
	s_addc_u32 s1, s31, s27
	s_add_i32 m0, s61, 0x14000
	v_bfe_u32 v15, v154, 2, 4
	s_mul_i32 s34, s28, s51
	global_load_lds_dwordx4 v134, s[0:1]
	s_add_i32 m0, s61, 0x16000
	v_or_b32_e32 v5, v16, v15
	s_add_u32 s38, s54, s34
	v_mul_lo_u32 v5, s6, v5
	v_or_b32_e32 v4, v17, v15
	s_addc_u32 s39, s55, s9
	s_add_i32 s62, s61, 0x2000
	v_add_lshl_u32 v132, v5, v2, 1
	v_mul_lo_u32 v3, s6, v4
	global_load_lds_dwordx4 v138, s[0:1]
	s_mov_b32 m0, s61
	s_add_u32 s22, s38, s26
	v_add_lshl_u32 v136, v3, v2, 1
	global_load_lds_dwordx4 v132, s[38:39]
	s_mov_b32 m0, s62
	s_addc_u32 s23, s39, s27
	s_add_i32 s63, s61, 0x4000
	global_load_lds_dwordx4 v136, s[38:39]
	s_mov_b32 m0, s63
	s_add_i32 s64, s61, 0x6000
	global_load_lds_dwordx4 v132, s[22:23]
	s_mov_b32 m0, s64
	v_mov_b32_e32 v0, 0
	global_load_lds_dwordx4 v136, s[22:23]
	s_mov_b64 s[36:37], s[86:87]
	s_nop 4
	s_mov_b64 s[34:35], s[86:87]
	s_nop 4
	s_mov_b64 s[22:23], s[86:87]
	s_nop 4
	s_nop 0
	s_mov_b64 s[20:21], s[86:87]
	s_nop 4
	s_nop 0
	s_mov_b64 s[18:19], s[86:87]
	s_nop 4
	s_nop 0
	s_load_dwordx2 s[12:13], s[12:13], 0x100
	s_nop 0
	s_load_dwordx2 s[16:17], s[16:17], 0xf0
	s_nop 0
	s_load_dwordx2 s[14:15], s[24:25], 0xf8
	v_mov_b32_e32 v135, v0
	v_mov_b32_e32 v139, v0
	v_mov_b32_e32 v133, v0
	v_mov_b32_e32 v137, v0
	v_lshl_add_u64 v[12:13], s[30:31], 0, v[134:135]
	v_lshl_add_u64 v[8:9], s[30:31], 0, v[138:139]
	v_lshl_add_u64 v[4:5], s[0:1], 0, v[134:135]
	v_lshl_add_u64 v[2:3], s[0:1], 0, v[138:139]
	v_lshl_add_u64 v[10:11], s[38:39], 0, v[132:133]
	s_cmp_lg_u32 s52, 1
	v_lshl_add_u64 v[6:7], s[38:39], 0, v[136:137]
	s_cbranch_scc1 .LBB0_1857
	s_barrier
